# GEMM K-loops: raised priority moved from the MFMA segments to the LDS-read / LDS-DMA segments
# speedup vs baseline: 1.0024x; 1.0024x over previous
; #define WAIT_V(n) asm volatile("s_waitcnt vmcnt(" #n ")" ::: "memory")
; #define WAIT_L(n) asm volatile("s_waitcnt lgkmcnt(" #n ")" ::: "memory")
; #define BAR __builtin_amdgcn_s_barrier()
; #define SCHED __builtin_amdgcn_sched_barrier(0)
; template <class Get, class Epi>
; DI void gemm_stream(LAS unsigned char* lds, const int K, const int ld, Get get, Epi epi) {
;     ...
;         for (int t = 0; t < nt; t += 2) {
;             const bool last = (t == nt - 2);
;             const char* a1 = cA + (size_t)(t + 1) * kstep;
;             const char* a2 = last ? nA : cA + (size_t)(t + 2) * kstep;
;             const char* b2 = last ? nB : cB + (size_t)(t + 2) * kstep;
;             const char* a3 = a2 + kstep;
;             const char* b3 = b2 + kstep;
;             LDB(B0, 0, 0); SCHED; LDA(At, 0, 0); STAGE(SAo(1, 1), a1 + hstep);
;             WAIT_L(8); BAR; WAIT_L(0); MMA(0, 0, At, B0); BAR; SCHED;
;             LDB(B1, 0, 1); STAGE(SBo(0, 0), b2);
;             BAR; WAIT_L(0); MMA(0, 1, At, B1); BAR;
;             LDA(At, 0, 1); STAGE(SAo(0, 0), a2);
;             BAR; WAIT_L(0); MMA(1, 0, At, B0); BAR; SCHED;
;             STAGE(SBo(0, 1), b2 + hstep);
;             WAIT_V(6); BAR; MMA(1, 1, At, B1); BAR;
.LBB0_726:
	ds_read_b128 v[128:131], v167
	ds_read_b128 v[132:135], v167 offset:1024
	ds_read_b128 v[136:139], v167 offset:2048
	ds_read_b128 v[154:157], v167 offset:3072
	s_add_u32 s6, s4, 0xfff80080
	s_addc_u32 s7, s5, -1
	s_cmp_eq_u32 vcc_lo, 28
	s_cselect_b32 s63, s59, s7
	s_cselect_b32 s62, s58, s6
	s_cselect_b32 s7, s61, s55
	s_cselect_b32 s6, s60, s29
	v_lshl_add_u64 v[140:141], s[4:5], 0, v[148:149]
	s_add_i32 m0, s74, 0xc000
	ds_read_b128 v[158:161], v168
	ds_read_b128 v[162:165], v168 offset:1024
	ds_read_b128 v[170:173], v168 offset:2048
	ds_read_b128 v[174:177], v168 offset:3072
	ds_read_b128 v[178:181], v168 offset:4096
	ds_read_b128 v[182:185], v168 offset:5120
	ds_read_b128 v[186:189], v168 offset:6144
	ds_read_b128 v[190:193], v168 offset:7168
	global_load_lds_dwordx4 v[140:141], off
	v_lshl_add_u64 v[140:141], s[4:5], 0, v[150:151]
	s_add_i32 m0, s74, 0xe000
	s_nop 0
	global_load_lds_dwordx4 v[140:141], off
	s_waitcnt lgkmcnt(8)
	s_barrier
	s_waitcnt lgkmcnt(0)
	s_setprio 0
	s_waitcnt lgkmcnt(0)
	v_mfma_f32_16x16x32_bf16 v[124:127], v[128:131], v[158:161], v[124:127]
	v_mfma_f32_16x16x32_bf16 v[120:123], v[136:139], v[158:161], v[120:123]
	v_mfma_f32_16x16x32_bf16 v[112:115], v[128:131], v[170:173], v[112:115]
	v_mfma_f32_16x16x32_bf16 v[108:111], v[136:139], v[170:173], v[108:111]
	v_mfma_f32_16x16x32_bf16 v[100:103], v[128:131], v[178:181], v[100:103]
	v_mfma_f32_16x16x32_bf16 v[92:95], v[136:139], v[178:181], v[92:95]
	v_mfma_f32_16x16x32_bf16 v[84:87], v[128:131], v[186:189], v[84:87]
	v_mfma_f32_16x16x32_bf16 v[76:79], v[136:139], v[186:189], v[76:79]
	v_mfma_f32_16x16x32_bf16 v[124:127], v[132:135], v[162:165], v[124:127]
	v_mfma_f32_16x16x32_bf16 v[120:123], v[154:157], v[162:165], v[120:123]
	v_mfma_f32_16x16x32_bf16 v[112:115], v[132:135], v[174:177], v[112:115]
	v_mfma_f32_16x16x32_bf16 v[108:111], v[154:157], v[174:177], v[108:111]
	v_mfma_f32_16x16x32_bf16 v[100:103], v[132:135], v[182:185], v[100:103]
	v_mfma_f32_16x16x32_bf16 v[92:95], v[154:157], v[182:185], v[92:95]
	v_mfma_f32_16x16x32_bf16 v[84:87], v[132:135], v[190:193], v[84:87]
	v_mfma_f32_16x16x32_bf16 v[76:79], v[154:157], v[190:193], v[76:79]
	s_setprio 1
	s_barrier
	s_add_i32 s86, s85, s35
	v_lshl_add_u64 v[140:141], s[6:7], 0, v[142:143]
	s_mov_b32 m0, s86
	ds_read_b128 v[194:197], v169
	ds_read_b128 v[198:201], v169 offset:1024
	ds_read_b128 v[202:205], v169 offset:2048
	ds_read_b128 v[208:211], v169 offset:3072
	global_load_lds_dwordx4 v[140:141], off
	v_lshl_add_u64 v[212:213], s[6:7], 0, v[144:145]
	s_add_i32 m0, s86, 0x2000
	s_nop 0
	global_load_lds_dwordx4 v[212:213], off
	s_barrier
	s_waitcnt lgkmcnt(0)
	s_setprio 0
	s_waitcnt lgkmcnt(0)
	v_mfma_f32_16x16x32_bf16 v[116:119], v[194:197], v[158:161], v[116:119]
	v_mfma_f32_16x16x32_bf16 v[104:107], v[202:205], v[158:161], v[104:107]
	v_mfma_f32_16x16x32_bf16 v[96:99], v[194:197], v[170:173], v[96:99]
	v_mfma_f32_16x16x32_bf16 v[88:91], v[202:205], v[170:173], v[88:91]
	v_mfma_f32_16x16x32_bf16 v[80:83], v[194:197], v[178:181], v[80:83]
	v_mfma_f32_16x16x32_bf16 v[72:75], v[202:205], v[178:181], v[72:75]
	v_mfma_f32_16x16x32_bf16 v[68:71], v[194:197], v[186:189], v[68:71]
	v_mfma_f32_16x16x32_bf16 v[64:67], v[202:205], v[186:189], v[64:67]
	v_mfma_f32_16x16x32_bf16 v[116:119], v[198:201], v[162:165], v[116:119]
	v_mfma_f32_16x16x32_bf16 v[104:107], v[208:211], v[162:165], v[104:107]
	v_mfma_f32_16x16x32_bf16 v[96:99], v[198:201], v[174:177], v[96:99]
	v_mfma_f32_16x16x32_bf16 v[88:91], v[208:211], v[174:177], v[88:91]
	v_mfma_f32_16x16x32_bf16 v[80:83], v[198:201], v[182:185], v[80:83]
	v_mfma_f32_16x16x32_bf16 v[72:75], v[208:211], v[182:185], v[72:75]
	v_mfma_f32_16x16x32_bf16 v[68:71], v[198:201], v[190:193], v[68:71]
	v_mfma_f32_16x16x32_bf16 v[64:67], v[208:211], v[190:193], v[64:67]
	s_setprio 1
	s_mov_b32 m0, s74
	v_lshl_add_u64 v[214:215], s[62:63], 0, v[142:143]
	s_barrier
	ds_read_b128 v[158:161], v168 offset:16384
	ds_read_b128 v[162:165], v168 offset:17408
	ds_read_b128 v[170:173], v168 offset:18432
	ds_read_b128 v[174:177], v168 offset:19456
	ds_read_b128 v[178:181], v168 offset:20480
	ds_read_b128 v[182:185], v168 offset:21504
	ds_read_b128 v[186:189], v168 offset:22528
	ds_read_b128 v[190:193], v168 offset:23552
	global_load_lds_dwordx4 v[214:215], off
	v_lshl_add_u64 v[216:217], s[62:63], 0, v[144:145]
	s_mov_b32 m0, s75
	s_nop 0
	global_load_lds_dwordx4 v[216:217], off
	s_barrier
	s_waitcnt lgkmcnt(0)
	s_setprio 0
	s_waitcnt lgkmcnt(0)
	v_mfma_f32_16x16x32_bf16 v[60:63], v[128:131], v[158:161], v[60:63]
	v_mfma_f32_16x16x32_bf16 v[56:59], v[136:139], v[158:161], v[56:59]
	v_mfma_f32_16x16x32_bf16 v[52:55], v[128:131], v[170:173], v[52:55]
	v_mfma_f32_16x16x32_bf16 v[44:47], v[136:139], v[170:173], v[44:47]
	v_mfma_f32_16x16x32_bf16 v[36:39], v[128:131], v[178:181], v[36:39]
	v_mfma_f32_16x16x32_bf16 v[28:31], v[136:139], v[178:181], v[28:31]
	v_mfma_f32_16x16x32_bf16 v[20:23], v[128:131], v[186:189], v[20:23]
	v_mfma_f32_16x16x32_bf16 v[12:15], v[136:139], v[186:189], v[12:15]
	v_mfma_f32_16x16x32_bf16 v[60:63], v[132:135], v[162:165], v[60:63]
	v_mfma_f32_16x16x32_bf16 v[56:59], v[154:157], v[162:165], v[56:59]
	v_mfma_f32_16x16x32_bf16 v[52:55], v[132:135], v[174:177], v[52:55]
	v_mfma_f32_16x16x32_bf16 v[44:47], v[154:157], v[174:177], v[44:47]
	v_mfma_f32_16x16x32_bf16 v[36:39], v[132:135], v[182:185], v[36:39]
	v_mfma_f32_16x16x32_bf16 v[28:31], v[154:157], v[182:185], v[28:31]
	v_mfma_f32_16x16x32_bf16 v[20:23], v[132:135], v[190:193], v[20:23]
	v_mfma_f32_16x16x32_bf16 v[12:15], v[154:157], v[190:193], v[12:15]
	s_setprio 1
	s_barrier
; #define WAIT_V(n) asm volatile("s_waitcnt vmcnt(" #n ")" ::: "memory")
; #define WAIT_L(n) asm volatile("s_waitcnt lgkmcnt(" #n ")" ::: "memory")
; #define BAR __builtin_amdgcn_s_barrier()
; #define SCHED __builtin_amdgcn_sched_barrier(0)
; template <class Get, class Epi>
; DI void gemm_stream(LAS unsigned char* lds, const int K, const int ld, Get get, Epi epi) {
;     ...
;             BAR; WAIT_L(0); MMA(1, 0, At, B0); BAR; SCHED;
;             STAGE(SBo(0, 1), b2 + hstep);
;             WAIT_V(6); BAR; MMA(1, 1, At, B1); BAR;
;             LDB(B0, 1, 0); SCHED; LDA(At, 1, 0); STAGE(SAo(0, 1), a2 + hstep);
;             WAIT_L(8); BAR; WAIT_L(0); MMA(0, 0, At, B0); BAR; SCHED;
;             LDB(B1, 1, 1); STAGE(SBo(1, 0), b3);
;             BAR; WAIT_L(0); MMA(0, 1, At, B1); BAR;
	s_add_u32 s86, s6, 0x80000
	s_addc_u32 s87, s7, 0
	s_add_i32 s88, s96, s35
	v_lshl_add_u64 v[128:129], s[86:87], 0, v[142:143]
	s_mov_b32 m0, s88
	s_nop 0
	global_load_lds_dwordx4 v[128:129], off
	v_lshl_add_u64 v[128:129], s[86:87], 0, v[144:145]
	s_add_i32 m0, s88, 0x2000
	s_nop 0
	global_load_lds_dwordx4 v[128:129], off
	s_waitcnt vmcnt(6)
	s_barrier
	s_setprio 0
	v_mfma_f32_16x16x32_bf16 v[48:51], v[194:197], v[158:161], v[48:51]
	v_mfma_f32_16x16x32_bf16 v[40:43], v[202:205], v[158:161], v[40:43]
	v_mfma_f32_16x16x32_bf16 v[32:35], v[194:197], v[170:173], v[32:35]
	v_mfma_f32_16x16x32_bf16 v[24:27], v[202:205], v[170:173], v[24:27]
	v_mfma_f32_16x16x32_bf16 v[16:19], v[194:197], v[178:181], v[16:19]
	v_mfma_f32_16x16x32_bf16 v[8:11], v[202:205], v[178:181], v[8:11]
	v_mfma_f32_16x16x32_bf16 v[4:7], v[194:197], v[186:189], v[4:7]
	v_mfma_f32_16x16x32_bf16 v[0:3], v[202:205], v[186:189], v[0:3]
	v_mfma_f32_16x16x32_bf16 v[48:51], v[198:201], v[162:165], v[48:51]
	v_mfma_f32_16x16x32_bf16 v[40:43], v[208:211], v[162:165], v[40:43]
	v_mfma_f32_16x16x32_bf16 v[32:35], v[198:201], v[174:177], v[32:35]
	v_mfma_f32_16x16x32_bf16 v[24:27], v[208:211], v[174:177], v[24:27]
	v_mfma_f32_16x16x32_bf16 v[16:19], v[198:201], v[182:185], v[16:19]
	v_mfma_f32_16x16x32_bf16 v[8:11], v[208:211], v[182:185], v[8:11]
	v_mfma_f32_16x16x32_bf16 v[4:7], v[198:201], v[190:193], v[4:7]
	v_mfma_f32_16x16x32_bf16 v[0:3], v[208:211], v[190:193], v[0:3]
	s_setprio 1
	s_add_i32 s86, 16, 0x18000
	v_add_u32_e32 v146, s86, v166
	s_barrier
	ds_read_b128 v[128:131], v146
	ds_read_b128 v[132:135], v146 offset:1024
	ds_read_b128 v[136:139], v146 offset:2048
	ds_read_b128 v[154:157], v146 offset:3072
	s_add_u32 s62, s62, 0x80000
	s_addc_u32 s63, s63, 0
	s_mov_b32 m0, s76
	v_lshl_add_u64 v[194:195], s[62:63], 0, v[142:143]
	ds_read_b128 v[158:161], v168 offset:32768
	ds_read_b128 v[162:165], v168 offset:33792
	ds_read_b128 v[170:173], v168 offset:34816
	ds_read_b128 v[174:177], v168 offset:35840
	ds_read_b128 v[178:181], v168 offset:36864
	ds_read_b128 v[182:185], v168 offset:37888
	ds_read_b128 v[186:189], v168 offset:38912
	ds_read_b128 v[190:193], v168 offset:39936
	global_load_lds_dwordx4 v[194:195], off
	v_lshl_add_u64 v[194:195], s[62:63], 0, v[144:145]
	s_mov_b32 m0, s77
	s_nop 0
	global_load_lds_dwordx4 v[194:195], off
	s_waitcnt lgkmcnt(8)
	s_barrier
	s_waitcnt lgkmcnt(0)
	s_setprio 0
	s_waitcnt lgkmcnt(0)
	v_mfma_f32_16x16x32_bf16 v[124:127], v[128:131], v[158:161], v[124:127]
	v_mfma_f32_16x16x32_bf16 v[120:123], v[136:139], v[158:161], v[120:123]
	v_mfma_f32_16x16x32_bf16 v[112:115], v[128:131], v[170:173], v[112:115]
	v_mfma_f32_16x16x32_bf16 v[108:111], v[136:139], v[170:173], v[108:111]
	v_mfma_f32_16x16x32_bf16 v[100:103], v[128:131], v[178:181], v[100:103]
	v_mfma_f32_16x16x32_bf16 v[92:95], v[136:139], v[178:181], v[92:95]
	v_mfma_f32_16x16x32_bf16 v[84:87], v[128:131], v[186:189], v[84:87]
	v_mfma_f32_16x16x32_bf16 v[76:79], v[136:139], v[186:189], v[76:79]
	v_mfma_f32_16x16x32_bf16 v[124:127], v[132:135], v[162:165], v[124:127]
	v_mfma_f32_16x16x32_bf16 v[120:123], v[154:157], v[162:165], v[120:123]
	v_mfma_f32_16x16x32_bf16 v[112:115], v[132:135], v[174:177], v[112:115]
	v_mfma_f32_16x16x32_bf16 v[108:111], v[154:157], v[174:177], v[108:111]
	v_mfma_f32_16x16x32_bf16 v[100:103], v[132:135], v[182:185], v[100:103]
	v_mfma_f32_16x16x32_bf16 v[92:95], v[154:157], v[182:185], v[92:95]
	v_mfma_f32_16x16x32_bf16 v[84:87], v[132:135], v[190:193], v[84:87]
	v_mfma_f32_16x16x32_bf16 v[76:79], v[154:157], v[190:193], v[76:79]
	s_setprio 1
	s_barrier
	s_add_i32 s62, 16, 0x1c000
	s_add_i32 s63, s86, s35
	v_add_u32_e32 v146, s62, v166
	v_lshl_add_u64 v[140:141], v[140:141], 0, s[0:1]
	s_mov_b32 m0, s63
	ds_read_b128 v[194:197], v146
	ds_read_b128 v[198:201], v146 offset:1024
	ds_read_b128 v[202:205], v146 offset:2048
	ds_read_b128 v[208:211], v146 offset:3072
	global_load_lds_dwordx4 v[140:141], off
	v_lshl_add_u64 v[140:141], v[212:213], 0, s[0:1]
	s_add_i32 m0, s63, 0x2000
	s_nop 0
	global_load_lds_dwordx4 v[140:141], off
	s_barrier
	s_waitcnt lgkmcnt(0)
	s_setprio 0
	s_waitcnt lgkmcnt(0)
	v_mfma_f32_16x16x32_bf16 v[116:119], v[194:197], v[158:161], v[116:119]
	v_mfma_f32_16x16x32_bf16 v[104:107], v[202:205], v[158:161], v[104:107]
	v_mfma_f32_16x16x32_bf16 v[96:99], v[194:197], v[170:173], v[96:99]
	v_mfma_f32_16x16x32_bf16 v[88:91], v[202:205], v[170:173], v[88:91]
	v_mfma_f32_16x16x32_bf16 v[80:83], v[194:197], v[178:181], v[80:83]
	v_mfma_f32_16x16x32_bf16 v[72:75], v[202:205], v[178:181], v[72:75]
	v_mfma_f32_16x16x32_bf16 v[68:71], v[194:197], v[186:189], v[68:71]
	v_mfma_f32_16x16x32_bf16 v[64:67], v[202:205], v[186:189], v[64:67]
	v_mfma_f32_16x16x32_bf16 v[116:119], v[198:201], v[162:165], v[116:119]
	v_mfma_f32_16x16x32_bf16 v[104:107], v[208:211], v[162:165], v[104:107]
	v_mfma_f32_16x16x32_bf16 v[96:99], v[198:201], v[174:177], v[96:99]
	v_mfma_f32_16x16x32_bf16 v[88:91], v[208:211], v[174:177], v[88:91]
	v_mfma_f32_16x16x32_bf16 v[80:83], v[198:201], v[182:185], v[80:83]
	v_mfma_f32_16x16x32_bf16 v[72:75], v[208:211], v[182:185], v[72:75]
	v_mfma_f32_16x16x32_bf16 v[68:71], v[198:201], v[190:193], v[68:71]
	v_mfma_f32_16x16x32_bf16 v[64:67], v[208:211], v[190:193], v[64:67]
	s_setprio 1
	s_mov_b32 m0, s80
	v_lshl_add_u64 v[140:141], v[214:215], 0, s[0:1]
	s_barrier
; #define WAIT_V(n) asm volatile("s_waitcnt vmcnt(" #n ")" ::: "memory")
; #define WAIT_L(n) asm volatile("s_waitcnt lgkmcnt(" #n ")" ::: "memory")
; #define BAR __builtin_amdgcn_s_barrier()
; #define SCHED __builtin_amdgcn_sched_barrier(0)
; template <class Get, class Epi>
; DI void gemm_stream(LAS unsigned char* lds, const int K, const int ld, Get get, Epi epi) {
;     ...
;             LDB(B0, 1, 0); SCHED; LDA(At, 1, 0); STAGE(SAo(0, 1), a2 + hstep);
;             WAIT_L(8); BAR; WAIT_L(0); MMA(0, 0, At, B0); BAR; SCHED;
;             LDB(B1, 1, 1); STAGE(SBo(1, 0), b3);
;             BAR; WAIT_L(0); MMA(0, 1, At, B1); BAR;
;             LDA(At, 1, 1); STAGE(SAo(1, 0), a3);
;             BAR; WAIT_L(0); MMA(1, 0, At, B0); BAR; SCHED;
;             STAGE(SBo(1, 1), b3 + hstep);
;             WAIT_V(6); BAR; MMA(1, 1, At, B1); BAR;
;         }
; DI void phase_inproj0(const P& p, char* shm) {
;     ...
;     auto epi = [&](const Acc& acc, const Unit& u) {
;         const int brow = u.pm * 256, pn = u.pn;
;         if (pn == 5) epi_T<64>(acc, 0, brow, (bf16_t*)(p.ws + O_VAT), 256, nullptr);
;         else if (pn < 4) epi_rope<128>(acc, p, brow, (bf16_t*)(p.ws + O_QA), 1024, pn * 256, 128, nullptr, 2);
;         else if (pn == 4) epi_rope<128>(acc, p, brow, (bf16_t*)(p.ws + O_KA), 256, 0, 128, nullptr, 2);
;         else if (pn < 8) epi_plain(acc, brow, (bf16_t*)(p.ws + O_QLAT), 512, (pn - 6) * 256, nullptr);
;         else if (pn == 8) epi_plain(acc, brow, (bf16_t*)(p.ws + O_KVLAT), 256, 0, nullptr);
;         else epi_rope<64>(acc, p, brow, (bf16_t*)(p.ws + O_KR), 64, 0, 64, nullptr, 1);
	ds_read_b128 v[158:161], v168 offset:49152
	ds_read_b128 v[162:165], v168 offset:50176
	ds_read_b128 v[170:173], v168 offset:51200
	ds_read_b128 v[174:177], v168 offset:52224
	ds_read_b128 v[178:181], v168 offset:53248
	ds_read_b128 v[182:185], v168 offset:54272
	ds_read_b128 v[186:189], v168 offset:55296
	ds_read_b128 v[190:193], v168 offset:56320
	global_load_lds_dwordx4 v[140:141], off
	v_lshl_add_u64 v[140:141], v[216:217], 0, s[0:1]
	s_mov_b32 m0, s81
	s_nop 0
	global_load_lds_dwordx4 v[140:141], off
	s_barrier
	s_waitcnt lgkmcnt(0)
	s_setprio 0
	s_waitcnt lgkmcnt(0)
	v_mfma_f32_16x16x32_bf16 v[60:63], v[128:131], v[158:161], v[60:63]
	v_mfma_f32_16x16x32_bf16 v[56:59], v[136:139], v[158:161], v[56:59]
	v_mfma_f32_16x16x32_bf16 v[52:55], v[128:131], v[170:173], v[52:55]
	v_mfma_f32_16x16x32_bf16 v[44:47], v[136:139], v[170:173], v[44:47]
	v_mfma_f32_16x16x32_bf16 v[36:39], v[128:131], v[178:181], v[36:39]
	v_mfma_f32_16x16x32_bf16 v[28:31], v[136:139], v[178:181], v[28:31]
	v_mfma_f32_16x16x32_bf16 v[20:23], v[128:131], v[186:189], v[20:23]
	v_mfma_f32_16x16x32_bf16 v[12:15], v[136:139], v[186:189], v[12:15]
	v_mfma_f32_16x16x32_bf16 v[60:63], v[132:135], v[162:165], v[60:63]
	v_mfma_f32_16x16x32_bf16 v[56:59], v[154:157], v[162:165], v[56:59]
	v_mfma_f32_16x16x32_bf16 v[52:55], v[132:135], v[174:177], v[52:55]
	v_mfma_f32_16x16x32_bf16 v[44:47], v[154:157], v[174:177], v[44:47]
	v_mfma_f32_16x16x32_bf16 v[36:39], v[132:135], v[182:185], v[36:39]
	v_mfma_f32_16x16x32_bf16 v[28:31], v[154:157], v[182:185], v[28:31]
	v_mfma_f32_16x16x32_bf16 v[20:23], v[132:135], v[190:193], v[20:23]
	v_mfma_f32_16x16x32_bf16 v[12:15], v[154:157], v[190:193], v[12:15]
	s_setprio 1
	s_barrier
	s_add_u32 s6, s6, 0x80080
	s_addc_u32 s7, s7, 0
	s_add_i32 s62, s62, s35
	v_lshl_add_u64 v[128:129], s[6:7], 0, v[142:143]
	s_mov_b32 m0, s62
	s_nop 0
	global_load_lds_dwordx4 v[128:129], off
	v_lshl_add_u64 v[128:129], s[6:7], 0, v[144:145]
	s_add_i32 m0, s62, 0x2000
	s_nop 0
	global_load_lds_dwordx4 v[128:129], off
	s_waitcnt vmcnt(6)
	s_barrier
	s_setprio 0
	v_mfma_f32_16x16x32_bf16 v[48:51], v[194:197], v[158:161], v[48:51]
	v_mfma_f32_16x16x32_bf16 v[40:43], v[202:205], v[158:161], v[40:43]
	v_mfma_f32_16x16x32_bf16 v[32:35], v[194:197], v[170:173], v[32:35]
	v_mfma_f32_16x16x32_bf16 v[24:27], v[202:205], v[170:173], v[24:27]
	v_mfma_f32_16x16x32_bf16 v[16:19], v[194:197], v[178:181], v[16:19]
	v_mfma_f32_16x16x32_bf16 v[8:11], v[202:205], v[178:181], v[8:11]
	v_mfma_f32_16x16x32_bf16 v[4:7], v[194:197], v[186:189], v[4:7]
	v_mfma_f32_16x16x32_bf16 v[0:3], v[202:205], v[186:189], v[0:3]
	v_mfma_f32_16x16x32_bf16 v[48:51], v[198:201], v[162:165], v[48:51]
	v_mfma_f32_16x16x32_bf16 v[40:43], v[208:211], v[162:165], v[40:43]
	v_mfma_f32_16x16x32_bf16 v[32:35], v[198:201], v[174:177], v[32:35]
	v_mfma_f32_16x16x32_bf16 v[24:27], v[208:211], v[174:177], v[24:27]
	v_mfma_f32_16x16x32_bf16 v[16:19], v[198:201], v[182:185], v[16:19]
	v_mfma_f32_16x16x32_bf16 v[8:11], v[208:211], v[182:185], v[8:11]
	v_mfma_f32_16x16x32_bf16 v[4:7], v[198:201], v[190:193], v[4:7]
	v_mfma_f32_16x16x32_bf16 v[0:3], v[208:211], v[190:193], v[0:3]
	s_setprio 1
	s_add_i32 vcc_lo, vcc_lo, 2
	s_add_u32 s4, s4, 0x100
	s_addc_u32 s5, s5, 0
	s_add_u32 s29, s29, 0x100
	s_addc_u32 s55, s55, 0
	s_cmp_gt_u32 vcc_lo, 29
	s_barrier
	s_cbranch_scc0 .LBB0_726
	s_lshl_b32 s29, s21, 8
	s_cmp_lg_u32 s28, 5
	s_mov_b64 s[4:5], -1
	s_cbranch_scc0 .LBB0_849
	s_cmp_gt_i32 s28, 3
	s_cbranch_scc0 .LBB0_814
	s_cmp_lg_u32 s28, 4
	s_cbranch_scc0 .LBB0_779
	s_cmp_gt_u32 s28, 7
	s_cbranch_scc0 .LBB0_776
	s_cmp_lg_u32 s28, 8
	s_cbranch_scc0 .LBB0_773
	s_mul_hi_i32 s4, s29, 0x78787879
	s_lshr_b32 s5, s4, 31
	s_ashr_i32 s4, s4, 11
	v_mov_b32_e32 v128, v206
	s_add_i32 s4, s4, s5
	s_mulk_i32 s4, 0x1100
	v_and_b32_e32 v129, 15, v128
	v_ashrrev_i32_e32 v130, 2, v128
	s_sub_i32 s55, s29, s4
	v_and_or_b32 v154, v130, s97, v129
	v_lshrrev_b32_e32 v129, 2, v128
	s_cmpk_gt_i32 s55, 0xff
	v_and_b32_e32 v129, 28, v129
	s_cselect_b64 s[4:5], -1, 0
	v_lshlrev_b32_e32 v146, 2, v129
	v_and_b32_e32 v128, 0x80, v128
	v_lshl_add_u64 v[138:139], s[14:15], 0, v[146:147]
	v_lshl_add_u64 v[140:141], s[12:13], 0, v[146:147]
	v_lshlrev_b32_e32 v146, 1, v129
	v_cmp_eq_u32_e64 s[6:7], 0, v128
	v_cndmask_b32_e64 v128, 0, 1, s[4:5]
	s_addk_i32 s55, 0xff00
	v_lshl_add_u64 v[136:137], s[10:11], 0, v[146:147]
	v_cmp_ne_u32_e64 s[4:5], 1, v128
	s_and_saveexec_b64 s[62:63], s[6:7]
	s_cbranch_execz .LBB0_737
	s_and_b64 vcc, exec, s[4:5]
	s_cbranch_vccnz .LBB0_735
	v_add_u32_e32 v128, s55, v154
	v_ashrrev_i32_e32 v129, 31, v128
	v_lshlrev_b64 v[128:129], 7, v[128:129]
	v_lshl_add_u64 v[132:133], v[138:139], 0, v[128:129]
	v_lshl_add_u64 v[128:129], v[140:141], 0, v[128:129]
	global_load_dwordx4 v[128:131], v[128:129], off
	s_nop 0
	global_load_dwordx4 v[132:135], v[132:133], off
	s_branch .LBB0_736

; #define WAIT_L(n) asm volatile("s_waitcnt lgkmcnt(" #n ")" ::: "memory")
; #define BAR __builtin_amdgcn_s_barrier()
; #define SCHED __builtin_amdgcn_sched_barrier(0)
; DI void gemm_tile(const bf16_t* __restrict__ A, const bf16_t* __restrict__ Bt, const int K, const int brow, const int bcol, LAS unsigned char* lds, Acc& acc) {
;     ...
;         LDB(B0, 0, 0); SCHED; LDA(At, 0, 0); STAGE(SAo(1, 1), a1 + hstep);
;         WAIT_L(8); BAR; WAIT_L(0); MMA(0, 0, At, B0); BAR; SCHED;
;         LDB(B1, 0, 1); STAGE(SBo(0, 0), b2);
;         BAR; WAIT_L(0); MMA(0, 1, At, B1); BAR;
;         LDA(At, 0, 1); STAGE(SAo(0, 0), a2);
;         BAR; WAIT_L(0); MMA(1, 0, At, B0); BAR; SCHED;
.LBB0_930:
	s_add_i32 s6, 16, 0x10000
	v_add_u32_e32 v154, s6, v149
	ds_read_b128 v[150:153], v154
	ds_read_b128 v[160:163], v154 offset:1024
	ds_read_b128 v[164:167], v154 offset:2048
	ds_read_b128 v[168:171], v154 offset:3072
	s_add_i32 s62, s62, 2
	v_lshl_add_u64 v[154:155], v[134:135], 0, s[60:61]
	s_add_i32 s81, s86, 0xc000
	v_lshl_add_u64 v[204:205], v[154:155], 0, s[36:37]
	s_mov_b32 m0, s81
	ds_read_b128 v[172:175], v148
	ds_read_b128 v[176:179], v148 offset:1024
	ds_read_b128 v[180:183], v148 offset:2048
	ds_read_b128 v[184:187], v148 offset:3072
	ds_read_b128 v[188:191], v148 offset:4096
	ds_read_b128 v[192:195], v148 offset:5120
	ds_read_b128 v[196:199], v148 offset:6144
	ds_read_b128 v[200:203], v148 offset:7168
	global_load_lds_dwordx4 v[204:205], off
	v_lshl_add_u64 v[204:205], v[136:137], 0, s[60:61]
	s_add_i32 s63, s86, 0xe000
	v_lshl_add_u64 v[208:209], v[204:205], 0, s[36:37]
	s_mov_b32 m0, s63
	s_nop 0
	global_load_lds_dwordx4 v[208:209], off
	s_waitcnt lgkmcnt(8)
	s_barrier
	s_waitcnt lgkmcnt(0)
	s_setprio 0
	s_waitcnt lgkmcnt(0)
	v_mfma_f32_16x16x32_bf16 v[124:127], v[150:153], v[172:175], v[124:127]
	v_mfma_f32_16x16x32_bf16 v[120:123], v[164:167], v[172:175], v[120:123]
	v_mfma_f32_16x16x32_bf16 v[116:119], v[150:153], v[180:183], v[116:119]
	v_mfma_f32_16x16x32_bf16 v[112:115], v[164:167], v[180:183], v[112:115]
	v_mfma_f32_16x16x32_bf16 v[108:111], v[150:153], v[188:191], v[108:111]
	v_mfma_f32_16x16x32_bf16 v[104:107], v[164:167], v[188:191], v[104:107]
	v_mfma_f32_16x16x32_bf16 v[100:103], v[150:153], v[196:199], v[100:103]
	v_mfma_f32_16x16x32_bf16 v[96:99], v[164:167], v[196:199], v[96:99]
	v_mfma_f32_16x16x32_bf16 v[124:127], v[160:163], v[176:179], v[124:127]
	v_mfma_f32_16x16x32_bf16 v[120:123], v[168:171], v[176:179], v[120:123]
	v_mfma_f32_16x16x32_bf16 v[116:119], v[160:163], v[184:187], v[116:119]
	v_mfma_f32_16x16x32_bf16 v[112:115], v[168:171], v[184:187], v[112:115]
	v_mfma_f32_16x16x32_bf16 v[108:111], v[160:163], v[192:195], v[108:111]
	v_mfma_f32_16x16x32_bf16 v[104:107], v[168:171], v[192:195], v[104:107]
	v_mfma_f32_16x16x32_bf16 v[100:103], v[160:163], v[200:203], v[100:103]
	v_mfma_f32_16x16x32_bf16 v[96:99], v[168:171], v[200:203], v[96:99]
	s_setprio 1
	s_barrier
	s_add_i32 s7, 16, 0x14000
	v_lshl_add_u64 v[224:225], v[138:139], 0, s[60:61]
	s_add_i32 s6, s6, s18
	v_add_u32_e32 v159, s7, v149
	v_lshl_add_u64 v[226:227], v[224:225], 0, s[38:39]
	s_mov_b32 m0, s6
	ds_read_b128 v[208:211], v159
	ds_read_b128 v[212:215], v159 offset:1024
	ds_read_b128 v[216:219], v159 offset:2048
	ds_read_b128 v[220:223], v159 offset:3072
	global_load_lds_dwordx4 v[226:227], off
	v_lshl_add_u64 v[226:227], v[140:141], 0, s[60:61]
	v_lshl_add_u64 v[228:229], v[226:227], 0, s[38:39]
	s_add_i32 m0, s6, 0x2000
	s_nop 0
	global_load_lds_dwordx4 v[228:229], off
	s_barrier
	s_waitcnt lgkmcnt(0)
	s_setprio 0
	s_waitcnt lgkmcnt(0)
	v_mfma_f32_16x16x32_bf16 v[92:95], v[208:211], v[172:175], v[92:95]
	v_mfma_f32_16x16x32_bf16 v[88:91], v[216:219], v[172:175], v[88:91]
	v_mfma_f32_16x16x32_bf16 v[84:87], v[208:211], v[180:183], v[84:87]
	v_mfma_f32_16x16x32_bf16 v[80:83], v[216:219], v[180:183], v[80:83]
	v_mfma_f32_16x16x32_bf16 v[76:79], v[208:211], v[188:191], v[76:79]
	v_mfma_f32_16x16x32_bf16 v[72:75], v[216:219], v[188:191], v[72:75]
	v_mfma_f32_16x16x32_bf16 v[68:71], v[208:211], v[196:199], v[68:71]
	v_mfma_f32_16x16x32_bf16 v[64:67], v[216:219], v[196:199], v[64:67]
	v_mfma_f32_16x16x32_bf16 v[92:95], v[212:215], v[176:179], v[92:95]
	v_mfma_f32_16x16x32_bf16 v[88:91], v[220:223], v[176:179], v[88:91]
	v_mfma_f32_16x16x32_bf16 v[84:87], v[212:215], v[184:187], v[84:87]
	v_mfma_f32_16x16x32_bf16 v[80:83], v[220:223], v[184:187], v[80:83]
	v_mfma_f32_16x16x32_bf16 v[76:79], v[212:215], v[192:195], v[76:79]
	v_mfma_f32_16x16x32_bf16 v[72:75], v[220:223], v[192:195], v[72:75]
	v_mfma_f32_16x16x32_bf16 v[68:71], v[212:215], v[200:203], v[68:71]
	v_mfma_f32_16x16x32_bf16 v[64:67], v[220:223], v[200:203], v[64:67]
	s_setprio 1
	v_lshl_add_u64 v[228:229], v[130:131], 0, s[60:61]
	s_mov_b32 m0, s86
	v_lshl_add_u64 v[230:231], v[228:229], 0, s[38:39]
	s_barrier
	ds_read_b128 v[172:175], v148 offset:16384
	ds_read_b128 v[176:179], v148 offset:17408
	ds_read_b128 v[180:183], v148 offset:18432
	ds_read_b128 v[184:187], v148 offset:19456
	ds_read_b128 v[188:191], v148 offset:20480
	ds_read_b128 v[192:195], v148 offset:21504
	ds_read_b128 v[196:199], v148 offset:22528
	ds_read_b128 v[200:203], v148 offset:23552
	global_load_lds_dwordx4 v[230:231], off
	v_lshl_add_u64 v[230:231], v[132:133], 0, s[60:61]
	v_lshl_add_u64 v[232:233], v[230:231], 0, s[38:39]
	s_mov_b32 m0, s82
	s_nop 0
	global_load_lds_dwordx4 v[232:233], off
	s_barrier
	s_waitcnt lgkmcnt(0)
	s_setprio 0
	s_waitcnt lgkmcnt(0)
	v_mfma_f32_16x16x32_bf16 v[60:63], v[150:153], v[172:175], v[60:63]
	v_mfma_f32_16x16x32_bf16 v[56:59], v[164:167], v[172:175], v[56:59]
	v_mfma_f32_16x16x32_bf16 v[52:55], v[150:153], v[180:183], v[52:55]
	v_mfma_f32_16x16x32_bf16 v[48:51], v[164:167], v[180:183], v[48:51]
	v_mfma_f32_16x16x32_bf16 v[44:47], v[150:153], v[188:191], v[44:47]
	v_mfma_f32_16x16x32_bf16 v[40:43], v[164:167], v[188:191], v[40:43]
	v_mfma_f32_16x16x32_bf16 v[36:39], v[150:153], v[196:199], v[36:39]
	v_mfma_f32_16x16x32_bf16 v[32:35], v[164:167], v[196:199], v[32:35]
	v_mfma_f32_16x16x32_bf16 v[60:63], v[160:163], v[176:179], v[60:63]
	v_mfma_f32_16x16x32_bf16 v[56:59], v[168:171], v[176:179], v[56:59]
	v_mfma_f32_16x16x32_bf16 v[52:55], v[160:163], v[184:187], v[52:55]
	v_mfma_f32_16x16x32_bf16 v[48:51], v[168:171], v[184:187], v[48:51]
	v_mfma_f32_16x16x32_bf16 v[44:47], v[160:163], v[192:195], v[44:47]
	v_mfma_f32_16x16x32_bf16 v[40:43], v[168:171], v[192:195], v[40:43]
	v_mfma_f32_16x16x32_bf16 v[36:39], v[160:163], v[200:203], v[36:39]
	v_mfma_f32_16x16x32_bf16 v[32:35], v[168:171], v[200:203], v[32:35]
	s_setprio 1
	s_barrier
; #define WAIT_V(n) asm volatile("s_waitcnt vmcnt(" #n ")" ::: "memory")
; #define WAIT_L(n) asm volatile("s_waitcnt lgkmcnt(" #n ")" ::: "memory")
; #define BAR __builtin_amdgcn_s_barrier()
; #define SCHED __builtin_amdgcn_sched_barrier(0)
; DI void gemm_tile(const bf16_t* __restrict__ A, const bf16_t* __restrict__ Bt, const int K, const int brow, const int bcol, LAS unsigned char* lds, Acc& acc) {
;     ...
;         BAR; WAIT_L(0); MMA(1, 0, At, B0); BAR; SCHED;
;         STAGE(SBo(0, 1), b2 + hstep);
;         WAIT_V(6); BAR; MMA(1, 1, At, B1); BAR;
;         LDB(B0, 1, 0); SCHED; LDA(At, 1, 0); STAGE(SAo(0, 1), a2 + hstep);
;         WAIT_L(8); BAR; WAIT_L(0); MMA(0, 0, At, B0); BAR; SCHED;
;         LDB(B1, 1, 1); STAGE(SBo(1, 0), b3);
;         BAR; WAIT_L(0); MMA(0, 1, At, B1); BAR;
;         LDA(At, 1, 1); STAGE(SAo(1, 0), a3);
;         BAR; WAIT_L(0); MMA(1, 0, At, B0); BAR; SCHED;
	v_lshl_add_u64 v[232:233], v[144:145], 0, s[60:61]
	s_add_i32 s6, s7, s18
	v_lshl_add_u64 v[150:151], v[232:233], 0, s[38:39]
	s_mov_b32 m0, s6
	v_lshl_add_u64 v[234:235], v[146:147], 0, s[60:61]
	global_load_lds_dwordx4 v[150:151], off
	v_lshl_add_u64 v[150:151], v[234:235], 0, s[38:39]
	s_add_i32 m0, s6, 0x2000
	s_nop 0
	global_load_lds_dwordx4 v[150:151], off
	s_waitcnt vmcnt(6)
	s_barrier
	s_setprio 0
	v_mfma_f32_16x16x32_bf16 v[28:31], v[208:211], v[172:175], v[28:31]
	v_mfma_f32_16x16x32_bf16 v[24:27], v[216:219], v[172:175], v[24:27]
	v_mfma_f32_16x16x32_bf16 v[20:23], v[208:211], v[180:183], v[20:23]
	v_mfma_f32_16x16x32_bf16 v[16:19], v[216:219], v[180:183], v[16:19]
	v_mfma_f32_16x16x32_bf16 v[12:15], v[208:211], v[188:191], v[12:15]
	v_mfma_f32_16x16x32_bf16 v[8:11], v[216:219], v[188:191], v[8:11]
	v_mfma_f32_16x16x32_bf16 v[4:7], v[208:211], v[196:199], v[4:7]
	v_mfma_f32_16x16x32_bf16 v[0:3], v[216:219], v[196:199], v[0:3]
	v_mfma_f32_16x16x32_bf16 v[28:31], v[212:215], v[176:179], v[28:31]
	v_mfma_f32_16x16x32_bf16 v[24:27], v[220:223], v[176:179], v[24:27]
	v_mfma_f32_16x16x32_bf16 v[20:23], v[212:215], v[184:187], v[20:23]
	v_mfma_f32_16x16x32_bf16 v[16:19], v[220:223], v[184:187], v[16:19]
	v_mfma_f32_16x16x32_bf16 v[12:15], v[212:215], v[192:195], v[12:15]
	v_mfma_f32_16x16x32_bf16 v[8:11], v[220:223], v[192:195], v[8:11]
	v_mfma_f32_16x16x32_bf16 v[4:7], v[212:215], v[200:203], v[4:7]
	v_mfma_f32_16x16x32_bf16 v[0:3], v[220:223], v[200:203], v[0:3]
	s_setprio 1
	s_add_i32 s6, 16, 0x18000
	v_add_u32_e32 v159, s6, v149
	s_barrier
	ds_read_b128 v[150:153], v159
	ds_read_b128 v[160:163], v159 offset:1024
	ds_read_b128 v[164:167], v159 offset:2048
	ds_read_b128 v[168:171], v159 offset:3072
	s_mov_b32 m0, s83
	v_lshl_add_u64 v[154:155], v[154:155], 0, s[38:39]
	ds_read_b128 v[172:175], v148 offset:32768
	ds_read_b128 v[176:179], v148 offset:33792
	ds_read_b128 v[180:183], v148 offset:34816
	ds_read_b128 v[184:187], v148 offset:35840
	ds_read_b128 v[188:191], v148 offset:36864
	ds_read_b128 v[192:195], v148 offset:37888
	ds_read_b128 v[196:199], v148 offset:38912
	ds_read_b128 v[200:203], v148 offset:39936
	global_load_lds_dwordx4 v[154:155], off
	v_lshl_add_u64 v[154:155], v[204:205], 0, s[38:39]
	s_mov_b32 m0, s85
	s_nop 0
	global_load_lds_dwordx4 v[154:155], off
	s_waitcnt lgkmcnt(8)
	s_barrier
	s_waitcnt lgkmcnt(0)
	s_setprio 0
	s_waitcnt lgkmcnt(0)
	v_mfma_f32_16x16x32_bf16 v[124:127], v[150:153], v[172:175], v[124:127]
	v_mfma_f32_16x16x32_bf16 v[120:123], v[164:167], v[172:175], v[120:123]
	v_mfma_f32_16x16x32_bf16 v[116:119], v[150:153], v[180:183], v[116:119]
	v_mfma_f32_16x16x32_bf16 v[112:115], v[164:167], v[180:183], v[112:115]
	v_mfma_f32_16x16x32_bf16 v[108:111], v[150:153], v[188:191], v[108:111]
	v_mfma_f32_16x16x32_bf16 v[104:107], v[164:167], v[188:191], v[104:107]
	v_mfma_f32_16x16x32_bf16 v[100:103], v[150:153], v[196:199], v[100:103]
	v_mfma_f32_16x16x32_bf16 v[96:99], v[164:167], v[196:199], v[96:99]
	v_mfma_f32_16x16x32_bf16 v[124:127], v[160:163], v[176:179], v[124:127]
	v_mfma_f32_16x16x32_bf16 v[120:123], v[168:171], v[176:179], v[120:123]
	v_mfma_f32_16x16x32_bf16 v[116:119], v[160:163], v[184:187], v[116:119]
	v_mfma_f32_16x16x32_bf16 v[112:115], v[168:171], v[184:187], v[112:115]
	v_mfma_f32_16x16x32_bf16 v[108:111], v[160:163], v[192:195], v[108:111]
	v_mfma_f32_16x16x32_bf16 v[104:107], v[168:171], v[192:195], v[104:107]
	v_mfma_f32_16x16x32_bf16 v[100:103], v[160:163], v[200:203], v[100:103]
	v_mfma_f32_16x16x32_bf16 v[96:99], v[168:171], v[200:203], v[96:99]
	s_setprio 1
	s_barrier
	s_add_i32 s7, 16, 0x1c000
	v_add_u32_e32 v154, s7, v149
	s_add_i32 s6, s6, s18
	ds_read_b128 v[208:211], v154
	ds_read_b128 v[212:215], v154 offset:1024
	ds_read_b128 v[216:219], v154 offset:2048
	ds_read_b128 v[220:223], v154 offset:3072
	v_lshl_add_u64 v[154:155], v[224:225], 0, s[40:41]
	s_mov_b32 m0, s6
	s_nop 0
	global_load_lds_dwordx4 v[154:155], off
	v_lshl_add_u64 v[154:155], v[226:227], 0, s[40:41]
	s_add_i32 m0, s6, 0x2000
	s_nop 0
	global_load_lds_dwordx4 v[154:155], off
	s_barrier
	s_waitcnt lgkmcnt(0)
	s_setprio 0
	s_waitcnt lgkmcnt(0)
	v_mfma_f32_16x16x32_bf16 v[92:95], v[208:211], v[172:175], v[92:95]
	v_mfma_f32_16x16x32_bf16 v[88:91], v[216:219], v[172:175], v[88:91]
	v_mfma_f32_16x16x32_bf16 v[84:87], v[208:211], v[180:183], v[84:87]
	v_mfma_f32_16x16x32_bf16 v[80:83], v[216:219], v[180:183], v[80:83]
	v_mfma_f32_16x16x32_bf16 v[76:79], v[208:211], v[188:191], v[76:79]
	v_mfma_f32_16x16x32_bf16 v[72:75], v[216:219], v[188:191], v[72:75]
	v_mfma_f32_16x16x32_bf16 v[68:71], v[208:211], v[196:199], v[68:71]
	v_mfma_f32_16x16x32_bf16 v[64:67], v[216:219], v[196:199], v[64:67]
	v_mfma_f32_16x16x32_bf16 v[92:95], v[212:215], v[176:179], v[92:95]
	v_mfma_f32_16x16x32_bf16 v[88:91], v[220:223], v[176:179], v[88:91]
	v_mfma_f32_16x16x32_bf16 v[84:87], v[212:215], v[184:187], v[84:87]
	v_mfma_f32_16x16x32_bf16 v[80:83], v[220:223], v[184:187], v[80:83]
	v_mfma_f32_16x16x32_bf16 v[76:79], v[212:215], v[192:195], v[76:79]
	v_mfma_f32_16x16x32_bf16 v[72:75], v[220:223], v[192:195], v[72:75]
	v_mfma_f32_16x16x32_bf16 v[68:71], v[212:215], v[200:203], v[68:71]
	v_mfma_f32_16x16x32_bf16 v[64:67], v[220:223], v[200:203], v[64:67]
	s_setprio 1
	s_mov_b32 m0, s97
	v_lshl_add_u64 v[154:155], v[228:229], 0, s[40:41]
	s_barrier
	ds_read_b128 v[172:175], v148 offset:49152
	ds_read_b128 v[176:179], v148 offset:50176
	ds_read_b128 v[180:183], v148 offset:51200
	ds_read_b128 v[184:187], v148 offset:52224
	ds_read_b128 v[188:191], v148 offset:53248
	ds_read_b128 v[192:195], v148 offset:54272
	ds_read_b128 v[196:199], v148 offset:55296
	ds_read_b128 v[200:203], v148 offset:56320
	global_load_lds_dwordx4 v[154:155], off
	v_lshl_add_u64 v[154:155], v[230:231], 0, s[40:41]
	s_mov_b32 m0, vcc_lo
	s_nop 0
	global_load_lds_dwordx4 v[154:155], off
	s_barrier
; #define WAIT_V(n) asm volatile("s_waitcnt vmcnt(" #n ")" ::: "memory")
; #define WAIT_L(n) asm volatile("s_waitcnt lgkmcnt(" #n ")" ::: "memory")
; #define BAR __builtin_amdgcn_s_barrier()
; #define SCHED __builtin_amdgcn_sched_barrier(0)
; DI void gemm_tile(const bf16_t* __restrict__ A, const bf16_t* __restrict__ Bt, const int K, const int brow, const int bcol, LAS unsigned char* lds, Acc& acc) {
;     ...
;         BAR; WAIT_L(0); MMA(1, 0, At, B0); BAR; SCHED;
;         STAGE(SBo(1, 1), b3 + hstep);
;         WAIT_V(6); BAR; MMA(1, 1, At, B1); BAR;
;     }
;     { LDB(B0, 0, 0); LDA(At, 0, 0); STAGE(SAo(1, 1), cA + (size_t)(nt - 1) * kstep + hstep);
	s_waitcnt lgkmcnt(0)
	s_setprio 0
	s_waitcnt lgkmcnt(0)
	v_mfma_f32_16x16x32_bf16 v[60:63], v[150:153], v[172:175], v[60:63]
	v_mfma_f32_16x16x32_bf16 v[56:59], v[164:167], v[172:175], v[56:59]
	v_mfma_f32_16x16x32_bf16 v[52:55], v[150:153], v[180:183], v[52:55]
	v_mfma_f32_16x16x32_bf16 v[48:51], v[164:167], v[180:183], v[48:51]
	v_mfma_f32_16x16x32_bf16 v[44:47], v[150:153], v[188:191], v[44:47]
	v_mfma_f32_16x16x32_bf16 v[40:43], v[164:167], v[188:191], v[40:43]
	v_mfma_f32_16x16x32_bf16 v[36:39], v[150:153], v[196:199], v[36:39]
	v_mfma_f32_16x16x32_bf16 v[32:35], v[164:167], v[196:199], v[32:35]
	v_mfma_f32_16x16x32_bf16 v[60:63], v[160:163], v[176:179], v[60:63]
	v_mfma_f32_16x16x32_bf16 v[56:59], v[168:171], v[176:179], v[56:59]
	v_mfma_f32_16x16x32_bf16 v[52:55], v[160:163], v[184:187], v[52:55]
	v_mfma_f32_16x16x32_bf16 v[48:51], v[168:171], v[184:187], v[48:51]
	v_mfma_f32_16x16x32_bf16 v[44:47], v[160:163], v[192:195], v[44:47]
	v_mfma_f32_16x16x32_bf16 v[40:43], v[168:171], v[192:195], v[40:43]
	v_mfma_f32_16x16x32_bf16 v[36:39], v[160:163], v[200:203], v[36:39]
	v_mfma_f32_16x16x32_bf16 v[32:35], v[168:171], v[200:203], v[32:35]
	s_setprio 1
	s_barrier
	s_add_i32 s6, s7, s18
	v_lshl_add_u64 v[150:151], v[232:233], 0, s[40:41]
	s_mov_b32 m0, s6
	s_nop 0
	global_load_lds_dwordx4 v[150:151], off
	v_lshl_add_u64 v[150:151], v[234:235], 0, s[40:41]
	s_add_i32 m0, s6, 0x2000
	s_nop 0
	global_load_lds_dwordx4 v[150:151], off
	s_waitcnt vmcnt(6)
	s_barrier
	s_setprio 0
	v_mfma_f32_16x16x32_bf16 v[28:31], v[208:211], v[172:175], v[28:31]
	v_mfma_f32_16x16x32_bf16 v[24:27], v[216:219], v[172:175], v[24:27]
	v_mfma_f32_16x16x32_bf16 v[20:23], v[208:211], v[180:183], v[20:23]
	v_mfma_f32_16x16x32_bf16 v[16:19], v[216:219], v[180:183], v[16:19]
	v_mfma_f32_16x16x32_bf16 v[12:15], v[208:211], v[188:191], v[12:15]
	v_mfma_f32_16x16x32_bf16 v[8:11], v[216:219], v[188:191], v[8:11]
	v_mfma_f32_16x16x32_bf16 v[4:7], v[208:211], v[196:199], v[4:7]
	v_mfma_f32_16x16x32_bf16 v[0:3], v[216:219], v[196:199], v[0:3]
	v_mfma_f32_16x16x32_bf16 v[28:31], v[212:215], v[176:179], v[28:31]
	v_mfma_f32_16x16x32_bf16 v[24:27], v[220:223], v[176:179], v[24:27]
	v_mfma_f32_16x16x32_bf16 v[20:23], v[212:215], v[184:187], v[20:23]
	v_mfma_f32_16x16x32_bf16 v[16:19], v[220:223], v[184:187], v[16:19]
	v_mfma_f32_16x16x32_bf16 v[12:15], v[212:215], v[192:195], v[12:15]
	v_mfma_f32_16x16x32_bf16 v[8:11], v[220:223], v[192:195], v[8:11]
	v_mfma_f32_16x16x32_bf16 v[4:7], v[212:215], v[200:203], v[4:7]
	v_mfma_f32_16x16x32_bf16 v[0:3], v[220:223], v[200:203], v[0:3]
	s_setprio 1
	s_add_u32 s60, s60, 0x100
	s_addc_u32 s61, s61, 0
	s_cmp_ge_u32 s62, vcc_hi
	s_barrier
	s_cbranch_scc0 .LBB0_930
	s_add_i32 s18, s96, -1
	s_lshl_b64 s[6:7], s[18:19], 7
	s_add_u32 s4, s4, s6
	s_addc_u32 s5, s5, s7
	s_add_u32 s4, s4, s55
	v_add_u32_e32 v149, 16, v149
	s_addc_u32 s5, s5, 0
	s_mov_b32 m0, s81
	v_add_u32_e32 v144, 0x10000, v149
	v_lshl_add_u64 v[154:155], s[4:5], 0, v[142:143]
	ds_read_b128 v[130:133], v144
	ds_read_b128 v[134:137], v144 offset:1024
	ds_read_b128 v[138:141], v144 offset:2048
	ds_read_b128 v[144:147], v144 offset:3072
	ds_read_b128 v[150:153], v148
	ds_read_b128 v[160:163], v148 offset:1024
	ds_read_b128 v[164:167], v148 offset:2048
	ds_read_b128 v[168:171], v148 offset:3072
	ds_read_b128 v[172:175], v148 offset:4096
	ds_read_b128 v[176:179], v148 offset:5120
	ds_read_b128 v[180:183], v148 offset:6144
	ds_read_b128 v[184:187], v148 offset:7168
	global_load_lds_dwordx4 v[154:155], off
	v_lshl_add_u64 v[128:129], s[4:5], 0, v[128:129]
	s_mov_b32 m0, s63
	s_nop 0
	global_load_lds_dwordx4 v[128:129], off
	s_barrier
	s_waitcnt lgkmcnt(0)
	s_setprio 0
	s_waitcnt lgkmcnt(0)
	v_mfma_f32_16x16x32_bf16 v[124:127], v[130:133], v[150:153], v[124:127]
	v_mfma_f32_16x16x32_bf16 v[120:123], v[138:141], v[150:153], v[120:123]
	v_mfma_f32_16x16x32_bf16 v[116:119], v[130:133], v[164:167], v[116:119]
	v_mfma_f32_16x16x32_bf16 v[112:115], v[138:141], v[164:167], v[112:115]
	v_mfma_f32_16x16x32_bf16 v[100:103], v[130:133], v[180:183], v[100:103]
	v_mfma_f32_16x16x32_bf16 v[96:99], v[138:141], v[180:183], v[96:99]
	v_mfma_f32_16x16x32_bf16 v[124:127], v[134:137], v[160:163], v[124:127]
	v_mfma_f32_16x16x32_bf16 v[120:123], v[144:147], v[160:163], v[120:123]
	v_mfma_f32_16x16x32_bf16 v[116:119], v[134:137], v[168:171], v[116:119]
	v_mfma_f32_16x16x32_bf16 v[112:115], v[144:147], v[168:171], v[112:115]
	v_mfma_f32_16x16x32_bf16 v[108:111], v[130:133], v[172:175], v[108:111]
	v_mfma_f32_16x16x32_bf16 v[104:107], v[138:141], v[172:175], v[104:107]
	v_mfma_f32_16x16x32_bf16 v[100:103], v[134:137], v[184:187], v[100:103]
	v_mfma_f32_16x16x32_bf16 v[96:99], v[144:147], v[184:187], v[96:99]
	v_mfma_f32_16x16x32_bf16 v[188:191], v[134:137], v[176:179], v[108:111]
	v_mfma_f32_16x16x32_bf16 v[192:195], v[144:147], v[176:179], v[104:107]
	s_setprio 1
	v_add_u32_e32 v128, 0x14000, v149
	s_barrier
	s_nop 0
	ds_read_b128 v[104:107], v128
	ds_read_b128 v[108:111], v128 offset:1024
	ds_read_b128 v[196:199], v128 offset:2048
	ds_read_b128 v[200:203], v128 offset:3072
	s_barrier
; #define WAIT_V(n) asm volatile("s_waitcnt vmcnt(" #n ")" ::: "memory")
; #define WAIT_L(n) asm volatile("s_waitcnt lgkmcnt(" #n ")" ::: "memory")
; #define BAR __builtin_amdgcn_s_barrier()
; DI void gemm_tile(const bf16_t* __restrict__ A, const bf16_t* __restrict__ Bt, const int K, const int brow, const int bcol, LAS unsigned char* lds, Acc& acc) {
;     ...
;     { LDB(B0, 0, 0); LDA(At, 0, 0); STAGE(SAo(1, 1), cA + (size_t)(nt - 1) * kstep + hstep);
;       BAR; WAIT_L(0); MMA(0, 0, At, B0); BAR;
;       LDB(B1, 0, 1); BAR; WAIT_L(0); MMA(0, 1, At, B1); BAR;
;       LDA(At, 0, 1); WAIT_V(4); BAR; WAIT_L(0); MMA(1, 0, At, B0); MMA(1, 1, At, B1); BAR; }
;     { LDB(B0, 1, 0); LDA(At, 1, 0); WAIT_V(2); BAR; WAIT_L(0); MMA(0, 0, At, B0); BAR;
	s_waitcnt lgkmcnt(0)
	s_setprio 0
	s_waitcnt lgkmcnt(0)
	v_mfma_f32_16x16x32_bf16 v[84:87], v[104:107], v[164:167], v[84:87]
	v_mfma_f32_16x16x32_bf16 v[80:83], v[196:199], v[164:167], v[80:83]
	v_mfma_f32_16x16x32_bf16 v[68:71], v[104:107], v[180:183], v[68:71]
	v_mfma_f32_16x16x32_bf16 v[64:67], v[196:199], v[180:183], v[64:67]
	v_mfma_f32_16x16x32_bf16 v[92:95], v[104:107], v[150:153], v[92:95]
	v_mfma_f32_16x16x32_bf16 v[88:91], v[196:199], v[150:153], v[88:91]
	v_mfma_f32_16x16x32_bf16 v[84:87], v[108:111], v[168:171], v[84:87]
	v_mfma_f32_16x16x32_bf16 v[80:83], v[200:203], v[168:171], v[80:83]
	v_mfma_f32_16x16x32_bf16 v[76:79], v[104:107], v[172:175], v[76:79]
	v_mfma_f32_16x16x32_bf16 v[72:75], v[196:199], v[172:175], v[72:75]
	v_mfma_f32_16x16x32_bf16 v[68:71], v[108:111], v[184:187], v[68:71]
	v_mfma_f32_16x16x32_bf16 v[64:67], v[200:203], v[184:187], v[64:67]
	v_mfma_f32_16x16x32_bf16 v[208:211], v[108:111], v[160:163], v[92:95]
	v_mfma_f32_16x16x32_bf16 v[150:153], v[200:203], v[160:163], v[88:91]
	v_mfma_f32_16x16x32_bf16 v[160:163], v[108:111], v[176:179], v[76:79]
	v_mfma_f32_16x16x32_bf16 v[164:167], v[200:203], v[176:179], v[72:75]
	s_setprio 1
	s_barrier
	s_nop 0
	ds_read_b128 v[72:75], v148 offset:16384
	ds_read_b128 v[76:79], v148 offset:17408
	ds_read_b128 v[88:91], v148 offset:18432
	ds_read_b128 v[92:95], v148 offset:19456
	ds_read_b128 v[168:171], v148 offset:20480
	ds_read_b128 v[172:175], v148 offset:21504
	ds_read_b128 v[176:179], v148 offset:22528
	ds_read_b128 v[180:183], v148 offset:23552
	s_waitcnt vmcnt(4)
	s_barrier
	s_waitcnt lgkmcnt(0)
	s_setprio 0
	s_waitcnt lgkmcnt(0)
	v_mfma_f32_16x16x32_bf16 v[60:63], v[130:133], v[72:75], v[60:63]
	v_mfma_f32_16x16x32_bf16 v[56:59], v[138:141], v[72:75], v[56:59]
	v_mfma_f32_16x16x32_bf16 v[52:55], v[130:133], v[88:91], v[52:55]
	v_mfma_f32_16x16x32_bf16 v[48:51], v[138:141], v[88:91], v[48:51]
	v_mfma_f32_16x16x32_bf16 v[36:39], v[130:133], v[176:179], v[36:39]
	v_mfma_f32_16x16x32_bf16 v[32:35], v[138:141], v[176:179], v[32:35]
	v_mfma_f32_16x16x32_bf16 v[60:63], v[134:137], v[76:79], v[60:63]
	v_mfma_f32_16x16x32_bf16 v[56:59], v[144:147], v[76:79], v[56:59]
	v_mfma_f32_16x16x32_bf16 v[52:55], v[134:137], v[92:95], v[52:55]
	v_mfma_f32_16x16x32_bf16 v[48:51], v[144:147], v[92:95], v[48:51]
	v_mfma_f32_16x16x32_bf16 v[44:47], v[130:133], v[168:171], v[44:47]
	v_mfma_f32_16x16x32_bf16 v[40:43], v[138:141], v[168:171], v[40:43]
	v_mfma_f32_16x16x32_bf16 v[36:39], v[134:137], v[180:183], v[36:39]
	v_mfma_f32_16x16x32_bf16 v[32:35], v[144:147], v[180:183], v[32:35]
	v_mfma_f32_16x16x32_bf16 v[184:187], v[134:137], v[172:175], v[44:47]
	v_mfma_f32_16x16x32_bf16 v[212:215], v[144:147], v[172:175], v[40:43]
	s_setprio 1
	s_setprio 0
	v_mfma_f32_16x16x32_bf16 v[20:23], v[104:107], v[88:91], v[20:23]
	v_mfma_f32_16x16x32_bf16 v[16:19], v[196:199], v[88:91], v[16:19]
	v_mfma_f32_16x16x32_bf16 v[4:7], v[104:107], v[176:179], v[4:7]
	v_mfma_f32_16x16x32_bf16 v[0:3], v[196:199], v[176:179], v[0:3]
	v_mfma_f32_16x16x32_bf16 v[28:31], v[104:107], v[72:75], v[28:31]
	v_mfma_f32_16x16x32_bf16 v[24:27], v[196:199], v[72:75], v[24:27]
	v_mfma_f32_16x16x32_bf16 v[20:23], v[108:111], v[92:95], v[20:23]
	v_mfma_f32_16x16x32_bf16 v[16:19], v[200:203], v[92:95], v[16:19]
	v_mfma_f32_16x16x32_bf16 v[12:15], v[104:107], v[168:171], v[12:15]
	v_mfma_f32_16x16x32_bf16 v[8:11], v[196:199], v[168:171], v[8:11]
	v_mfma_f32_16x16x32_bf16 v[4:7], v[108:111], v[180:183], v[4:7]
	v_mfma_f32_16x16x32_bf16 v[0:3], v[200:203], v[180:183], v[0:3]
	v_mfma_f32_16x16x32_bf16 v[128:131], v[108:111], v[76:79], v[28:31]
	v_mfma_f32_16x16x32_bf16 v[132:135], v[200:203], v[76:79], v[24:27]
	v_mfma_f32_16x16x32_bf16 v[136:139], v[108:111], v[172:175], v[12:15]
	v_mfma_f32_16x16x32_bf16 v[144:147], v[200:203], v[172:175], v[8:11]
	s_setprio 1
	v_add_u32_e32 v24, 0x18000, v149
	s_barrier
	ds_read_b128 v[8:11], v24
	ds_read_b128 v[12:15], v24 offset:1024
	ds_read_b128 v[168:171], v24 offset:2048
	ds_read_b128 v[172:175], v24 offset:3072
	ds_read_b128 v[24:27], v148 offset:32768
	ds_read_b128 v[28:31], v148 offset:33792
	ds_read_b128 v[40:43], v148 offset:34816
	ds_read_b128 v[44:47], v148 offset:35840
	ds_read_b128 v[176:179], v148 offset:36864
	ds_read_b128 v[180:183], v148 offset:37888
	ds_read_b128 v[196:199], v148 offset:38912
	ds_read_b128 v[200:203], v148 offset:39936
	s_waitcnt vmcnt(2)
	s_barrier
; #define WAIT_V(n) asm volatile("s_waitcnt vmcnt(" #n ")" ::: "memory")
; #define WAIT_L(n) asm volatile("s_waitcnt lgkmcnt(" #n ")" ::: "memory")
; #define BAR __builtin_amdgcn_s_barrier()
; DI void gemm_tile(const bf16_t* __restrict__ A, const bf16_t* __restrict__ Bt, const int K, const int brow, const int bcol, LAS unsigned char* lds, Acc& acc) {
;     ...
;       LDA(At, 0, 1); WAIT_V(4); BAR; WAIT_L(0); MMA(1, 0, At, B0); MMA(1, 1, At, B1); BAR; }
;     { LDB(B0, 1, 0); LDA(At, 1, 0); WAIT_V(2); BAR; WAIT_L(0); MMA(0, 0, At, B0); BAR;
;       LDB(B1, 1, 1); WAIT_V(0); BAR; WAIT_L(0); MMA(0, 1, At, B1); BAR;
;       LDA(At, 1, 1); BAR; WAIT_L(0); MMA(1, 0, At, B0); MMA(1, 1, At, B1); BAR; }
;     if (wr == 0) BAR;
; DI void phase_qkvb(const P& p, char* shm) {
;     ...
;         if (isq) {
;             if (pn < 4) {
	s_waitcnt lgkmcnt(0)
	s_setprio 0
	s_waitcnt lgkmcnt(0)
	v_mfma_f32_16x16x32_bf16 v[72:75], v[8:11], v[24:27], v[124:127]
	v_mfma_f32_16x16x32_bf16 v[124:127], v[12:15], v[28:31], v[72:75]
	v_mfma_f32_16x16x32_bf16 v[72:75], v[168:171], v[24:27], v[120:123]
	v_mfma_f32_16x16x32_bf16 v[120:123], v[172:175], v[28:31], v[72:75]
	v_mfma_f32_16x16x32_bf16 v[72:75], v[8:11], v[40:43], v[116:119]
	v_mfma_f32_16x16x32_bf16 v[108:111], v[12:15], v[44:47], v[72:75]
	v_mfma_f32_16x16x32_bf16 v[72:75], v[168:171], v[40:43], v[112:115]
	v_mfma_f32_16x16x32_bf16 v[104:107], v[172:175], v[44:47], v[72:75]
	v_mfma_f32_16x16x32_bf16 v[72:75], v[8:11], v[176:179], v[188:191]
	v_mfma_f32_16x16x32_bf16 v[92:95], v[12:15], v[180:183], v[72:75]
	v_mfma_f32_16x16x32_bf16 v[72:75], v[168:171], v[176:179], v[192:195]
	v_mfma_f32_16x16x32_bf16 v[88:91], v[172:175], v[180:183], v[72:75]
	v_mfma_f32_16x16x32_bf16 v[72:75], v[8:11], v[196:199], v[100:103]
	v_mfma_f32_16x16x32_bf16 v[76:79], v[12:15], v[200:203], v[72:75]
	v_mfma_f32_16x16x32_bf16 v[72:75], v[168:171], v[196:199], v[96:99]
	v_mfma_f32_16x16x32_bf16 v[72:75], v[172:175], v[200:203], v[72:75]
	s_setprio 1
	s_nop 0
	v_add_u32_e32 v96, 0x1c000, v149
	s_barrier
	ds_read_b128 v[188:191], v96
	ds_read_b128 v[192:195], v96 offset:1024
	ds_read_b128 v[216:219], v96 offset:2048
	ds_read_b128 v[220:223], v96 offset:3072
	s_waitcnt vmcnt(0)
	s_barrier
	s_waitcnt lgkmcnt(0)
	s_setprio 0
	s_waitcnt lgkmcnt(0)
	v_mfma_f32_16x16x32_bf16 v[96:99], v[188:191], v[24:27], v[208:211]
	v_mfma_f32_16x16x32_bf16 v[24:27], v[216:219], v[24:27], v[150:153]
	v_mfma_f32_16x16x32_bf16 v[112:115], v[220:223], v[28:31], v[24:27]
	v_mfma_f32_16x16x32_bf16 v[24:27], v[188:191], v[40:43], v[84:87]
	v_mfma_f32_16x16x32_bf16 v[100:103], v[192:195], v[44:47], v[24:27]
	v_mfma_f32_16x16x32_bf16 v[24:27], v[216:219], v[40:43], v[80:83]
	v_mfma_f32_16x16x32_bf16 v[116:119], v[192:195], v[28:31], v[96:99]
	v_mfma_f32_16x16x32_bf16 v[96:99], v[220:223], v[44:47], v[24:27]
	v_mfma_f32_16x16x32_bf16 v[24:27], v[188:191], v[176:179], v[160:163]
	v_mfma_f32_16x16x32_bf16 v[84:87], v[192:195], v[180:183], v[24:27]
	v_mfma_f32_16x16x32_bf16 v[24:27], v[216:219], v[176:179], v[164:167]
	v_mfma_f32_16x16x32_bf16 v[80:83], v[220:223], v[180:183], v[24:27]
	v_mfma_f32_16x16x32_bf16 v[24:27], v[188:191], v[196:199], v[68:71]
	v_mfma_f32_16x16x32_bf16 v[68:71], v[192:195], v[200:203], v[24:27]
	v_mfma_f32_16x16x32_bf16 v[24:27], v[216:219], v[196:199], v[64:67]
	v_mfma_f32_16x16x32_bf16 v[64:67], v[220:223], v[200:203], v[24:27]
	s_setprio 1
	s_barrier
	ds_read_b128 v[150:153], v148 offset:49152
	ds_read_b128 v[160:163], v148 offset:50176
	ds_read_b128 v[164:167], v148 offset:51200
	ds_read_b128 v[176:179], v148 offset:52224
	ds_read_b128 v[180:183], v148 offset:53248
	ds_read_b128 v[196:199], v148 offset:54272
	ds_read_b128 v[200:203], v148 offset:55296
	ds_read_b128 v[208:211], v148 offset:56320
	s_barrier
	s_waitcnt lgkmcnt(0)
	s_setprio 0
	s_waitcnt lgkmcnt(0)
	v_mfma_f32_16x16x32_bf16 v[24:27], v[8:11], v[150:153], v[60:63]
	v_mfma_f32_16x16x32_bf16 v[60:63], v[12:15], v[160:163], v[24:27]
	v_mfma_f32_16x16x32_bf16 v[24:27], v[168:171], v[150:153], v[56:59]
	v_mfma_f32_16x16x32_bf16 v[56:59], v[172:175], v[160:163], v[24:27]
	v_mfma_f32_16x16x32_bf16 v[24:27], v[8:11], v[164:167], v[52:55]
	v_mfma_f32_16x16x32_bf16 v[44:47], v[12:15], v[176:179], v[24:27]
	v_mfma_f32_16x16x32_bf16 v[24:27], v[168:171], v[164:167], v[48:51]
	v_mfma_f32_16x16x32_bf16 v[40:43], v[172:175], v[176:179], v[24:27]
	v_mfma_f32_16x16x32_bf16 v[24:27], v[8:11], v[180:183], v[184:187]
	v_mfma_f32_16x16x32_bf16 v[8:11], v[8:11], v[200:203], v[36:39]
	v_mfma_f32_16x16x32_bf16 v[28:31], v[12:15], v[196:199], v[24:27]
	v_mfma_f32_16x16x32_bf16 v[24:27], v[168:171], v[180:183], v[212:215]
	v_mfma_f32_16x16x32_bf16 v[12:15], v[12:15], v[208:211], v[8:11]
	v_mfma_f32_16x16x32_bf16 v[8:11], v[168:171], v[200:203], v[32:35]
	v_mfma_f32_16x16x32_bf16 v[24:27], v[172:175], v[196:199], v[24:27]
	v_mfma_f32_16x16x32_bf16 v[8:11], v[172:175], v[208:211], v[8:11]
	s_setprio 1
	s_setprio 0
	v_mfma_f32_16x16x32_bf16 v[32:35], v[188:191], v[150:153], v[128:131]
	v_mfma_f32_16x16x32_bf16 v[52:55], v[192:195], v[160:163], v[32:35]
	v_mfma_f32_16x16x32_bf16 v[32:35], v[216:219], v[150:153], v[132:135]
	v_mfma_f32_16x16x32_bf16 v[16:19], v[216:219], v[164:167], v[16:19]
	v_mfma_f32_16x16x32_bf16 v[48:51], v[220:223], v[160:163], v[32:35]
	v_mfma_f32_16x16x32_bf16 v[20:23], v[188:191], v[164:167], v[20:23]
	v_mfma_f32_16x16x32_bf16 v[32:35], v[220:223], v[176:179], v[16:19]
	v_mfma_f32_16x16x32_bf16 v[16:19], v[188:191], v[180:183], v[136:139]
	v_mfma_f32_16x16x32_bf16 v[36:39], v[192:195], v[176:179], v[20:23]
	v_mfma_f32_16x16x32_bf16 v[20:23], v[192:195], v[196:199], v[16:19]
	v_mfma_f32_16x16x32_bf16 v[16:19], v[216:219], v[180:183], v[144:147]
	v_mfma_f32_16x16x32_bf16 v[4:7], v[188:191], v[200:203], v[4:7]
	v_mfma_f32_16x16x32_bf16 v[0:3], v[216:219], v[200:203], v[0:3]
	v_mfma_f32_16x16x32_bf16 v[16:19], v[220:223], v[196:199], v[16:19]
	v_mfma_f32_16x16x32_bf16 v[4:7], v[192:195], v[208:211], v[4:7]
	v_mfma_f32_16x16x32_bf16 v[0:3], v[220:223], v[208:211], v[0:3]
	s_setprio 1
	s_cmpk_lt_u32 s29, 0x100
	s_mov_b32 s89, s23
	s_mov_b32 s90, s35
	s_mov_b32 s91, s8
	s_barrier
	s_cbranch_scc0 .LBB0_934
	s_barrier
	s_and_b64 vcc, exec, s[2:3]
	s_mov_b64 s[2:3], -1
	s_cbranch_vccz .LBB0_935

; #define WAIT_V(n) asm volatile("s_waitcnt vmcnt(" #n ")" ::: "memory")
; #define WAIT_L(n) asm volatile("s_waitcnt lgkmcnt(" #n ")" ::: "memory")
; #define BAR __builtin_amdgcn_s_barrier()
; #define SCHED __builtin_amdgcn_sched_barrier(0)
; template <class Get, class Epi>
; DI void gemm_stream(LAS unsigned char* lds, const int K, const int ld, Get get, Epi epi) {
;     ...
;             const bool last = (t == nt - 2);
;             const char* a1 = cA + (size_t)(t + 1) * kstep;
;             const char* a2 = last ? nA : cA + (size_t)(t + 2) * kstep;
;             const char* b2 = last ? nB : cB + (size_t)(t + 2) * kstep;
;             const char* a3 = a2 + kstep;
;             const char* b3 = b2 + kstep;
;             LDB(B0, 0, 0); SCHED; LDA(At, 0, 0); STAGE(SAo(1, 1), a1 + hstep);
;             WAIT_L(8); BAR; WAIT_L(0); MMA(0, 0, At, B0); BAR; SCHED;
;             LDB(B1, 0, 1); STAGE(SBo(0, 0), b2);
;             BAR; WAIT_L(0); MMA(0, 1, At, B1); BAR;
;             LDA(At, 0, 1); STAGE(SAo(0, 0), a2);
;             BAR; WAIT_L(0); MMA(1, 0, At, B0); BAR; SCHED;
;             STAGE(SBo(0, 1), b2 + hstep);
;             WAIT_V(6); BAR; MMA(1, 1, At, B1); BAR;
.LBB0_1238:
	ds_read_b128 v[128:131], v198
	ds_read_b128 v[132:135], v198 offset:1024
	ds_read_b128 v[136:139], v198 offset:2048
	ds_read_b128 v[140:143], v198 offset:3072
	s_add_u32 s8, s6, 0x100
	s_addc_u32 s9, s7, 0
	s_cmp_eq_u32 s18, 28
	s_cselect_b32 s13, s39, s9
	s_cselect_b32 s12, s38, s8
	s_cselect_b32 s11, s41, s17
	s_cselect_b32 s10, s40, s16
	s_mov_b32 m0, s74
	v_lshl_add_u64 v[186:187], s[6:7], 0, v[168:169]
	ds_read_b128 v[144:147], v199
	ds_read_b128 v[148:151], v199 offset:1024
	ds_read_b128 v[152:155], v199 offset:2048
	ds_read_b128 v[156:159], v199 offset:3072
	ds_read_b128 v[160:163], v199 offset:4096
	ds_read_b128 v[174:177], v199 offset:5120
	ds_read_b128 v[178:181], v199 offset:6144
	ds_read_b128 v[182:185], v199 offset:7168
	global_load_lds_dwordx4 v[186:187], off
	v_lshl_add_u64 v[186:187], s[6:7], 0, v[170:171]
	s_mov_b32 m0, s75
	s_nop 0
	global_load_lds_dwordx4 v[186:187], off
	s_waitcnt lgkmcnt(8)
	s_barrier
	s_waitcnt lgkmcnt(0)
	s_setprio 0
	s_waitcnt lgkmcnt(0)
	v_mfma_f32_16x16x32_bf16 v[124:127], v[128:131], v[144:147], v[124:127]
	v_mfma_f32_16x16x32_bf16 v[92:95], v[136:139], v[144:147], v[92:95]
	v_mfma_f32_16x16x32_bf16 v[120:123], v[128:131], v[152:155], v[120:123]
	v_mfma_f32_16x16x32_bf16 v[88:91], v[136:139], v[152:155], v[88:91]
	v_mfma_f32_16x16x32_bf16 v[116:119], v[128:131], v[160:163], v[116:119]
	v_mfma_f32_16x16x32_bf16 v[84:87], v[136:139], v[160:163], v[84:87]
	v_mfma_f32_16x16x32_bf16 v[112:115], v[128:131], v[178:181], v[112:115]
	v_mfma_f32_16x16x32_bf16 v[80:83], v[136:139], v[178:181], v[80:83]
	v_mfma_f32_16x16x32_bf16 v[124:127], v[132:135], v[148:151], v[124:127]
	v_mfma_f32_16x16x32_bf16 v[92:95], v[140:143], v[148:151], v[92:95]
	v_mfma_f32_16x16x32_bf16 v[120:123], v[132:135], v[156:159], v[120:123]
	v_mfma_f32_16x16x32_bf16 v[88:91], v[140:143], v[156:159], v[88:91]
	v_mfma_f32_16x16x32_bf16 v[116:119], v[132:135], v[174:177], v[116:119]
	v_mfma_f32_16x16x32_bf16 v[84:87], v[140:143], v[174:177], v[84:87]
	v_mfma_f32_16x16x32_bf16 v[112:115], v[132:135], v[182:185], v[112:115]
	v_mfma_f32_16x16x32_bf16 v[80:83], v[140:143], v[182:185], v[80:83]
	s_setprio 1
	s_barrier
	s_mov_b32 m0, s80
	v_lshl_add_u64 v[204:205], s[10:11], 0, v[164:165]
	ds_read_b128 v[186:189], v200
	ds_read_b128 v[190:193], v200 offset:1024
	ds_read_b128 v[194:197], v200 offset:2048
	ds_read_b128 v[208:211], v200 offset:3072
	global_load_lds_dwordx4 v[204:205], off
	v_lshl_add_u64 v[212:213], s[10:11], 0, v[166:167]
	s_mov_b32 m0, s81
	s_nop 0
	global_load_lds_dwordx4 v[212:213], off
	s_barrier
	s_waitcnt lgkmcnt(0)
	s_setprio 0
	s_waitcnt lgkmcnt(0)
	v_mfma_f32_16x16x32_bf16 v[60:63], v[186:189], v[144:147], v[60:63]
	v_mfma_f32_16x16x32_bf16 v[28:31], v[194:197], v[144:147], v[28:31]
	v_mfma_f32_16x16x32_bf16 v[56:59], v[186:189], v[152:155], v[56:59]
	v_mfma_f32_16x16x32_bf16 v[24:27], v[194:197], v[152:155], v[24:27]
	v_mfma_f32_16x16x32_bf16 v[52:55], v[186:189], v[160:163], v[52:55]
	v_mfma_f32_16x16x32_bf16 v[20:23], v[194:197], v[160:163], v[20:23]
	v_mfma_f32_16x16x32_bf16 v[48:51], v[186:189], v[178:181], v[48:51]
	v_mfma_f32_16x16x32_bf16 v[16:19], v[194:197], v[178:181], v[16:19]
	v_mfma_f32_16x16x32_bf16 v[60:63], v[190:193], v[148:151], v[60:63]
	v_mfma_f32_16x16x32_bf16 v[28:31], v[208:211], v[148:151], v[28:31]
	v_mfma_f32_16x16x32_bf16 v[56:59], v[190:193], v[156:159], v[56:59]
	v_mfma_f32_16x16x32_bf16 v[24:27], v[208:211], v[156:159], v[24:27]
	v_mfma_f32_16x16x32_bf16 v[52:55], v[190:193], v[174:177], v[52:55]
	v_mfma_f32_16x16x32_bf16 v[20:23], v[208:211], v[174:177], v[20:23]
	v_mfma_f32_16x16x32_bf16 v[48:51], v[190:193], v[182:185], v[48:51]
	v_mfma_f32_16x16x32_bf16 v[16:19], v[208:211], v[182:185], v[16:19]
	s_setprio 1
	s_mov_b32 m0, s21
	v_lshl_add_u64 v[214:215], s[12:13], 0, v[164:165]
	s_barrier
	ds_read_b128 v[144:147], v199 offset:16384
	ds_read_b128 v[148:151], v199 offset:17408
	ds_read_b128 v[152:155], v199 offset:18432
	ds_read_b128 v[156:159], v199 offset:19456
	ds_read_b128 v[160:163], v199 offset:20480
	ds_read_b128 v[174:177], v199 offset:21504
	ds_read_b128 v[178:181], v199 offset:22528
	ds_read_b128 v[182:185], v199 offset:23552
	global_load_lds_dwordx4 v[214:215], off
	v_lshl_add_u64 v[216:217], s[12:13], 0, v[166:167]
	s_mov_b32 m0, s58
	s_nop 0
	global_load_lds_dwordx4 v[216:217], off
	s_barrier
	s_waitcnt lgkmcnt(0)
	s_setprio 0
	s_waitcnt lgkmcnt(0)
	v_mfma_f32_16x16x32_bf16 v[108:111], v[128:131], v[144:147], v[108:111]
	v_mfma_f32_16x16x32_bf16 v[76:79], v[136:139], v[144:147], v[76:79]
	v_mfma_f32_16x16x32_bf16 v[104:107], v[128:131], v[152:155], v[104:107]
	v_mfma_f32_16x16x32_bf16 v[72:75], v[136:139], v[152:155], v[72:75]
	v_mfma_f32_16x16x32_bf16 v[100:103], v[128:131], v[160:163], v[100:103]
	v_mfma_f32_16x16x32_bf16 v[68:71], v[136:139], v[160:163], v[68:71]
	v_mfma_f32_16x16x32_bf16 v[96:99], v[128:131], v[178:181], v[96:99]
	v_mfma_f32_16x16x32_bf16 v[64:67], v[136:139], v[178:181], v[64:67]
	v_mfma_f32_16x16x32_bf16 v[108:111], v[132:135], v[148:151], v[108:111]
	v_mfma_f32_16x16x32_bf16 v[76:79], v[140:143], v[148:151], v[76:79]
	v_mfma_f32_16x16x32_bf16 v[104:107], v[132:135], v[156:159], v[104:107]
	v_mfma_f32_16x16x32_bf16 v[72:75], v[140:143], v[156:159], v[72:75]
	v_mfma_f32_16x16x32_bf16 v[100:103], v[132:135], v[174:177], v[100:103]
	v_mfma_f32_16x16x32_bf16 v[68:71], v[140:143], v[174:177], v[68:71]
	v_mfma_f32_16x16x32_bf16 v[96:99], v[132:135], v[182:185], v[96:99]
	v_mfma_f32_16x16x32_bf16 v[64:67], v[140:143], v[182:185], v[64:67]
	s_setprio 1
	s_barrier
; #define WAIT_V(n) asm volatile("s_waitcnt vmcnt(" #n ")" ::: "memory")
; #define WAIT_L(n) asm volatile("s_waitcnt lgkmcnt(" #n ")" ::: "memory")
; #define BAR __builtin_amdgcn_s_barrier()
; #define SCHED __builtin_amdgcn_sched_barrier(0)
; template <class Get, class Epi>
; DI void gemm_stream(LAS unsigned char* lds, const int K, const int ld, Get get, Epi epi) {
;     ...
;             WAIT_V(6); BAR; MMA(1, 1, At, B1); BAR;
;             LDB(B0, 1, 0); SCHED; LDA(At, 1, 0); STAGE(SAo(0, 1), a2 + hstep);
;             WAIT_L(8); BAR; WAIT_L(0); MMA(0, 0, At, B0); BAR; SCHED;
;             LDB(B1, 1, 1); STAGE(SBo(1, 0), b3);
;             BAR; WAIT_L(0); MMA(0, 1, At, B1); BAR;
;             LDA(At, 1, 1); STAGE(SAo(1, 0), a3);
;             BAR; WAIT_L(0); MMA(1, 0, At, B0); BAR; SCHED;
;             STAGE(SBo(1, 1), b3 + hstep);
	s_add_u32 s6, s10, 0x80000
	s_addc_u32 s7, s11, 0
	s_mov_b32 m0, s82
	v_lshl_add_u64 v[128:129], s[6:7], 0, v[164:165]
	global_load_lds_dwordx4 v[128:129], off
	v_lshl_add_u64 v[128:129], s[6:7], 0, v[166:167]
	s_mov_b32 m0, s83
	s_nop 0
	global_load_lds_dwordx4 v[128:129], off
	s_waitcnt vmcnt(6)
	s_barrier
	s_setprio 0
	v_mfma_f32_16x16x32_bf16 v[44:47], v[186:189], v[144:147], v[44:47]
	v_mfma_f32_16x16x32_bf16 v[12:15], v[194:197], v[144:147], v[12:15]
	v_mfma_f32_16x16x32_bf16 v[40:43], v[186:189], v[152:155], v[40:43]
	v_mfma_f32_16x16x32_bf16 v[8:11], v[194:197], v[152:155], v[8:11]
	v_mfma_f32_16x16x32_bf16 v[36:39], v[186:189], v[160:163], v[36:39]
	v_mfma_f32_16x16x32_bf16 v[4:7], v[194:197], v[160:163], v[4:7]
	v_mfma_f32_16x16x32_bf16 v[32:35], v[186:189], v[178:181], v[32:35]
	v_mfma_f32_16x16x32_bf16 v[0:3], v[194:197], v[178:181], v[0:3]
	v_mfma_f32_16x16x32_bf16 v[44:47], v[190:193], v[148:151], v[44:47]
	v_mfma_f32_16x16x32_bf16 v[12:15], v[208:211], v[148:151], v[12:15]
	v_mfma_f32_16x16x32_bf16 v[40:43], v[190:193], v[156:159], v[40:43]
	v_mfma_f32_16x16x32_bf16 v[8:11], v[208:211], v[156:159], v[8:11]
	v_mfma_f32_16x16x32_bf16 v[36:39], v[190:193], v[174:177], v[36:39]
	v_mfma_f32_16x16x32_bf16 v[4:7], v[208:211], v[174:177], v[4:7]
	v_mfma_f32_16x16x32_bf16 v[32:35], v[190:193], v[182:185], v[32:35]
	v_mfma_f32_16x16x32_bf16 v[0:3], v[208:211], v[182:185], v[0:3]
	s_setprio 1
	s_barrier
	ds_read_b128 v[128:131], v201
	ds_read_b128 v[132:135], v201 offset:1024
	ds_read_b128 v[136:139], v201 offset:2048
	ds_read_b128 v[140:143], v201 offset:3072
	s_add_u32 s6, s12, 0x80000
	s_addc_u32 s7, s13, 0
	s_mov_b32 m0, s59
	v_lshl_add_u64 v[186:187], s[6:7], 0, v[164:165]
	ds_read_b128 v[144:147], v199 offset:32768
	ds_read_b128 v[148:151], v199 offset:33792
	ds_read_b128 v[152:155], v199 offset:34816
	ds_read_b128 v[156:159], v199 offset:35840
	ds_read_b128 v[160:163], v199 offset:36864
	ds_read_b128 v[174:177], v199 offset:37888
	ds_read_b128 v[178:181], v199 offset:38912
	ds_read_b128 v[182:185], v199 offset:39936
	global_load_lds_dwordx4 v[186:187], off
	v_lshl_add_u64 v[186:187], s[6:7], 0, v[166:167]
	s_mov_b32 m0, s60
	s_nop 0
	global_load_lds_dwordx4 v[186:187], off
	s_waitcnt lgkmcnt(8)
	s_barrier
	s_waitcnt lgkmcnt(0)
	s_setprio 0
	s_waitcnt lgkmcnt(0)
	v_mfma_f32_16x16x32_bf16 v[124:127], v[128:131], v[144:147], v[124:127]
	v_mfma_f32_16x16x32_bf16 v[92:95], v[136:139], v[144:147], v[92:95]
	v_mfma_f32_16x16x32_bf16 v[120:123], v[128:131], v[152:155], v[120:123]
	v_mfma_f32_16x16x32_bf16 v[88:91], v[136:139], v[152:155], v[88:91]
	v_mfma_f32_16x16x32_bf16 v[116:119], v[128:131], v[160:163], v[116:119]
	v_mfma_f32_16x16x32_bf16 v[84:87], v[136:139], v[160:163], v[84:87]
	v_mfma_f32_16x16x32_bf16 v[112:115], v[128:131], v[178:181], v[112:115]
	v_mfma_f32_16x16x32_bf16 v[80:83], v[136:139], v[178:181], v[80:83]
	v_mfma_f32_16x16x32_bf16 v[124:127], v[132:135], v[148:151], v[124:127]
	v_mfma_f32_16x16x32_bf16 v[92:95], v[140:143], v[148:151], v[92:95]
	v_mfma_f32_16x16x32_bf16 v[120:123], v[132:135], v[156:159], v[120:123]
	v_mfma_f32_16x16x32_bf16 v[88:91], v[140:143], v[156:159], v[88:91]
	v_mfma_f32_16x16x32_bf16 v[116:119], v[132:135], v[174:177], v[116:119]
	v_mfma_f32_16x16x32_bf16 v[84:87], v[140:143], v[174:177], v[84:87]
	v_mfma_f32_16x16x32_bf16 v[112:115], v[132:135], v[182:185], v[112:115]
	v_mfma_f32_16x16x32_bf16 v[80:83], v[140:143], v[182:185], v[80:83]
	s_setprio 1
	s_barrier
	s_mov_b32 m0, s85
	v_lshl_add_u64 v[204:205], v[204:205], 0, s[0:1]
	ds_read_b128 v[186:189], v202
	ds_read_b128 v[190:193], v202 offset:1024
	ds_read_b128 v[194:197], v202 offset:2048
	ds_read_b128 v[208:211], v202 offset:3072
	global_load_lds_dwordx4 v[204:205], off
	v_lshl_add_u64 v[204:205], v[212:213], 0, s[0:1]
	s_mov_b32 m0, s96
	s_nop 0
	global_load_lds_dwordx4 v[204:205], off
	s_barrier
	s_waitcnt lgkmcnt(0)
	s_setprio 0
	s_waitcnt lgkmcnt(0)
	v_mfma_f32_16x16x32_bf16 v[60:63], v[186:189], v[144:147], v[60:63]
	v_mfma_f32_16x16x32_bf16 v[28:31], v[194:197], v[144:147], v[28:31]
	v_mfma_f32_16x16x32_bf16 v[56:59], v[186:189], v[152:155], v[56:59]
	v_mfma_f32_16x16x32_bf16 v[24:27], v[194:197], v[152:155], v[24:27]
	v_mfma_f32_16x16x32_bf16 v[52:55], v[186:189], v[160:163], v[52:55]
	v_mfma_f32_16x16x32_bf16 v[20:23], v[194:197], v[160:163], v[20:23]
	v_mfma_f32_16x16x32_bf16 v[48:51], v[186:189], v[178:181], v[48:51]
	v_mfma_f32_16x16x32_bf16 v[16:19], v[194:197], v[178:181], v[16:19]
	v_mfma_f32_16x16x32_bf16 v[60:63], v[190:193], v[148:151], v[60:63]
	v_mfma_f32_16x16x32_bf16 v[28:31], v[208:211], v[148:151], v[28:31]
	v_mfma_f32_16x16x32_bf16 v[56:59], v[190:193], v[156:159], v[56:59]
	v_mfma_f32_16x16x32_bf16 v[24:27], v[208:211], v[156:159], v[24:27]
	v_mfma_f32_16x16x32_bf16 v[52:55], v[190:193], v[174:177], v[52:55]
	v_mfma_f32_16x16x32_bf16 v[20:23], v[208:211], v[174:177], v[20:23]
	v_mfma_f32_16x16x32_bf16 v[48:51], v[190:193], v[182:185], v[48:51]
	v_mfma_f32_16x16x32_bf16 v[16:19], v[208:211], v[182:185], v[16:19]
	s_setprio 1
	s_mov_b32 m0, s61
	v_lshl_add_u64 v[204:205], v[214:215], 0, s[0:1]
	s_barrier
	ds_read_b128 v[144:147], v199 offset:49152
	ds_read_b128 v[148:151], v199 offset:50176
	ds_read_b128 v[152:155], v199 offset:51200
	ds_read_b128 v[156:159], v199 offset:52224
	ds_read_b128 v[160:163], v199 offset:53248
	ds_read_b128 v[174:177], v199 offset:54272
	ds_read_b128 v[178:181], v199 offset:55296
	ds_read_b128 v[182:185], v199 offset:56320
	global_load_lds_dwordx4 v[204:205], off
	v_lshl_add_u64 v[204:205], v[216:217], 0, s[0:1]
	s_mov_b32 m0, s62
	s_nop 0
	global_load_lds_dwordx4 v[204:205], off
	s_barrier
; #define WAIT_V(n) asm volatile("s_waitcnt vmcnt(" #n ")" ::: "memory")
; #define WAIT_L(n) asm volatile("s_waitcnt lgkmcnt(" #n ")" ::: "memory")
; #define BAR __builtin_amdgcn_s_barrier()
; #define SCHED __builtin_amdgcn_sched_barrier(0)
; template <class Get, class Epi>
; DI void gemm_stream(LAS unsigned char* lds, const int K, const int ld, Get get, Epi epi) {
;     ...
;             BAR; WAIT_L(0); MMA(1, 0, At, B0); BAR; SCHED;
;             STAGE(SBo(1, 1), b3 + hstep);
;             WAIT_V(6); BAR; MMA(1, 1, At, B1); BAR;
;         }
;         epi(acc, cur);
; DI void epi_resid(const Acc& acc, const P& p, int brow, int bcol, int layer, int gch, bool from_input) {
;     ...
;     const float* gate = modv(p, layer, brow, gch);
; #pragma unroll
;     for (int bj = 0; bj < 2; ++bj)
; #pragma unroll
;         for (int n = 0; n < 2; ++n) {
;             const int c0 = bcol + bj * 128 + wc * 32 + n * 16 + fq * 4;
;             const f32x4 g = *(const f32x4*)(gate + c0);
;             f32x4 xv[2][4];
; #pragma unroll
;             for (int ai = 0; ai < 2; ++ai)
; #pragma unroll
;                 for (int m = 0; m < 4; ++m) {
;                     const int r = brow + ai * 128 + wr * 64 + m * 16 + fr;
;                     const float* sp = (from_input ? inrow(p, r) : xrow(p, r)) + c0;
;                     xv[ai][m] = *(const f32x4*)sp;
;                 }
	s_waitcnt lgkmcnt(0)
	s_setprio 0
	s_waitcnt lgkmcnt(0)
	v_mfma_f32_16x16x32_bf16 v[108:111], v[128:131], v[144:147], v[108:111]
	v_mfma_f32_16x16x32_bf16 v[76:79], v[136:139], v[144:147], v[76:79]
	v_mfma_f32_16x16x32_bf16 v[104:107], v[128:131], v[152:155], v[104:107]
	v_mfma_f32_16x16x32_bf16 v[72:75], v[136:139], v[152:155], v[72:75]
	v_mfma_f32_16x16x32_bf16 v[100:103], v[128:131], v[160:163], v[100:103]
	v_mfma_f32_16x16x32_bf16 v[68:71], v[136:139], v[160:163], v[68:71]
	v_mfma_f32_16x16x32_bf16 v[96:99], v[128:131], v[178:181], v[96:99]
	v_mfma_f32_16x16x32_bf16 v[64:67], v[136:139], v[178:181], v[64:67]
	v_mfma_f32_16x16x32_bf16 v[108:111], v[132:135], v[148:151], v[108:111]
	v_mfma_f32_16x16x32_bf16 v[76:79], v[140:143], v[148:151], v[76:79]
	v_mfma_f32_16x16x32_bf16 v[104:107], v[132:135], v[156:159], v[104:107]
	v_mfma_f32_16x16x32_bf16 v[72:75], v[140:143], v[156:159], v[72:75]
	v_mfma_f32_16x16x32_bf16 v[100:103], v[132:135], v[174:177], v[100:103]
	v_mfma_f32_16x16x32_bf16 v[68:71], v[140:143], v[174:177], v[68:71]
	v_mfma_f32_16x16x32_bf16 v[96:99], v[132:135], v[182:185], v[96:99]
	v_mfma_f32_16x16x32_bf16 v[64:67], v[140:143], v[182:185], v[64:67]
	s_setprio 1
	s_barrier
	s_add_u32 s6, s10, 0x80080
	s_addc_u32 s7, s11, 0
	s_mov_b32 m0, s97
	v_lshl_add_u64 v[128:129], s[6:7], 0, v[164:165]
	global_load_lds_dwordx4 v[128:129], off
	v_lshl_add_u64 v[128:129], s[6:7], 0, v[166:167]
	s_add_i32 m0, s97, 0x2000
	s_nop 0
	global_load_lds_dwordx4 v[128:129], off
	s_waitcnt vmcnt(6)
	s_barrier
	s_setprio 0
	v_mfma_f32_16x16x32_bf16 v[44:47], v[186:189], v[144:147], v[44:47]
	v_mfma_f32_16x16x32_bf16 v[12:15], v[194:197], v[144:147], v[12:15]
	v_mfma_f32_16x16x32_bf16 v[40:43], v[186:189], v[152:155], v[40:43]
	v_mfma_f32_16x16x32_bf16 v[8:11], v[194:197], v[152:155], v[8:11]
	v_mfma_f32_16x16x32_bf16 v[36:39], v[186:189], v[160:163], v[36:39]
	v_mfma_f32_16x16x32_bf16 v[4:7], v[194:197], v[160:163], v[4:7]
	v_mfma_f32_16x16x32_bf16 v[32:35], v[186:189], v[178:181], v[32:35]
	v_mfma_f32_16x16x32_bf16 v[0:3], v[194:197], v[178:181], v[0:3]
	v_mfma_f32_16x16x32_bf16 v[44:47], v[190:193], v[148:151], v[44:47]
	v_mfma_f32_16x16x32_bf16 v[12:15], v[208:211], v[148:151], v[12:15]
	v_mfma_f32_16x16x32_bf16 v[40:43], v[190:193], v[156:159], v[40:43]
	v_mfma_f32_16x16x32_bf16 v[8:11], v[208:211], v[156:159], v[8:11]
	v_mfma_f32_16x16x32_bf16 v[36:39], v[190:193], v[174:177], v[36:39]
	v_mfma_f32_16x16x32_bf16 v[4:7], v[208:211], v[174:177], v[4:7]
	v_mfma_f32_16x16x32_bf16 v[32:35], v[190:193], v[182:185], v[32:35]
	v_mfma_f32_16x16x32_bf16 v[0:3], v[208:211], v[182:185], v[0:3]
	s_setprio 1
	s_add_i32 s18, s18, 2
	s_add_u32 s16, s16, 0x100
	s_addc_u32 s17, s17, 0
	s_cmp_gt_u32 s18, 29
	s_mov_b64 s[6:7], s[8:9]
	s_barrier
	s_cbranch_scc0 .LBB0_1238
	s_lshr_b32 s6, s15, 4
	s_lshl_b32 s7, s15, 8
	s_mulk_i32 s6, 0x1100
	s_and_b32 s7, s7, 0xf00
	s_add_i32 s6, s6, s7
	s_add_i32 s8, s6, 0x100
	s_mul_hi_i32 s6, s8, 0x78787879
	s_lshr_b32 s7, s6, 31
	s_ashr_i32 s6, s6, 11
	s_add_i32 s6, s6, s7
	s_mul_i32 s7, s6, 0xffffef00
	s_mul_i32 s6, s6, 6
	s_lshl_b32 s9, s14, 8
	s_add_i32 s7, s7, s8
	s_add_i32 s6, s6, 2
	s_cmpk_gt_i32 s7, 0xff
	v_mov_b32_e32 v132, v206
	s_cselect_b32 s6, s6, 26
	s_ashr_i32 s7, s6, 31
	v_lshrrev_b32_e32 v128, 1, v132
	v_lshrrev_b32_e32 v129, 2, v132
	s_lshl_b64 s[6:7], s[6:7], 13
	v_and_b32_e32 v128, 0x60, v128
	v_and_b32_e32 v129, 12, v129
	s_add_u32 s6, s26, s6
	v_or3_b32 v174, v128, s9, v129
	s_addc_u32 s7, s27, s7
	v_ashrrev_i32_e32 v175, 31, v174
	v_lshl_add_u64 v[192:193], v[174:175], 2, s[6:7]
	global_load_dwordx4 v[128:131], v[192:193], off
	v_ashrrev_i32_e32 v133, 2, v132
	v_and_b32_e32 v133, 0xffffffc0, v133
	v_and_or_b32 v132, v132, 15, s8
	v_add_u32_e32 v176, v132, v133
	v_mul_hi_i32 v132, v176, s76
	v_lshrrev_b32_e32 v133, 31, v132
	v_ashrrev_i32_e32 v132, 11, v132
	v_add_u32_e32 v203, v132, v133
	v_mad_i32_i24 v204, v203, s77, v176
	v_lshlrev_b32_e32 v211, 12, v203
	v_cmp_lt_i32_e64 s[18:19], s78, v204
	v_mov_b64_e32 v[132:133], s[56:57]
	v_add3_u32 v190, v211, v204, s79
	s_and_saveexec_b64 s[6:7], s[18:19]
	s_xor_b64 s[6:7], exec, s[6:7]
	v_add3_u32 v134, v211, v204, s79
	v_mov_b64_e32 v[132:133], s[52:53]
	s_or_saveexec_b64 s[6:7], s[6:7]
	v_lshl_add_u32 v191, v203, 8, v204
	s_xor_b64 exec, exec, s[6:7]
	v_lshl_add_u32 v134, v203, 8, v204
	s_or_b64 exec, exec, s[6:7]
	v_ashrrev_i32_e32 v135, 31, v134
	v_lshlrev_b64 v[134:135], 13, v[134:135]
	v_lshl_add_u64 v[132:133], v[132:133], 0, v[134:135]
	v_lshl_add_u64 v[132:133], v[174:175], 2, v[132:133]
	global_load_dwordx4 v[160:163], v[132:133], off
	v_or_b32_e32 v132, 16, v176
	v_mul_hi_i32 v133, v132, s76
	v_lshrrev_b32_e32 v134, 31, v133
	v_ashrrev_i32_e32 v133, 11, v133
	v_add_u32_e32 v205, v133, v134
	v_mad_i32_i24 v208, v205, s77, v132
	v_lshlrev_b32_e32 v216, 12, v205
	v_cmp_lt_i32_e64 s[16:17], s78, v208
	v_mov_b64_e32 v[132:133], s[56:57]
	v_add3_u32 v188, v216, v208, s79
	s_and_saveexec_b64 s[6:7], s[16:17]
	s_xor_b64 s[6:7], exec, s[6:7]
	v_add3_u32 v134, v216, v208, s79
	v_mov_b64_e32 v[132:133], s[52:53]
	s_or_saveexec_b64 s[6:7], s[6:7]
	v_lshl_add_u32 v189, v205, 8, v208
	s_xor_b64 exec, exec, s[6:7]
	v_lshl_add_u32 v134, v205, 8, v208
	s_or_b64 exec, exec, s[6:7]
	v_ashrrev_i32_e32 v135, 31, v134
	v_lshlrev_b64 v[134:135], 13, v[134:135]
	v_lshl_add_u64 v[132:133], v[132:133], 0, v[134:135]
	v_lshl_add_u64 v[132:133], v[174:175], 2, v[132:133]
	global_load_dwordx4 v[156:159], v[132:133], off
	v_or_b32_e32 v132, 32, v176
	v_mul_hi_i32 v133, v132, s76
	v_lshrrev_b32_e32 v134, 31, v133
	v_ashrrev_i32_e32 v133, 11, v133
	v_add_u32_e32 v209, v133, v134
; DI void epi_resid(const Acc& acc, const P& p, int brow, int bcol, int layer, int gch, bool from_input) {
;     ...
;             const int c0 = bcol + bj * 128 + wc * 32 + n * 16 + fq * 4;
;             const f32x4 g = *(const f32x4*)(gate + c0);
;             f32x4 xv[2][4];
; #pragma unroll
;             for (int ai = 0; ai < 2; ++ai)
; #pragma unroll
;                 for (int m = 0; m < 4; ++m) {
;                     const int r = brow + ai * 128 + wr * 64 + m * 16 + fr;
;                     const float* sp = (from_input ? inrow(p, r) : xrow(p, r)) + c0;
;                     xv[ai][m] = *(const f32x4*)sp;
;                 }
	v_mad_i32_i24 v210, v209, s77, v132
	v_lshlrev_b32_e32 v219, 12, v209
	v_cmp_lt_i32_e64 s[14:15], s78, v210
	v_mov_b64_e32 v[132:133], s[56:57]
	v_add3_u32 v186, v219, v210, s79
	s_and_saveexec_b64 s[6:7], s[14:15]
	s_xor_b64 s[6:7], exec, s[6:7]
	v_add3_u32 v134, v219, v210, s79
	v_mov_b64_e32 v[132:133], s[52:53]
	s_or_saveexec_b64 s[6:7], s[6:7]
	v_lshl_add_u32 v187, v209, 8, v210
	s_xor_b64 exec, exec, s[6:7]
	v_lshl_add_u32 v134, v209, 8, v210
	s_or_b64 exec, exec, s[6:7]
	v_ashrrev_i32_e32 v135, 31, v134
	v_lshlrev_b64 v[134:135], 13, v[134:135]
	v_lshl_add_u64 v[132:133], v[132:133], 0, v[134:135]
	v_lshl_add_u64 v[132:133], v[174:175], 2, v[132:133]
	global_load_dwordx4 v[152:155], v[132:133], off
	v_or_b32_e32 v132, 48, v176
	v_mul_hi_i32 v133, v132, s76
	v_lshrrev_b32_e32 v134, 31, v133
	v_ashrrev_i32_e32 v133, 11, v133
	v_add_u32_e32 v212, v133, v134
	v_mad_i32_i24 v213, v212, s77, v132
	v_lshlrev_b32_e32 v222, 12, v212
	v_cmp_lt_i32_e64 s[12:13], s78, v213
	v_mov_b64_e32 v[132:133], s[56:57]
	v_add3_u32 v184, v222, v213, s79
	s_and_saveexec_b64 s[6:7], s[12:13]
	s_xor_b64 s[6:7], exec, s[6:7]
	v_add3_u32 v134, v222, v213, s79
	v_mov_b64_e32 v[132:133], s[52:53]
	s_or_saveexec_b64 s[6:7], s[6:7]
	v_lshl_add_u32 v185, v212, 8, v213
	s_xor_b64 exec, exec, s[6:7]
	v_lshl_add_u32 v134, v212, 8, v213
	s_or_b64 exec, exec, s[6:7]
	v_ashrrev_i32_e32 v135, 31, v134
	v_lshlrev_b64 v[134:135], 13, v[134:135]
	v_lshl_add_u64 v[132:133], v[132:133], 0, v[134:135]
	v_lshl_add_u64 v[132:133], v[174:175], 2, v[132:133]
	global_load_dwordx4 v[148:151], v[132:133], off
	v_add_u32_e32 v132, 0x80, v176
	v_mul_hi_i32 v133, v132, s76
	v_lshrrev_b32_e32 v134, 31, v133
	v_ashrrev_i32_e32 v133, 11, v133
	v_add_u32_e32 v214, v133, v134
	v_mad_i32_i24 v215, v214, s77, v132
	v_lshlrev_b32_e32 v225, 12, v214
	v_cmp_lt_i32_e64 s[10:11], s78, v215
	v_mov_b64_e32 v[132:133], s[56:57]
	v_add3_u32 v182, v225, v215, s79
	s_and_saveexec_b64 s[6:7], s[10:11]
	s_xor_b64 s[6:7], exec, s[6:7]
	v_add3_u32 v134, v225, v215, s79
	v_mov_b64_e32 v[132:133], s[52:53]
	s_or_saveexec_b64 s[6:7], s[6:7]
	v_lshl_add_u32 v183, v214, 8, v215
	s_xor_b64 exec, exec, s[6:7]
	v_lshl_add_u32 v134, v214, 8, v215
	s_or_b64 exec, exec, s[6:7]
	v_ashrrev_i32_e32 v135, 31, v134
	v_lshlrev_b64 v[134:135], 13, v[134:135]
	v_lshl_add_u64 v[132:133], v[132:133], 0, v[134:135]
	v_lshl_add_u64 v[132:133], v[174:175], 2, v[132:133]
	global_load_dwordx4 v[144:147], v[132:133], off
	v_add_u32_e32 v132, 0x90, v176
	v_mul_hi_i32 v133, v132, s76
	v_lshrrev_b32_e32 v134, 31, v133
	v_ashrrev_i32_e32 v133, 11, v133
	v_add_u32_e32 v217, v133, v134
	v_mad_i32_i24 v218, v217, s77, v132
	v_lshlrev_b32_e32 v226, 12, v217
	v_cmp_lt_i32_e64 s[8:9], s78, v218
	v_mov_b64_e32 v[132:133], s[56:57]
	v_add3_u32 v180, v226, v218, s79
	s_and_saveexec_b64 s[6:7], s[8:9]
	s_xor_b64 s[6:7], exec, s[6:7]
	v_add3_u32 v134, v226, v218, s79
	v_mov_b64_e32 v[132:133], s[52:53]
	s_or_saveexec_b64 s[6:7], s[6:7]
	v_lshl_add_u32 v181, v217, 8, v218
	s_xor_b64 exec, exec, s[6:7]
	v_lshl_add_u32 v134, v217, 8, v218
	s_or_b64 exec, exec, s[6:7]
	v_ashrrev_i32_e32 v135, 31, v134
	v_lshlrev_b64 v[134:135], 13, v[134:135]
	v_lshl_add_u64 v[132:133], v[132:133], 0, v[134:135]
	v_lshl_add_u64 v[132:133], v[174:175], 2, v[132:133]
	global_load_dwordx4 v[140:143], v[132:133], off
	v_add_u32_e32 v132, 0xa0, v176
	v_mul_hi_i32 v133, v132, s76
	v_lshrrev_b32_e32 v134, 31, v133
	v_ashrrev_i32_e32 v133, 11, v133
	v_add_u32_e32 v220, v133, v134
	v_mad_i32_i24 v221, v220, s77, v132
	v_lshlrev_b32_e32 v227, 12, v220
	v_cmp_lt_i32_e64 s[6:7], s78, v221
	v_mov_b64_e32 v[132:133], s[56:57]
	v_add3_u32 v178, v227, v221, s79
	s_and_saveexec_b64 s[28:29], s[6:7]
	s_xor_b64 s[54:55], exec, s[28:29]
	v_add3_u32 v134, v227, v221, s79
	v_mov_b64_e32 v[132:133], s[52:53]
	s_or_saveexec_b64 s[54:55], s[54:55]
	v_lshl_add_u32 v179, v220, 8, v221
	s_xor_b64 exec, exec, s[54:55]
	v_lshl_add_u32 v134, v220, 8, v221
	s_or_b64 exec, exec, s[54:55]
	v_ashrrev_i32_e32 v135, 31, v134
	v_lshlrev_b64 v[134:135], 13, v[134:135]
	v_lshl_add_u64 v[132:133], v[132:133], 0, v[134:135]
	v_lshl_add_u64 v[132:133], v[174:175], 2, v[132:133]
	global_load_dwordx4 v[136:139], v[132:133], off
	v_add_u32_e32 v132, 0xb0, v176
	v_mul_hi_i32 v133, v132, s76
	v_lshrrev_b32_e32 v134, 31, v133
	v_ashrrev_i32_e32 v133, 11, v133
	v_add_u32_e32 v223, v133, v134
	v_mad_i32_i24 v224, v223, s77, v132
	v_lshlrev_b32_e32 v228, 12, v223
	v_cmp_lt_i32_e32 vcc, s78, v224
	v_mov_b64_e32 v[132:133], s[56:57]
	v_add3_u32 v176, v228, v224, s79
	s_and_saveexec_b64 s[28:29], vcc
	s_xor_b64 s[54:55], exec, s[28:29]
	v_add3_u32 v134, v228, v224, s79
	v_mov_b64_e32 v[132:133], s[52:53]
	s_or_saveexec_b64 s[54:55], s[54:55]
	v_lshl_add_u32 v177, v223, 8, v224
	s_xor_b64 exec, exec, s[54:55]
	v_lshl_add_u32 v134, v223, 8, v224
	s_or_b64 exec, exec, s[54:55]
	v_ashrrev_i32_e32 v135, 31, v134
	v_lshlrev_b64 v[134:135], 13, v[134:135]
	v_lshl_add_u64 v[132:133], v[132:133], 0, v[134:135]
	v_lshl_add_u64 v[132:133], v[174:175], 2, v[132:133]
	global_load_dwordx4 v[132:135], v[132:133], off
	s_and_saveexec_b64 s[28:29], s[18:19]
	s_xor_b64 s[54:55], exec, s[28:29]
	v_add3_u32 v194, v211, v204, s79
	s_or_saveexec_b64 s[54:55], s[54:55]
	v_mov_b64_e32 v[196:197], s[24:25]
	s_xor_b64 exec, exec, s[54:55]
	v_lshl_add_u32 v194, v203, 8, v204
	v_mov_b64_e32 v[196:197], s[36:37]
	s_or_b64 exec, exec, s[54:55]
	v_ashrrev_i32_e32 v195, 31, v194
	s_waitcnt vmcnt(0)
; DI void epi_resid(const Acc& acc, const P& p, int brow, int bcol, int layer, int gch, bool from_input) {
;     ...
;             __builtin_amdgcn_sched_barrier(0);
; #pragma unroll
;             for (int ai = 0; ai < 2; ++ai)
; #pragma unroll
;                 for (int m = 0; m < 4; ++m) {
;                     const int r = brow + ai * 128 + wr * 64 + m * 16 + fr;
;                     *(f32x4*)(xrow(p, r) + c0) = xv[ai][m] + g * acc[ai][bj][m][n];
;                 }
;             __builtin_amdgcn_sched_barrier(0);
	v_pk_fma_f32 v[124:125], v[124:125], v[128:129], v[160:161]
	v_lshlrev_b64 v[160:161], 13, v[194:195]
	v_lshl_add_u64 v[160:161], v[196:197], 0, v[160:161]
	v_pk_fma_f32 v[126:127], v[126:127], v[130:131], v[162:163]
	v_lshl_add_u64 v[160:161], v[174:175], 2, v[160:161]
	global_store_dwordx4 v[160:161], v[124:127], off
	s_and_saveexec_b64 s[28:29], s[16:17]
	s_xor_b64 s[54:55], exec, s[28:29]
	v_add3_u32 v124, v216, v208, s79
	s_or_saveexec_b64 s[54:55], s[54:55]
	v_mov_b64_e32 v[126:127], s[24:25]
	s_xor_b64 exec, exec, s[54:55]
	v_lshl_add_u32 v124, v205, 8, v208
	v_mov_b64_e32 v[126:127], s[36:37]
	s_or_b64 exec, exec, s[54:55]
	v_ashrrev_i32_e32 v125, 31, v124
	v_lshlrev_b64 v[124:125], 13, v[124:125]
	v_lshl_add_u64 v[124:125], v[126:127], 0, v[124:125]
	v_pk_fma_f32 v[122:123], v[122:123], v[130:131], v[158:159]
	v_pk_fma_f32 v[120:121], v[120:121], v[128:129], v[156:157]
	v_lshl_add_u64 v[124:125], v[174:175], 2, v[124:125]
	global_store_dwordx4 v[124:125], v[120:123], off
	s_and_saveexec_b64 s[28:29], s[14:15]
	s_xor_b64 s[54:55], exec, s[28:29]
	v_add3_u32 v120, v219, v210, s79
	s_or_saveexec_b64 s[54:55], s[54:55]
	v_mov_b64_e32 v[122:123], s[24:25]
	s_xor_b64 exec, exec, s[54:55]
	v_lshl_add_u32 v120, v209, 8, v210
	v_mov_b64_e32 v[122:123], s[36:37]
	s_or_b64 exec, exec, s[54:55]
	v_ashrrev_i32_e32 v121, 31, v120
	v_lshlrev_b64 v[120:121], 13, v[120:121]
	v_lshl_add_u64 v[120:121], v[122:123], 0, v[120:121]
	v_pk_fma_f32 v[118:119], v[118:119], v[130:131], v[154:155]
	v_pk_fma_f32 v[116:117], v[116:117], v[128:129], v[152:153]
	v_lshl_add_u64 v[120:121], v[174:175], 2, v[120:121]
	global_store_dwordx4 v[120:121], v[116:119], off
	s_and_saveexec_b64 s[28:29], s[12:13]
	s_xor_b64 s[54:55], exec, s[28:29]
	v_add3_u32 v116, v222, v213, s79
	s_or_saveexec_b64 s[54:55], s[54:55]
	v_mov_b64_e32 v[118:119], s[24:25]
	s_xor_b64 exec, exec, s[54:55]
	v_lshl_add_u32 v116, v212, 8, v213
	v_mov_b64_e32 v[118:119], s[36:37]
	s_or_b64 exec, exec, s[54:55]
	v_ashrrev_i32_e32 v117, 31, v116
	v_lshlrev_b64 v[116:117], 13, v[116:117]
	v_lshl_add_u64 v[116:117], v[118:119], 0, v[116:117]
	v_pk_fma_f32 v[114:115], v[114:115], v[130:131], v[150:151]
	v_pk_fma_f32 v[112:113], v[112:113], v[128:129], v[148:149]
	v_lshl_add_u64 v[116:117], v[174:175], 2, v[116:117]
	global_store_dwordx4 v[116:117], v[112:115], off
	s_and_saveexec_b64 s[28:29], s[10:11]
	s_xor_b64 s[54:55], exec, s[28:29]
	v_add3_u32 v112, v225, v215, s79
	s_or_saveexec_b64 s[54:55], s[54:55]
	v_mov_b64_e32 v[114:115], s[24:25]
	s_xor_b64 exec, exec, s[54:55]
	v_lshl_add_u32 v112, v214, 8, v215
	v_mov_b64_e32 v[114:115], s[36:37]
	s_or_b64 exec, exec, s[54:55]
	v_ashrrev_i32_e32 v113, 31, v112
	v_lshlrev_b64 v[112:113], 13, v[112:113]
	v_lshl_add_u64 v[112:113], v[114:115], 0, v[112:113]
	v_pk_fma_f32 v[110:111], v[110:111], v[130:131], v[146:147]
	v_pk_fma_f32 v[108:109], v[108:109], v[128:129], v[144:145]
	v_lshl_add_u64 v[112:113], v[174:175], 2, v[112:113]
	global_store_dwordx4 v[112:113], v[108:111], off
	s_and_saveexec_b64 s[28:29], s[8:9]
	s_xor_b64 s[54:55], exec, s[28:29]
	v_add3_u32 v108, v226, v218, s79
	s_or_saveexec_b64 s[54:55], s[54:55]
	v_mov_b64_e32 v[110:111], s[24:25]
	s_xor_b64 exec, exec, s[54:55]
	v_lshl_add_u32 v108, v217, 8, v218
	v_mov_b64_e32 v[110:111], s[36:37]
	s_or_b64 exec, exec, s[54:55]
	v_ashrrev_i32_e32 v109, 31, v108
	v_lshlrev_b64 v[108:109], 13, v[108:109]
	v_lshl_add_u64 v[108:109], v[110:111], 0, v[108:109]
	v_pk_fma_f32 v[106:107], v[106:107], v[130:131], v[142:143]
	v_pk_fma_f32 v[104:105], v[104:105], v[128:129], v[140:141]
	v_lshl_add_u64 v[108:109], v[174:175], 2, v[108:109]
	global_store_dwordx4 v[108:109], v[104:107], off
	s_and_saveexec_b64 s[28:29], s[6:7]
	s_xor_b64 s[54:55], exec, s[28:29]
	v_add3_u32 v104, v227, v221, s79
	s_or_saveexec_b64 s[54:55], s[54:55]
	v_mov_b64_e32 v[106:107], s[24:25]
	s_xor_b64 exec, exec, s[54:55]
	v_lshl_add_u32 v104, v220, 8, v221
	v_mov_b64_e32 v[106:107], s[36:37]
	s_or_b64 exec, exec, s[54:55]
	v_ashrrev_i32_e32 v105, 31, v104
	v_lshlrev_b64 v[104:105], 13, v[104:105]
	v_lshl_add_u64 v[104:105], v[106:107], 0, v[104:105]
	v_pk_fma_f32 v[102:103], v[102:103], v[130:131], v[138:139]
	v_pk_fma_f32 v[100:101], v[100:101], v[128:129], v[136:137]
	v_lshl_add_u64 v[104:105], v[174:175], 2, v[104:105]
	global_store_dwordx4 v[104:105], v[100:103], off
	s_and_saveexec_b64 s[28:29], vcc
	s_xor_b64 s[54:55], exec, s[28:29]
	v_add3_u32 v100, v228, v224, s79
	s_or_saveexec_b64 s[54:55], s[54:55]
	v_mov_b64_e32 v[102:103], s[24:25]
	s_xor_b64 exec, exec, s[54:55]
	v_lshl_add_u32 v100, v223, 8, v224
	v_mov_b64_e32 v[102:103], s[36:37]
	s_or_b64 exec, exec, s[54:55]
	v_ashrrev_i32_e32 v101, 31, v100
	v_lshlrev_b64 v[100:101], 13, v[100:101]
	v_lshl_add_u64 v[100:101], v[102:103], 0, v[100:101]
	v_pk_fma_f32 v[98:99], v[98:99], v[130:131], v[134:135]
	v_pk_fma_f32 v[96:97], v[96:97], v[128:129], v[132:133]
	v_lshl_add_u64 v[100:101], v[174:175], 2, v[100:101]
	global_store_dwordx4 v[100:101], v[96:99], off
	global_load_dwordx4 v[96:99], v[192:193], off offset:64
	v_mov_b64_e32 v[100:101], s[56:57]
	s_and_saveexec_b64 s[28:29], s[18:19]
	s_xor_b64 s[54:55], exec, s[28:29]
	v_add3_u32 v102, v211, v204, s79
	v_mov_b64_e32 v[100:101], s[52:53]
	s_andn2_saveexec_b64 s[54:55], s[54:55]
	v_lshl_add_u32 v102, v203, 8, v204
	s_or_b64 exec, exec, s[54:55]
	v_ashrrev_i32_e32 v103, 31, v102
	v_lshlrev_b64 v[102:103], 13, v[102:103]
	v_lshl_add_u64 v[100:101], v[100:101], 0, v[102:103]
	v_lshl_add_u64 v[100:101], v[174:175], 2, v[100:101]
	global_load_dwordx4 v[128:131], v[100:101], off offset:64
	v_mov_b64_e32 v[100:101], s[56:57]
; DI void epi_resid(const Acc& acc, const P& p, int brow, int bcol, int layer, int gch, bool from_input) {
;     ...
;             for (int ai = 0; ai < 2; ++ai)
; #pragma unroll
;                 for (int m = 0; m < 4; ++m) {
;                     const int r = brow + ai * 128 + wr * 64 + m * 16 + fr;
;                     const float* sp = (from_input ? inrow(p, r) : xrow(p, r)) + c0;
;                     xv[ai][m] = *(const f32x4*)sp;
;                 }
;             __builtin_amdgcn_sched_barrier(0);
; #pragma unroll
;             for (int ai = 0; ai < 2; ++ai)
; #pragma unroll
;                 for (int m = 0; m < 4; ++m) {
;                     const int r = brow + ai * 128 + wr * 64 + m * 16 + fr;
;                     *(f32x4*)(xrow(p, r) + c0) = xv[ai][m] + g * acc[ai][bj][m][n];
;                 }
;             __builtin_amdgcn_sched_barrier(0);
	s_and_saveexec_b64 s[28:29], s[16:17]
	s_xor_b64 s[54:55], exec, s[28:29]
	v_add3_u32 v102, v216, v208, s79
	v_mov_b64_e32 v[100:101], s[52:53]
	s_andn2_saveexec_b64 s[54:55], s[54:55]
	v_lshl_add_u32 v102, v205, 8, v208
	s_or_b64 exec, exec, s[54:55]
	v_ashrrev_i32_e32 v103, 31, v102
	v_lshlrev_b64 v[102:103], 13, v[102:103]
	v_lshl_add_u64 v[100:101], v[100:101], 0, v[102:103]
	v_lshl_add_u64 v[100:101], v[174:175], 2, v[100:101]
	global_load_dwordx4 v[124:127], v[100:101], off offset:64
	v_mov_b64_e32 v[100:101], s[56:57]
	s_and_saveexec_b64 s[28:29], s[14:15]
	s_xor_b64 s[54:55], exec, s[28:29]
	v_add3_u32 v102, v219, v210, s79
	v_mov_b64_e32 v[100:101], s[52:53]
	s_andn2_saveexec_b64 s[54:55], s[54:55]
	v_lshl_add_u32 v102, v209, 8, v210
	s_or_b64 exec, exec, s[54:55]
	v_ashrrev_i32_e32 v103, 31, v102
	v_lshlrev_b64 v[102:103], 13, v[102:103]
	v_lshl_add_u64 v[100:101], v[100:101], 0, v[102:103]
	v_lshl_add_u64 v[100:101], v[174:175], 2, v[100:101]
	global_load_dwordx4 v[120:123], v[100:101], off offset:64
	v_mov_b64_e32 v[100:101], s[56:57]
	s_and_saveexec_b64 s[28:29], s[12:13]
	s_xor_b64 s[54:55], exec, s[28:29]
	v_add3_u32 v102, v222, v213, s79
	v_mov_b64_e32 v[100:101], s[52:53]
	s_andn2_saveexec_b64 s[54:55], s[54:55]
	v_lshl_add_u32 v102, v212, 8, v213
	s_or_b64 exec, exec, s[54:55]
	v_ashrrev_i32_e32 v103, 31, v102
	v_lshlrev_b64 v[102:103], 13, v[102:103]
	v_lshl_add_u64 v[100:101], v[100:101], 0, v[102:103]
	v_lshl_add_u64 v[100:101], v[174:175], 2, v[100:101]
	global_load_dwordx4 v[116:119], v[100:101], off offset:64
	v_mov_b64_e32 v[100:101], s[56:57]
	s_and_saveexec_b64 s[28:29], s[10:11]
	s_xor_b64 s[54:55], exec, s[28:29]
	v_add3_u32 v102, v225, v215, s79
	v_mov_b64_e32 v[100:101], s[52:53]
	s_andn2_saveexec_b64 s[54:55], s[54:55]
	v_lshl_add_u32 v102, v214, 8, v215
	s_or_b64 exec, exec, s[54:55]
	v_ashrrev_i32_e32 v103, 31, v102
	v_lshlrev_b64 v[102:103], 13, v[102:103]
	v_lshl_add_u64 v[100:101], v[100:101], 0, v[102:103]
	v_lshl_add_u64 v[100:101], v[174:175], 2, v[100:101]
	global_load_dwordx4 v[112:115], v[100:101], off offset:64
	v_mov_b64_e32 v[100:101], s[56:57]
	s_and_saveexec_b64 s[28:29], s[8:9]
	s_xor_b64 s[54:55], exec, s[28:29]
	v_add3_u32 v102, v226, v218, s79
	v_mov_b64_e32 v[100:101], s[52:53]
	s_andn2_saveexec_b64 s[54:55], s[54:55]
	v_lshl_add_u32 v102, v217, 8, v218
	s_or_b64 exec, exec, s[54:55]
	v_ashrrev_i32_e32 v103, 31, v102
	v_lshlrev_b64 v[102:103], 13, v[102:103]
	v_lshl_add_u64 v[100:101], v[100:101], 0, v[102:103]
	v_lshl_add_u64 v[100:101], v[174:175], 2, v[100:101]
	global_load_dwordx4 v[108:111], v[100:101], off offset:64
	v_mov_b64_e32 v[100:101], s[56:57]
	s_and_saveexec_b64 s[28:29], s[6:7]
	s_xor_b64 s[54:55], exec, s[28:29]
	v_add3_u32 v102, v227, v221, s79
	v_mov_b64_e32 v[100:101], s[52:53]
	s_andn2_saveexec_b64 s[54:55], s[54:55]
	v_lshl_add_u32 v102, v220, 8, v221
	s_or_b64 exec, exec, s[54:55]
	v_ashrrev_i32_e32 v103, 31, v102
	v_lshlrev_b64 v[102:103], 13, v[102:103]
	v_lshl_add_u64 v[100:101], v[100:101], 0, v[102:103]
	v_lshl_add_u64 v[100:101], v[174:175], 2, v[100:101]
	global_load_dwordx4 v[104:107], v[100:101], off offset:64
	v_mov_b64_e32 v[100:101], s[56:57]
	s_and_saveexec_b64 s[28:29], vcc
	s_xor_b64 s[54:55], exec, s[28:29]
	v_add3_u32 v102, v228, v224, s79
	v_mov_b64_e32 v[100:101], s[52:53]
	s_andn2_saveexec_b64 s[54:55], s[54:55]
	v_lshl_add_u32 v102, v223, 8, v224
	s_or_b64 exec, exec, s[54:55]
	v_ashrrev_i32_e32 v103, 31, v102
	v_lshlrev_b64 v[102:103], 13, v[102:103]
	v_lshl_add_u64 v[100:101], v[100:101], 0, v[102:103]
	v_lshl_add_u64 v[100:101], v[174:175], 2, v[100:101]
	global_load_dwordx4 v[100:103], v[100:101], off offset:64
	s_and_saveexec_b64 s[28:29], s[18:19]
	s_xor_b64 s[54:55], exec, s[28:29]
	v_add3_u32 v132, v211, v204, s79
	s_or_saveexec_b64 s[54:55], s[54:55]
	v_mov_b64_e32 v[134:135], s[24:25]
	s_xor_b64 exec, exec, s[54:55]
	v_lshl_add_u32 v132, v203, 8, v204
	v_mov_b64_e32 v[134:135], s[36:37]
	s_or_b64 exec, exec, s[54:55]
	v_ashrrev_i32_e32 v133, 31, v132
	s_waitcnt vmcnt(0)
	v_pk_fma_f32 v[92:93], v[92:93], v[96:97], v[128:129]
	v_lshlrev_b64 v[128:129], 13, v[132:133]
	v_lshl_add_u64 v[128:129], v[134:135], 0, v[128:129]
	v_pk_fma_f32 v[94:95], v[94:95], v[98:99], v[130:131]
	v_lshl_add_u64 v[128:129], v[174:175], 2, v[128:129]
	global_store_dwordx4 v[128:129], v[92:95], off offset:64
	s_and_saveexec_b64 s[28:29], s[16:17]
	s_xor_b64 s[54:55], exec, s[28:29]
	v_add3_u32 v92, v216, v208, s79
	s_or_saveexec_b64 s[54:55], s[54:55]
	v_mov_b64_e32 v[94:95], s[24:25]
	s_xor_b64 exec, exec, s[54:55]
	v_lshl_add_u32 v92, v205, 8, v208
	v_mov_b64_e32 v[94:95], s[36:37]
	s_or_b64 exec, exec, s[54:55]
	v_ashrrev_i32_e32 v93, 31, v92
	v_lshlrev_b64 v[92:93], 13, v[92:93]
	v_lshl_add_u64 v[92:93], v[94:95], 0, v[92:93]
	v_pk_fma_f32 v[90:91], v[90:91], v[98:99], v[126:127]
	v_pk_fma_f32 v[88:89], v[88:89], v[96:97], v[124:125]
	v_lshl_add_u64 v[92:93], v[174:175], 2, v[92:93]
	global_store_dwordx4 v[92:93], v[88:91], off offset:64
	s_and_saveexec_b64 s[28:29], s[14:15]
	s_xor_b64 s[54:55], exec, s[28:29]
	v_add3_u32 v88, v219, v210, s79
	s_or_saveexec_b64 s[54:55], s[54:55]
	v_mov_b64_e32 v[90:91], s[24:25]
	s_xor_b64 exec, exec, s[54:55]
	v_lshl_add_u32 v88, v209, 8, v210
	v_mov_b64_e32 v[90:91], s[36:37]
	s_or_b64 exec, exec, s[54:55]
	v_ashrrev_i32_e32 v89, 31, v88
	v_lshlrev_b64 v[88:89], 13, v[88:89]
	v_lshl_add_u64 v[88:89], v[90:91], 0, v[88:89]
	v_pk_fma_f32 v[86:87], v[86:87], v[98:99], v[122:123]
	v_pk_fma_f32 v[84:85], v[84:85], v[96:97], v[120:121]
	v_lshl_add_u64 v[88:89], v[174:175], 2, v[88:89]
	global_store_dwordx4 v[88:89], v[84:87], off offset:64
; DI void epi_resid(const Acc& acc, const P& p, int brow, int bcol, int layer, int gch, bool from_input) {
;     ...
;             for (int ai = 0; ai < 2; ++ai)
; #pragma unroll
;                 for (int m = 0; m < 4; ++m) {
;                     const int r = brow + ai * 128 + wr * 64 + m * 16 + fr;
;                     const float* sp = (from_input ? inrow(p, r) : xrow(p, r)) + c0;
;                     xv[ai][m] = *(const f32x4*)sp;
;                 }
;             __builtin_amdgcn_sched_barrier(0);
; #pragma unroll
;             for (int ai = 0; ai < 2; ++ai)
; #pragma unroll
;                 for (int m = 0; m < 4; ++m) {
;                     const int r = brow + ai * 128 + wr * 64 + m * 16 + fr;
;                     *(f32x4*)(xrow(p, r) + c0) = xv[ai][m] + g * acc[ai][bj][m][n];
;                 }
;             __builtin_amdgcn_sched_barrier(0);
	s_and_saveexec_b64 s[28:29], s[12:13]
	s_xor_b64 s[54:55], exec, s[28:29]
	v_add3_u32 v84, v222, v213, s79
	s_or_saveexec_b64 s[54:55], s[54:55]
	v_mov_b64_e32 v[86:87], s[24:25]
	s_xor_b64 exec, exec, s[54:55]
	v_lshl_add_u32 v84, v212, 8, v213
	v_mov_b64_e32 v[86:87], s[36:37]
	s_or_b64 exec, exec, s[54:55]
	v_ashrrev_i32_e32 v85, 31, v84
	v_lshlrev_b64 v[84:85], 13, v[84:85]
	v_lshl_add_u64 v[84:85], v[86:87], 0, v[84:85]
	v_pk_fma_f32 v[82:83], v[82:83], v[98:99], v[118:119]
	v_pk_fma_f32 v[80:81], v[80:81], v[96:97], v[116:117]
	v_lshl_add_u64 v[84:85], v[174:175], 2, v[84:85]
	global_store_dwordx4 v[84:85], v[80:83], off offset:64
	s_and_saveexec_b64 s[28:29], s[10:11]
	s_xor_b64 s[54:55], exec, s[28:29]
	v_add3_u32 v80, v225, v215, s79
	s_or_saveexec_b64 s[54:55], s[54:55]
	v_mov_b64_e32 v[82:83], s[24:25]
	s_xor_b64 exec, exec, s[54:55]
	v_lshl_add_u32 v80, v214, 8, v215
	v_mov_b64_e32 v[82:83], s[36:37]
	s_or_b64 exec, exec, s[54:55]
	v_ashrrev_i32_e32 v81, 31, v80
	v_lshlrev_b64 v[80:81], 13, v[80:81]
	v_lshl_add_u64 v[80:81], v[82:83], 0, v[80:81]
	v_pk_fma_f32 v[78:79], v[78:79], v[98:99], v[114:115]
	v_pk_fma_f32 v[76:77], v[76:77], v[96:97], v[112:113]
	v_lshl_add_u64 v[80:81], v[174:175], 2, v[80:81]
	global_store_dwordx4 v[80:81], v[76:79], off offset:64
	s_and_saveexec_b64 s[28:29], s[8:9]
	s_xor_b64 s[54:55], exec, s[28:29]
	v_add3_u32 v76, v226, v218, s79
	s_or_saveexec_b64 s[54:55], s[54:55]
	v_mov_b64_e32 v[78:79], s[24:25]
	s_xor_b64 exec, exec, s[54:55]
	v_lshl_add_u32 v76, v217, 8, v218
	v_mov_b64_e32 v[78:79], s[36:37]
	s_or_b64 exec, exec, s[54:55]
	v_ashrrev_i32_e32 v77, 31, v76
	v_lshlrev_b64 v[76:77], 13, v[76:77]
	v_lshl_add_u64 v[76:77], v[78:79], 0, v[76:77]
	v_pk_fma_f32 v[74:75], v[74:75], v[98:99], v[110:111]
	v_pk_fma_f32 v[72:73], v[72:73], v[96:97], v[108:109]
	v_lshl_add_u64 v[76:77], v[174:175], 2, v[76:77]
	global_store_dwordx4 v[76:77], v[72:75], off offset:64
	s_and_saveexec_b64 s[28:29], s[6:7]
	s_xor_b64 s[54:55], exec, s[28:29]
	v_add3_u32 v72, v227, v221, s79
	s_or_saveexec_b64 s[54:55], s[54:55]
	v_mov_b64_e32 v[74:75], s[24:25]
	s_xor_b64 exec, exec, s[54:55]
	v_lshl_add_u32 v72, v220, 8, v221
	v_mov_b64_e32 v[74:75], s[36:37]
	s_or_b64 exec, exec, s[54:55]
	v_ashrrev_i32_e32 v73, 31, v72
	v_lshlrev_b64 v[72:73], 13, v[72:73]
	v_lshl_add_u64 v[72:73], v[74:75], 0, v[72:73]
	v_pk_fma_f32 v[70:71], v[70:71], v[98:99], v[106:107]
	v_pk_fma_f32 v[68:69], v[68:69], v[96:97], v[104:105]
	v_lshl_add_u64 v[72:73], v[174:175], 2, v[72:73]
	global_store_dwordx4 v[72:73], v[68:71], off offset:64
	s_and_saveexec_b64 s[28:29], vcc
	s_xor_b64 s[54:55], exec, s[28:29]
	v_add3_u32 v68, v228, v224, s79
	s_or_saveexec_b64 s[54:55], s[54:55]
	v_mov_b64_e32 v[70:71], s[24:25]
	s_xor_b64 exec, exec, s[54:55]
	v_lshl_add_u32 v68, v223, 8, v224
	v_mov_b64_e32 v[70:71], s[36:37]
	s_or_b64 exec, exec, s[54:55]
	v_ashrrev_i32_e32 v69, 31, v68
	v_lshlrev_b64 v[68:69], 13, v[68:69]
	v_lshl_add_u64 v[68:69], v[70:71], 0, v[68:69]
	v_pk_fma_f32 v[66:67], v[66:67], v[98:99], v[102:103]
	v_pk_fma_f32 v[64:65], v[64:65], v[96:97], v[100:101]
	v_lshl_add_u64 v[68:69], v[174:175], 2, v[68:69]
	global_store_dwordx4 v[68:69], v[64:67], off offset:64
	global_load_dwordx4 v[64:67], v[192:193], off offset:512
	v_mov_b64_e32 v[68:69], s[56:57]
	s_and_saveexec_b64 s[28:29], s[18:19]
	s_xor_b64 s[54:55], exec, s[28:29]
	v_add3_u32 v70, v211, v204, s79
	v_mov_b64_e32 v[68:69], s[52:53]
	s_andn2_saveexec_b64 s[54:55], s[54:55]
	v_lshl_add_u32 v70, v203, 8, v204
	s_or_b64 exec, exec, s[54:55]
	v_ashrrev_i32_e32 v71, 31, v70
	v_lshlrev_b64 v[70:71], 13, v[70:71]
	v_lshl_add_u64 v[68:69], v[68:69], 0, v[70:71]
	v_lshl_add_u64 v[68:69], v[174:175], 2, v[68:69]
	global_load_dwordx4 v[96:99], v[68:69], off offset:512
	v_mov_b64_e32 v[68:69], s[56:57]
	s_and_saveexec_b64 s[28:29], s[16:17]
	s_xor_b64 s[54:55], exec, s[28:29]
	v_add3_u32 v70, v216, v208, s79
	v_mov_b64_e32 v[68:69], s[52:53]
	s_andn2_saveexec_b64 s[54:55], s[54:55]
	v_lshl_add_u32 v70, v205, 8, v208
	s_or_b64 exec, exec, s[54:55]
	v_ashrrev_i32_e32 v71, 31, v70
	v_lshlrev_b64 v[70:71], 13, v[70:71]
	v_lshl_add_u64 v[68:69], v[68:69], 0, v[70:71]
	v_lshl_add_u64 v[68:69], v[174:175], 2, v[68:69]
	global_load_dwordx4 v[92:95], v[68:69], off offset:512
	v_mov_b64_e32 v[68:69], s[56:57]
	s_and_saveexec_b64 s[28:29], s[14:15]
	s_xor_b64 s[54:55], exec, s[28:29]
	v_add3_u32 v70, v219, v210, s79
	v_mov_b64_e32 v[68:69], s[52:53]
	s_andn2_saveexec_b64 s[54:55], s[54:55]
	v_lshl_add_u32 v70, v209, 8, v210
	s_or_b64 exec, exec, s[54:55]
	v_ashrrev_i32_e32 v71, 31, v70
	v_lshlrev_b64 v[70:71], 13, v[70:71]
	v_lshl_add_u64 v[68:69], v[68:69], 0, v[70:71]
	v_lshl_add_u64 v[68:69], v[174:175], 2, v[68:69]
	global_load_dwordx4 v[88:91], v[68:69], off offset:512
	v_mov_b64_e32 v[68:69], s[56:57]
	s_and_saveexec_b64 s[28:29], s[12:13]
	s_xor_b64 s[54:55], exec, s[28:29]
	v_add3_u32 v70, v222, v213, s79
	v_mov_b64_e32 v[68:69], s[52:53]
	s_andn2_saveexec_b64 s[54:55], s[54:55]
	v_lshl_add_u32 v70, v212, 8, v213
	s_or_b64 exec, exec, s[54:55]
	v_ashrrev_i32_e32 v71, 31, v70
	v_lshlrev_b64 v[70:71], 13, v[70:71]
	v_lshl_add_u64 v[68:69], v[68:69], 0, v[70:71]
	v_lshl_add_u64 v[68:69], v[174:175], 2, v[68:69]
	global_load_dwordx4 v[84:87], v[68:69], off offset:512
	v_mov_b64_e32 v[68:69], s[56:57]
	s_and_saveexec_b64 s[28:29], s[10:11]
	s_xor_b64 s[54:55], exec, s[28:29]
	v_add3_u32 v70, v225, v215, s79
	v_mov_b64_e32 v[68:69], s[52:53]
	s_andn2_saveexec_b64 s[54:55], s[54:55]
	v_lshl_add_u32 v70, v214, 8, v215
	s_or_b64 exec, exec, s[54:55]
	v_ashrrev_i32_e32 v71, 31, v70
; DI void epi_resid(const Acc& acc, const P& p, int brow, int bcol, int layer, int gch, bool from_input) {
;     ...
;             for (int ai = 0; ai < 2; ++ai)
; #pragma unroll
;                 for (int m = 0; m < 4; ++m) {
;                     const int r = brow + ai * 128 + wr * 64 + m * 16 + fr;
;                     const float* sp = (from_input ? inrow(p, r) : xrow(p, r)) + c0;
;                     xv[ai][m] = *(const f32x4*)sp;
;                 }
;             __builtin_amdgcn_sched_barrier(0);
; #pragma unroll
;             for (int ai = 0; ai < 2; ++ai)
; #pragma unroll
;                 for (int m = 0; m < 4; ++m) {
;                     const int r = brow + ai * 128 + wr * 64 + m * 16 + fr;
;                     *(f32x4*)(xrow(p, r) + c0) = xv[ai][m] + g * acc[ai][bj][m][n];
;                 }
;             __builtin_amdgcn_sched_barrier(0);
	v_lshlrev_b64 v[70:71], 13, v[70:71]
	v_lshl_add_u64 v[68:69], v[68:69], 0, v[70:71]
	v_lshl_add_u64 v[68:69], v[174:175], 2, v[68:69]
	global_load_dwordx4 v[80:83], v[68:69], off offset:512
	v_mov_b64_e32 v[68:69], s[56:57]
	s_and_saveexec_b64 s[28:29], s[8:9]
	s_xor_b64 s[54:55], exec, s[28:29]
	v_add3_u32 v70, v226, v218, s79
	v_mov_b64_e32 v[68:69], s[52:53]
	s_andn2_saveexec_b64 s[54:55], s[54:55]
	v_lshl_add_u32 v70, v217, 8, v218
	s_or_b64 exec, exec, s[54:55]
	v_ashrrev_i32_e32 v71, 31, v70
	v_lshlrev_b64 v[70:71], 13, v[70:71]
	v_lshl_add_u64 v[68:69], v[68:69], 0, v[70:71]
	v_lshl_add_u64 v[68:69], v[174:175], 2, v[68:69]
	global_load_dwordx4 v[76:79], v[68:69], off offset:512
	v_mov_b64_e32 v[68:69], s[56:57]
	s_and_saveexec_b64 s[28:29], s[6:7]
	s_xor_b64 s[54:55], exec, s[28:29]
	v_add3_u32 v70, v227, v221, s79
	v_mov_b64_e32 v[68:69], s[52:53]
	s_andn2_saveexec_b64 s[54:55], s[54:55]
	v_lshl_add_u32 v70, v220, 8, v221
	s_or_b64 exec, exec, s[54:55]
	v_ashrrev_i32_e32 v71, 31, v70
	v_lshlrev_b64 v[70:71], 13, v[70:71]
	v_lshl_add_u64 v[68:69], v[68:69], 0, v[70:71]
	v_lshl_add_u64 v[68:69], v[174:175], 2, v[68:69]
	global_load_dwordx4 v[72:75], v[68:69], off offset:512
	v_mov_b64_e32 v[68:69], s[56:57]
	s_and_saveexec_b64 s[28:29], vcc
	s_xor_b64 s[54:55], exec, s[28:29]
	v_add3_u32 v70, v228, v224, s79
	v_mov_b64_e32 v[68:69], s[52:53]
	s_andn2_saveexec_b64 s[54:55], s[54:55]
	v_lshl_add_u32 v70, v223, 8, v224
	s_or_b64 exec, exec, s[54:55]
	v_ashrrev_i32_e32 v71, 31, v70
	v_lshlrev_b64 v[70:71], 13, v[70:71]
	v_lshl_add_u64 v[68:69], v[68:69], 0, v[70:71]
	v_lshl_add_u64 v[68:69], v[174:175], 2, v[68:69]
	global_load_dwordx4 v[68:71], v[68:69], off offset:512
	s_and_saveexec_b64 s[28:29], s[18:19]
	s_xor_b64 s[54:55], exec, s[28:29]
	v_add3_u32 v100, v211, v204, s79
	s_or_saveexec_b64 s[54:55], s[54:55]
	v_mov_b64_e32 v[102:103], s[24:25]
	s_xor_b64 exec, exec, s[54:55]
	v_lshl_add_u32 v100, v203, 8, v204
	v_mov_b64_e32 v[102:103], s[36:37]
	s_or_b64 exec, exec, s[54:55]
	v_ashrrev_i32_e32 v101, 31, v100
	s_waitcnt vmcnt(0)
	v_pk_fma_f32 v[60:61], v[60:61], v[64:65], v[96:97]
	v_lshlrev_b64 v[96:97], 13, v[100:101]
	v_lshl_add_u64 v[96:97], v[102:103], 0, v[96:97]
	v_pk_fma_f32 v[62:63], v[62:63], v[66:67], v[98:99]
	v_lshl_add_u64 v[96:97], v[174:175], 2, v[96:97]
	global_store_dwordx4 v[96:97], v[60:63], off offset:512
	s_and_saveexec_b64 s[28:29], s[16:17]
	s_xor_b64 s[54:55], exec, s[28:29]
	v_add3_u32 v60, v216, v208, s79
	s_or_saveexec_b64 s[54:55], s[54:55]
	v_mov_b64_e32 v[62:63], s[24:25]
	s_xor_b64 exec, exec, s[54:55]
	v_lshl_add_u32 v60, v205, 8, v208
	v_mov_b64_e32 v[62:63], s[36:37]
	s_or_b64 exec, exec, s[54:55]
	v_ashrrev_i32_e32 v61, 31, v60
	v_lshlrev_b64 v[60:61], 13, v[60:61]
	v_lshl_add_u64 v[60:61], v[62:63], 0, v[60:61]
	v_pk_fma_f32 v[58:59], v[58:59], v[66:67], v[94:95]
	v_pk_fma_f32 v[56:57], v[56:57], v[64:65], v[92:93]
	v_lshl_add_u64 v[60:61], v[174:175], 2, v[60:61]
	global_store_dwordx4 v[60:61], v[56:59], off offset:512
	s_and_saveexec_b64 s[28:29], s[14:15]
	s_xor_b64 s[54:55], exec, s[28:29]
	v_add3_u32 v56, v219, v210, s79
	s_or_saveexec_b64 s[54:55], s[54:55]
	v_mov_b64_e32 v[58:59], s[24:25]
	s_xor_b64 exec, exec, s[54:55]
	v_lshl_add_u32 v56, v209, 8, v210
	v_mov_b64_e32 v[58:59], s[36:37]
	s_or_b64 exec, exec, s[54:55]
	v_ashrrev_i32_e32 v57, 31, v56
	v_lshlrev_b64 v[56:57], 13, v[56:57]
	v_lshl_add_u64 v[56:57], v[58:59], 0, v[56:57]
	v_pk_fma_f32 v[54:55], v[54:55], v[66:67], v[90:91]
	v_pk_fma_f32 v[52:53], v[52:53], v[64:65], v[88:89]
	v_lshl_add_u64 v[56:57], v[174:175], 2, v[56:57]
	global_store_dwordx4 v[56:57], v[52:55], off offset:512
	s_and_saveexec_b64 s[28:29], s[12:13]
	s_xor_b64 s[54:55], exec, s[28:29]
	v_add3_u32 v52, v222, v213, s79
	s_or_saveexec_b64 s[54:55], s[54:55]
	v_mov_b64_e32 v[54:55], s[24:25]
	s_xor_b64 exec, exec, s[54:55]
	v_lshl_add_u32 v52, v212, 8, v213
	v_mov_b64_e32 v[54:55], s[36:37]
	s_or_b64 exec, exec, s[54:55]
	v_ashrrev_i32_e32 v53, 31, v52
	v_lshlrev_b64 v[52:53], 13, v[52:53]
	v_lshl_add_u64 v[52:53], v[54:55], 0, v[52:53]
	v_pk_fma_f32 v[50:51], v[50:51], v[66:67], v[86:87]
	v_pk_fma_f32 v[48:49], v[48:49], v[64:65], v[84:85]
	v_lshl_add_u64 v[52:53], v[174:175], 2, v[52:53]
	global_store_dwordx4 v[52:53], v[48:51], off offset:512
	s_and_saveexec_b64 s[28:29], s[10:11]
	s_xor_b64 s[54:55], exec, s[28:29]
	v_add3_u32 v48, v225, v215, s79
	s_or_saveexec_b64 s[54:55], s[54:55]
	v_mov_b64_e32 v[50:51], s[24:25]
	s_xor_b64 exec, exec, s[54:55]
	v_lshl_add_u32 v48, v214, 8, v215
	v_mov_b64_e32 v[50:51], s[36:37]
	s_or_b64 exec, exec, s[54:55]
	v_ashrrev_i32_e32 v49, 31, v48
	v_lshlrev_b64 v[48:49], 13, v[48:49]
	v_lshl_add_u64 v[48:49], v[50:51], 0, v[48:49]
	v_pk_fma_f32 v[46:47], v[46:47], v[66:67], v[82:83]
	v_pk_fma_f32 v[44:45], v[44:45], v[64:65], v[80:81]
	v_lshl_add_u64 v[48:49], v[174:175], 2, v[48:49]
	global_store_dwordx4 v[48:49], v[44:47], off offset:512
	s_and_saveexec_b64 s[28:29], s[8:9]
	s_xor_b64 s[54:55], exec, s[28:29]
	v_add3_u32 v44, v226, v218, s79
	s_or_saveexec_b64 s[54:55], s[54:55]
	v_mov_b64_e32 v[46:47], s[24:25]
	s_xor_b64 exec, exec, s[54:55]
	v_lshl_add_u32 v44, v217, 8, v218
	v_mov_b64_e32 v[46:47], s[36:37]
	s_or_b64 exec, exec, s[54:55]
	v_ashrrev_i32_e32 v45, 31, v44
	v_lshlrev_b64 v[44:45], 13, v[44:45]
	v_lshl_add_u64 v[44:45], v[46:47], 0, v[44:45]
	v_pk_fma_f32 v[42:43], v[42:43], v[66:67], v[78:79]
	v_pk_fma_f32 v[40:41], v[40:41], v[64:65], v[76:77]
	v_lshl_add_u64 v[44:45], v[174:175], 2, v[44:45]
	global_store_dwordx4 v[44:45], v[40:43], off offset:512
	s_and_saveexec_b64 s[28:29], s[6:7]
; DI void epi_resid(const Acc& acc, const P& p, int brow, int bcol, int layer, int gch, bool from_input) {
;     ...
;             for (int ai = 0; ai < 2; ++ai)
; #pragma unroll
;                 for (int m = 0; m < 4; ++m) {
;                     const int r = brow + ai * 128 + wr * 64 + m * 16 + fr;
;                     const float* sp = (from_input ? inrow(p, r) : xrow(p, r)) + c0;
;                     xv[ai][m] = *(const f32x4*)sp;
;                 }
;             __builtin_amdgcn_sched_barrier(0);
; #pragma unroll
;             for (int ai = 0; ai < 2; ++ai)
; #pragma unroll
;                 for (int m = 0; m < 4; ++m) {
;                     const int r = brow + ai * 128 + wr * 64 + m * 16 + fr;
;                     *(f32x4*)(xrow(p, r) + c0) = xv[ai][m] + g * acc[ai][bj][m][n];
;                 }
;             __builtin_amdgcn_sched_barrier(0);
	s_xor_b64 s[54:55], exec, s[28:29]
	v_add3_u32 v40, v227, v221, s79
	s_or_saveexec_b64 s[54:55], s[54:55]
	v_mov_b64_e32 v[42:43], s[24:25]
	s_xor_b64 exec, exec, s[54:55]
	v_lshl_add_u32 v40, v220, 8, v221
	v_mov_b64_e32 v[42:43], s[36:37]
	s_or_b64 exec, exec, s[54:55]
	v_ashrrev_i32_e32 v41, 31, v40
	v_lshlrev_b64 v[40:41], 13, v[40:41]
	v_lshl_add_u64 v[40:41], v[42:43], 0, v[40:41]
	v_pk_fma_f32 v[38:39], v[38:39], v[66:67], v[74:75]
	v_pk_fma_f32 v[36:37], v[36:37], v[64:65], v[72:73]
	v_lshl_add_u64 v[40:41], v[174:175], 2, v[40:41]
	global_store_dwordx4 v[40:41], v[36:39], off offset:512
	s_and_saveexec_b64 s[28:29], vcc
	s_xor_b64 s[54:55], exec, s[28:29]
	v_add3_u32 v36, v228, v224, s79
	s_or_saveexec_b64 s[54:55], s[54:55]
	v_mov_b64_e32 v[38:39], s[24:25]
	s_xor_b64 exec, exec, s[54:55]
	v_lshl_add_u32 v36, v223, 8, v224
	v_mov_b64_e32 v[38:39], s[36:37]
	s_or_b64 exec, exec, s[54:55]
	v_ashrrev_i32_e32 v37, 31, v36
	v_lshlrev_b64 v[36:37], 13, v[36:37]
	v_lshl_add_u64 v[36:37], v[38:39], 0, v[36:37]
	v_pk_fma_f32 v[34:35], v[34:35], v[66:67], v[70:71]
	v_pk_fma_f32 v[32:33], v[32:33], v[64:65], v[68:69]
	v_lshl_add_u64 v[36:37], v[174:175], 2, v[36:37]
	global_store_dwordx4 v[36:37], v[32:35], off offset:512
	global_load_dwordx4 v[32:35], v[192:193], off offset:576
	v_mov_b64_e32 v[36:37], s[56:57]
	s_and_saveexec_b64 s[28:29], s[18:19]
	s_xor_b64 s[54:55], exec, s[28:29]
	v_add3_u32 v38, v211, v204, s79
	v_mov_b64_e32 v[36:37], s[52:53]
	s_andn2_saveexec_b64 s[54:55], s[54:55]
	v_lshl_add_u32 v38, v203, 8, v204
	s_or_b64 exec, exec, s[54:55]
	v_ashrrev_i32_e32 v39, 31, v38
	v_lshlrev_b64 v[38:39], 13, v[38:39]
	v_lshl_add_u64 v[36:37], v[36:37], 0, v[38:39]
	v_lshl_add_u64 v[36:37], v[174:175], 2, v[36:37]
	global_load_dwordx4 v[64:67], v[36:37], off offset:576
	v_mov_b64_e32 v[36:37], s[56:57]
	s_and_saveexec_b64 s[28:29], s[16:17]
	s_xor_b64 s[54:55], exec, s[28:29]
	v_add3_u32 v38, v216, v208, s79
	v_mov_b64_e32 v[36:37], s[52:53]
	s_andn2_saveexec_b64 s[54:55], s[54:55]
	v_lshl_add_u32 v38, v205, 8, v208
	s_or_b64 exec, exec, s[54:55]
	v_ashrrev_i32_e32 v39, 31, v38
	v_lshlrev_b64 v[38:39], 13, v[38:39]
	v_lshl_add_u64 v[36:37], v[36:37], 0, v[38:39]
	v_lshl_add_u64 v[36:37], v[174:175], 2, v[36:37]
	global_load_dwordx4 v[60:63], v[36:37], off offset:576
	v_mov_b64_e32 v[36:37], s[56:57]
	s_and_saveexec_b64 s[28:29], s[14:15]
	s_xor_b64 s[54:55], exec, s[28:29]
	v_add3_u32 v38, v219, v210, s79
	v_mov_b64_e32 v[36:37], s[52:53]
	s_andn2_saveexec_b64 s[54:55], s[54:55]
	v_lshl_add_u32 v38, v209, 8, v210
	s_or_b64 exec, exec, s[54:55]
	v_ashrrev_i32_e32 v39, 31, v38
	v_lshlrev_b64 v[38:39], 13, v[38:39]
	v_lshl_add_u64 v[36:37], v[36:37], 0, v[38:39]
	v_lshl_add_u64 v[36:37], v[174:175], 2, v[36:37]
	global_load_dwordx4 v[56:59], v[36:37], off offset:576
	v_mov_b64_e32 v[36:37], s[56:57]
	s_and_saveexec_b64 s[28:29], s[12:13]
	s_xor_b64 s[54:55], exec, s[28:29]
	v_add3_u32 v38, v222, v213, s79
	v_mov_b64_e32 v[36:37], s[52:53]
	s_andn2_saveexec_b64 s[54:55], s[54:55]
	v_lshl_add_u32 v38, v212, 8, v213
	s_or_b64 exec, exec, s[54:55]
	v_ashrrev_i32_e32 v39, 31, v38
	v_lshlrev_b64 v[38:39], 13, v[38:39]
	v_lshl_add_u64 v[36:37], v[36:37], 0, v[38:39]
	v_lshl_add_u64 v[36:37], v[174:175], 2, v[36:37]
	global_load_dwordx4 v[52:55], v[36:37], off offset:576
	v_mov_b64_e32 v[36:37], s[56:57]
	s_and_saveexec_b64 s[28:29], s[10:11]
	s_xor_b64 s[54:55], exec, s[28:29]
	v_add3_u32 v38, v225, v215, s79
	v_mov_b64_e32 v[36:37], s[52:53]
	s_andn2_saveexec_b64 s[54:55], s[54:55]
	v_lshl_add_u32 v38, v214, 8, v215
	s_or_b64 exec, exec, s[54:55]
	v_ashrrev_i32_e32 v39, 31, v38
	v_lshlrev_b64 v[38:39], 13, v[38:39]
	v_lshl_add_u64 v[36:37], v[36:37], 0, v[38:39]
	v_lshl_add_u64 v[36:37], v[174:175], 2, v[36:37]
	global_load_dwordx4 v[48:51], v[36:37], off offset:576
	v_mov_b64_e32 v[36:37], s[56:57]
	s_and_saveexec_b64 s[28:29], s[8:9]
	s_xor_b64 s[54:55], exec, s[28:29]
	v_add3_u32 v38, v226, v218, s79
	v_mov_b64_e32 v[36:37], s[52:53]
	s_andn2_saveexec_b64 s[54:55], s[54:55]
	v_lshl_add_u32 v38, v217, 8, v218
	s_or_b64 exec, exec, s[54:55]
	v_ashrrev_i32_e32 v39, 31, v38
	v_lshlrev_b64 v[38:39], 13, v[38:39]
	v_lshl_add_u64 v[36:37], v[36:37], 0, v[38:39]
	v_lshl_add_u64 v[36:37], v[174:175], 2, v[36:37]
	global_load_dwordx4 v[44:47], v[36:37], off offset:576
	v_mov_b64_e32 v[36:37], s[56:57]
	s_and_saveexec_b64 s[28:29], s[6:7]
	s_xor_b64 s[54:55], exec, s[28:29]
	v_add3_u32 v38, v227, v221, s79
	v_mov_b64_e32 v[36:37], s[52:53]
	s_andn2_saveexec_b64 s[54:55], s[54:55]
	v_lshl_add_u32 v38, v220, 8, v221
	s_or_b64 exec, exec, s[54:55]
	v_ashrrev_i32_e32 v39, 31, v38
	v_lshlrev_b64 v[38:39], 13, v[38:39]
	v_lshl_add_u64 v[36:37], v[36:37], 0, v[38:39]
	v_lshl_add_u64 v[36:37], v[174:175], 2, v[36:37]
	global_load_dwordx4 v[40:43], v[36:37], off offset:576
	v_mov_b64_e32 v[36:37], s[56:57]
	s_and_saveexec_b64 s[28:29], vcc
	s_xor_b64 s[54:55], exec, s[28:29]
	v_add3_u32 v38, v228, v224, s79
	v_mov_b64_e32 v[36:37], s[52:53]
	s_andn2_saveexec_b64 s[54:55], s[54:55]
	v_lshl_add_u32 v38, v223, 8, v224
	s_or_b64 exec, exec, s[54:55]
	v_ashrrev_i32_e32 v39, 31, v38
	v_lshlrev_b64 v[38:39], 13, v[38:39]
	v_lshl_add_u64 v[36:37], v[36:37], 0, v[38:39]
	v_lshl_add_u64 v[36:37], v[174:175], 2, v[36:37]
	global_load_dwordx4 v[36:39], v[36:37], off offset:576
	s_and_saveexec_b64 s[28:29], s[18:19]
	s_xor_b64 s[18:19], exec, s[28:29]
	s_or_saveexec_b64 s[18:19], s[18:19]
	v_mov_b64_e32 v[68:69], s[24:25]
	s_xor_b64 exec, exec, s[18:19]
	v_mov_b64_e32 v[68:69], s[36:37]
	v_mov_b32_e32 v190, v191
	s_or_b64 exec, exec, s[18:19]
	v_ashrrev_i32_e32 v191, 31, v190
	s_waitcnt vmcnt(0)
; DI void epi_resid(const Acc& acc, const P& p, int brow, int bcol, int layer, int gch, bool from_input) {
;     ...
;             __builtin_amdgcn_sched_barrier(0);
; #pragma unroll
;             for (int ai = 0; ai < 2; ++ai)
; #pragma unroll
;                 for (int m = 0; m < 4; ++m) {
;                     const int r = brow + ai * 128 + wr * 64 + m * 16 + fr;
;                     *(f32x4*)(xrow(p, r) + c0) = xv[ai][m] + g * acc[ai][bj][m][n];
;                 }
;             __builtin_amdgcn_sched_barrier(0);
	v_pk_fma_f32 v[28:29], v[28:29], v[32:33], v[64:65]
	v_lshlrev_b64 v[64:65], 13, v[190:191]
	v_lshl_add_u64 v[64:65], v[68:69], 0, v[64:65]
	v_pk_fma_f32 v[30:31], v[30:31], v[34:35], v[66:67]
	v_lshl_add_u64 v[64:65], v[174:175], 2, v[64:65]
	global_store_dwordx4 v[64:65], v[28:31], off offset:576
	s_and_saveexec_b64 s[18:19], s[16:17]
	s_xor_b64 s[16:17], exec, s[18:19]
	s_or_saveexec_b64 s[16:17], s[16:17]
	v_mov_b64_e32 v[28:29], s[24:25]
	s_xor_b64 exec, exec, s[16:17]
	v_mov_b64_e32 v[28:29], s[36:37]
	v_mov_b32_e32 v188, v189
	s_or_b64 exec, exec, s[16:17]
	v_ashrrev_i32_e32 v189, 31, v188
	v_lshlrev_b64 v[30:31], 13, v[188:189]
	v_lshl_add_u64 v[28:29], v[28:29], 0, v[30:31]
	v_pk_fma_f32 v[26:27], v[26:27], v[34:35], v[62:63]
	v_pk_fma_f32 v[24:25], v[24:25], v[32:33], v[60:61]
	v_lshl_add_u64 v[28:29], v[174:175], 2, v[28:29]
	global_store_dwordx4 v[28:29], v[24:27], off offset:576
	s_and_saveexec_b64 s[16:17], s[14:15]
	s_xor_b64 s[14:15], exec, s[16:17]
	s_or_saveexec_b64 s[14:15], s[14:15]
	v_mov_b64_e32 v[24:25], s[24:25]
	s_xor_b64 exec, exec, s[14:15]
	v_mov_b64_e32 v[24:25], s[36:37]
	v_mov_b32_e32 v186, v187
	s_or_b64 exec, exec, s[14:15]
	v_ashrrev_i32_e32 v187, 31, v186
	v_lshlrev_b64 v[26:27], 13, v[186:187]
	v_lshl_add_u64 v[24:25], v[24:25], 0, v[26:27]
	v_pk_fma_f32 v[22:23], v[22:23], v[34:35], v[58:59]
	v_pk_fma_f32 v[20:21], v[20:21], v[32:33], v[56:57]
	v_lshl_add_u64 v[24:25], v[174:175], 2, v[24:25]
	global_store_dwordx4 v[24:25], v[20:23], off offset:576
	s_and_saveexec_b64 s[14:15], s[12:13]
	s_xor_b64 s[12:13], exec, s[14:15]
	s_or_saveexec_b64 s[12:13], s[12:13]
	v_mov_b64_e32 v[20:21], s[24:25]
	s_xor_b64 exec, exec, s[12:13]
	v_mov_b64_e32 v[20:21], s[36:37]
	v_mov_b32_e32 v184, v185
	s_or_b64 exec, exec, s[12:13]
	v_ashrrev_i32_e32 v185, 31, v184
	v_lshlrev_b64 v[22:23], 13, v[184:185]
	v_lshl_add_u64 v[20:21], v[20:21], 0, v[22:23]
	v_pk_fma_f32 v[18:19], v[18:19], v[34:35], v[54:55]
	v_pk_fma_f32 v[16:17], v[16:17], v[32:33], v[52:53]
	v_lshl_add_u64 v[20:21], v[174:175], 2, v[20:21]
	global_store_dwordx4 v[20:21], v[16:19], off offset:576
	s_and_saveexec_b64 s[12:13], s[10:11]
	s_xor_b64 s[10:11], exec, s[12:13]
	s_or_saveexec_b64 s[10:11], s[10:11]
	v_mov_b64_e32 v[16:17], s[24:25]
	s_xor_b64 exec, exec, s[10:11]
	v_mov_b64_e32 v[16:17], s[36:37]
	v_mov_b32_e32 v182, v183
	s_or_b64 exec, exec, s[10:11]
	v_ashrrev_i32_e32 v183, 31, v182
	v_lshlrev_b64 v[18:19], 13, v[182:183]
	v_lshl_add_u64 v[16:17], v[16:17], 0, v[18:19]
	v_pk_fma_f32 v[14:15], v[14:15], v[34:35], v[50:51]
	v_pk_fma_f32 v[12:13], v[12:13], v[32:33], v[48:49]
	v_lshl_add_u64 v[16:17], v[174:175], 2, v[16:17]
	global_store_dwordx4 v[16:17], v[12:15], off offset:576
	s_and_saveexec_b64 s[10:11], s[8:9]
	s_xor_b64 s[8:9], exec, s[10:11]
	s_or_saveexec_b64 s[8:9], s[8:9]
	v_mov_b64_e32 v[12:13], s[24:25]
	s_xor_b64 exec, exec, s[8:9]
	v_mov_b64_e32 v[12:13], s[36:37]
	v_mov_b32_e32 v180, v181
	s_or_b64 exec, exec, s[8:9]
	v_ashrrev_i32_e32 v181, 31, v180
	v_lshlrev_b64 v[14:15], 13, v[180:181]
	v_lshl_add_u64 v[12:13], v[12:13], 0, v[14:15]
	v_pk_fma_f32 v[10:11], v[10:11], v[34:35], v[46:47]
	v_pk_fma_f32 v[8:9], v[8:9], v[32:33], v[44:45]
	v_lshl_add_u64 v[12:13], v[174:175], 2, v[12:13]
	global_store_dwordx4 v[12:13], v[8:11], off offset:576
	s_and_saveexec_b64 s[8:9], s[6:7]
	s_xor_b64 s[6:7], exec, s[8:9]
	s_or_saveexec_b64 s[6:7], s[6:7]
	v_mov_b64_e32 v[8:9], s[24:25]
	s_xor_b64 exec, exec, s[6:7]
	v_mov_b64_e32 v[8:9], s[36:37]
	v_mov_b32_e32 v178, v179
	s_or_b64 exec, exec, s[6:7]
	v_ashrrev_i32_e32 v179, 31, v178
	v_lshlrev_b64 v[10:11], 13, v[178:179]
	v_lshl_add_u64 v[8:9], v[8:9], 0, v[10:11]
	v_pk_fma_f32 v[6:7], v[6:7], v[34:35], v[42:43]
	v_pk_fma_f32 v[4:5], v[4:5], v[32:33], v[40:41]
	v_lshl_add_u64 v[8:9], v[174:175], 2, v[8:9]
	global_store_dwordx4 v[8:9], v[4:7], off offset:576
	s_and_saveexec_b64 s[6:7], vcc
	s_xor_b64 s[6:7], exec, s[6:7]
	s_or_saveexec_b64 s[6:7], s[6:7]
	v_mov_b64_e32 v[4:5], s[24:25]
	s_xor_b64 exec, exec, s[6:7]
	s_cbranch_execz .LBB0_1234
	v_mov_b64_e32 v[4:5], s[36:37]
	v_mov_b32_e32 v176, v177
	s_branch .LBB0_1234

; #define WAIT_L(n) asm volatile("s_waitcnt lgkmcnt(" #n ")" ::: "memory")
; #define BAR __builtin_amdgcn_s_barrier()
; #define SCHED __builtin_amdgcn_sched_barrier(0)
; template <class Get, class Epi>
; DI void gemm_stream(LAS unsigned char* lds, const int K, const int ld, Get get, Epi epi) {
;     ...
;             const bool last = (t == nt - 2);
;             const char* a1 = cA + (size_t)(t + 1) * kstep;
;             const char* a2 = last ? nA : cA + (size_t)(t + 2) * kstep;
;             const char* b2 = last ? nB : cB + (size_t)(t + 2) * kstep;
;             const char* a3 = a2 + kstep;
;             const char* b3 = b2 + kstep;
;             LDB(B0, 0, 0); SCHED; LDA(At, 0, 0); STAGE(SAo(1, 1), a1 + hstep);
;             WAIT_L(8); BAR; WAIT_L(0); MMA(0, 0, At, B0); BAR; SCHED;
;             LDB(B1, 0, 1); STAGE(SBo(0, 0), b2);
;             BAR; WAIT_L(0); MMA(0, 1, At, B1); BAR;
;             LDA(At, 0, 1); STAGE(SAo(0, 0), a2);
;             BAR; WAIT_L(0); MMA(1, 0, At, B0); BAR; SCHED;
.LBB0_1505:
	s_add_u32 s38, s8, s0
	s_addc_u32 s39, s9, 0
	s_add_u32 s40, s38, 0x100
	s_addc_u32 s41, s39, 0
	s_and_b64 s[36:37], s[18:19], exec
	s_cselect_b32 s41, s13, s41
	s_cselect_b32 s40, s12, s40
	s_add_u32 s0, s10, s0
	s_addc_u32 s36, s11, 0
	s_add_u32 s0, s0, 0x100
	s_addc_u32 s36, s36, 0
	s_and_b64 s[18:19], s[18:19], exec
	s_cselect_b32 s53, s15, s36
	s_cselect_b32 s52, s14, s0
	s_add_u32 s54, s38, 0x80080
	s_addc_u32 s55, s39, 0
	s_add_i32 s87, s63, 0x2000
	s_add_u32 s38, s52, 0x80000
	s_addc_u32 s39, s53, 0
	s_add_i32 s86, s60, s3
	s_add_i32 s85, s86, 0x2000
	s_add_i32 s83, 16, 0x18000
	ds_read_b128 v[140:143], v137
	ds_read_b128 v[144:147], v137 offset:1024
	ds_read_b128 v[148:151], v137 offset:2048
	ds_read_b128 v[152:155], v137 offset:3072
	s_add_u32 s36, s40, 0x80000
	s_addc_u32 s37, s41, 0
	s_add_i32 s82, s83, s3
	s_add_i32 s81, 16, 0x1c000
	s_add_i32 s80, s82, 0x2000
	s_add_u32 s18, s52, 0x80080
	s_addc_u32 s19, s53, 0
	s_add_i32 s79, s81, s3
	s_add_i32 s0, s79, 0x2000
	s_mov_b32 m0, s61
	v_lshl_add_u64 v[188:189], s[54:55], 0, v[130:131]
	ds_read_b128 v[156:159], v138
	ds_read_b128 v[160:163], v138 offset:1024
	ds_read_b128 v[164:167], v138 offset:2048
	ds_read_b128 v[168:171], v138 offset:3072
	ds_read_b128 v[172:175], v138 offset:4096
	ds_read_b128 v[176:179], v138 offset:5120
	ds_read_b128 v[180:183], v138 offset:6144
	ds_read_b128 v[184:187], v138 offset:7168
	global_load_lds_dwordx4 v[188:189], off
	v_lshl_add_u64 v[188:189], s[54:55], 0, v[128:129]
	s_mov_b32 m0, s62
	s_nop 0
	global_load_lds_dwordx4 v[188:189], off
	s_waitcnt lgkmcnt(8)
	s_barrier
	s_waitcnt lgkmcnt(0)
	s_setprio 0
	s_waitcnt lgkmcnt(0)
	v_mfma_f32_16x16x32_bf16 v[124:127], v[140:143], v[156:159], v[124:127]
	v_mfma_f32_16x16x32_bf16 v[120:123], v[148:151], v[156:159], v[120:123]
	v_mfma_f32_16x16x32_bf16 v[116:119], v[140:143], v[164:167], v[116:119]
	v_mfma_f32_16x16x32_bf16 v[112:115], v[148:151], v[164:167], v[112:115]
	v_mfma_f32_16x16x32_bf16 v[104:107], v[140:143], v[172:175], v[104:107]
	v_mfma_f32_16x16x32_bf16 v[96:99], v[148:151], v[172:175], v[96:99]
	v_mfma_f32_16x16x32_bf16 v[88:91], v[140:143], v[180:183], v[88:91]
	v_mfma_f32_16x16x32_bf16 v[80:83], v[148:151], v[180:183], v[80:83]
	v_mfma_f32_16x16x32_bf16 v[124:127], v[144:147], v[160:163], v[124:127]
	v_mfma_f32_16x16x32_bf16 v[120:123], v[152:155], v[160:163], v[120:123]
	v_mfma_f32_16x16x32_bf16 v[116:119], v[144:147], v[168:171], v[116:119]
	v_mfma_f32_16x16x32_bf16 v[112:115], v[152:155], v[168:171], v[112:115]
	v_mfma_f32_16x16x32_bf16 v[104:107], v[144:147], v[176:179], v[104:107]
	v_mfma_f32_16x16x32_bf16 v[96:99], v[152:155], v[176:179], v[96:99]
	v_mfma_f32_16x16x32_bf16 v[88:91], v[144:147], v[184:187], v[88:91]
	v_mfma_f32_16x16x32_bf16 v[80:83], v[152:155], v[184:187], v[80:83]
	s_setprio 1
	s_barrier
	s_mov_b32 m0, s63
	v_lshl_add_u64 v[204:205], s[52:53], 0, v[130:131]
	ds_read_b128 v[188:191], v139
	ds_read_b128 v[192:195], v139 offset:1024
	ds_read_b128 v[196:199], v139 offset:2048
	ds_read_b128 v[200:203], v139 offset:3072
	global_load_lds_dwordx4 v[204:205], off
	v_lshl_add_u64 v[208:209], s[52:53], 0, v[128:129]
	s_mov_b32 m0, s87
	s_nop 0
	global_load_lds_dwordx4 v[208:209], off
	s_barrier
	s_waitcnt lgkmcnt(0)
	s_setprio 0
	s_waitcnt lgkmcnt(0)
	v_mfma_f32_16x16x32_bf16 v[108:111], v[188:191], v[156:159], v[108:111]
	v_mfma_f32_16x16x32_bf16 v[100:103], v[196:199], v[156:159], v[100:103]
	v_mfma_f32_16x16x32_bf16 v[92:95], v[188:191], v[164:167], v[92:95]
	v_mfma_f32_16x16x32_bf16 v[84:87], v[196:199], v[164:167], v[84:87]
	v_mfma_f32_16x16x32_bf16 v[76:79], v[188:191], v[172:175], v[76:79]
	v_mfma_f32_16x16x32_bf16 v[72:75], v[196:199], v[172:175], v[72:75]
	v_mfma_f32_16x16x32_bf16 v[68:71], v[188:191], v[180:183], v[68:71]
	v_mfma_f32_16x16x32_bf16 v[64:67], v[196:199], v[180:183], v[64:67]
	v_mfma_f32_16x16x32_bf16 v[108:111], v[192:195], v[160:163], v[108:111]
	v_mfma_f32_16x16x32_bf16 v[100:103], v[200:203], v[160:163], v[100:103]
	v_mfma_f32_16x16x32_bf16 v[92:95], v[192:195], v[168:171], v[92:95]
	v_mfma_f32_16x16x32_bf16 v[84:87], v[200:203], v[168:171], v[84:87]
	v_mfma_f32_16x16x32_bf16 v[76:79], v[192:195], v[176:179], v[76:79]
	v_mfma_f32_16x16x32_bf16 v[72:75], v[200:203], v[176:179], v[72:75]
	v_mfma_f32_16x16x32_bf16 v[68:71], v[192:195], v[184:187], v[68:71]
	v_mfma_f32_16x16x32_bf16 v[64:67], v[200:203], v[184:187], v[64:67]
	s_setprio 1
	s_mov_b32 m0, s20
	v_lshl_add_u64 v[210:211], s[40:41], 0, v[130:131]
	s_barrier
	ds_read_b128 v[156:159], v138 offset:16384
	ds_read_b128 v[160:163], v138 offset:17408
	ds_read_b128 v[164:167], v138 offset:18432
	ds_read_b128 v[168:171], v138 offset:19456
	ds_read_b128 v[172:175], v138 offset:20480
	ds_read_b128 v[176:179], v138 offset:21504
	ds_read_b128 v[180:183], v138 offset:22528
	ds_read_b128 v[184:187], v138 offset:23552
	global_load_lds_dwordx4 v[210:211], off
	v_lshl_add_u64 v[212:213], s[40:41], 0, v[128:129]
	s_mov_b32 m0, s21
	s_nop 0
	global_load_lds_dwordx4 v[212:213], off
	s_barrier
	s_waitcnt lgkmcnt(0)
	s_setprio 0
	s_waitcnt lgkmcnt(0)
	v_mfma_f32_16x16x32_bf16 v[60:63], v[140:143], v[156:159], v[60:63]
	v_mfma_f32_16x16x32_bf16 v[56:59], v[148:151], v[156:159], v[56:59]
	v_mfma_f32_16x16x32_bf16 v[52:55], v[140:143], v[164:167], v[52:55]
	v_mfma_f32_16x16x32_bf16 v[48:51], v[148:151], v[164:167], v[48:51]
	v_mfma_f32_16x16x32_bf16 v[40:43], v[140:143], v[172:175], v[40:43]
	v_mfma_f32_16x16x32_bf16 v[32:35], v[148:151], v[172:175], v[32:35]
	v_mfma_f32_16x16x32_bf16 v[24:27], v[140:143], v[180:183], v[24:27]
	v_mfma_f32_16x16x32_bf16 v[16:19], v[148:151], v[180:183], v[16:19]
	v_mfma_f32_16x16x32_bf16 v[60:63], v[144:147], v[160:163], v[60:63]
	v_mfma_f32_16x16x32_bf16 v[56:59], v[152:155], v[160:163], v[56:59]
	v_mfma_f32_16x16x32_bf16 v[52:55], v[144:147], v[168:171], v[52:55]
	v_mfma_f32_16x16x32_bf16 v[48:51], v[152:155], v[168:171], v[48:51]
	v_mfma_f32_16x16x32_bf16 v[40:43], v[144:147], v[176:179], v[40:43]
	v_mfma_f32_16x16x32_bf16 v[32:35], v[152:155], v[176:179], v[32:35]
	v_mfma_f32_16x16x32_bf16 v[24:27], v[144:147], v[184:187], v[24:27]
	v_mfma_f32_16x16x32_bf16 v[16:19], v[152:155], v[184:187], v[16:19]
	s_setprio 1
	s_barrier
; #define WAIT_V(n) asm volatile("s_waitcnt vmcnt(" #n ")" ::: "memory")
; #define WAIT_L(n) asm volatile("s_waitcnt lgkmcnt(" #n ")" ::: "memory")
; #define BAR __builtin_amdgcn_s_barrier()
; #define SCHED __builtin_amdgcn_sched_barrier(0)
; template <class Get, class Epi>
; DI void gemm_stream(LAS unsigned char* lds, const int K, const int ld, Get get, Epi epi) {
;     ...
;             BAR; WAIT_L(0); MMA(1, 0, At, B0); BAR; SCHED;
;             STAGE(SBo(0, 1), b2 + hstep);
;             WAIT_V(6); BAR; MMA(1, 1, At, B1); BAR;
;             LDB(B0, 1, 0); SCHED; LDA(At, 1, 0); STAGE(SAo(0, 1), a2 + hstep);
;             WAIT_L(8); BAR; WAIT_L(0); MMA(0, 0, At, B0); BAR; SCHED;
;             LDB(B1, 1, 1); STAGE(SBo(1, 0), b3);
;             BAR; WAIT_L(0); MMA(0, 1, At, B1); BAR;
;             LDA(At, 1, 1); STAGE(SAo(1, 0), a3);
;             BAR; WAIT_L(0); MMA(1, 0, At, B0); BAR; SCHED;
;             STAGE(SBo(1, 1), b3 + hstep);
	s_mov_b32 m0, s86
	v_lshl_add_u64 v[140:141], s[38:39], 0, v[130:131]
	global_load_lds_dwordx4 v[140:141], off
	v_lshl_add_u64 v[140:141], s[38:39], 0, v[128:129]
	s_mov_b32 m0, s85
	s_nop 0
	global_load_lds_dwordx4 v[140:141], off
	s_waitcnt vmcnt(6)
	s_barrier
	s_setprio 0
	v_mfma_f32_16x16x32_bf16 v[44:47], v[188:191], v[156:159], v[44:47]
	v_mfma_f32_16x16x32_bf16 v[36:39], v[196:199], v[156:159], v[36:39]
	v_mfma_f32_16x16x32_bf16 v[28:31], v[188:191], v[164:167], v[28:31]
	v_mfma_f32_16x16x32_bf16 v[20:23], v[196:199], v[164:167], v[20:23]
	v_mfma_f32_16x16x32_bf16 v[12:15], v[188:191], v[172:175], v[12:15]
	v_mfma_f32_16x16x32_bf16 v[8:11], v[196:199], v[172:175], v[8:11]
	v_mfma_f32_16x16x32_bf16 v[4:7], v[188:191], v[180:183], v[4:7]
	v_mfma_f32_16x16x32_bf16 v[0:3], v[196:199], v[180:183], v[0:3]
	v_mfma_f32_16x16x32_bf16 v[44:47], v[192:195], v[160:163], v[44:47]
	v_mfma_f32_16x16x32_bf16 v[36:39], v[200:203], v[160:163], v[36:39]
	v_mfma_f32_16x16x32_bf16 v[28:31], v[192:195], v[168:171], v[28:31]
	v_mfma_f32_16x16x32_bf16 v[20:23], v[200:203], v[168:171], v[20:23]
	v_mfma_f32_16x16x32_bf16 v[12:15], v[192:195], v[176:179], v[12:15]
	v_mfma_f32_16x16x32_bf16 v[8:11], v[200:203], v[176:179], v[8:11]
	v_mfma_f32_16x16x32_bf16 v[4:7], v[192:195], v[184:187], v[4:7]
	v_mfma_f32_16x16x32_bf16 v[0:3], v[200:203], v[184:187], v[0:3]
	s_setprio 1
	v_add_u32_e32 v132, s83, v136
	s_barrier
	ds_read_b128 v[140:143], v132
	ds_read_b128 v[144:147], v132 offset:1024
	ds_read_b128 v[148:151], v132 offset:2048
	ds_read_b128 v[152:155], v132 offset:3072
	s_mov_b32 m0, s28
	v_lshl_add_u64 v[188:189], s[36:37], 0, v[130:131]
	ds_read_b128 v[156:159], v138 offset:32768
	ds_read_b128 v[160:163], v138 offset:33792
	ds_read_b128 v[164:167], v138 offset:34816
	ds_read_b128 v[168:171], v138 offset:35840
	ds_read_b128 v[172:175], v138 offset:36864
	ds_read_b128 v[176:179], v138 offset:37888
	ds_read_b128 v[180:183], v138 offset:38912
	ds_read_b128 v[184:187], v138 offset:39936
	global_load_lds_dwordx4 v[188:189], off
	v_lshl_add_u64 v[188:189], s[36:37], 0, v[128:129]
	s_mov_b32 m0, s29
	s_nop 0
	global_load_lds_dwordx4 v[188:189], off
	s_waitcnt lgkmcnt(8)
	s_barrier
	s_waitcnt lgkmcnt(0)
	s_setprio 0
	s_waitcnt lgkmcnt(0)
	v_mfma_f32_16x16x32_bf16 v[124:127], v[140:143], v[156:159], v[124:127]
	v_mfma_f32_16x16x32_bf16 v[120:123], v[148:151], v[156:159], v[120:123]
	v_mfma_f32_16x16x32_bf16 v[116:119], v[140:143], v[164:167], v[116:119]
	v_mfma_f32_16x16x32_bf16 v[112:115], v[148:151], v[164:167], v[112:115]
	v_mfma_f32_16x16x32_bf16 v[104:107], v[140:143], v[172:175], v[104:107]
	v_mfma_f32_16x16x32_bf16 v[96:99], v[148:151], v[172:175], v[96:99]
	v_mfma_f32_16x16x32_bf16 v[88:91], v[140:143], v[180:183], v[88:91]
	v_mfma_f32_16x16x32_bf16 v[80:83], v[148:151], v[180:183], v[80:83]
	v_mfma_f32_16x16x32_bf16 v[124:127], v[144:147], v[160:163], v[124:127]
	v_mfma_f32_16x16x32_bf16 v[120:123], v[152:155], v[160:163], v[120:123]
	v_mfma_f32_16x16x32_bf16 v[116:119], v[144:147], v[168:171], v[116:119]
	v_mfma_f32_16x16x32_bf16 v[112:115], v[152:155], v[168:171], v[112:115]
	v_mfma_f32_16x16x32_bf16 v[104:107], v[144:147], v[176:179], v[104:107]
	v_mfma_f32_16x16x32_bf16 v[96:99], v[152:155], v[176:179], v[96:99]
	v_mfma_f32_16x16x32_bf16 v[88:91], v[144:147], v[184:187], v[88:91]
	v_mfma_f32_16x16x32_bf16 v[80:83], v[152:155], v[184:187], v[80:83]
	s_setprio 1
	s_barrier
	s_mov_b32 m0, s82
	v_add_u32_e32 v132, s81, v136
	v_lshl_add_u64 v[204:205], v[204:205], 0, s[6:7]
	ds_read_b128 v[188:191], v132
	ds_read_b128 v[192:195], v132 offset:1024
	ds_read_b128 v[196:199], v132 offset:2048
	ds_read_b128 v[200:203], v132 offset:3072
	global_load_lds_dwordx4 v[204:205], off
	v_lshl_add_u64 v[204:205], v[208:209], 0, s[6:7]
	s_mov_b32 m0, s80
	s_nop 0
	global_load_lds_dwordx4 v[204:205], off
	s_barrier
	s_waitcnt lgkmcnt(0)
	s_setprio 0
	s_waitcnt lgkmcnt(0)
	v_mfma_f32_16x16x32_bf16 v[108:111], v[188:191], v[156:159], v[108:111]
	v_mfma_f32_16x16x32_bf16 v[100:103], v[196:199], v[156:159], v[100:103]
	v_mfma_f32_16x16x32_bf16 v[92:95], v[188:191], v[164:167], v[92:95]
	v_mfma_f32_16x16x32_bf16 v[84:87], v[196:199], v[164:167], v[84:87]
	v_mfma_f32_16x16x32_bf16 v[76:79], v[188:191], v[172:175], v[76:79]
	v_mfma_f32_16x16x32_bf16 v[72:75], v[196:199], v[172:175], v[72:75]
	v_mfma_f32_16x16x32_bf16 v[68:71], v[188:191], v[180:183], v[68:71]
	v_mfma_f32_16x16x32_bf16 v[64:67], v[196:199], v[180:183], v[64:67]
	v_mfma_f32_16x16x32_bf16 v[108:111], v[192:195], v[160:163], v[108:111]
	v_mfma_f32_16x16x32_bf16 v[100:103], v[200:203], v[160:163], v[100:103]
	v_mfma_f32_16x16x32_bf16 v[92:95], v[192:195], v[168:171], v[92:95]
	v_mfma_f32_16x16x32_bf16 v[84:87], v[200:203], v[168:171], v[84:87]
	v_mfma_f32_16x16x32_bf16 v[76:79], v[192:195], v[176:179], v[76:79]
	v_mfma_f32_16x16x32_bf16 v[72:75], v[200:203], v[176:179], v[72:75]
	v_mfma_f32_16x16x32_bf16 v[68:71], v[192:195], v[184:187], v[68:71]
	v_mfma_f32_16x16x32_bf16 v[64:67], v[200:203], v[184:187], v[64:67]
	s_setprio 1
	s_mov_b32 m0, s56
	v_lshl_add_u64 v[204:205], v[210:211], 0, s[6:7]
	s_barrier
	ds_read_b128 v[156:159], v138 offset:49152
	ds_read_b128 v[160:163], v138 offset:50176
	ds_read_b128 v[164:167], v138 offset:51200
	ds_read_b128 v[168:171], v138 offset:52224
	ds_read_b128 v[172:175], v138 offset:53248
	ds_read_b128 v[176:179], v138 offset:54272
	ds_read_b128 v[180:183], v138 offset:55296
	ds_read_b128 v[184:187], v138 offset:56320
	global_load_lds_dwordx4 v[204:205], off
	v_lshl_add_u64 v[204:205], v[212:213], 0, s[6:7]
	s_mov_b32 m0, s57
	s_nop 0
	global_load_lds_dwordx4 v[204:205], off
	s_barrier
; #define WAIT_V(n) asm volatile("s_waitcnt vmcnt(" #n ")" ::: "memory")
; #define BAR __builtin_amdgcn_s_barrier()
; template <class Get, class Epi>
; DI void gemm_stream(LAS unsigned char* lds, const int K, const int ld, Get get, Epi epi) {
;     ...
;             STAGE(SBo(1, 1), b3 + hstep);
;             WAIT_V(6); BAR; MMA(1, 1, At, B1); BAR;
;         }
;         epi(acc, cur);
; DI void epi_part(const Acc& acc, const P& p, int brow, int bcol, int sl) {
;     EPI_IDX
;     const int b = brow / PB;
;     float* part = (float*)(p.ws + O_PART) + ((size_t)sl * (NBATCH * CTXL) + b * CTXL) * DM;
; #pragma unroll
;     for (int ai = 0; ai < 2; ++ai)
; #pragma unroll
;         for (int m = 0; m < 4; ++m) {
;             float* rp = part + (size_t)(ai * 128 + wr * 64 + m * 16 + fr) * DM + bcol + wc * 32 + fq * 4;
; #pragma unroll
;             for (int bj = 0; bj < 2; ++bj)
; #pragma unroll
;                 for (int n = 0; n < 2; ++n) *(f32x4*)(rp + bj * 128 + n * 16) = acc[ai][bj][m][n];
;         }
	s_waitcnt lgkmcnt(0)
	s_setprio 0
	s_waitcnt lgkmcnt(0)
	v_mfma_f32_16x16x32_bf16 v[60:63], v[140:143], v[156:159], v[60:63]
	v_mfma_f32_16x16x32_bf16 v[56:59], v[148:151], v[156:159], v[56:59]
	v_mfma_f32_16x16x32_bf16 v[52:55], v[140:143], v[164:167], v[52:55]
	v_mfma_f32_16x16x32_bf16 v[48:51], v[148:151], v[164:167], v[48:51]
	v_mfma_f32_16x16x32_bf16 v[40:43], v[140:143], v[172:175], v[40:43]
	v_mfma_f32_16x16x32_bf16 v[32:35], v[148:151], v[172:175], v[32:35]
	v_mfma_f32_16x16x32_bf16 v[24:27], v[140:143], v[180:183], v[24:27]
	v_mfma_f32_16x16x32_bf16 v[16:19], v[148:151], v[180:183], v[16:19]
	v_mfma_f32_16x16x32_bf16 v[60:63], v[144:147], v[160:163], v[60:63]
	v_mfma_f32_16x16x32_bf16 v[56:59], v[152:155], v[160:163], v[56:59]
	v_mfma_f32_16x16x32_bf16 v[52:55], v[144:147], v[168:171], v[52:55]
	v_mfma_f32_16x16x32_bf16 v[48:51], v[152:155], v[168:171], v[48:51]
	v_mfma_f32_16x16x32_bf16 v[40:43], v[144:147], v[176:179], v[40:43]
	v_mfma_f32_16x16x32_bf16 v[32:35], v[152:155], v[176:179], v[32:35]
	v_mfma_f32_16x16x32_bf16 v[24:27], v[144:147], v[184:187], v[24:27]
	v_mfma_f32_16x16x32_bf16 v[16:19], v[152:155], v[184:187], v[16:19]
	s_setprio 1
	s_barrier
	s_mov_b32 m0, s79
	v_lshl_add_u64 v[140:141], s[18:19], 0, v[130:131]
	global_load_lds_dwordx4 v[140:141], off
	v_lshl_add_u64 v[140:141], s[18:19], 0, v[128:129]
	s_mov_b32 m0, s0
	s_nop 0
	global_load_lds_dwordx4 v[140:141], off
	s_waitcnt vmcnt(6)
	s_barrier
	s_setprio 0
	v_mfma_f32_16x16x32_bf16 v[44:47], v[188:191], v[156:159], v[44:47]
	v_mfma_f32_16x16x32_bf16 v[36:39], v[196:199], v[156:159], v[36:39]
	v_mfma_f32_16x16x32_bf16 v[28:31], v[188:191], v[164:167], v[28:31]
	v_mfma_f32_16x16x32_bf16 v[20:23], v[196:199], v[164:167], v[20:23]
	v_mfma_f32_16x16x32_bf16 v[12:15], v[188:191], v[172:175], v[12:15]
	v_mfma_f32_16x16x32_bf16 v[8:11], v[196:199], v[172:175], v[8:11]
	v_mfma_f32_16x16x32_bf16 v[4:7], v[188:191], v[180:183], v[4:7]
	v_mfma_f32_16x16x32_bf16 v[0:3], v[196:199], v[180:183], v[0:3]
	v_mfma_f32_16x16x32_bf16 v[44:47], v[192:195], v[160:163], v[44:47]
	v_mfma_f32_16x16x32_bf16 v[36:39], v[200:203], v[160:163], v[36:39]
	v_mfma_f32_16x16x32_bf16 v[28:31], v[192:195], v[168:171], v[28:31]
	v_mfma_f32_16x16x32_bf16 v[20:23], v[200:203], v[168:171], v[20:23]
	v_mfma_f32_16x16x32_bf16 v[12:15], v[192:195], v[176:179], v[12:15]
	v_mfma_f32_16x16x32_bf16 v[8:11], v[200:203], v[176:179], v[8:11]
	v_mfma_f32_16x16x32_bf16 v[4:7], v[192:195], v[184:187], v[4:7]
	v_mfma_f32_16x16x32_bf16 v[0:3], v[200:203], v[184:187], v[0:3]
	s_setprio 1
	s_movk_i32 s0, 0x100
	s_andn2_b64 vcc, exec, s[16:17]
	s_mov_b64 s[18:19], -1
	s_mov_b64 s[16:17], 0
	s_barrier
	s_cbranch_vccz .LBB0_1505
	s_mul_hi_i32 s0, s78, 0x78787879
	s_lshr_b32 s9, s0, 31
	s_lshr_b32 s0, s0, 3
	s_ashr_i32 s8, s77, 4
	s_add_i32 s0, s0, s9
	s_ashr_i32 s9, s8, 31
	s_lshl_b32 s10, s0, 8
	s_ashr_i32 s11, s10, 31
	s_lshl_b64 s[8:9], s[8:9], 23
	s_add_u32 s0, s58, s8
	v_mov_b32_e32 v141, v206
	s_addc_u32 s16, s59, s9
	s_lshl_b64 s[8:9], s[10:11], 13
	s_add_u32 s0, s0, s8
	v_and_b32_e32 v132, 15, v141
	v_ashrrev_i32_e32 v140, 2, v141
	s_movk_i32 s8, 0xffc0
	s_addc_u32 s9, s16, s9
	v_and_or_b32 v140, v140, s8, v132
	s_lshl_b32 s8, s77, 10
	s_and_b32 s8, s8, 0x3c00
	s_add_u32 s8, s0, s8
	v_lshlrev_b32_e32 v132, 1, v141
	s_addc_u32 s9, s9, 0
	v_and_b32_e32 v132, 0x180, v132
	v_lshl_add_u64 v[142:143], s[8:9], 0, v[132:133]
	v_and_b32_e32 v132, 48, v141
	v_ashrrev_i32_e32 v141, 31, v140
	v_lshl_add_u64 v[142:143], v[142:143], 0, v[132:133]
	v_lshlrev_b64 v[144:145], 13, v[140:141]
	v_lshl_add_u64 v[144:145], v[142:143], 0, v[144:145]
	global_store_dwordx4 v[144:145], v[124:127], off
	global_store_dwordx4 v[144:145], v[120:123], off offset:64
	global_store_dwordx4 v[144:145], v[108:111], off offset:512
	global_store_dwordx4 v[144:145], v[100:103], off offset:576
	s_mov_b32 s0, 0x100000
	s_mov_b64 s[8:9], 0x100000
	v_or_b32_e32 v100, 16, v140
	v_ashrrev_i32_e32 v101, 31, v100
	v_lshlrev_b64 v[100:101], 13, v[100:101]
	v_lshl_add_u64 v[100:101], v[142:143], 0, v[100:101]
	global_store_dwordx4 v[100:101], v[116:119], off
	global_store_dwordx4 v[100:101], v[112:115], off offset:64
	global_store_dwordx4 v[100:101], v[92:95], off offset:512
	global_store_dwordx4 v[100:101], v[84:87], off offset:576
	s_mov_b32 s77, s76
	s_mov_b32 s78, s74
	v_or_b32_e32 v84, 32, v140
	v_ashrrev_i32_e32 v85, 31, v84
	v_lshlrev_b64 v[84:85], 13, v[84:85]
	v_lshl_add_u64 v[84:85], v[142:143], 0, v[84:85]
	global_store_dwordx4 v[84:85], v[104:107], off
	global_store_dwordx4 v[84:85], v[96:99], off offset:64
	global_store_dwordx4 v[84:85], v[76:79], off offset:512
	global_store_dwordx4 v[84:85], v[72:75], off offset:576
	s_mov_b64 s[10:11], s[14:15]
	s_nop 0
	v_or_b32_e32 v72, 48, v140
	v_ashrrev_i32_e32 v73, 31, v72
	v_lshlrev_b64 v[72:73], 13, v[72:73]
	v_lshl_add_u64 v[72:73], v[142:143], 0, v[72:73]
	global_store_dwordx4 v[72:73], v[88:91], off
	global_store_dwordx4 v[72:73], v[80:83], off offset:64
	global_store_dwordx4 v[72:73], v[68:71], off offset:512
	global_store_dwordx4 v[72:73], v[64:67], off offset:576
	s_nop 1
	v_add_co_u32_e32 v66, vcc, s0, v144
	s_mov_b32 s0, 0x120000
	s_nop 0
	v_addc_co_u32_e32 v67, vcc, 0, v145, vcc
	v_lshl_add_u64 v[64:65], v[144:145], 0, s[8:9]
	global_store_dwordx4 v[66:67], v[60:63], off
	global_store_dwordx4 v[64:65], v[56:59], off offset:64
	global_store_dwordx4 v[64:65], v[44:47], off offset:512
	global_store_dwordx4 v[64:65], v[36:39], off offset:576
	s_mov_b64 s[8:9], 0x120000
	s_nop 0
	v_add_co_u32_e32 v38, vcc, s0, v144
	s_mov_b32 s0, 0x140000
	s_nop 0
	v_addc_co_u32_e32 v39, vcc, 0, v145, vcc
	v_lshl_add_u64 v[36:37], v[144:145], 0, s[8:9]
	global_store_dwordx4 v[38:39], v[52:55], off
	global_store_dwordx4 v[36:37], v[48:51], off offset:64
	global_store_dwordx4 v[36:37], v[28:31], off offset:512
	global_store_dwordx4 v[36:37], v[20:23], off offset:576
	s_mov_b64 s[8:9], 0x140000
	s_nop 0
	v_add_co_u32_e32 v22, vcc, s0, v144
	v_lshl_add_u64 v[20:21], v[144:145], 0, s[8:9]
	s_nop 0
	v_addc_co_u32_e32 v23, vcc, 0, v145, vcc
	global_store_dwordx4 v[22:23], v[40:43], off
	global_store_dwordx4 v[20:21], v[32:35], off offset:64
	global_store_dwordx4 v[20:21], v[12:15], off offset:512
	global_store_dwordx4 v[20:21], v[8:11], off offset:576
	s_mov_b64 s[8:9], 0x160000
	s_nop 0
	v_add_co_u32_e32 v10, vcc, 0x160000, v144
	v_lshl_add_u64 v[8:9], v[144:145], 0, s[8:9]
	s_nop 0
	v_addc_co_u32_e32 v11, vcc, 0, v145, vcc
	s_and_b64 vcc, exec, s[4:5]
	s_mov_b64 s[8:9], s[12:13]
	global_store_dwordx4 v[10:11], v[24:27], off
	global_store_dwordx4 v[8:9], v[16:19], off offset:64
	global_store_dwordx4 v[8:9], v[4:7], off offset:512
	global_store_dwordx4 v[8:9], v[0:3], off offset:576
	s_cbranch_vccz .LBB0_1502
	s_waitcnt vmcnt(0)
	s_cmpk_gt_u32 s2, 0xff
	v_readlane_b32 s76, v254, 10
	s_cbranch_scc1 .LBB0_1509
	s_barrier

; #define WAIT_L(n) asm volatile("s_waitcnt lgkmcnt(" #n ")" ::: "memory")
; #define BAR __builtin_amdgcn_s_barrier()
; #define SCHED __builtin_amdgcn_sched_barrier(0)
; template <class Get, class Epi>
; DI void gemm_stream(LAS unsigned char* lds, const int K, const int ld, Get get, Epi epi) {
;     ...
;             LDB(B0, 0, 0); SCHED; LDA(At, 0, 0); STAGE(SAo(1, 1), a1 + hstep);
;             WAIT_L(8); BAR; WAIT_L(0); MMA(0, 0, At, B0); BAR; SCHED;
;             LDB(B1, 0, 1); STAGE(SBo(0, 0), b2);
;             BAR; WAIT_L(0); MMA(0, 1, At, B1); BAR;
;             LDA(At, 0, 1); STAGE(SAo(0, 0), a2);
;             BAR; WAIT_L(0); MMA(1, 0, At, B0); BAR; SCHED;
.LBB0_1630:
	ds_read_b128 v[148:151], v142
	ds_read_b128 v[152:155], v142 offset:1024
	ds_read_b128 v[156:159], v142 offset:2048
	ds_read_b128 v[160:163], v142 offset:3072
	s_add_u32 s12, s10, 0xfff80080
	s_addc_u32 s13, s11, -1
	s_cmp_eq_u32 s59, 28
	s_cselect_b32 s15, s7, s13
	s_cselect_b32 s14, s6, s12
	s_cselect_b32 s13, s9, s58
	s_cselect_b32 s12, s8, s57
	s_mov_b32 m0, s28
	v_lshl_add_u64 v[140:141], s[10:11], 0, v[134:135]
	ds_read_b128 v[164:167], v143
	ds_read_b128 v[168:171], v143 offset:1024
	ds_read_b128 v[172:175], v143 offset:2048
	ds_read_b128 v[176:179], v143 offset:3072
	ds_read_b128 v[180:183], v143 offset:4096
	ds_read_b128 v[184:187], v143 offset:5120
	ds_read_b128 v[188:191], v143 offset:6144
	ds_read_b128 v[192:195], v143 offset:7168
	global_load_lds_dwordx4 v[140:141], off
	v_lshl_add_u64 v[140:141], s[10:11], 0, v[136:137]
	s_mov_b32 m0, s29
	s_nop 0
	global_load_lds_dwordx4 v[140:141], off
	s_waitcnt lgkmcnt(8)
	s_barrier
	s_waitcnt lgkmcnt(0)
	s_setprio 0
	s_waitcnt lgkmcnt(0)
	v_mfma_f32_16x16x32_bf16 v[124:127], v[148:151], v[164:167], v[124:127]
	v_mfma_f32_16x16x32_bf16 v[116:119], v[156:159], v[164:167], v[116:119]
	v_mfma_f32_16x16x32_bf16 v[108:111], v[148:151], v[172:175], v[108:111]
	v_mfma_f32_16x16x32_bf16 v[100:103], v[156:159], v[172:175], v[100:103]
	v_mfma_f32_16x16x32_bf16 v[92:95], v[148:151], v[180:183], v[92:95]
	v_mfma_f32_16x16x32_bf16 v[84:87], v[156:159], v[180:183], v[84:87]
	v_mfma_f32_16x16x32_bf16 v[76:79], v[148:151], v[188:191], v[76:79]
	v_mfma_f32_16x16x32_bf16 v[68:71], v[156:159], v[188:191], v[68:71]
	v_mfma_f32_16x16x32_bf16 v[124:127], v[152:155], v[168:171], v[124:127]
	v_mfma_f32_16x16x32_bf16 v[116:119], v[160:163], v[168:171], v[116:119]
	v_mfma_f32_16x16x32_bf16 v[108:111], v[152:155], v[176:179], v[108:111]
	v_mfma_f32_16x16x32_bf16 v[100:103], v[160:163], v[176:179], v[100:103]
	v_mfma_f32_16x16x32_bf16 v[92:95], v[152:155], v[184:187], v[92:95]
	v_mfma_f32_16x16x32_bf16 v[84:87], v[160:163], v[184:187], v[84:87]
	v_mfma_f32_16x16x32_bf16 v[76:79], v[152:155], v[192:195], v[76:79]
	v_mfma_f32_16x16x32_bf16 v[68:71], v[160:163], v[192:195], v[68:71]
	s_setprio 1
	s_barrier
	s_mov_b32 m0, s35
	v_lshl_add_u64 v[140:141], s[12:13], 0, v[130:131]
	ds_read_b128 v[196:199], v144
	ds_read_b128 v[200:203], v144 offset:1024
	ds_read_b128 v[208:211], v144 offset:2048
	ds_read_b128 v[212:215], v144 offset:3072
	global_load_lds_dwordx4 v[140:141], off
	v_lshl_add_u64 v[204:205], s[12:13], 0, v[128:129]
	s_mov_b32 m0, s36
	s_nop 0
	global_load_lds_dwordx4 v[204:205], off
	s_barrier
	s_waitcnt lgkmcnt(0)
	s_setprio 0
	s_waitcnt lgkmcnt(0)
	v_mfma_f32_16x16x32_bf16 v[120:123], v[196:199], v[164:167], v[120:123]
	v_mfma_f32_16x16x32_bf16 v[112:115], v[208:211], v[164:167], v[112:115]
	v_mfma_f32_16x16x32_bf16 v[104:107], v[196:199], v[172:175], v[104:107]
	v_mfma_f32_16x16x32_bf16 v[96:99], v[208:211], v[172:175], v[96:99]
	v_mfma_f32_16x16x32_bf16 v[88:91], v[196:199], v[180:183], v[88:91]
	v_mfma_f32_16x16x32_bf16 v[80:83], v[208:211], v[180:183], v[80:83]
	v_mfma_f32_16x16x32_bf16 v[72:75], v[196:199], v[188:191], v[72:75]
	v_mfma_f32_16x16x32_bf16 v[64:67], v[208:211], v[188:191], v[64:67]
	v_mfma_f32_16x16x32_bf16 v[120:123], v[200:203], v[168:171], v[120:123]
	v_mfma_f32_16x16x32_bf16 v[112:115], v[212:215], v[168:171], v[112:115]
	v_mfma_f32_16x16x32_bf16 v[104:107], v[200:203], v[176:179], v[104:107]
	v_mfma_f32_16x16x32_bf16 v[96:99], v[212:215], v[176:179], v[96:99]
	v_mfma_f32_16x16x32_bf16 v[88:91], v[200:203], v[184:187], v[88:91]
	v_mfma_f32_16x16x32_bf16 v[80:83], v[212:215], v[184:187], v[80:83]
	v_mfma_f32_16x16x32_bf16 v[72:75], v[200:203], v[192:195], v[72:75]
	v_mfma_f32_16x16x32_bf16 v[64:67], v[212:215], v[192:195], v[64:67]
	s_setprio 1
	s_mov_b32 m0, s3
	v_lshl_add_u64 v[216:217], s[14:15], 0, v[130:131]
	s_barrier
	ds_read_b128 v[164:167], v143 offset:16384
	ds_read_b128 v[168:171], v143 offset:17408
	ds_read_b128 v[172:175], v143 offset:18432
	ds_read_b128 v[176:179], v143 offset:19456
	ds_read_b128 v[180:183], v143 offset:20480
	ds_read_b128 v[184:187], v143 offset:21504
	ds_read_b128 v[188:191], v143 offset:22528
	ds_read_b128 v[192:195], v143 offset:23552
	global_load_lds_dwordx4 v[216:217], off
	v_lshl_add_u64 v[218:219], s[14:15], 0, v[128:129]
	s_mov_b32 m0, s16
	s_nop 0
	global_load_lds_dwordx4 v[218:219], off
	s_barrier
	s_waitcnt lgkmcnt(0)
	s_setprio 0
	s_waitcnt lgkmcnt(0)
	v_mfma_f32_16x16x32_bf16 v[60:63], v[148:151], v[164:167], v[60:63]
	v_mfma_f32_16x16x32_bf16 v[52:55], v[156:159], v[164:167], v[52:55]
	v_mfma_f32_16x16x32_bf16 v[44:47], v[148:151], v[172:175], v[44:47]
	v_mfma_f32_16x16x32_bf16 v[36:39], v[156:159], v[172:175], v[36:39]
	v_mfma_f32_16x16x32_bf16 v[28:31], v[148:151], v[180:183], v[28:31]
	v_mfma_f32_16x16x32_bf16 v[20:23], v[156:159], v[180:183], v[20:23]
	v_mfma_f32_16x16x32_bf16 v[12:15], v[148:151], v[188:191], v[12:15]
	v_mfma_f32_16x16x32_bf16 v[4:7], v[156:159], v[188:191], v[4:7]
	v_mfma_f32_16x16x32_bf16 v[60:63], v[152:155], v[168:171], v[60:63]
	v_mfma_f32_16x16x32_bf16 v[52:55], v[160:163], v[168:171], v[52:55]
	v_mfma_f32_16x16x32_bf16 v[44:47], v[152:155], v[176:179], v[44:47]
	v_mfma_f32_16x16x32_bf16 v[36:39], v[160:163], v[176:179], v[36:39]
	v_mfma_f32_16x16x32_bf16 v[28:31], v[152:155], v[184:187], v[28:31]
	v_mfma_f32_16x16x32_bf16 v[20:23], v[160:163], v[184:187], v[20:23]
	v_mfma_f32_16x16x32_bf16 v[12:15], v[152:155], v[192:195], v[12:15]
	v_mfma_f32_16x16x32_bf16 v[4:7], v[160:163], v[192:195], v[4:7]
	s_setprio 1
	s_barrier
; #define WAIT_V(n) asm volatile("s_waitcnt vmcnt(" #n ")" ::: "memory")
; #define WAIT_L(n) asm volatile("s_waitcnt lgkmcnt(" #n ")" ::: "memory")
; #define BAR __builtin_amdgcn_s_barrier()
; #define SCHED __builtin_amdgcn_sched_barrier(0)
; template <class Get, class Epi>
; DI void gemm_stream(LAS unsigned char* lds, const int K, const int ld, Get get, Epi epi) {
;     ...
;             STAGE(SBo(0, 1), b2 + hstep);
;             WAIT_V(6); BAR; MMA(1, 1, At, B1); BAR;
;             LDB(B0, 1, 0); SCHED; LDA(At, 1, 0); STAGE(SAo(0, 1), a2 + hstep);
;             WAIT_L(8); BAR; WAIT_L(0); MMA(0, 0, At, B0); BAR; SCHED;
;             LDB(B1, 1, 1); STAGE(SBo(1, 0), b3);
;             BAR; WAIT_L(0); MMA(0, 1, At, B1); BAR;
;             LDA(At, 1, 1); STAGE(SAo(1, 0), a3);
;             BAR; WAIT_L(0); MMA(1, 0, At, B0); BAR; SCHED;
;             STAGE(SBo(1, 1), b3 + hstep);
;             WAIT_V(6); BAR; MMA(1, 1, At, B1); BAR;
	s_add_u32 s60, s12, 0x80000
	s_addc_u32 s61, s13, 0
	s_mov_b32 m0, s37
	v_lshl_add_u64 v[148:149], s[60:61], 0, v[130:131]
	global_load_lds_dwordx4 v[148:149], off
	v_lshl_add_u64 v[148:149], s[60:61], 0, v[128:129]
	s_mov_b32 m0, s38
	s_nop 0
	global_load_lds_dwordx4 v[148:149], off
	s_waitcnt vmcnt(6)
	s_barrier
	s_setprio 0
	v_mfma_f32_16x16x32_bf16 v[56:59], v[196:199], v[164:167], v[56:59]
	v_mfma_f32_16x16x32_bf16 v[48:51], v[208:211], v[164:167], v[48:51]
	v_mfma_f32_16x16x32_bf16 v[40:43], v[196:199], v[172:175], v[40:43]
	v_mfma_f32_16x16x32_bf16 v[32:35], v[208:211], v[172:175], v[32:35]
	v_mfma_f32_16x16x32_bf16 v[24:27], v[196:199], v[180:183], v[24:27]
	v_mfma_f32_16x16x32_bf16 v[16:19], v[208:211], v[180:183], v[16:19]
	v_mfma_f32_16x16x32_bf16 v[8:11], v[196:199], v[188:191], v[8:11]
	v_mfma_f32_16x16x32_bf16 v[0:3], v[208:211], v[188:191], v[0:3]
	v_mfma_f32_16x16x32_bf16 v[56:59], v[200:203], v[168:171], v[56:59]
	v_mfma_f32_16x16x32_bf16 v[48:51], v[212:215], v[168:171], v[48:51]
	v_mfma_f32_16x16x32_bf16 v[40:43], v[200:203], v[176:179], v[40:43]
	v_mfma_f32_16x16x32_bf16 v[32:35], v[212:215], v[176:179], v[32:35]
	v_mfma_f32_16x16x32_bf16 v[24:27], v[200:203], v[184:187], v[24:27]
	v_mfma_f32_16x16x32_bf16 v[16:19], v[212:215], v[184:187], v[16:19]
	v_mfma_f32_16x16x32_bf16 v[8:11], v[200:203], v[192:195], v[8:11]
	v_mfma_f32_16x16x32_bf16 v[0:3], v[212:215], v[192:195], v[0:3]
	s_setprio 1
	s_barrier
	ds_read_b128 v[148:151], v145
	ds_read_b128 v[152:155], v145 offset:1024
	ds_read_b128 v[156:159], v145 offset:2048
	ds_read_b128 v[160:163], v145 offset:3072
	s_add_u32 s14, s14, 0x80000
	s_addc_u32 s15, s15, 0
	s_mov_b32 m0, s17
	v_lshl_add_u64 v[196:197], s[14:15], 0, v[130:131]
	ds_read_b128 v[164:167], v143 offset:32768
	ds_read_b128 v[168:171], v143 offset:33792
	ds_read_b128 v[172:175], v143 offset:34816
	ds_read_b128 v[176:179], v143 offset:35840
	ds_read_b128 v[180:183], v143 offset:36864
	ds_read_b128 v[184:187], v143 offset:37888
	ds_read_b128 v[188:191], v143 offset:38912
	ds_read_b128 v[192:195], v143 offset:39936
	global_load_lds_dwordx4 v[196:197], off
	v_lshl_add_u64 v[196:197], s[14:15], 0, v[128:129]
	s_mov_b32 m0, s18
	s_nop 0
	global_load_lds_dwordx4 v[196:197], off
	s_waitcnt lgkmcnt(8)
	s_barrier
	s_waitcnt lgkmcnt(0)
	s_setprio 0
	s_waitcnt lgkmcnt(0)
	v_mfma_f32_16x16x32_bf16 v[124:127], v[148:151], v[164:167], v[124:127]
	v_mfma_f32_16x16x32_bf16 v[116:119], v[156:159], v[164:167], v[116:119]
	v_mfma_f32_16x16x32_bf16 v[108:111], v[148:151], v[172:175], v[108:111]
	v_mfma_f32_16x16x32_bf16 v[100:103], v[156:159], v[172:175], v[100:103]
	v_mfma_f32_16x16x32_bf16 v[92:95], v[148:151], v[180:183], v[92:95]
	v_mfma_f32_16x16x32_bf16 v[84:87], v[156:159], v[180:183], v[84:87]
	v_mfma_f32_16x16x32_bf16 v[76:79], v[148:151], v[188:191], v[76:79]
	v_mfma_f32_16x16x32_bf16 v[68:71], v[156:159], v[188:191], v[68:71]
	v_mfma_f32_16x16x32_bf16 v[124:127], v[152:155], v[168:171], v[124:127]
	v_mfma_f32_16x16x32_bf16 v[116:119], v[160:163], v[168:171], v[116:119]
	v_mfma_f32_16x16x32_bf16 v[108:111], v[152:155], v[176:179], v[108:111]
	v_mfma_f32_16x16x32_bf16 v[100:103], v[160:163], v[176:179], v[100:103]
	v_mfma_f32_16x16x32_bf16 v[92:95], v[152:155], v[184:187], v[92:95]
	v_mfma_f32_16x16x32_bf16 v[84:87], v[160:163], v[184:187], v[84:87]
	v_mfma_f32_16x16x32_bf16 v[76:79], v[152:155], v[192:195], v[76:79]
	v_mfma_f32_16x16x32_bf16 v[68:71], v[160:163], v[192:195], v[68:71]
	s_setprio 1
	s_barrier
	s_mov_b32 m0, s39
	v_lshl_add_u64 v[140:141], v[140:141], 0, s[0:1]
	ds_read_b128 v[196:199], v146
	ds_read_b128 v[200:203], v146 offset:1024
	ds_read_b128 v[208:211], v146 offset:2048
	ds_read_b128 v[212:215], v146 offset:3072
	global_load_lds_dwordx4 v[140:141], off
	v_lshl_add_u64 v[140:141], v[204:205], 0, s[0:1]
	s_mov_b32 m0, s40
	s_nop 0
	global_load_lds_dwordx4 v[140:141], off
	s_barrier
	s_waitcnt lgkmcnt(0)
	s_setprio 0
	s_waitcnt lgkmcnt(0)
	v_mfma_f32_16x16x32_bf16 v[120:123], v[196:199], v[164:167], v[120:123]
	v_mfma_f32_16x16x32_bf16 v[112:115], v[208:211], v[164:167], v[112:115]
	v_mfma_f32_16x16x32_bf16 v[104:107], v[196:199], v[172:175], v[104:107]
	v_mfma_f32_16x16x32_bf16 v[96:99], v[208:211], v[172:175], v[96:99]
	v_mfma_f32_16x16x32_bf16 v[88:91], v[196:199], v[180:183], v[88:91]
	v_mfma_f32_16x16x32_bf16 v[80:83], v[208:211], v[180:183], v[80:83]
	v_mfma_f32_16x16x32_bf16 v[72:75], v[196:199], v[188:191], v[72:75]
	v_mfma_f32_16x16x32_bf16 v[64:67], v[208:211], v[188:191], v[64:67]
	v_mfma_f32_16x16x32_bf16 v[120:123], v[200:203], v[168:171], v[120:123]
	v_mfma_f32_16x16x32_bf16 v[112:115], v[212:215], v[168:171], v[112:115]
	v_mfma_f32_16x16x32_bf16 v[104:107], v[200:203], v[176:179], v[104:107]
	v_mfma_f32_16x16x32_bf16 v[96:99], v[212:215], v[176:179], v[96:99]
	v_mfma_f32_16x16x32_bf16 v[88:91], v[200:203], v[184:187], v[88:91]
	v_mfma_f32_16x16x32_bf16 v[80:83], v[212:215], v[184:187], v[80:83]
	v_mfma_f32_16x16x32_bf16 v[72:75], v[200:203], v[192:195], v[72:75]
	v_mfma_f32_16x16x32_bf16 v[64:67], v[212:215], v[192:195], v[64:67]
	s_setprio 1
	s_mov_b32 m0, s20
	v_lshl_add_u64 v[140:141], v[216:217], 0, s[0:1]
	s_barrier
	ds_read_b128 v[164:167], v143 offset:49152
	ds_read_b128 v[168:171], v143 offset:50176
	ds_read_b128 v[172:175], v143 offset:51200
	ds_read_b128 v[176:179], v143 offset:52224
	ds_read_b128 v[180:183], v143 offset:53248
	ds_read_b128 v[184:187], v143 offset:54272
	ds_read_b128 v[188:191], v143 offset:55296
	ds_read_b128 v[192:195], v143 offset:56320
	global_load_lds_dwordx4 v[140:141], off
	v_lshl_add_u64 v[140:141], v[218:219], 0, s[0:1]
	s_mov_b32 m0, s21
	s_nop 0
	global_load_lds_dwordx4 v[140:141], off
	s_barrier
; DI float silu_f(float g) { return g * __builtin_amdgcn_rcpf(1.f + __builtin_amdgcn_exp2f(-LOG2E * g)); }
; #define WAIT_V(n) asm volatile("s_waitcnt vmcnt(" #n ")" ::: "memory")
; #define WAIT_L(n) asm volatile("s_waitcnt lgkmcnt(" #n ")" ::: "memory")
; #define BAR __builtin_amdgcn_s_barrier()
; #define SCHED __builtin_amdgcn_sched_barrier(0)
; template <class Get, class Epi>
; DI void gemm_stream(LAS unsigned char* lds, const int K, const int ld, Get get, Epi epi) {
;     ...
;             BAR; WAIT_L(0); MMA(1, 0, At, B0); BAR; SCHED;
;             STAGE(SBo(1, 1), b3 + hstep);
;             WAIT_V(6); BAR; MMA(1, 1, At, B1); BAR;
; DI void epi_swiglu(const Acc& acc, int brow, int pn, bf16_t* hid) {
;     EPI_IDX
; #pragma unroll
;     for (int ai = 0; ai < 2; ++ai)
; #pragma unroll
;         for (int m = 0; m < 4; ++m) {
;             const int r = brow + ai * 128 + wr * 64 + m * 16 + fr;
;             bf16_t* rp = hid + (size_t)r * FF + pn * 128 + wc * 32 + fq * 4;
; #pragma unroll
;             for (int n = 0; n < 2; ++n) {
;                 const f32x4 g = acc[ai][0][m][n], u = acc[ai][1][m][n];
;                 float o[4];
; #pragma unroll
;                 for (int j = 0; j < 4; ++j) o[j] = silu_f(g[j]) * u[j];
;                 st4(rp + n * 16, o[0], o[1], o[2], o[3]);
;             }
	s_waitcnt lgkmcnt(0)
	s_setprio 0
	s_waitcnt lgkmcnt(0)
	v_mfma_f32_16x16x32_bf16 v[60:63], v[148:151], v[164:167], v[60:63]
	v_mfma_f32_16x16x32_bf16 v[52:55], v[156:159], v[164:167], v[52:55]
	v_mfma_f32_16x16x32_bf16 v[44:47], v[148:151], v[172:175], v[44:47]
	v_mfma_f32_16x16x32_bf16 v[36:39], v[156:159], v[172:175], v[36:39]
	v_mfma_f32_16x16x32_bf16 v[28:31], v[148:151], v[180:183], v[28:31]
	v_mfma_f32_16x16x32_bf16 v[20:23], v[156:159], v[180:183], v[20:23]
	v_mfma_f32_16x16x32_bf16 v[12:15], v[148:151], v[188:191], v[12:15]
	v_mfma_f32_16x16x32_bf16 v[4:7], v[156:159], v[188:191], v[4:7]
	v_mfma_f32_16x16x32_bf16 v[60:63], v[152:155], v[168:171], v[60:63]
	v_mfma_f32_16x16x32_bf16 v[52:55], v[160:163], v[168:171], v[52:55]
	v_mfma_f32_16x16x32_bf16 v[44:47], v[152:155], v[176:179], v[44:47]
	v_mfma_f32_16x16x32_bf16 v[36:39], v[160:163], v[176:179], v[36:39]
	v_mfma_f32_16x16x32_bf16 v[28:31], v[152:155], v[184:187], v[28:31]
	v_mfma_f32_16x16x32_bf16 v[20:23], v[160:163], v[184:187], v[20:23]
	v_mfma_f32_16x16x32_bf16 v[12:15], v[152:155], v[192:195], v[12:15]
	v_mfma_f32_16x16x32_bf16 v[4:7], v[160:163], v[192:195], v[4:7]
	s_setprio 1
	s_barrier
	s_add_u32 s12, s12, 0x80080
	s_addc_u32 s13, s13, 0
	s_mov_b32 m0, s41
	v_lshl_add_u64 v[140:141], s[12:13], 0, v[130:131]
	global_load_lds_dwordx4 v[140:141], off
	v_lshl_add_u64 v[140:141], s[12:13], 0, v[128:129]
	s_mov_b32 m0, s52
	s_nop 0
	global_load_lds_dwordx4 v[140:141], off
	s_waitcnt vmcnt(6)
	s_barrier
	s_setprio 0
	v_mfma_f32_16x16x32_bf16 v[56:59], v[196:199], v[164:167], v[56:59]
	v_mfma_f32_16x16x32_bf16 v[48:51], v[208:211], v[164:167], v[48:51]
	v_mfma_f32_16x16x32_bf16 v[40:43], v[196:199], v[172:175], v[40:43]
	v_mfma_f32_16x16x32_bf16 v[32:35], v[208:211], v[172:175], v[32:35]
	v_mfma_f32_16x16x32_bf16 v[24:27], v[196:199], v[180:183], v[24:27]
	v_mfma_f32_16x16x32_bf16 v[16:19], v[208:211], v[180:183], v[16:19]
	v_mfma_f32_16x16x32_bf16 v[8:11], v[196:199], v[188:191], v[8:11]
	v_mfma_f32_16x16x32_bf16 v[0:3], v[208:211], v[188:191], v[0:3]
	v_mfma_f32_16x16x32_bf16 v[56:59], v[200:203], v[168:171], v[56:59]
	v_mfma_f32_16x16x32_bf16 v[48:51], v[212:215], v[168:171], v[48:51]
	v_mfma_f32_16x16x32_bf16 v[40:43], v[200:203], v[176:179], v[40:43]
	v_mfma_f32_16x16x32_bf16 v[32:35], v[212:215], v[176:179], v[32:35]
	v_mfma_f32_16x16x32_bf16 v[24:27], v[200:203], v[184:187], v[24:27]
	v_mfma_f32_16x16x32_bf16 v[16:19], v[212:215], v[184:187], v[16:19]
	v_mfma_f32_16x16x32_bf16 v[8:11], v[200:203], v[192:195], v[8:11]
	v_mfma_f32_16x16x32_bf16 v[0:3], v[212:215], v[192:195], v[0:3]
	s_setprio 1
	s_add_i32 s59, s59, 2
	s_add_u32 s10, s10, 0x100
	s_addc_u32 s11, s11, 0
	s_add_u32 s57, s57, 0x100
	s_addc_u32 s58, s58, 0
	s_cmp_gt_u32 s59, 29
	s_barrier
	s_cbranch_scc0 .LBB0_1630
	s_lshl_b32 s10, s55, 8
	v_mov_b32_e32 v132, v206
	v_mul_f32_e32 v149, 0xbfb8aa3b, v125
	v_and_or_b32 v141, v132, 15, s10
	s_lshl_b32 s10, s56, 7
	s_ashr_i32 s11, s10, 31
	s_lshl_b64 s[10:11], s[10:11], 1
	v_ashrrev_i32_e32 v140, 2, v132
	s_add_u32 s10, s80, s10
	v_and_b32_e32 v140, 0xffffffc0, v140
	s_addc_u32 s11, s81, s11
	v_lshrrev_b32_e32 v148, 1, v132
	v_and_b32_e32 v132, 0xc0, v132
	v_add_u32_e32 v147, v141, v140
	v_lshl_add_u64 v[140:141], s[10:11], 0, v[132:133]
	v_and_b32_e32 v132, 24, v148
	v_mul_f32_e32 v148, 0xbfb8aa3b, v124
	v_exp_f32_e32 v148, v148
	v_exp_f32_e32 v149, v149
	v_lshl_add_u64 v[140:141], v[140:141], 0, v[132:133]
	v_mad_i64_i32 v[152:153], s[10:11], v147, s23, v[140:141]
	v_add_f32_e32 v132, 1.0, v148
	v_rcp_f32_e32 v148, v132
	v_add_f32_e32 v132, 1.0, v149
	v_mul_f32_e32 v149, 0xbfb8aa3b, v126
	v_exp_f32_e32 v150, v149
	v_mul_f32_e32 v149, 0xbfb8aa3b, v127
	v_exp_f32_e32 v151, v149
	v_rcp_f32_e32 v149, v132
	v_add_f32_e32 v132, 1.0, v150
	v_rcp_f32_e32 v150, v132
	v_add_f32_e32 v132, 1.0, v151
	v_rcp_f32_e32 v151, v132
	v_pk_mul_f32 v[124:125], v[124:125], v[148:149]
	s_and_b64 vcc, exec, s[4:5]
	v_pk_mul_f32 v[120:121], v[124:125], v[120:121]
	v_pk_mul_f32 v[124:125], v[126:127], v[150:151]
	v_cvt_pk_bf16_f32 v120, v120, v121
	v_mul_f32_e32 v121, 0xbfb8aa3b, v116
	v_pk_mul_f32 v[122:123], v[124:125], v[122:123]
	v_exp_f32_e32 v124, v121
	v_mul_f32_e32 v121, 0xbfb8aa3b, v117
	v_exp_f32_e32 v125, v121
	v_cvt_pk_bf16_f32 v121, v122, v123
	v_add_f32_e32 v122, 1.0, v124
	v_mul_f32_e32 v124, 0xbfb8aa3b, v118
	v_add_f32_e32 v123, 1.0, v125
	v_mul_f32_e32 v125, 0xbfb8aa3b, v119
	v_exp_f32_e32 v124, v124
	v_exp_f32_e32 v125, v125
	v_rcp_f32_e32 v122, v122
	v_rcp_f32_e32 v123, v123
	v_add_f32_e32 v124, 1.0, v124
	v_add_f32_e32 v125, 1.0, v125
	v_rcp_f32_e32 v124, v124
	v_rcp_f32_e32 v125, v125
	v_pk_mul_f32 v[116:117], v[116:117], v[122:123]
	s_mov_b32 s56, s53
	v_pk_mul_f32 v[112:113], v[116:117], v[112:113]
	v_pk_mul_f32 v[116:117], v[118:119], v[124:125]
	v_cvt_pk_bf16_f32 v112, v112, v113
	v_pk_mul_f32 v[114:115], v[116:117], v[114:115]
	v_or_b32_e32 v116, 16, v147
	v_cvt_pk_bf16_f32 v113, v114, v115
	global_store_dwordx2 v[152:153], v[112:113], off offset:32
	v_mul_f32_e32 v112, 0xbfb8aa3b, v108
	v_mul_f32_e32 v113, 0xbfb8aa3b, v109
	v_exp_f32_e32 v112, v112
	v_exp_f32_e32 v113, v113
	v_mul_f32_e32 v114, 0xbfb8aa3b, v110
	v_mul_f32_e32 v115, 0xbfb8aa3b, v111
	v_exp_f32_e32 v114, v114
	v_exp_f32_e32 v115, v115
	v_add_f32_e32 v112, 1.0, v112
	v_add_f32_e32 v113, 1.0, v113
	v_rcp_f32_e32 v112, v112
	v_rcp_f32_e32 v113, v113
	v_add_f32_e32 v114, 1.0, v114
	v_add_f32_e32 v115, 1.0, v115
	v_rcp_f32_e32 v114, v114
	v_rcp_f32_e32 v115, v115
	v_pk_mul_f32 v[108:109], v[108:109], v[112:113]
	v_mad_i64_i32 v[116:117], s[10:11], v116, s23, v[140:141]
	v_pk_mul_f32 v[104:105], v[108:109], v[104:105]
; DI float silu_f(float g) { return g * __builtin_amdgcn_rcpf(1.f + __builtin_amdgcn_exp2f(-LOG2E * g)); }
; DI void epi_swiglu(const Acc& acc, int brow, int pn, bf16_t* hid) {
;     ...
;     for (int ai = 0; ai < 2; ++ai)
; #pragma unroll
;         for (int m = 0; m < 4; ++m) {
;             const int r = brow + ai * 128 + wr * 64 + m * 16 + fr;
;             bf16_t* rp = hid + (size_t)r * FF + pn * 128 + wc * 32 + fq * 4;
; #pragma unroll
;             for (int n = 0; n < 2; ++n) {
;                 const f32x4 g = acc[ai][0][m][n], u = acc[ai][1][m][n];
;                 float o[4];
; #pragma unroll
;                 for (int j = 0; j < 4; ++j) o[j] = silu_f(g[j]) * u[j];
;                 st4(rp + n * 16, o[0], o[1], o[2], o[3]);
;             }
	v_pk_mul_f32 v[108:109], v[110:111], v[114:115]
	v_cvt_pk_bf16_f32 v104, v104, v105
	v_mul_f32_e32 v105, 0xbfb8aa3b, v100
	v_pk_mul_f32 v[106:107], v[108:109], v[106:107]
	v_exp_f32_e32 v108, v105
	v_mul_f32_e32 v105, 0xbfb8aa3b, v101
	v_exp_f32_e32 v109, v105
	v_cvt_pk_bf16_f32 v105, v106, v107
	v_add_f32_e32 v106, 1.0, v108
	v_mul_f32_e32 v108, 0xbfb8aa3b, v102
	v_add_f32_e32 v107, 1.0, v109
	v_mul_f32_e32 v109, 0xbfb8aa3b, v103
	v_exp_f32_e32 v108, v108
	v_exp_f32_e32 v109, v109
	v_rcp_f32_e32 v106, v106
	v_rcp_f32_e32 v107, v107
	v_add_f32_e32 v108, 1.0, v108
	v_add_f32_e32 v109, 1.0, v109
	v_rcp_f32_e32 v108, v108
	v_rcp_f32_e32 v109, v109
	v_pk_mul_f32 v[100:101], v[100:101], v[106:107]
	s_mov_b32 s55, s54
	v_pk_mul_f32 v[96:97], v[100:101], v[96:97]
	v_pk_mul_f32 v[100:101], v[102:103], v[108:109]
	v_cvt_pk_bf16_f32 v96, v96, v97
	v_pk_mul_f32 v[98:99], v[100:101], v[98:99]
	v_or_b32_e32 v100, 32, v147
	v_cvt_pk_bf16_f32 v97, v98, v99
	global_store_dwordx2 v[116:117], v[96:97], off offset:32
	v_mul_f32_e32 v96, 0xbfb8aa3b, v92
	v_mul_f32_e32 v97, 0xbfb8aa3b, v93
	v_exp_f32_e32 v96, v96
	v_exp_f32_e32 v97, v97
	v_mul_f32_e32 v98, 0xbfb8aa3b, v94
	v_mul_f32_e32 v99, 0xbfb8aa3b, v95
	v_exp_f32_e32 v98, v98
	v_exp_f32_e32 v99, v99
	v_add_f32_e32 v96, 1.0, v96
	v_add_f32_e32 v97, 1.0, v97
	v_rcp_f32_e32 v96, v96
	v_rcp_f32_e32 v97, v97
	v_add_f32_e32 v98, 1.0, v98
	v_add_f32_e32 v99, 1.0, v99
	v_rcp_f32_e32 v98, v98
	v_rcp_f32_e32 v99, v99
	v_pk_mul_f32 v[92:93], v[92:93], v[96:97]
	v_mad_i64_i32 v[100:101], s[10:11], v100, s23, v[140:141]
	v_pk_mul_f32 v[88:89], v[92:93], v[88:89]
	v_pk_mul_f32 v[92:93], v[94:95], v[98:99]
	v_cvt_pk_bf16_f32 v88, v88, v89
	v_mul_f32_e32 v89, 0xbfb8aa3b, v84
	v_pk_mul_f32 v[90:91], v[92:93], v[90:91]
	v_exp_f32_e32 v92, v89
	v_mul_f32_e32 v89, 0xbfb8aa3b, v85
	v_exp_f32_e32 v93, v89
	v_cvt_pk_bf16_f32 v89, v90, v91
	v_add_f32_e32 v90, 1.0, v92
	v_mul_f32_e32 v92, 0xbfb8aa3b, v86
	v_add_f32_e32 v91, 1.0, v93
	v_mul_f32_e32 v93, 0xbfb8aa3b, v87
	v_exp_f32_e32 v92, v92
	v_exp_f32_e32 v93, v93
	v_rcp_f32_e32 v90, v90
	v_rcp_f32_e32 v91, v91
	v_add_f32_e32 v92, 1.0, v92
	v_add_f32_e32 v93, 1.0, v93
	v_rcp_f32_e32 v92, v92
	v_rcp_f32_e32 v93, v93
	v_pk_mul_f32 v[84:85], v[84:85], v[90:91]
	s_mov_b64 s[12:13], s[8:9]
	v_pk_mul_f32 v[80:81], v[84:85], v[80:81]
	v_pk_mul_f32 v[84:85], v[86:87], v[92:93]
	v_cvt_pk_bf16_f32 v80, v80, v81
	v_pk_mul_f32 v[82:83], v[84:85], v[82:83]
	v_or_b32_e32 v84, 48, v147
	v_cvt_pk_bf16_f32 v81, v82, v83
	global_store_dwordx2 v[100:101], v[80:81], off offset:32
	v_mul_f32_e32 v80, 0xbfb8aa3b, v76
	v_mul_f32_e32 v81, 0xbfb8aa3b, v77
	v_exp_f32_e32 v80, v80
	v_exp_f32_e32 v81, v81
	v_mul_f32_e32 v82, 0xbfb8aa3b, v78
	v_mul_f32_e32 v83, 0xbfb8aa3b, v79
	v_exp_f32_e32 v82, v82
	v_exp_f32_e32 v83, v83
	v_add_f32_e32 v80, 1.0, v80
	v_add_f32_e32 v81, 1.0, v81
	v_rcp_f32_e32 v80, v80
	v_rcp_f32_e32 v81, v81
	v_add_f32_e32 v82, 1.0, v82
	v_add_f32_e32 v83, 1.0, v83
	v_rcp_f32_e32 v82, v82
	v_rcp_f32_e32 v83, v83
	v_pk_mul_f32 v[76:77], v[76:77], v[80:81]
	v_mad_i64_i32 v[84:85], s[10:11], v84, s23, v[140:141]
	v_pk_mul_f32 v[72:73], v[76:77], v[72:73]
	v_pk_mul_f32 v[76:77], v[78:79], v[82:83]
	v_cvt_pk_bf16_f32 v72, v72, v73
	v_mul_f32_e32 v73, 0xbfb8aa3b, v68
	v_pk_mul_f32 v[74:75], v[76:77], v[74:75]
	v_exp_f32_e32 v76, v73
	v_mul_f32_e32 v73, 0xbfb8aa3b, v69
	v_exp_f32_e32 v77, v73
	v_cvt_pk_bf16_f32 v73, v74, v75
	v_add_f32_e32 v74, 1.0, v76
	v_mul_f32_e32 v76, 0xbfb8aa3b, v70
	v_add_f32_e32 v75, 1.0, v77
	v_mul_f32_e32 v77, 0xbfb8aa3b, v71
	v_exp_f32_e32 v76, v76
	v_exp_f32_e32 v77, v77
	v_rcp_f32_e32 v74, v74
	v_rcp_f32_e32 v75, v75
	v_add_f32_e32 v76, 1.0, v76
	v_add_f32_e32 v77, 1.0, v77
	v_rcp_f32_e32 v76, v76
	v_rcp_f32_e32 v77, v77
	v_pk_mul_f32 v[68:69], v[68:69], v[74:75]
	global_store_dwordx2 v[152:153], v[120:121], off
	v_pk_mul_f32 v[64:65], v[68:69], v[64:65]
	v_pk_mul_f32 v[68:69], v[70:71], v[76:77]
	v_cvt_pk_bf16_f32 v64, v64, v65
	v_pk_mul_f32 v[66:67], v[68:69], v[66:67]
	v_add_u32_e32 v68, 0x80, v147
	v_cvt_pk_bf16_f32 v65, v66, v67
	global_store_dwordx2 v[84:85], v[64:65], off offset:32
	v_mul_f32_e32 v64, 0xbfb8aa3b, v60
	v_mul_f32_e32 v65, 0xbfb8aa3b, v61
	v_exp_f32_e32 v64, v64
	v_exp_f32_e32 v65, v65
	v_mul_f32_e32 v66, 0xbfb8aa3b, v62
	v_mul_f32_e32 v67, 0xbfb8aa3b, v63
	v_exp_f32_e32 v66, v66
	v_exp_f32_e32 v67, v67
	v_add_f32_e32 v64, 1.0, v64
	v_add_f32_e32 v65, 1.0, v65
	v_rcp_f32_e32 v64, v64
	v_rcp_f32_e32 v65, v65
	v_add_f32_e32 v66, 1.0, v66
	v_add_f32_e32 v67, 1.0, v67
	v_rcp_f32_e32 v66, v66
	v_rcp_f32_e32 v67, v67
	v_pk_mul_f32 v[60:61], v[60:61], v[64:65]
	v_mad_i64_i32 v[68:69], s[10:11], v68, s23, v[140:141]
	v_pk_mul_f32 v[56:57], v[60:61], v[56:57]
	v_pk_mul_f32 v[60:61], v[62:63], v[66:67]
	v_cvt_pk_bf16_f32 v56, v56, v57
	v_mul_f32_e32 v57, 0xbfb8aa3b, v52
	v_pk_mul_f32 v[58:59], v[60:61], v[58:59]
	v_exp_f32_e32 v60, v57
	v_mul_f32_e32 v57, 0xbfb8aa3b, v53
	v_exp_f32_e32 v61, v57
	v_cvt_pk_bf16_f32 v57, v58, v59
	v_add_f32_e32 v58, 1.0, v60
	v_mul_f32_e32 v60, 0xbfb8aa3b, v54
	v_add_f32_e32 v59, 1.0, v61
	v_mul_f32_e32 v61, 0xbfb8aa3b, v55
	v_exp_f32_e32 v60, v60
	v_exp_f32_e32 v61, v61
	v_rcp_f32_e32 v58, v58
	v_rcp_f32_e32 v59, v59
	v_add_f32_e32 v60, 1.0, v60
	v_add_f32_e32 v61, 1.0, v61
	v_rcp_f32_e32 v60, v60
; DI float silu_f(float g) { return g * __builtin_amdgcn_rcpf(1.f + __builtin_amdgcn_exp2f(-LOG2E * g)); }
; #define WAIT_V(n) asm volatile("s_waitcnt vmcnt(" #n ")" ::: "memory")
; #define BAR __builtin_amdgcn_s_barrier()
; template <class Get, class Epi>
; DI void gemm_stream(LAS unsigned char* lds, const int K, const int ld, Get get, Epi epi) {
;     ...
;         if (!has_next) break;
;         ZERO_ACC;
;         cur = nxt; cA = nA; cB = nB; ++ui;
;     }
;     WAIT_V(0);
;     if (wr == 0) BAR;
;     BAR;
; DI void epi_swiglu(const Acc& acc, int brow, int pn, bf16_t* hid) {
;     ...
;     for (int ai = 0; ai < 2; ++ai)
; #pragma unroll
;         for (int m = 0; m < 4; ++m) {
;             const int r = brow + ai * 128 + wr * 64 + m * 16 + fr;
;             bf16_t* rp = hid + (size_t)r * FF + pn * 128 + wc * 32 + fq * 4;
; #pragma unroll
;             for (int n = 0; n < 2; ++n) {
;                 const f32x4 g = acc[ai][0][m][n], u = acc[ai][1][m][n];
;                 float o[4];
; #pragma unroll
;                 for (int j = 0; j < 4; ++j) o[j] = silu_f(g[j]) * u[j];
;                 st4(rp + n * 16, o[0], o[1], o[2], o[3]);
;             }
	v_rcp_f32_e32 v61, v61
	v_pk_mul_f32 v[52:53], v[52:53], v[58:59]
	global_store_dwordx2 v[116:117], v[104:105], off
	v_pk_mul_f32 v[48:49], v[52:53], v[48:49]
	v_pk_mul_f32 v[52:53], v[54:55], v[60:61]
	v_cvt_pk_bf16_f32 v48, v48, v49
	v_pk_mul_f32 v[50:51], v[52:53], v[50:51]
	v_add_u32_e32 v52, 0x90, v147
	v_cvt_pk_bf16_f32 v49, v50, v51
	global_store_dwordx2 v[68:69], v[48:49], off offset:32
	v_mul_f32_e32 v48, 0xbfb8aa3b, v44
	v_mul_f32_e32 v49, 0xbfb8aa3b, v45
	v_exp_f32_e32 v48, v48
	v_exp_f32_e32 v49, v49
	v_mul_f32_e32 v50, 0xbfb8aa3b, v46
	v_mul_f32_e32 v51, 0xbfb8aa3b, v47
	v_exp_f32_e32 v50, v50
	v_exp_f32_e32 v51, v51
	v_add_f32_e32 v48, 1.0, v48
	v_add_f32_e32 v49, 1.0, v49
	v_rcp_f32_e32 v48, v48
	v_rcp_f32_e32 v49, v49
	v_add_f32_e32 v50, 1.0, v50
	v_add_f32_e32 v51, 1.0, v51
	v_rcp_f32_e32 v50, v50
	v_rcp_f32_e32 v51, v51
	v_pk_mul_f32 v[44:45], v[44:45], v[48:49]
	v_mad_i64_i32 v[52:53], s[10:11], v52, s23, v[140:141]
	v_pk_mul_f32 v[40:41], v[44:45], v[40:41]
	v_pk_mul_f32 v[44:45], v[46:47], v[50:51]
	v_cvt_pk_bf16_f32 v40, v40, v41
	v_mul_f32_e32 v41, 0xbfb8aa3b, v36
	v_pk_mul_f32 v[42:43], v[44:45], v[42:43]
	v_exp_f32_e32 v44, v41
	v_mul_f32_e32 v41, 0xbfb8aa3b, v37
	v_exp_f32_e32 v45, v41
	v_cvt_pk_bf16_f32 v41, v42, v43
	v_add_f32_e32 v42, 1.0, v44
	v_mul_f32_e32 v44, 0xbfb8aa3b, v38
	v_add_f32_e32 v43, 1.0, v45
	v_mul_f32_e32 v45, 0xbfb8aa3b, v39
	v_exp_f32_e32 v44, v44
	v_exp_f32_e32 v45, v45
	v_rcp_f32_e32 v42, v42
	v_rcp_f32_e32 v43, v43
	v_add_f32_e32 v44, 1.0, v44
	v_add_f32_e32 v45, 1.0, v45
	v_rcp_f32_e32 v44, v44
	v_rcp_f32_e32 v45, v45
	v_pk_mul_f32 v[36:37], v[36:37], v[42:43]
	global_store_dwordx2 v[100:101], v[88:89], off
	v_pk_mul_f32 v[32:33], v[36:37], v[32:33]
	v_pk_mul_f32 v[36:37], v[38:39], v[44:45]
	v_cvt_pk_bf16_f32 v32, v32, v33
	v_pk_mul_f32 v[34:35], v[36:37], v[34:35]
	v_add_u32_e32 v36, 0xa0, v147
	v_cvt_pk_bf16_f32 v33, v34, v35
	global_store_dwordx2 v[52:53], v[32:33], off offset:32
	v_mul_f32_e32 v32, 0xbfb8aa3b, v28
	v_mul_f32_e32 v33, 0xbfb8aa3b, v29
	v_exp_f32_e32 v32, v32
	v_exp_f32_e32 v33, v33
	v_mul_f32_e32 v34, 0xbfb8aa3b, v30
	v_mul_f32_e32 v35, 0xbfb8aa3b, v31
	v_exp_f32_e32 v34, v34
	v_exp_f32_e32 v35, v35
	v_add_f32_e32 v32, 1.0, v32
	v_add_f32_e32 v33, 1.0, v33
	v_rcp_f32_e32 v32, v32
	v_rcp_f32_e32 v33, v33
	v_add_f32_e32 v34, 1.0, v34
	v_add_f32_e32 v35, 1.0, v35
	v_rcp_f32_e32 v34, v34
	v_rcp_f32_e32 v35, v35
	v_pk_mul_f32 v[28:29], v[28:29], v[32:33]
	v_mad_i64_i32 v[36:37], s[10:11], v36, s23, v[140:141]
	v_pk_mul_f32 v[24:25], v[28:29], v[24:25]
	v_pk_mul_f32 v[28:29], v[30:31], v[34:35]
	v_cvt_pk_bf16_f32 v24, v24, v25
	v_mul_f32_e32 v25, 0xbfb8aa3b, v20
	v_pk_mul_f32 v[26:27], v[28:29], v[26:27]
	v_exp_f32_e32 v28, v25
	v_mul_f32_e32 v25, 0xbfb8aa3b, v21
	v_exp_f32_e32 v29, v25
	v_cvt_pk_bf16_f32 v25, v26, v27
	v_add_f32_e32 v26, 1.0, v28
	v_mul_f32_e32 v28, 0xbfb8aa3b, v22
	v_add_f32_e32 v27, 1.0, v29
	v_mul_f32_e32 v29, 0xbfb8aa3b, v23
	v_exp_f32_e32 v28, v28
	v_exp_f32_e32 v29, v29
	v_rcp_f32_e32 v26, v26
	v_rcp_f32_e32 v27, v27
	v_add_f32_e32 v28, 1.0, v28
	v_add_f32_e32 v29, 1.0, v29
	v_rcp_f32_e32 v28, v28
	v_rcp_f32_e32 v29, v29
	v_pk_mul_f32 v[20:21], v[20:21], v[26:27]
	global_store_dwordx2 v[84:85], v[72:73], off
	v_pk_mul_f32 v[16:17], v[20:21], v[16:17]
	v_pk_mul_f32 v[20:21], v[22:23], v[28:29]
	v_cvt_pk_bf16_f32 v16, v16, v17
	v_pk_mul_f32 v[18:19], v[20:21], v[18:19]
	v_add_u32_e32 v20, 0xb0, v147
	v_cvt_pk_bf16_f32 v17, v18, v19
	global_store_dwordx2 v[36:37], v[16:17], off offset:32
	v_mul_f32_e32 v16, 0xbfb8aa3b, v12
	v_mul_f32_e32 v17, 0xbfb8aa3b, v13
	v_exp_f32_e32 v16, v16
	v_exp_f32_e32 v17, v17
	v_mul_f32_e32 v18, 0xbfb8aa3b, v14
	v_mul_f32_e32 v19, 0xbfb8aa3b, v15
	v_exp_f32_e32 v18, v18
	v_exp_f32_e32 v19, v19
	v_add_f32_e32 v16, 1.0, v16
	v_add_f32_e32 v17, 1.0, v17
	v_rcp_f32_e32 v16, v16
	v_rcp_f32_e32 v17, v17
	v_add_f32_e32 v18, 1.0, v18
	v_add_f32_e32 v19, 1.0, v19
	v_rcp_f32_e32 v18, v18
	v_rcp_f32_e32 v19, v19
	v_pk_mul_f32 v[12:13], v[12:13], v[16:17]
	v_mad_i64_i32 v[20:21], s[10:11], v20, s23, v[140:141]
	v_pk_mul_f32 v[8:9], v[12:13], v[8:9]
	v_pk_mul_f32 v[12:13], v[14:15], v[18:19]
	v_cvt_pk_bf16_f32 v8, v8, v9
	v_mul_f32_e32 v9, 0xbfb8aa3b, v4
	v_pk_mul_f32 v[10:11], v[12:13], v[10:11]
	v_exp_f32_e32 v12, v9
	v_mul_f32_e32 v9, 0xbfb8aa3b, v5
	v_exp_f32_e32 v13, v9
	v_cvt_pk_bf16_f32 v9, v10, v11
	v_add_f32_e32 v10, 1.0, v12
	v_mul_f32_e32 v12, 0xbfb8aa3b, v6
	v_add_f32_e32 v11, 1.0, v13
	v_mul_f32_e32 v13, 0xbfb8aa3b, v7
	v_exp_f32_e32 v12, v12
	v_exp_f32_e32 v13, v13
	v_rcp_f32_e32 v10, v10
	v_rcp_f32_e32 v11, v11
	v_add_f32_e32 v12, 1.0, v12
	v_add_f32_e32 v13, 1.0, v13
	v_rcp_f32_e32 v12, v12
	v_rcp_f32_e32 v13, v13
	v_pk_mul_f32 v[4:5], v[4:5], v[10:11]
	s_mov_b64 s[10:11], s[6:7]
	v_pk_mul_f32 v[0:1], v[4:5], v[0:1]
	v_pk_mul_f32 v[4:5], v[6:7], v[12:13]
	v_cvt_pk_bf16_f32 v0, v0, v1
	v_pk_mul_f32 v[2:3], v[4:5], v[2:3]
	global_store_dwordx2 v[68:69], v[56:57], off
	v_cvt_pk_bf16_f32 v1, v2, v3
	global_store_dwordx2 v[52:53], v[40:41], off
	global_store_dwordx2 v[36:37], v[24:25], off
	global_store_dwordx2 v[20:21], v[8:9], off
	global_store_dwordx2 v[20:21], v[0:1], off offset:32
	s_cbranch_vccz .LBB0_1627
	s_waitcnt vmcnt(0)
	s_cmpk_gt_u32 s2, 0xff
	s_cbranch_scc1 .LBB0_1634
	s_barrier

; #define WAIT_V(n) asm volatile("s_waitcnt vmcnt(" #n ")" ::: "memory")
; #define WAIT_L(n) asm volatile("s_waitcnt lgkmcnt(" #n ")" ::: "memory")
; #define BAR __builtin_amdgcn_s_barrier()
; #define SCHED __builtin_amdgcn_sched_barrier(0)
; template <class Get, class Epi>
; DI void gemm_stream(LAS unsigned char* lds, const int K, const int ld, Get get, Epi epi) {
;     ...
;         for (int t = 0; t < nt; t += 2) {
;             const bool last = (t == nt - 2);
;             const char* a1 = cA + (size_t)(t + 1) * kstep;
;             const char* a2 = last ? nA : cA + (size_t)(t + 2) * kstep;
;             const char* b2 = last ? nB : cB + (size_t)(t + 2) * kstep;
;             const char* a3 = a2 + kstep;
;             const char* b3 = b2 + kstep;
;             LDB(B0, 0, 0); SCHED; LDA(At, 0, 0); STAGE(SAo(1, 1), a1 + hstep);
;             WAIT_L(8); BAR; WAIT_L(0); MMA(0, 0, At, B0); BAR; SCHED;
;             LDB(B1, 0, 1); STAGE(SBo(0, 0), b2);
;             BAR; WAIT_L(0); MMA(0, 1, At, B1); BAR;
;             LDA(At, 0, 1); STAGE(SAo(0, 0), a2);
;             BAR; WAIT_L(0); MMA(1, 0, At, B0); BAR; SCHED;
;             STAGE(SBo(0, 1), b2 + hstep);
;             WAIT_V(6); BAR; MMA(1, 1, At, B1); BAR;
;             LDB(B0, 1, 0); SCHED; LDA(At, 1, 0); STAGE(SAo(0, 1), a2 + hstep);
;             WAIT_L(8); BAR; WAIT_L(0); MMA(0, 0, At, B0); BAR; SCHED;
;             LDB(B1, 1, 1); STAGE(SBo(1, 0), b3);
;             BAR; WAIT_L(0); MMA(0, 1, At, B1); BAR;
.LBB0_1697:
	ds_read_b128 v[128:131], v199
	ds_read_b128 v[132:135], v199 offset:1024
	ds_read_b128 v[136:139], v199 offset:2048
	ds_read_b128 v[140:143], v199 offset:3072
	s_add_u32 s8, s6, 0x100
	s_addc_u32 s9, s7, 0
	s_cmpk_eq_i32 s16, 0x54
	s_cselect_b32 s13, s39, s9
	s_cselect_b32 s12, s38, s8
	s_cselect_b32 s11, s41, s15
	s_cselect_b32 s10, s40, s14
	s_mov_b32 m0, s63
	v_lshl_add_u64 v[186:187], s[6:7], 0, v[168:169]
	ds_read_b128 v[144:147], v200
	ds_read_b128 v[148:151], v200 offset:1024
	ds_read_b128 v[152:155], v200 offset:2048
	ds_read_b128 v[156:159], v200 offset:3072
	ds_read_b128 v[160:163], v200 offset:4096
	ds_read_b128 v[174:177], v200 offset:5120
	ds_read_b128 v[178:181], v200 offset:6144
	ds_read_b128 v[182:185], v200 offset:7168
	global_load_lds_dwordx4 v[186:187], off
	v_lshl_add_u64 v[186:187], s[6:7], 0, v[170:171]
	s_mov_b32 m0, s74
	s_nop 0
	global_load_lds_dwordx4 v[186:187], off
	s_waitcnt lgkmcnt(8)
	s_barrier
	s_waitcnt lgkmcnt(0)
	s_setprio 0
	s_waitcnt lgkmcnt(0)
	v_mfma_f32_16x16x32_bf16 v[124:127], v[128:131], v[144:147], v[124:127]
	v_mfma_f32_16x16x32_bf16 v[92:95], v[136:139], v[144:147], v[92:95]
	v_mfma_f32_16x16x32_bf16 v[120:123], v[128:131], v[152:155], v[120:123]
	v_mfma_f32_16x16x32_bf16 v[88:91], v[136:139], v[152:155], v[88:91]
	v_mfma_f32_16x16x32_bf16 v[116:119], v[128:131], v[160:163], v[116:119]
	v_mfma_f32_16x16x32_bf16 v[84:87], v[136:139], v[160:163], v[84:87]
	v_mfma_f32_16x16x32_bf16 v[112:115], v[128:131], v[178:181], v[112:115]
	v_mfma_f32_16x16x32_bf16 v[80:83], v[136:139], v[178:181], v[80:83]
	v_mfma_f32_16x16x32_bf16 v[124:127], v[132:135], v[148:151], v[124:127]
	v_mfma_f32_16x16x32_bf16 v[92:95], v[140:143], v[148:151], v[92:95]
	v_mfma_f32_16x16x32_bf16 v[120:123], v[132:135], v[156:159], v[120:123]
	v_mfma_f32_16x16x32_bf16 v[88:91], v[140:143], v[156:159], v[88:91]
	v_mfma_f32_16x16x32_bf16 v[116:119], v[132:135], v[174:177], v[116:119]
	v_mfma_f32_16x16x32_bf16 v[84:87], v[140:143], v[174:177], v[84:87]
	v_mfma_f32_16x16x32_bf16 v[112:115], v[132:135], v[182:185], v[112:115]
	v_mfma_f32_16x16x32_bf16 v[80:83], v[140:143], v[182:185], v[80:83]
	s_setprio 1
	s_barrier
	s_mov_b32 m0, s75
	v_lshl_add_u64 v[208:209], s[10:11], 0, v[164:165]
	ds_read_b128 v[186:189], v201
	ds_read_b128 v[190:193], v201 offset:1024
	ds_read_b128 v[194:197], v201 offset:2048
	ds_read_b128 v[202:205], v201 offset:3072
	global_load_lds_dwordx4 v[208:209], off
	v_lshl_add_u64 v[210:211], s[10:11], 0, v[166:167]
	s_mov_b32 m0, s76
	s_nop 0
	global_load_lds_dwordx4 v[210:211], off
	s_barrier
	s_waitcnt lgkmcnt(0)
	s_setprio 0
	s_waitcnt lgkmcnt(0)
	v_mfma_f32_16x16x32_bf16 v[60:63], v[186:189], v[144:147], v[60:63]
	v_mfma_f32_16x16x32_bf16 v[28:31], v[194:197], v[144:147], v[28:31]
	v_mfma_f32_16x16x32_bf16 v[56:59], v[186:189], v[152:155], v[56:59]
	v_mfma_f32_16x16x32_bf16 v[24:27], v[194:197], v[152:155], v[24:27]
	v_mfma_f32_16x16x32_bf16 v[52:55], v[186:189], v[160:163], v[52:55]
	v_mfma_f32_16x16x32_bf16 v[20:23], v[194:197], v[160:163], v[20:23]
	v_mfma_f32_16x16x32_bf16 v[48:51], v[186:189], v[178:181], v[48:51]
	v_mfma_f32_16x16x32_bf16 v[16:19], v[194:197], v[178:181], v[16:19]
	v_mfma_f32_16x16x32_bf16 v[60:63], v[190:193], v[148:151], v[60:63]
	v_mfma_f32_16x16x32_bf16 v[28:31], v[202:205], v[148:151], v[28:31]
	v_mfma_f32_16x16x32_bf16 v[56:59], v[190:193], v[156:159], v[56:59]
	v_mfma_f32_16x16x32_bf16 v[24:27], v[202:205], v[156:159], v[24:27]
	v_mfma_f32_16x16x32_bf16 v[52:55], v[190:193], v[174:177], v[52:55]
	v_mfma_f32_16x16x32_bf16 v[20:23], v[202:205], v[174:177], v[20:23]
	v_mfma_f32_16x16x32_bf16 v[48:51], v[190:193], v[182:185], v[48:51]
	v_mfma_f32_16x16x32_bf16 v[16:19], v[202:205], v[182:185], v[16:19]
	s_setprio 1
	s_mov_b32 m0, s23
	v_lshl_add_u64 v[212:213], s[12:13], 0, v[164:165]
	s_barrier
	ds_read_b128 v[144:147], v200 offset:16384
	ds_read_b128 v[148:151], v200 offset:17408
	ds_read_b128 v[152:155], v200 offset:18432
	ds_read_b128 v[156:159], v200 offset:19456
	ds_read_b128 v[160:163], v200 offset:20480
	ds_read_b128 v[174:177], v200 offset:21504
	ds_read_b128 v[178:181], v200 offset:22528
	ds_read_b128 v[182:185], v200 offset:23552
	global_load_lds_dwordx4 v[212:213], off
	v_lshl_add_u64 v[214:215], s[12:13], 0, v[166:167]
	s_mov_b32 m0, s35
	s_nop 0
	global_load_lds_dwordx4 v[214:215], off
	s_barrier
	s_waitcnt lgkmcnt(0)
	s_setprio 0
	s_waitcnt lgkmcnt(0)
	v_mfma_f32_16x16x32_bf16 v[108:111], v[128:131], v[144:147], v[108:111]
	v_mfma_f32_16x16x32_bf16 v[76:79], v[136:139], v[144:147], v[76:79]
	v_mfma_f32_16x16x32_bf16 v[104:107], v[128:131], v[152:155], v[104:107]
	v_mfma_f32_16x16x32_bf16 v[72:75], v[136:139], v[152:155], v[72:75]
	v_mfma_f32_16x16x32_bf16 v[100:103], v[128:131], v[160:163], v[100:103]
	v_mfma_f32_16x16x32_bf16 v[68:71], v[136:139], v[160:163], v[68:71]
	v_mfma_f32_16x16x32_bf16 v[96:99], v[128:131], v[178:181], v[96:99]
	v_mfma_f32_16x16x32_bf16 v[64:67], v[136:139], v[178:181], v[64:67]
	v_mfma_f32_16x16x32_bf16 v[108:111], v[132:135], v[148:151], v[108:111]
	v_mfma_f32_16x16x32_bf16 v[76:79], v[140:143], v[148:151], v[76:79]
	v_mfma_f32_16x16x32_bf16 v[104:107], v[132:135], v[156:159], v[104:107]
	v_mfma_f32_16x16x32_bf16 v[72:75], v[140:143], v[156:159], v[72:75]
	v_mfma_f32_16x16x32_bf16 v[100:103], v[132:135], v[174:177], v[100:103]
	v_mfma_f32_16x16x32_bf16 v[68:71], v[140:143], v[174:177], v[68:71]
	v_mfma_f32_16x16x32_bf16 v[96:99], v[132:135], v[182:185], v[96:99]
	v_mfma_f32_16x16x32_bf16 v[64:67], v[140:143], v[182:185], v[64:67]
	s_setprio 1
	s_barrier
; #define WAIT_V(n) asm volatile("s_waitcnt vmcnt(" #n ")" ::: "memory")
; #define WAIT_L(n) asm volatile("s_waitcnt lgkmcnt(" #n ")" ::: "memory")
; #define BAR __builtin_amdgcn_s_barrier()
; #define SCHED __builtin_amdgcn_sched_barrier(0)
; template <class Get, class Epi>
; DI void gemm_stream(LAS unsigned char* lds, const int K, const int ld, Get get, Epi epi) {
;     ...
;             STAGE(SBo(0, 1), b2 + hstep);
;             WAIT_V(6); BAR; MMA(1, 1, At, B1); BAR;
;             LDB(B0, 1, 0); SCHED; LDA(At, 1, 0); STAGE(SAo(0, 1), a2 + hstep);
;             WAIT_L(8); BAR; WAIT_L(0); MMA(0, 0, At, B0); BAR; SCHED;
;             LDB(B1, 1, 1); STAGE(SBo(1, 0), b3);
;             BAR; WAIT_L(0); MMA(0, 1, At, B1); BAR;
;             LDA(At, 1, 1); STAGE(SAo(1, 0), a3);
;             BAR; WAIT_L(0); MMA(1, 0, At, B0); BAR; SCHED;
	s_add_u32 s6, s10, 0x160000
	s_addc_u32 s7, s11, 0
	s_mov_b32 m0, s77
	v_lshl_add_u64 v[128:129], s[6:7], 0, v[164:165]
	global_load_lds_dwordx4 v[128:129], off
	v_lshl_add_u64 v[128:129], s[6:7], 0, v[166:167]
	s_mov_b32 m0, s78
	s_nop 0
	global_load_lds_dwordx4 v[128:129], off
	s_waitcnt vmcnt(6)
	s_barrier
	s_setprio 0
	v_mfma_f32_16x16x32_bf16 v[44:47], v[186:189], v[144:147], v[44:47]
	v_mfma_f32_16x16x32_bf16 v[12:15], v[194:197], v[144:147], v[12:15]
	v_mfma_f32_16x16x32_bf16 v[40:43], v[186:189], v[152:155], v[40:43]
	v_mfma_f32_16x16x32_bf16 v[8:11], v[194:197], v[152:155], v[8:11]
	v_mfma_f32_16x16x32_bf16 v[36:39], v[186:189], v[160:163], v[36:39]
	v_mfma_f32_16x16x32_bf16 v[4:7], v[194:197], v[160:163], v[4:7]
	v_mfma_f32_16x16x32_bf16 v[32:35], v[186:189], v[178:181], v[32:35]
	v_mfma_f32_16x16x32_bf16 v[0:3], v[194:197], v[178:181], v[0:3]
	v_mfma_f32_16x16x32_bf16 v[44:47], v[190:193], v[148:151], v[44:47]
	v_mfma_f32_16x16x32_bf16 v[12:15], v[202:205], v[148:151], v[12:15]
	v_mfma_f32_16x16x32_bf16 v[40:43], v[190:193], v[156:159], v[40:43]
	v_mfma_f32_16x16x32_bf16 v[8:11], v[202:205], v[156:159], v[8:11]
	v_mfma_f32_16x16x32_bf16 v[36:39], v[190:193], v[174:177], v[36:39]
	v_mfma_f32_16x16x32_bf16 v[4:7], v[202:205], v[174:177], v[4:7]
	v_mfma_f32_16x16x32_bf16 v[32:35], v[190:193], v[182:185], v[32:35]
	v_mfma_f32_16x16x32_bf16 v[0:3], v[202:205], v[182:185], v[0:3]
	s_setprio 1
	s_add_i32 s17, 16, 0x18000
	v_add_u32_e32 v140, s17, v198
	s_barrier
	ds_read_b128 v[128:131], v140
	ds_read_b128 v[132:135], v140 offset:1024
	ds_read_b128 v[136:139], v140 offset:2048
	ds_read_b128 v[140:143], v140 offset:3072
	s_add_u32 s6, s12, 0x160000
	s_addc_u32 s7, s13, 0
	s_mov_b32 m0, s54
	v_lshl_add_u64 v[186:187], s[6:7], 0, v[164:165]
	ds_read_b128 v[144:147], v200 offset:32768
	ds_read_b128 v[148:151], v200 offset:33792
	ds_read_b128 v[152:155], v200 offset:34816
	ds_read_b128 v[156:159], v200 offset:35840
	ds_read_b128 v[160:163], v200 offset:36864
	ds_read_b128 v[174:177], v200 offset:37888
	ds_read_b128 v[178:181], v200 offset:38912
	ds_read_b128 v[182:185], v200 offset:39936
	global_load_lds_dwordx4 v[186:187], off
	v_lshl_add_u64 v[186:187], s[6:7], 0, v[166:167]
	s_mov_b32 m0, s55
	s_nop 0
	global_load_lds_dwordx4 v[186:187], off
	s_waitcnt lgkmcnt(8)
	s_barrier
	s_waitcnt lgkmcnt(0)
	s_setprio 0
	s_waitcnt lgkmcnt(0)
	v_mfma_f32_16x16x32_bf16 v[124:127], v[128:131], v[144:147], v[124:127]
	v_mfma_f32_16x16x32_bf16 v[92:95], v[136:139], v[144:147], v[92:95]
	v_mfma_f32_16x16x32_bf16 v[120:123], v[128:131], v[152:155], v[120:123]
	v_mfma_f32_16x16x32_bf16 v[88:91], v[136:139], v[152:155], v[88:91]
	v_mfma_f32_16x16x32_bf16 v[116:119], v[128:131], v[160:163], v[116:119]
	v_mfma_f32_16x16x32_bf16 v[84:87], v[136:139], v[160:163], v[84:87]
	v_mfma_f32_16x16x32_bf16 v[112:115], v[128:131], v[178:181], v[112:115]
	v_mfma_f32_16x16x32_bf16 v[80:83], v[136:139], v[178:181], v[80:83]
	v_mfma_f32_16x16x32_bf16 v[124:127], v[132:135], v[148:151], v[124:127]
	v_mfma_f32_16x16x32_bf16 v[92:95], v[140:143], v[148:151], v[92:95]
	v_mfma_f32_16x16x32_bf16 v[120:123], v[132:135], v[156:159], v[120:123]
	v_mfma_f32_16x16x32_bf16 v[88:91], v[140:143], v[156:159], v[88:91]
	v_mfma_f32_16x16x32_bf16 v[116:119], v[132:135], v[174:177], v[116:119]
	v_mfma_f32_16x16x32_bf16 v[84:87], v[140:143], v[174:177], v[84:87]
	v_mfma_f32_16x16x32_bf16 v[112:115], v[132:135], v[182:185], v[112:115]
	v_mfma_f32_16x16x32_bf16 v[80:83], v[140:143], v[182:185], v[80:83]
	s_setprio 1
	s_barrier
	s_add_i32 s12, 16, 0x1c000
	s_add_i32 s6, s17, s21
	v_add_u32_e32 v202, s12, v198
	v_lshl_add_u64 v[208:209], v[208:209], 0, s[0:1]
	s_mov_b32 m0, s6
	ds_read_b128 v[186:189], v202
	ds_read_b128 v[190:193], v202 offset:1024
	ds_read_b128 v[194:197], v202 offset:2048
	ds_read_b128 v[202:205], v202 offset:3072
	global_load_lds_dwordx4 v[208:209], off
	v_lshl_add_u64 v[208:209], v[210:211], 0, s[0:1]
	s_add_i32 m0, s6, 0x2000
	s_nop 0
	global_load_lds_dwordx4 v[208:209], off
	s_barrier
	s_waitcnt lgkmcnt(0)
	s_setprio 0
	s_waitcnt lgkmcnt(0)
	v_mfma_f32_16x16x32_bf16 v[60:63], v[186:189], v[144:147], v[60:63]
	v_mfma_f32_16x16x32_bf16 v[28:31], v[194:197], v[144:147], v[28:31]
	v_mfma_f32_16x16x32_bf16 v[56:59], v[186:189], v[152:155], v[56:59]
	v_mfma_f32_16x16x32_bf16 v[24:27], v[194:197], v[152:155], v[24:27]
	v_mfma_f32_16x16x32_bf16 v[52:55], v[186:189], v[160:163], v[52:55]
	v_mfma_f32_16x16x32_bf16 v[20:23], v[194:197], v[160:163], v[20:23]
	v_mfma_f32_16x16x32_bf16 v[48:51], v[186:189], v[178:181], v[48:51]
	v_mfma_f32_16x16x32_bf16 v[16:19], v[194:197], v[178:181], v[16:19]
	v_mfma_f32_16x16x32_bf16 v[60:63], v[190:193], v[148:151], v[60:63]
	v_mfma_f32_16x16x32_bf16 v[28:31], v[202:205], v[148:151], v[28:31]
	v_mfma_f32_16x16x32_bf16 v[56:59], v[190:193], v[156:159], v[56:59]
	v_mfma_f32_16x16x32_bf16 v[24:27], v[202:205], v[156:159], v[24:27]
	v_mfma_f32_16x16x32_bf16 v[52:55], v[190:193], v[174:177], v[52:55]
	v_mfma_f32_16x16x32_bf16 v[20:23], v[202:205], v[174:177], v[20:23]
	v_mfma_f32_16x16x32_bf16 v[48:51], v[190:193], v[182:185], v[48:51]
	v_mfma_f32_16x16x32_bf16 v[16:19], v[202:205], v[182:185], v[16:19]
	s_setprio 1
	s_mov_b32 m0, s56
	v_lshl_add_u64 v[208:209], v[212:213], 0, s[0:1]
	s_barrier
	ds_read_b128 v[144:147], v200 offset:49152
	ds_read_b128 v[148:151], v200 offset:50176
	ds_read_b128 v[152:155], v200 offset:51200
	ds_read_b128 v[156:159], v200 offset:52224
	ds_read_b128 v[160:163], v200 offset:53248
	ds_read_b128 v[174:177], v200 offset:54272
	ds_read_b128 v[178:181], v200 offset:55296
	ds_read_b128 v[182:185], v200 offset:56320
	global_load_lds_dwordx4 v[208:209], off
	v_lshl_add_u64 v[208:209], v[214:215], 0, s[0:1]
	s_mov_b32 m0, s57
	s_nop 0
	global_load_lds_dwordx4 v[208:209], off
	s_barrier
; #define WAIT_V(n) asm volatile("s_waitcnt vmcnt(" #n ")" ::: "memory")
; #define WAIT_L(n) asm volatile("s_waitcnt lgkmcnt(" #n ")" ::: "memory")
; #define BAR __builtin_amdgcn_s_barrier()
; #define SCHED __builtin_amdgcn_sched_barrier(0)
; template <class Get, class Epi>
; DI void gemm_stream(LAS unsigned char* lds, const int K, const int ld, Get get, Epi epi) {
;     ...
;             BAR; WAIT_L(0); MMA(1, 0, At, B0); BAR; SCHED;
;             STAGE(SBo(1, 1), b3 + hstep);
;             WAIT_V(6); BAR; MMA(1, 1, At, B1); BAR;
;         }
; DI void epi_resid(const Acc& acc, const P& p, int brow, int bcol, int layer, int gch, bool from_input) {
;     EPI_IDX
;     const float* gate = modv(p, layer, brow, gch);
; #pragma unroll
;     for (int bj = 0; bj < 2; ++bj)
; #pragma unroll
;         for (int n = 0; n < 2; ++n) {
;             const int c0 = bcol + bj * 128 + wc * 32 + n * 16 + fq * 4;
;             const f32x4 g = *(const f32x4*)(gate + c0);
	s_waitcnt lgkmcnt(0)
	s_setprio 0
	s_waitcnt lgkmcnt(0)
	v_mfma_f32_16x16x32_bf16 v[108:111], v[128:131], v[144:147], v[108:111]
	v_mfma_f32_16x16x32_bf16 v[76:79], v[136:139], v[144:147], v[76:79]
	v_mfma_f32_16x16x32_bf16 v[104:107], v[128:131], v[152:155], v[104:107]
	v_mfma_f32_16x16x32_bf16 v[72:75], v[136:139], v[152:155], v[72:75]
	v_mfma_f32_16x16x32_bf16 v[100:103], v[128:131], v[160:163], v[100:103]
	v_mfma_f32_16x16x32_bf16 v[68:71], v[136:139], v[160:163], v[68:71]
	v_mfma_f32_16x16x32_bf16 v[96:99], v[128:131], v[178:181], v[96:99]
	v_mfma_f32_16x16x32_bf16 v[64:67], v[136:139], v[178:181], v[64:67]
	v_mfma_f32_16x16x32_bf16 v[108:111], v[132:135], v[148:151], v[108:111]
	v_mfma_f32_16x16x32_bf16 v[76:79], v[140:143], v[148:151], v[76:79]
	v_mfma_f32_16x16x32_bf16 v[104:107], v[132:135], v[156:159], v[104:107]
	v_mfma_f32_16x16x32_bf16 v[72:75], v[140:143], v[156:159], v[72:75]
	v_mfma_f32_16x16x32_bf16 v[100:103], v[132:135], v[174:177], v[100:103]
	v_mfma_f32_16x16x32_bf16 v[68:71], v[140:143], v[174:177], v[68:71]
	v_mfma_f32_16x16x32_bf16 v[96:99], v[132:135], v[182:185], v[96:99]
	v_mfma_f32_16x16x32_bf16 v[64:67], v[140:143], v[182:185], v[64:67]
	s_setprio 1
	s_barrier
	s_add_u32 s6, s10, 0x160080
	s_addc_u32 s7, s11, 0
	s_add_i32 s10, s12, s21
	v_lshl_add_u64 v[128:129], s[6:7], 0, v[164:165]
	s_mov_b32 m0, s10
	s_nop 0
	global_load_lds_dwordx4 v[128:129], off
	v_lshl_add_u64 v[128:129], s[6:7], 0, v[166:167]
	s_add_i32 m0, s10, 0x2000
	s_nop 0
	global_load_lds_dwordx4 v[128:129], off
	s_waitcnt vmcnt(6)
	s_barrier
	s_setprio 0
	v_mfma_f32_16x16x32_bf16 v[44:47], v[186:189], v[144:147], v[44:47]
	v_mfma_f32_16x16x32_bf16 v[12:15], v[194:197], v[144:147], v[12:15]
	v_mfma_f32_16x16x32_bf16 v[40:43], v[186:189], v[152:155], v[40:43]
	v_mfma_f32_16x16x32_bf16 v[8:11], v[194:197], v[152:155], v[8:11]
	v_mfma_f32_16x16x32_bf16 v[36:39], v[186:189], v[160:163], v[36:39]
	v_mfma_f32_16x16x32_bf16 v[4:7], v[194:197], v[160:163], v[4:7]
	v_mfma_f32_16x16x32_bf16 v[32:35], v[186:189], v[178:181], v[32:35]
	v_mfma_f32_16x16x32_bf16 v[0:3], v[194:197], v[178:181], v[0:3]
	v_mfma_f32_16x16x32_bf16 v[44:47], v[190:193], v[148:151], v[44:47]
	v_mfma_f32_16x16x32_bf16 v[12:15], v[202:205], v[148:151], v[12:15]
	v_mfma_f32_16x16x32_bf16 v[40:43], v[190:193], v[156:159], v[40:43]
	v_mfma_f32_16x16x32_bf16 v[8:11], v[202:205], v[156:159], v[8:11]
	v_mfma_f32_16x16x32_bf16 v[36:39], v[190:193], v[174:177], v[36:39]
	v_mfma_f32_16x16x32_bf16 v[4:7], v[202:205], v[174:177], v[4:7]
	v_mfma_f32_16x16x32_bf16 v[32:35], v[190:193], v[182:185], v[32:35]
	v_mfma_f32_16x16x32_bf16 v[0:3], v[202:205], v[182:185], v[0:3]
	s_setprio 1
	s_add_i32 s16, s16, 2
	s_add_u32 s14, s14, 0x100
	s_addc_u32 s15, s15, 0
	s_cmpk_gt_u32 s16, 0x55
	s_mov_b64 s[6:7], s[8:9]
	s_barrier
	s_cbranch_scc0 .LBB0_1697
	s_lshr_b32 s6, s3, 4
	s_lshl_b32 s3, s3, 8
	s_mulk_i32 s6, 0x1100
	s_and_b32 s3, s3, 0xf00
	s_add_i32 s3, s6, s3
	s_add_i32 s6, s3, 0x100
	s_lshl_b32 s7, s2, 8
	s_mul_hi_i32 s2, s6, 0x78787879
	s_lshr_b32 s3, s2, 31
	s_ashr_i32 s2, s2, 11
	s_add_i32 s2, s2, s3
	s_mul_i32 s3, s2, 0xffffef00
	s_mul_i32 s2, s2, 6
	s_add_i32 s3, s3, s6
	s_add_i32 s2, s2, 5
	s_cmpk_gt_i32 s3, 0xff
	v_mov_b32_e32 v132, v206
	s_cselect_b32 s2, s2, 29
	s_ashr_i32 s3, s2, 31
	v_lshrrev_b32_e32 v128, 1, v132
	v_lshrrev_b32_e32 v129, 2, v132
	s_lshl_b64 s[2:3], s[2:3], 13
	v_and_b32_e32 v128, 0x60, v128
	v_and_b32_e32 v129, 12, v129
	s_add_u32 s2, s26, s2
	v_or3_b32 v174, v128, s7, v129
	s_addc_u32 s3, s27, s3
	v_ashrrev_i32_e32 v175, 31, v174
	v_lshl_add_u64 v[192:193], v[174:175], 2, s[2:3]
	global_load_dwordx4 v[128:131], v[192:193], off
	v_ashrrev_i32_e32 v133, 2, v132
	v_and_b32_e32 v133, 0xffffffc0, v133
	v_and_or_b32 v132, v132, 15, s6
	v_add_u32_e32 v176, v132, v133
	v_mul_hi_i32 v132, v176, s59
	v_lshrrev_b32_e32 v133, 31, v132
	v_ashrrev_i32_e32 v132, 11, v132
	v_add_u32_e32 v203, v132, v133
	v_mad_i32_i24 v202, v203, s60, v176
	v_lshlrev_b32_e32 v212, 12, v203
	v_cmp_lt_i32_e64 s[18:19], s61, v202
	v_add3_u32 v190, v212, v202, s62
	s_and_saveexec_b64 s[2:3], s[18:19]
	s_xor_b64 s[6:7], exec, s[2:3]
	v_add3_u32 v132, v212, v202, s62
	s_or_saveexec_b64 s[6:7], s[6:7]
	v_mov_b64_e32 v[134:135], s[24:25]
	v_lshl_add_u32 v191, v203, 8, v202
	s_xor_b64 exec, exec, s[6:7]
	v_lshl_add_u32 v132, v203, 8, v202
	v_mov_b64_e32 v[134:135], s[36:37]
	s_or_b64 exec, exec, s[6:7]
	v_ashrrev_i32_e32 v133, 31, v132
	v_lshlrev_b64 v[132:133], 13, v[132:133]
	v_lshl_add_u64 v[132:133], v[134:135], 0, v[132:133]
	v_lshl_add_u64 v[132:133], v[174:175], 2, v[132:133]
	global_load_dwordx4 v[160:163], v[132:133], off
	v_or_b32_e32 v132, 16, v176
	v_mul_hi_i32 v133, v132, s59
	v_lshrrev_b32_e32 v134, 31, v133
	v_ashrrev_i32_e32 v133, 11, v133
	v_add_u32_e32 v205, v133, v134
	v_mad_i32_i24 v204, v205, s60, v132
	v_lshlrev_b32_e32 v217, 12, v205
	v_cmp_lt_i32_e64 s[16:17], s61, v204
	v_add3_u32 v188, v217, v204, s62
	s_and_saveexec_b64 s[2:3], s[16:17]
	s_xor_b64 s[6:7], exec, s[2:3]
	v_add3_u32 v132, v217, v204, s62
	s_or_saveexec_b64 s[6:7], s[6:7]
	v_mov_b64_e32 v[134:135], s[24:25]
	v_lshl_add_u32 v189, v205, 8, v204
	s_xor_b64 exec, exec, s[6:7]
	v_lshl_add_u32 v132, v205, 8, v204
	v_mov_b64_e32 v[134:135], s[36:37]
	s_or_b64 exec, exec, s[6:7]
	v_ashrrev_i32_e32 v133, 31, v132
	v_lshlrev_b64 v[132:133], 13, v[132:133]
	v_lshl_add_u64 v[132:133], v[134:135], 0, v[132:133]
	v_lshl_add_u64 v[132:133], v[174:175], 2, v[132:133]
	global_load_dwordx4 v[156:159], v[132:133], off
	v_or_b32_e32 v132, 32, v176
	v_mul_hi_i32 v133, v132, s59
	v_lshrrev_b32_e32 v134, 31, v133
	v_ashrrev_i32_e32 v133, 11, v133
; DI void epi_resid(const Acc& acc, const P& p, int brow, int bcol, int layer, int gch, bool from_input) {
;     ...
;             const int c0 = bcol + bj * 128 + wc * 32 + n * 16 + fq * 4;
;             const f32x4 g = *(const f32x4*)(gate + c0);
;             f32x4 xv[2][4];
; #pragma unroll
;             for (int ai = 0; ai < 2; ++ai)
; #pragma unroll
;                 for (int m = 0; m < 4; ++m) {
;                     const int r = brow + ai * 128 + wr * 64 + m * 16 + fr;
;                     const float* sp = (from_input ? inrow(p, r) : xrow(p, r)) + c0;
;                     xv[ai][m] = *(const f32x4*)sp;
;                 }
	v_add_u32_e32 v209, v133, v134
	v_mad_i32_i24 v208, v209, s60, v132
	v_lshlrev_b32_e32 v220, 12, v209
	v_cmp_lt_i32_e64 s[14:15], s61, v208
	v_add3_u32 v186, v220, v208, s62
	s_and_saveexec_b64 s[2:3], s[14:15]
	s_xor_b64 s[6:7], exec, s[2:3]
	v_add3_u32 v132, v220, v208, s62
	s_or_saveexec_b64 s[6:7], s[6:7]
	v_mov_b64_e32 v[134:135], s[24:25]
	v_lshl_add_u32 v187, v209, 8, v208
	s_xor_b64 exec, exec, s[6:7]
	v_lshl_add_u32 v132, v209, 8, v208
	v_mov_b64_e32 v[134:135], s[36:37]
	s_or_b64 exec, exec, s[6:7]
	v_ashrrev_i32_e32 v133, 31, v132
	v_lshlrev_b64 v[132:133], 13, v[132:133]
	v_lshl_add_u64 v[132:133], v[134:135], 0, v[132:133]
	v_lshl_add_u64 v[132:133], v[174:175], 2, v[132:133]
	global_load_dwordx4 v[152:155], v[132:133], off
	v_or_b32_e32 v132, 48, v176
	v_mul_hi_i32 v133, v132, s59
	v_lshrrev_b32_e32 v134, 31, v133
	v_ashrrev_i32_e32 v133, 11, v133
	v_add_u32_e32 v211, v133, v134
	v_mad_i32_i24 v210, v211, s60, v132
	v_lshlrev_b32_e32 v223, 12, v211
	v_cmp_lt_i32_e64 s[12:13], s61, v210
	v_add3_u32 v184, v223, v210, s62
	s_and_saveexec_b64 s[2:3], s[12:13]
	s_xor_b64 s[6:7], exec, s[2:3]
	v_add3_u32 v132, v223, v210, s62
	s_or_saveexec_b64 s[6:7], s[6:7]
	v_mov_b64_e32 v[134:135], s[24:25]
	v_lshl_add_u32 v185, v211, 8, v210
	s_xor_b64 exec, exec, s[6:7]
	v_lshl_add_u32 v132, v211, 8, v210
	v_mov_b64_e32 v[134:135], s[36:37]
	s_or_b64 exec, exec, s[6:7]
	v_ashrrev_i32_e32 v133, 31, v132
	v_lshlrev_b64 v[132:133], 13, v[132:133]
	v_lshl_add_u64 v[132:133], v[134:135], 0, v[132:133]
	v_lshl_add_u64 v[132:133], v[174:175], 2, v[132:133]
	global_load_dwordx4 v[148:151], v[132:133], off
	v_add_u32_e32 v132, 0x80, v176
	v_mul_hi_i32 v133, v132, s59
	v_lshrrev_b32_e32 v134, 31, v133
	v_ashrrev_i32_e32 v133, 11, v133
	v_add_u32_e32 v214, v133, v134
	v_mad_i32_i24 v213, v214, s60, v132
	v_lshlrev_b32_e32 v224, 12, v214
	v_cmp_lt_i32_e64 s[10:11], s61, v213
	v_add3_u32 v182, v224, v213, s62
	s_and_saveexec_b64 s[2:3], s[10:11]
	s_xor_b64 s[6:7], exec, s[2:3]
	v_add3_u32 v132, v224, v213, s62
	s_or_saveexec_b64 s[6:7], s[6:7]
	v_mov_b64_e32 v[134:135], s[24:25]
	v_lshl_add_u32 v183, v214, 8, v213
	s_xor_b64 exec, exec, s[6:7]
	v_lshl_add_u32 v132, v214, 8, v213
	v_mov_b64_e32 v[134:135], s[36:37]
	s_or_b64 exec, exec, s[6:7]
	v_ashrrev_i32_e32 v133, 31, v132
	v_lshlrev_b64 v[132:133], 13, v[132:133]
	v_lshl_add_u64 v[132:133], v[134:135], 0, v[132:133]
	v_lshl_add_u64 v[132:133], v[174:175], 2, v[132:133]
	global_load_dwordx4 v[144:147], v[132:133], off
	v_add_u32_e32 v132, 0x90, v176
	v_mul_hi_i32 v133, v132, s59
	v_lshrrev_b32_e32 v134, 31, v133
	v_ashrrev_i32_e32 v133, 11, v133
	v_add_u32_e32 v216, v133, v134
	v_mad_i32_i24 v215, v216, s60, v132
	v_lshlrev_b32_e32 v225, 12, v216
	v_cmp_lt_i32_e64 s[8:9], s61, v215
	v_add3_u32 v180, v225, v215, s62
	s_and_saveexec_b64 s[2:3], s[8:9]
	s_xor_b64 s[6:7], exec, s[2:3]
	v_add3_u32 v132, v225, v215, s62
	s_or_saveexec_b64 s[6:7], s[6:7]
	v_mov_b64_e32 v[134:135], s[24:25]
	v_lshl_add_u32 v181, v216, 8, v215
	s_xor_b64 exec, exec, s[6:7]
	v_lshl_add_u32 v132, v216, 8, v215
	v_mov_b64_e32 v[134:135], s[36:37]
	s_or_b64 exec, exec, s[6:7]
	v_ashrrev_i32_e32 v133, 31, v132
	v_lshlrev_b64 v[132:133], 13, v[132:133]
	v_lshl_add_u64 v[132:133], v[134:135], 0, v[132:133]
	v_lshl_add_u64 v[132:133], v[174:175], 2, v[132:133]
	global_load_dwordx4 v[140:143], v[132:133], off
	v_add_u32_e32 v132, 0xa0, v176
	v_mul_hi_i32 v133, v132, s59
	v_lshrrev_b32_e32 v134, 31, v133
	v_ashrrev_i32_e32 v133, 11, v133
	v_add_u32_e32 v219, v133, v134
	v_mad_i32_i24 v218, v219, s60, v132
	v_lshlrev_b32_e32 v226, 12, v219
	v_cmp_lt_i32_e64 s[6:7], s61, v218
	v_add3_u32 v178, v226, v218, s62
	s_and_saveexec_b64 s[2:3], s[6:7]
	s_xor_b64 s[52:53], exec, s[2:3]
	v_add3_u32 v132, v226, v218, s62
	s_or_saveexec_b64 s[52:53], s[52:53]
	v_mov_b64_e32 v[134:135], s[24:25]
	v_lshl_add_u32 v179, v219, 8, v218
	s_xor_b64 exec, exec, s[52:53]
	v_lshl_add_u32 v132, v219, 8, v218
	v_mov_b64_e32 v[134:135], s[36:37]
	s_or_b64 exec, exec, s[52:53]
	v_ashrrev_i32_e32 v133, 31, v132
	v_lshlrev_b64 v[132:133], 13, v[132:133]
	v_lshl_add_u64 v[132:133], v[134:135], 0, v[132:133]
	v_lshl_add_u64 v[132:133], v[174:175], 2, v[132:133]
	global_load_dwordx4 v[136:139], v[132:133], off
	v_add_u32_e32 v132, 0xb0, v176
	v_mul_hi_i32 v133, v132, s59
	v_lshrrev_b32_e32 v134, 31, v133
	v_ashrrev_i32_e32 v133, 11, v133
	v_add_u32_e32 v222, v133, v134
	v_mad_i32_i24 v221, v222, s60, v132
	v_lshlrev_b32_e32 v227, 12, v222
	v_cmp_lt_i32_e32 vcc, s61, v221
	v_add3_u32 v176, v227, v221, s62
	s_and_saveexec_b64 s[2:3], vcc
	s_xor_b64 s[52:53], exec, s[2:3]
	v_add3_u32 v132, v227, v221, s62
	s_or_saveexec_b64 s[52:53], s[52:53]
	v_mov_b64_e32 v[134:135], s[24:25]
	v_lshl_add_u32 v177, v222, 8, v221
	s_xor_b64 exec, exec, s[52:53]
	v_lshl_add_u32 v132, v222, 8, v221
	v_mov_b64_e32 v[134:135], s[36:37]
	s_or_b64 exec, exec, s[52:53]
	v_ashrrev_i32_e32 v133, 31, v132
	v_lshlrev_b64 v[132:133], 13, v[132:133]
	v_lshl_add_u64 v[132:133], v[134:135], 0, v[132:133]
	v_lshl_add_u64 v[132:133], v[174:175], 2, v[132:133]
	global_load_dwordx4 v[132:135], v[132:133], off
	s_and_saveexec_b64 s[2:3], s[18:19]
	s_xor_b64 s[52:53], exec, s[2:3]
	v_add3_u32 v194, v212, v202, s62
	s_or_saveexec_b64 s[52:53], s[52:53]
	v_mov_b64_e32 v[196:197], s[24:25]
	s_xor_b64 exec, exec, s[52:53]
	v_lshl_add_u32 v194, v203, 8, v202
	v_mov_b64_e32 v[196:197], s[36:37]
	s_or_b64 exec, exec, s[52:53]
	v_ashrrev_i32_e32 v195, 31, v194
	s_waitcnt vmcnt(0)
; DI void epi_resid(const Acc& acc, const P& p, int brow, int bcol, int layer, int gch, bool from_input) {
;     ...
;             __builtin_amdgcn_sched_barrier(0);
; #pragma unroll
;             for (int ai = 0; ai < 2; ++ai)
; #pragma unroll
;                 for (int m = 0; m < 4; ++m) {
;                     const int r = brow + ai * 128 + wr * 64 + m * 16 + fr;
;                     *(f32x4*)(xrow(p, r) + c0) = xv[ai][m] + g * acc[ai][bj][m][n];
;                 }
;             __builtin_amdgcn_sched_barrier(0);
;         }
	v_pk_fma_f32 v[124:125], v[124:125], v[128:129], v[160:161]
	v_lshlrev_b64 v[160:161], 13, v[194:195]
	v_lshl_add_u64 v[160:161], v[196:197], 0, v[160:161]
	v_pk_fma_f32 v[126:127], v[126:127], v[130:131], v[162:163]
	v_lshl_add_u64 v[160:161], v[174:175], 2, v[160:161]
	global_store_dwordx4 v[160:161], v[124:127], off
	s_and_saveexec_b64 s[2:3], s[16:17]
	s_xor_b64 s[52:53], exec, s[2:3]
	v_add3_u32 v124, v217, v204, s62
	s_or_saveexec_b64 s[52:53], s[52:53]
	v_mov_b64_e32 v[126:127], s[24:25]
	s_xor_b64 exec, exec, s[52:53]
	v_lshl_add_u32 v124, v205, 8, v204
	v_mov_b64_e32 v[126:127], s[36:37]
	s_or_b64 exec, exec, s[52:53]
	v_ashrrev_i32_e32 v125, 31, v124
	v_lshlrev_b64 v[124:125], 13, v[124:125]
	v_lshl_add_u64 v[124:125], v[126:127], 0, v[124:125]
	v_pk_fma_f32 v[122:123], v[122:123], v[130:131], v[158:159]
	v_pk_fma_f32 v[120:121], v[120:121], v[128:129], v[156:157]
	v_lshl_add_u64 v[124:125], v[174:175], 2, v[124:125]
	global_store_dwordx4 v[124:125], v[120:123], off
	s_and_saveexec_b64 s[2:3], s[14:15]
	s_xor_b64 s[52:53], exec, s[2:3]
	v_add3_u32 v120, v220, v208, s62
	s_or_saveexec_b64 s[52:53], s[52:53]
	v_mov_b64_e32 v[122:123], s[24:25]
	s_xor_b64 exec, exec, s[52:53]
	v_lshl_add_u32 v120, v209, 8, v208
	v_mov_b64_e32 v[122:123], s[36:37]
	s_or_b64 exec, exec, s[52:53]
	v_ashrrev_i32_e32 v121, 31, v120
	v_lshlrev_b64 v[120:121], 13, v[120:121]
	v_lshl_add_u64 v[120:121], v[122:123], 0, v[120:121]
	v_pk_fma_f32 v[118:119], v[118:119], v[130:131], v[154:155]
	v_pk_fma_f32 v[116:117], v[116:117], v[128:129], v[152:153]
	v_lshl_add_u64 v[120:121], v[174:175], 2, v[120:121]
	global_store_dwordx4 v[120:121], v[116:119], off
	s_and_saveexec_b64 s[2:3], s[12:13]
	s_xor_b64 s[52:53], exec, s[2:3]
	v_add3_u32 v116, v223, v210, s62
	s_or_saveexec_b64 s[52:53], s[52:53]
	v_mov_b64_e32 v[118:119], s[24:25]
	s_xor_b64 exec, exec, s[52:53]
	v_lshl_add_u32 v116, v211, 8, v210
	v_mov_b64_e32 v[118:119], s[36:37]
	s_or_b64 exec, exec, s[52:53]
	v_ashrrev_i32_e32 v117, 31, v116
	v_lshlrev_b64 v[116:117], 13, v[116:117]
	v_lshl_add_u64 v[116:117], v[118:119], 0, v[116:117]
	v_pk_fma_f32 v[114:115], v[114:115], v[130:131], v[150:151]
	v_pk_fma_f32 v[112:113], v[112:113], v[128:129], v[148:149]
	v_lshl_add_u64 v[116:117], v[174:175], 2, v[116:117]
	global_store_dwordx4 v[116:117], v[112:115], off
	s_and_saveexec_b64 s[2:3], s[10:11]
	s_xor_b64 s[52:53], exec, s[2:3]
	v_add3_u32 v112, v224, v213, s62
	s_or_saveexec_b64 s[52:53], s[52:53]
	v_mov_b64_e32 v[114:115], s[24:25]
	s_xor_b64 exec, exec, s[52:53]
	v_lshl_add_u32 v112, v214, 8, v213
	v_mov_b64_e32 v[114:115], s[36:37]
	s_or_b64 exec, exec, s[52:53]
	v_ashrrev_i32_e32 v113, 31, v112
	v_lshlrev_b64 v[112:113], 13, v[112:113]
	v_lshl_add_u64 v[112:113], v[114:115], 0, v[112:113]
	v_pk_fma_f32 v[110:111], v[110:111], v[130:131], v[146:147]
	v_pk_fma_f32 v[108:109], v[108:109], v[128:129], v[144:145]
	v_lshl_add_u64 v[112:113], v[174:175], 2, v[112:113]
	global_store_dwordx4 v[112:113], v[108:111], off
	s_and_saveexec_b64 s[2:3], s[8:9]
	s_xor_b64 s[52:53], exec, s[2:3]
	v_add3_u32 v108, v225, v215, s62
	s_or_saveexec_b64 s[52:53], s[52:53]
	v_mov_b64_e32 v[110:111], s[24:25]
	s_xor_b64 exec, exec, s[52:53]
	v_lshl_add_u32 v108, v216, 8, v215
	v_mov_b64_e32 v[110:111], s[36:37]
	s_or_b64 exec, exec, s[52:53]
	v_ashrrev_i32_e32 v109, 31, v108
	v_lshlrev_b64 v[108:109], 13, v[108:109]
	v_lshl_add_u64 v[108:109], v[110:111], 0, v[108:109]
	v_pk_fma_f32 v[106:107], v[106:107], v[130:131], v[142:143]
	v_pk_fma_f32 v[104:105], v[104:105], v[128:129], v[140:141]
	v_lshl_add_u64 v[108:109], v[174:175], 2, v[108:109]
	global_store_dwordx4 v[108:109], v[104:107], off
	s_and_saveexec_b64 s[2:3], s[6:7]
	s_xor_b64 s[52:53], exec, s[2:3]
	v_add3_u32 v104, v226, v218, s62
	s_or_saveexec_b64 s[52:53], s[52:53]
	v_mov_b64_e32 v[106:107], s[24:25]
	s_xor_b64 exec, exec, s[52:53]
	v_lshl_add_u32 v104, v219, 8, v218
	v_mov_b64_e32 v[106:107], s[36:37]
	s_or_b64 exec, exec, s[52:53]
	v_ashrrev_i32_e32 v105, 31, v104
	v_lshlrev_b64 v[104:105], 13, v[104:105]
	v_lshl_add_u64 v[104:105], v[106:107], 0, v[104:105]
	v_pk_fma_f32 v[102:103], v[102:103], v[130:131], v[138:139]
	v_pk_fma_f32 v[100:101], v[100:101], v[128:129], v[136:137]
	v_lshl_add_u64 v[104:105], v[174:175], 2, v[104:105]
	global_store_dwordx4 v[104:105], v[100:103], off
	s_and_saveexec_b64 s[2:3], vcc
	s_xor_b64 s[52:53], exec, s[2:3]
	v_add3_u32 v100, v227, v221, s62
	s_or_saveexec_b64 s[52:53], s[52:53]
	v_mov_b64_e32 v[102:103], s[24:25]
	s_xor_b64 exec, exec, s[52:53]
	v_lshl_add_u32 v100, v222, 8, v221
	v_mov_b64_e32 v[102:103], s[36:37]
	s_or_b64 exec, exec, s[52:53]
	v_ashrrev_i32_e32 v101, 31, v100
	v_lshlrev_b64 v[100:101], 13, v[100:101]
	v_lshl_add_u64 v[100:101], v[102:103], 0, v[100:101]
	v_pk_fma_f32 v[98:99], v[98:99], v[130:131], v[134:135]
	v_pk_fma_f32 v[96:97], v[96:97], v[128:129], v[132:133]
	v_lshl_add_u64 v[100:101], v[174:175], 2, v[100:101]
	global_store_dwordx4 v[100:101], v[96:99], off
	global_load_dwordx4 v[96:99], v[192:193], off offset:64
	s_and_saveexec_b64 s[2:3], s[18:19]
	s_xor_b64 s[52:53], exec, s[2:3]
	v_add3_u32 v100, v212, v202, s62
	s_or_saveexec_b64 s[52:53], s[52:53]
	v_mov_b64_e32 v[102:103], s[24:25]
	s_xor_b64 exec, exec, s[52:53]
	v_lshl_add_u32 v100, v203, 8, v202
	v_mov_b64_e32 v[102:103], s[36:37]
	s_or_b64 exec, exec, s[52:53]
	v_ashrrev_i32_e32 v101, 31, v100
	v_lshlrev_b64 v[100:101], 13, v[100:101]
	v_lshl_add_u64 v[100:101], v[102:103], 0, v[100:101]
	v_lshl_add_u64 v[100:101], v[174:175], 2, v[100:101]
	global_load_dwordx4 v[128:131], v[100:101], off offset:64
	s_and_saveexec_b64 s[2:3], s[16:17]
; DI void epi_resid(const Acc& acc, const P& p, int brow, int bcol, int layer, int gch, bool from_input) {
;     ...
; #pragma unroll
;             for (int ai = 0; ai < 2; ++ai)
; #pragma unroll
;                 for (int m = 0; m < 4; ++m) {
;                     const int r = brow + ai * 128 + wr * 64 + m * 16 + fr;
;                     const float* sp = (from_input ? inrow(p, r) : xrow(p, r)) + c0;
;                     xv[ai][m] = *(const f32x4*)sp;
;                 }
;             __builtin_amdgcn_sched_barrier(0);
; #pragma unroll
;             for (int ai = 0; ai < 2; ++ai)
; #pragma unroll
;                 for (int m = 0; m < 4; ++m) {
;                     const int r = brow + ai * 128 + wr * 64 + m * 16 + fr;
;                     *(f32x4*)(xrow(p, r) + c0) = xv[ai][m] + g * acc[ai][bj][m][n];
;                 }
	s_xor_b64 s[52:53], exec, s[2:3]
	v_add3_u32 v100, v217, v204, s62
	s_or_saveexec_b64 s[52:53], s[52:53]
	v_mov_b64_e32 v[102:103], s[24:25]
	s_xor_b64 exec, exec, s[52:53]
	v_lshl_add_u32 v100, v205, 8, v204
	v_mov_b64_e32 v[102:103], s[36:37]
	s_or_b64 exec, exec, s[52:53]
	v_ashrrev_i32_e32 v101, 31, v100
	v_lshlrev_b64 v[100:101], 13, v[100:101]
	v_lshl_add_u64 v[100:101], v[102:103], 0, v[100:101]
	v_lshl_add_u64 v[100:101], v[174:175], 2, v[100:101]
	global_load_dwordx4 v[124:127], v[100:101], off offset:64
	s_and_saveexec_b64 s[2:3], s[14:15]
	s_xor_b64 s[52:53], exec, s[2:3]
	v_add3_u32 v100, v220, v208, s62
	s_or_saveexec_b64 s[52:53], s[52:53]
	v_mov_b64_e32 v[102:103], s[24:25]
	s_xor_b64 exec, exec, s[52:53]
	v_lshl_add_u32 v100, v209, 8, v208
	v_mov_b64_e32 v[102:103], s[36:37]
	s_or_b64 exec, exec, s[52:53]
	v_ashrrev_i32_e32 v101, 31, v100
	v_lshlrev_b64 v[100:101], 13, v[100:101]
	v_lshl_add_u64 v[100:101], v[102:103], 0, v[100:101]
	v_lshl_add_u64 v[100:101], v[174:175], 2, v[100:101]
	global_load_dwordx4 v[120:123], v[100:101], off offset:64
	s_and_saveexec_b64 s[2:3], s[12:13]
	s_xor_b64 s[52:53], exec, s[2:3]
	v_add3_u32 v100, v223, v210, s62
	s_or_saveexec_b64 s[52:53], s[52:53]
	v_mov_b64_e32 v[102:103], s[24:25]
	s_xor_b64 exec, exec, s[52:53]
	v_lshl_add_u32 v100, v211, 8, v210
	v_mov_b64_e32 v[102:103], s[36:37]
	s_or_b64 exec, exec, s[52:53]
	v_ashrrev_i32_e32 v101, 31, v100
	v_lshlrev_b64 v[100:101], 13, v[100:101]
	v_lshl_add_u64 v[100:101], v[102:103], 0, v[100:101]
	v_lshl_add_u64 v[100:101], v[174:175], 2, v[100:101]
	global_load_dwordx4 v[116:119], v[100:101], off offset:64
	s_and_saveexec_b64 s[2:3], s[10:11]
	s_xor_b64 s[52:53], exec, s[2:3]
	v_add3_u32 v100, v224, v213, s62
	s_or_saveexec_b64 s[52:53], s[52:53]
	v_mov_b64_e32 v[102:103], s[24:25]
	s_xor_b64 exec, exec, s[52:53]
	v_lshl_add_u32 v100, v214, 8, v213
	v_mov_b64_e32 v[102:103], s[36:37]
	s_or_b64 exec, exec, s[52:53]
	v_ashrrev_i32_e32 v101, 31, v100
	v_lshlrev_b64 v[100:101], 13, v[100:101]
	v_lshl_add_u64 v[100:101], v[102:103], 0, v[100:101]
	v_lshl_add_u64 v[100:101], v[174:175], 2, v[100:101]
	global_load_dwordx4 v[112:115], v[100:101], off offset:64
	s_and_saveexec_b64 s[2:3], s[8:9]
	s_xor_b64 s[52:53], exec, s[2:3]
	v_add3_u32 v100, v225, v215, s62
	s_or_saveexec_b64 s[52:53], s[52:53]
	v_mov_b64_e32 v[102:103], s[24:25]
	s_xor_b64 exec, exec, s[52:53]
	v_lshl_add_u32 v100, v216, 8, v215
	v_mov_b64_e32 v[102:103], s[36:37]
	s_or_b64 exec, exec, s[52:53]
	v_ashrrev_i32_e32 v101, 31, v100
	v_lshlrev_b64 v[100:101], 13, v[100:101]
	v_lshl_add_u64 v[100:101], v[102:103], 0, v[100:101]
	v_lshl_add_u64 v[100:101], v[174:175], 2, v[100:101]
	global_load_dwordx4 v[108:111], v[100:101], off offset:64
	s_and_saveexec_b64 s[2:3], s[6:7]
	s_xor_b64 s[52:53], exec, s[2:3]
	v_add3_u32 v100, v226, v218, s62
	s_or_saveexec_b64 s[52:53], s[52:53]
	v_mov_b64_e32 v[102:103], s[24:25]
	s_xor_b64 exec, exec, s[52:53]
	v_lshl_add_u32 v100, v219, 8, v218
	v_mov_b64_e32 v[102:103], s[36:37]
	s_or_b64 exec, exec, s[52:53]
	v_ashrrev_i32_e32 v101, 31, v100
	v_lshlrev_b64 v[100:101], 13, v[100:101]
	v_lshl_add_u64 v[100:101], v[102:103], 0, v[100:101]
	v_lshl_add_u64 v[100:101], v[174:175], 2, v[100:101]
	global_load_dwordx4 v[104:107], v[100:101], off offset:64
	s_and_saveexec_b64 s[2:3], vcc
	s_xor_b64 s[52:53], exec, s[2:3]
	v_add3_u32 v100, v227, v221, s62
	s_or_saveexec_b64 s[52:53], s[52:53]
	v_mov_b64_e32 v[102:103], s[24:25]
	s_xor_b64 exec, exec, s[52:53]
	v_lshl_add_u32 v100, v222, 8, v221
	v_mov_b64_e32 v[102:103], s[36:37]
	s_or_b64 exec, exec, s[52:53]
	v_ashrrev_i32_e32 v101, 31, v100
	v_lshlrev_b64 v[100:101], 13, v[100:101]
	v_lshl_add_u64 v[100:101], v[102:103], 0, v[100:101]
	v_lshl_add_u64 v[100:101], v[174:175], 2, v[100:101]
	global_load_dwordx4 v[100:103], v[100:101], off offset:64
	s_and_saveexec_b64 s[2:3], s[18:19]
	s_xor_b64 s[52:53], exec, s[2:3]
	v_add3_u32 v132, v212, v202, s62
	s_or_saveexec_b64 s[52:53], s[52:53]
	v_mov_b64_e32 v[134:135], s[24:25]
	s_xor_b64 exec, exec, s[52:53]
	v_lshl_add_u32 v132, v203, 8, v202
	v_mov_b64_e32 v[134:135], s[36:37]
	s_or_b64 exec, exec, s[52:53]
	v_ashrrev_i32_e32 v133, 31, v132
	s_waitcnt vmcnt(0)
	v_pk_fma_f32 v[92:93], v[92:93], v[96:97], v[128:129]
	v_lshlrev_b64 v[128:129], 13, v[132:133]
	v_lshl_add_u64 v[128:129], v[134:135], 0, v[128:129]
	v_pk_fma_f32 v[94:95], v[94:95], v[98:99], v[130:131]
	v_lshl_add_u64 v[128:129], v[174:175], 2, v[128:129]
	global_store_dwordx4 v[128:129], v[92:95], off offset:64
	s_and_saveexec_b64 s[2:3], s[16:17]
	s_xor_b64 s[52:53], exec, s[2:3]
	v_add3_u32 v92, v217, v204, s62
	s_or_saveexec_b64 s[52:53], s[52:53]
	v_mov_b64_e32 v[94:95], s[24:25]
	s_xor_b64 exec, exec, s[52:53]
	v_lshl_add_u32 v92, v205, 8, v204
	v_mov_b64_e32 v[94:95], s[36:37]
	s_or_b64 exec, exec, s[52:53]
	v_ashrrev_i32_e32 v93, 31, v92
	v_lshlrev_b64 v[92:93], 13, v[92:93]
	v_lshl_add_u64 v[92:93], v[94:95], 0, v[92:93]
	v_pk_fma_f32 v[90:91], v[90:91], v[98:99], v[126:127]
	v_pk_fma_f32 v[88:89], v[88:89], v[96:97], v[124:125]
	v_lshl_add_u64 v[92:93], v[174:175], 2, v[92:93]
	global_store_dwordx4 v[92:93], v[88:91], off offset:64
	s_and_saveexec_b64 s[2:3], s[14:15]
	s_xor_b64 s[52:53], exec, s[2:3]
	v_add3_u32 v88, v220, v208, s62
	s_or_saveexec_b64 s[52:53], s[52:53]
	v_mov_b64_e32 v[90:91], s[24:25]
	s_xor_b64 exec, exec, s[52:53]
	v_lshl_add_u32 v88, v209, 8, v208
	v_mov_b64_e32 v[90:91], s[36:37]
	s_or_b64 exec, exec, s[52:53]
	v_ashrrev_i32_e32 v89, 31, v88
	v_lshlrev_b64 v[88:89], 13, v[88:89]
	v_lshl_add_u64 v[88:89], v[90:91], 0, v[88:89]
	v_pk_fma_f32 v[86:87], v[86:87], v[98:99], v[122:123]
; DI void epi_resid(const Acc& acc, const P& p, int brow, int bcol, int layer, int gch, bool from_input) {
;     ...
; #pragma unroll
;             for (int ai = 0; ai < 2; ++ai)
; #pragma unroll
;                 for (int m = 0; m < 4; ++m) {
;                     const int r = brow + ai * 128 + wr * 64 + m * 16 + fr;
;                     const float* sp = (from_input ? inrow(p, r) : xrow(p, r)) + c0;
;                     xv[ai][m] = *(const f32x4*)sp;
;                 }
;             __builtin_amdgcn_sched_barrier(0);
; #pragma unroll
;             for (int ai = 0; ai < 2; ++ai)
; #pragma unroll
;                 for (int m = 0; m < 4; ++m) {
;                     const int r = brow + ai * 128 + wr * 64 + m * 16 + fr;
;                     *(f32x4*)(xrow(p, r) + c0) = xv[ai][m] + g * acc[ai][bj][m][n];
;                 }
	v_pk_fma_f32 v[84:85], v[84:85], v[96:97], v[120:121]
	v_lshl_add_u64 v[88:89], v[174:175], 2, v[88:89]
	global_store_dwordx4 v[88:89], v[84:87], off offset:64
	s_and_saveexec_b64 s[2:3], s[12:13]
	s_xor_b64 s[52:53], exec, s[2:3]
	v_add3_u32 v84, v223, v210, s62
	s_or_saveexec_b64 s[52:53], s[52:53]
	v_mov_b64_e32 v[86:87], s[24:25]
	s_xor_b64 exec, exec, s[52:53]
	v_lshl_add_u32 v84, v211, 8, v210
	v_mov_b64_e32 v[86:87], s[36:37]
	s_or_b64 exec, exec, s[52:53]
	v_ashrrev_i32_e32 v85, 31, v84
	v_lshlrev_b64 v[84:85], 13, v[84:85]
	v_lshl_add_u64 v[84:85], v[86:87], 0, v[84:85]
	v_pk_fma_f32 v[82:83], v[82:83], v[98:99], v[118:119]
	v_pk_fma_f32 v[80:81], v[80:81], v[96:97], v[116:117]
	v_lshl_add_u64 v[84:85], v[174:175], 2, v[84:85]
	global_store_dwordx4 v[84:85], v[80:83], off offset:64
	s_and_saveexec_b64 s[2:3], s[10:11]
	s_xor_b64 s[52:53], exec, s[2:3]
	v_add3_u32 v80, v224, v213, s62
	s_or_saveexec_b64 s[52:53], s[52:53]
	v_mov_b64_e32 v[82:83], s[24:25]
	s_xor_b64 exec, exec, s[52:53]
	v_lshl_add_u32 v80, v214, 8, v213
	v_mov_b64_e32 v[82:83], s[36:37]
	s_or_b64 exec, exec, s[52:53]
	v_ashrrev_i32_e32 v81, 31, v80
	v_lshlrev_b64 v[80:81], 13, v[80:81]
	v_lshl_add_u64 v[80:81], v[82:83], 0, v[80:81]
	v_pk_fma_f32 v[78:79], v[78:79], v[98:99], v[114:115]
	v_pk_fma_f32 v[76:77], v[76:77], v[96:97], v[112:113]
	v_lshl_add_u64 v[80:81], v[174:175], 2, v[80:81]
	global_store_dwordx4 v[80:81], v[76:79], off offset:64
	s_and_saveexec_b64 s[2:3], s[8:9]
	s_xor_b64 s[52:53], exec, s[2:3]
	v_add3_u32 v76, v225, v215, s62
	s_or_saveexec_b64 s[52:53], s[52:53]
	v_mov_b64_e32 v[78:79], s[24:25]
	s_xor_b64 exec, exec, s[52:53]
	v_lshl_add_u32 v76, v216, 8, v215
	v_mov_b64_e32 v[78:79], s[36:37]
	s_or_b64 exec, exec, s[52:53]
	v_ashrrev_i32_e32 v77, 31, v76
	v_lshlrev_b64 v[76:77], 13, v[76:77]
	v_lshl_add_u64 v[76:77], v[78:79], 0, v[76:77]
	v_pk_fma_f32 v[74:75], v[74:75], v[98:99], v[110:111]
	v_pk_fma_f32 v[72:73], v[72:73], v[96:97], v[108:109]
	v_lshl_add_u64 v[76:77], v[174:175], 2, v[76:77]
	global_store_dwordx4 v[76:77], v[72:75], off offset:64
	s_and_saveexec_b64 s[2:3], s[6:7]
	s_xor_b64 s[52:53], exec, s[2:3]
	v_add3_u32 v72, v226, v218, s62
	s_or_saveexec_b64 s[52:53], s[52:53]
	v_mov_b64_e32 v[74:75], s[24:25]
	s_xor_b64 exec, exec, s[52:53]
	v_lshl_add_u32 v72, v219, 8, v218
	v_mov_b64_e32 v[74:75], s[36:37]
	s_or_b64 exec, exec, s[52:53]
	v_ashrrev_i32_e32 v73, 31, v72
	v_lshlrev_b64 v[72:73], 13, v[72:73]
	v_lshl_add_u64 v[72:73], v[74:75], 0, v[72:73]
	v_pk_fma_f32 v[70:71], v[70:71], v[98:99], v[106:107]
	v_pk_fma_f32 v[68:69], v[68:69], v[96:97], v[104:105]
	v_lshl_add_u64 v[72:73], v[174:175], 2, v[72:73]
	global_store_dwordx4 v[72:73], v[68:71], off offset:64
	s_and_saveexec_b64 s[2:3], vcc
	s_xor_b64 s[52:53], exec, s[2:3]
	v_add3_u32 v68, v227, v221, s62
	s_or_saveexec_b64 s[52:53], s[52:53]
	v_mov_b64_e32 v[70:71], s[24:25]
	s_xor_b64 exec, exec, s[52:53]
	v_lshl_add_u32 v68, v222, 8, v221
	v_mov_b64_e32 v[70:71], s[36:37]
	s_or_b64 exec, exec, s[52:53]
	v_ashrrev_i32_e32 v69, 31, v68
	v_lshlrev_b64 v[68:69], 13, v[68:69]
	v_lshl_add_u64 v[68:69], v[70:71], 0, v[68:69]
	v_pk_fma_f32 v[66:67], v[66:67], v[98:99], v[102:103]
	v_pk_fma_f32 v[64:65], v[64:65], v[96:97], v[100:101]
	v_lshl_add_u64 v[68:69], v[174:175], 2, v[68:69]
	global_store_dwordx4 v[68:69], v[64:67], off offset:64
	global_load_dwordx4 v[64:67], v[192:193], off offset:512
	s_and_saveexec_b64 s[2:3], s[18:19]
	s_xor_b64 s[52:53], exec, s[2:3]
	v_add3_u32 v68, v212, v202, s62
	s_or_saveexec_b64 s[52:53], s[52:53]
	v_mov_b64_e32 v[70:71], s[24:25]
	s_xor_b64 exec, exec, s[52:53]
	v_lshl_add_u32 v68, v203, 8, v202
	v_mov_b64_e32 v[70:71], s[36:37]
	s_or_b64 exec, exec, s[52:53]
	v_ashrrev_i32_e32 v69, 31, v68
	v_lshlrev_b64 v[68:69], 13, v[68:69]
	v_lshl_add_u64 v[68:69], v[70:71], 0, v[68:69]
	v_lshl_add_u64 v[68:69], v[174:175], 2, v[68:69]
	global_load_dwordx4 v[96:99], v[68:69], off offset:512
	s_and_saveexec_b64 s[2:3], s[16:17]
	s_xor_b64 s[52:53], exec, s[2:3]
	v_add3_u32 v68, v217, v204, s62
	s_or_saveexec_b64 s[52:53], s[52:53]
	v_mov_b64_e32 v[70:71], s[24:25]
	s_xor_b64 exec, exec, s[52:53]
	v_lshl_add_u32 v68, v205, 8, v204
	v_mov_b64_e32 v[70:71], s[36:37]
	s_or_b64 exec, exec, s[52:53]
	v_ashrrev_i32_e32 v69, 31, v68
	v_lshlrev_b64 v[68:69], 13, v[68:69]
	v_lshl_add_u64 v[68:69], v[70:71], 0, v[68:69]
	v_lshl_add_u64 v[68:69], v[174:175], 2, v[68:69]
	global_load_dwordx4 v[92:95], v[68:69], off offset:512
	s_and_saveexec_b64 s[2:3], s[14:15]
	s_xor_b64 s[52:53], exec, s[2:3]
	v_add3_u32 v68, v220, v208, s62
	s_or_saveexec_b64 s[52:53], s[52:53]
	v_mov_b64_e32 v[70:71], s[24:25]
	s_xor_b64 exec, exec, s[52:53]
	v_lshl_add_u32 v68, v209, 8, v208
	v_mov_b64_e32 v[70:71], s[36:37]
	s_or_b64 exec, exec, s[52:53]
	v_ashrrev_i32_e32 v69, 31, v68
	v_lshlrev_b64 v[68:69], 13, v[68:69]
	v_lshl_add_u64 v[68:69], v[70:71], 0, v[68:69]
	v_lshl_add_u64 v[68:69], v[174:175], 2, v[68:69]
	global_load_dwordx4 v[88:91], v[68:69], off offset:512
	s_and_saveexec_b64 s[2:3], s[12:13]
	s_xor_b64 s[52:53], exec, s[2:3]
	v_add3_u32 v68, v223, v210, s62
	s_or_saveexec_b64 s[52:53], s[52:53]
	v_mov_b64_e32 v[70:71], s[24:25]
	s_xor_b64 exec, exec, s[52:53]
	v_lshl_add_u32 v68, v211, 8, v210
	v_mov_b64_e32 v[70:71], s[36:37]
	s_or_b64 exec, exec, s[52:53]
	v_ashrrev_i32_e32 v69, 31, v68
	v_lshlrev_b64 v[68:69], 13, v[68:69]
	v_lshl_add_u64 v[68:69], v[70:71], 0, v[68:69]
	v_lshl_add_u64 v[68:69], v[174:175], 2, v[68:69]
	global_load_dwordx4 v[84:87], v[68:69], off offset:512
	s_and_saveexec_b64 s[2:3], s[10:11]
	s_xor_b64 s[52:53], exec, s[2:3]
	v_add3_u32 v68, v224, v213, s62
; DI void epi_resid(const Acc& acc, const P& p, int brow, int bcol, int layer, int gch, bool from_input) {
;     ...
; #pragma unroll
;             for (int ai = 0; ai < 2; ++ai)
; #pragma unroll
;                 for (int m = 0; m < 4; ++m) {
;                     const int r = brow + ai * 128 + wr * 64 + m * 16 + fr;
;                     const float* sp = (from_input ? inrow(p, r) : xrow(p, r)) + c0;
;                     xv[ai][m] = *(const f32x4*)sp;
;                 }
;             __builtin_amdgcn_sched_barrier(0);
; #pragma unroll
;             for (int ai = 0; ai < 2; ++ai)
; #pragma unroll
;                 for (int m = 0; m < 4; ++m) {
;                     const int r = brow + ai * 128 + wr * 64 + m * 16 + fr;
;                     *(f32x4*)(xrow(p, r) + c0) = xv[ai][m] + g * acc[ai][bj][m][n];
;                 }
	s_or_saveexec_b64 s[52:53], s[52:53]
	v_mov_b64_e32 v[70:71], s[24:25]
	s_xor_b64 exec, exec, s[52:53]
	v_lshl_add_u32 v68, v214, 8, v213
	v_mov_b64_e32 v[70:71], s[36:37]
	s_or_b64 exec, exec, s[52:53]
	v_ashrrev_i32_e32 v69, 31, v68
	v_lshlrev_b64 v[68:69], 13, v[68:69]
	v_lshl_add_u64 v[68:69], v[70:71], 0, v[68:69]
	v_lshl_add_u64 v[68:69], v[174:175], 2, v[68:69]
	global_load_dwordx4 v[80:83], v[68:69], off offset:512
	s_and_saveexec_b64 s[2:3], s[8:9]
	s_xor_b64 s[52:53], exec, s[2:3]
	v_add3_u32 v68, v225, v215, s62
	s_or_saveexec_b64 s[52:53], s[52:53]
	v_mov_b64_e32 v[70:71], s[24:25]
	s_xor_b64 exec, exec, s[52:53]
	v_lshl_add_u32 v68, v216, 8, v215
	v_mov_b64_e32 v[70:71], s[36:37]
	s_or_b64 exec, exec, s[52:53]
	v_ashrrev_i32_e32 v69, 31, v68
	v_lshlrev_b64 v[68:69], 13, v[68:69]
	v_lshl_add_u64 v[68:69], v[70:71], 0, v[68:69]
	v_lshl_add_u64 v[68:69], v[174:175], 2, v[68:69]
	global_load_dwordx4 v[76:79], v[68:69], off offset:512
	s_and_saveexec_b64 s[2:3], s[6:7]
	s_xor_b64 s[52:53], exec, s[2:3]
	v_add3_u32 v68, v226, v218, s62
	s_or_saveexec_b64 s[52:53], s[52:53]
	v_mov_b64_e32 v[70:71], s[24:25]
	s_xor_b64 exec, exec, s[52:53]
	v_lshl_add_u32 v68, v219, 8, v218
	v_mov_b64_e32 v[70:71], s[36:37]
	s_or_b64 exec, exec, s[52:53]
	v_ashrrev_i32_e32 v69, 31, v68
	v_lshlrev_b64 v[68:69], 13, v[68:69]
	v_lshl_add_u64 v[68:69], v[70:71], 0, v[68:69]
	v_lshl_add_u64 v[68:69], v[174:175], 2, v[68:69]
	global_load_dwordx4 v[72:75], v[68:69], off offset:512
	s_and_saveexec_b64 s[2:3], vcc
	s_xor_b64 s[52:53], exec, s[2:3]
	v_add3_u32 v68, v227, v221, s62
	s_or_saveexec_b64 s[52:53], s[52:53]
	v_mov_b64_e32 v[70:71], s[24:25]
	s_xor_b64 exec, exec, s[52:53]
	v_lshl_add_u32 v68, v222, 8, v221
	v_mov_b64_e32 v[70:71], s[36:37]
	s_or_b64 exec, exec, s[52:53]
	v_ashrrev_i32_e32 v69, 31, v68
	v_lshlrev_b64 v[68:69], 13, v[68:69]
	v_lshl_add_u64 v[68:69], v[70:71], 0, v[68:69]
	v_lshl_add_u64 v[68:69], v[174:175], 2, v[68:69]
	global_load_dwordx4 v[68:71], v[68:69], off offset:512
	s_and_saveexec_b64 s[2:3], s[18:19]
	s_xor_b64 s[52:53], exec, s[2:3]
	v_add3_u32 v100, v212, v202, s62
	s_or_saveexec_b64 s[52:53], s[52:53]
	v_mov_b64_e32 v[102:103], s[24:25]
	s_xor_b64 exec, exec, s[52:53]
	v_lshl_add_u32 v100, v203, 8, v202
	v_mov_b64_e32 v[102:103], s[36:37]
	s_or_b64 exec, exec, s[52:53]
	v_ashrrev_i32_e32 v101, 31, v100
	s_waitcnt vmcnt(0)
	v_pk_fma_f32 v[60:61], v[60:61], v[64:65], v[96:97]
	v_lshlrev_b64 v[96:97], 13, v[100:101]
	v_lshl_add_u64 v[96:97], v[102:103], 0, v[96:97]
	v_pk_fma_f32 v[62:63], v[62:63], v[66:67], v[98:99]
	v_lshl_add_u64 v[96:97], v[174:175], 2, v[96:97]
	global_store_dwordx4 v[96:97], v[60:63], off offset:512
	s_and_saveexec_b64 s[2:3], s[16:17]
	s_xor_b64 s[52:53], exec, s[2:3]
	v_add3_u32 v60, v217, v204, s62
	s_or_saveexec_b64 s[52:53], s[52:53]
	v_mov_b64_e32 v[62:63], s[24:25]
	s_xor_b64 exec, exec, s[52:53]
	v_lshl_add_u32 v60, v205, 8, v204
	v_mov_b64_e32 v[62:63], s[36:37]
	s_or_b64 exec, exec, s[52:53]
	v_ashrrev_i32_e32 v61, 31, v60
	v_lshlrev_b64 v[60:61], 13, v[60:61]
	v_lshl_add_u64 v[60:61], v[62:63], 0, v[60:61]
	v_pk_fma_f32 v[58:59], v[58:59], v[66:67], v[94:95]
	v_pk_fma_f32 v[56:57], v[56:57], v[64:65], v[92:93]
	v_lshl_add_u64 v[60:61], v[174:175], 2, v[60:61]
	global_store_dwordx4 v[60:61], v[56:59], off offset:512
	s_and_saveexec_b64 s[2:3], s[14:15]
	s_xor_b64 s[52:53], exec, s[2:3]
	v_add3_u32 v56, v220, v208, s62
	s_or_saveexec_b64 s[52:53], s[52:53]
	v_mov_b64_e32 v[58:59], s[24:25]
	s_xor_b64 exec, exec, s[52:53]
	v_lshl_add_u32 v56, v209, 8, v208
	v_mov_b64_e32 v[58:59], s[36:37]
	s_or_b64 exec, exec, s[52:53]
	v_ashrrev_i32_e32 v57, 31, v56
	v_lshlrev_b64 v[56:57], 13, v[56:57]
	v_lshl_add_u64 v[56:57], v[58:59], 0, v[56:57]
	v_pk_fma_f32 v[54:55], v[54:55], v[66:67], v[90:91]
	v_pk_fma_f32 v[52:53], v[52:53], v[64:65], v[88:89]
	v_lshl_add_u64 v[56:57], v[174:175], 2, v[56:57]
	global_store_dwordx4 v[56:57], v[52:55], off offset:512
	s_and_saveexec_b64 s[2:3], s[12:13]
	s_xor_b64 s[52:53], exec, s[2:3]
	v_add3_u32 v52, v223, v210, s62
	s_or_saveexec_b64 s[52:53], s[52:53]
	v_mov_b64_e32 v[54:55], s[24:25]
	s_xor_b64 exec, exec, s[52:53]
	v_lshl_add_u32 v52, v211, 8, v210
	v_mov_b64_e32 v[54:55], s[36:37]
	s_or_b64 exec, exec, s[52:53]
	v_ashrrev_i32_e32 v53, 31, v52
	v_lshlrev_b64 v[52:53], 13, v[52:53]
	v_lshl_add_u64 v[52:53], v[54:55], 0, v[52:53]
	v_pk_fma_f32 v[50:51], v[50:51], v[66:67], v[86:87]
	v_pk_fma_f32 v[48:49], v[48:49], v[64:65], v[84:85]
	v_lshl_add_u64 v[52:53], v[174:175], 2, v[52:53]
	global_store_dwordx4 v[52:53], v[48:51], off offset:512
	s_and_saveexec_b64 s[2:3], s[10:11]
	s_xor_b64 s[52:53], exec, s[2:3]
	v_add3_u32 v48, v224, v213, s62
	s_or_saveexec_b64 s[52:53], s[52:53]
	v_mov_b64_e32 v[50:51], s[24:25]
	s_xor_b64 exec, exec, s[52:53]
	v_lshl_add_u32 v48, v214, 8, v213
	v_mov_b64_e32 v[50:51], s[36:37]
	s_or_b64 exec, exec, s[52:53]
	v_ashrrev_i32_e32 v49, 31, v48
	v_lshlrev_b64 v[48:49], 13, v[48:49]
	v_lshl_add_u64 v[48:49], v[50:51], 0, v[48:49]
	v_pk_fma_f32 v[46:47], v[46:47], v[66:67], v[82:83]
	v_pk_fma_f32 v[44:45], v[44:45], v[64:65], v[80:81]
	v_lshl_add_u64 v[48:49], v[174:175], 2, v[48:49]
	global_store_dwordx4 v[48:49], v[44:47], off offset:512
	s_and_saveexec_b64 s[2:3], s[8:9]
	s_xor_b64 s[52:53], exec, s[2:3]
	v_add3_u32 v44, v225, v215, s62
	s_or_saveexec_b64 s[52:53], s[52:53]
	v_mov_b64_e32 v[46:47], s[24:25]
	s_xor_b64 exec, exec, s[52:53]
	v_lshl_add_u32 v44, v216, 8, v215
	v_mov_b64_e32 v[46:47], s[36:37]
	s_or_b64 exec, exec, s[52:53]
	v_ashrrev_i32_e32 v45, 31, v44
	v_lshlrev_b64 v[44:45], 13, v[44:45]
; DI void epi_resid(const Acc& acc, const P& p, int brow, int bcol, int layer, int gch, bool from_input) {
;     ...
; #pragma unroll
;             for (int ai = 0; ai < 2; ++ai)
; #pragma unroll
;                 for (int m = 0; m < 4; ++m) {
;                     const int r = brow + ai * 128 + wr * 64 + m * 16 + fr;
;                     const float* sp = (from_input ? inrow(p, r) : xrow(p, r)) + c0;
;                     xv[ai][m] = *(const f32x4*)sp;
;                 }
;             __builtin_amdgcn_sched_barrier(0);
; #pragma unroll
;             for (int ai = 0; ai < 2; ++ai)
; #pragma unroll
;                 for (int m = 0; m < 4; ++m) {
;                     const int r = brow + ai * 128 + wr * 64 + m * 16 + fr;
;                     *(f32x4*)(xrow(p, r) + c0) = xv[ai][m] + g * acc[ai][bj][m][n];
;                 }
	v_lshl_add_u64 v[44:45], v[46:47], 0, v[44:45]
	v_pk_fma_f32 v[42:43], v[42:43], v[66:67], v[78:79]
	v_pk_fma_f32 v[40:41], v[40:41], v[64:65], v[76:77]
	v_lshl_add_u64 v[44:45], v[174:175], 2, v[44:45]
	global_store_dwordx4 v[44:45], v[40:43], off offset:512
	s_and_saveexec_b64 s[2:3], s[6:7]
	s_xor_b64 s[52:53], exec, s[2:3]
	v_add3_u32 v40, v226, v218, s62
	s_or_saveexec_b64 s[52:53], s[52:53]
	v_mov_b64_e32 v[42:43], s[24:25]
	s_xor_b64 exec, exec, s[52:53]
	v_lshl_add_u32 v40, v219, 8, v218
	v_mov_b64_e32 v[42:43], s[36:37]
	s_or_b64 exec, exec, s[52:53]
	v_ashrrev_i32_e32 v41, 31, v40
	v_lshlrev_b64 v[40:41], 13, v[40:41]
	v_lshl_add_u64 v[40:41], v[42:43], 0, v[40:41]
	v_pk_fma_f32 v[38:39], v[38:39], v[66:67], v[74:75]
	v_pk_fma_f32 v[36:37], v[36:37], v[64:65], v[72:73]
	v_lshl_add_u64 v[40:41], v[174:175], 2, v[40:41]
	global_store_dwordx4 v[40:41], v[36:39], off offset:512
	s_and_saveexec_b64 s[2:3], vcc
	s_xor_b64 s[52:53], exec, s[2:3]
	v_add3_u32 v36, v227, v221, s62
	s_or_saveexec_b64 s[52:53], s[52:53]
	v_mov_b64_e32 v[38:39], s[24:25]
	s_xor_b64 exec, exec, s[52:53]
	v_lshl_add_u32 v36, v222, 8, v221
	v_mov_b64_e32 v[38:39], s[36:37]
	s_or_b64 exec, exec, s[52:53]
	v_ashrrev_i32_e32 v37, 31, v36
	v_lshlrev_b64 v[36:37], 13, v[36:37]
	v_lshl_add_u64 v[36:37], v[38:39], 0, v[36:37]
	v_pk_fma_f32 v[34:35], v[34:35], v[66:67], v[70:71]
	v_pk_fma_f32 v[32:33], v[32:33], v[64:65], v[68:69]
	v_lshl_add_u64 v[36:37], v[174:175], 2, v[36:37]
	global_store_dwordx4 v[36:37], v[32:35], off offset:512
	global_load_dwordx4 v[32:35], v[192:193], off offset:576
	s_and_saveexec_b64 s[2:3], s[18:19]
	s_xor_b64 s[52:53], exec, s[2:3]
	v_add3_u32 v36, v212, v202, s62
	s_or_saveexec_b64 s[52:53], s[52:53]
	v_mov_b64_e32 v[38:39], s[24:25]
	s_xor_b64 exec, exec, s[52:53]
	v_lshl_add_u32 v36, v203, 8, v202
	v_mov_b64_e32 v[38:39], s[36:37]
	s_or_b64 exec, exec, s[52:53]
	v_ashrrev_i32_e32 v37, 31, v36
	v_lshlrev_b64 v[36:37], 13, v[36:37]
	v_lshl_add_u64 v[36:37], v[38:39], 0, v[36:37]
	v_lshl_add_u64 v[36:37], v[174:175], 2, v[36:37]
	global_load_dwordx4 v[64:67], v[36:37], off offset:576
	s_and_saveexec_b64 s[2:3], s[16:17]
	s_xor_b64 s[52:53], exec, s[2:3]
	v_add3_u32 v36, v217, v204, s62
	s_or_saveexec_b64 s[52:53], s[52:53]
	v_mov_b64_e32 v[38:39], s[24:25]
	s_xor_b64 exec, exec, s[52:53]
	v_lshl_add_u32 v36, v205, 8, v204
	v_mov_b64_e32 v[38:39], s[36:37]
	s_or_b64 exec, exec, s[52:53]
	v_ashrrev_i32_e32 v37, 31, v36
	v_lshlrev_b64 v[36:37], 13, v[36:37]
	v_lshl_add_u64 v[36:37], v[38:39], 0, v[36:37]
	v_lshl_add_u64 v[36:37], v[174:175], 2, v[36:37]
	global_load_dwordx4 v[60:63], v[36:37], off offset:576
	s_and_saveexec_b64 s[2:3], s[14:15]
	s_xor_b64 s[52:53], exec, s[2:3]
	v_add3_u32 v36, v220, v208, s62
	s_or_saveexec_b64 s[52:53], s[52:53]
	v_mov_b64_e32 v[38:39], s[24:25]
	s_xor_b64 exec, exec, s[52:53]
	v_lshl_add_u32 v36, v209, 8, v208
	v_mov_b64_e32 v[38:39], s[36:37]
	s_or_b64 exec, exec, s[52:53]
	v_ashrrev_i32_e32 v37, 31, v36
	v_lshlrev_b64 v[36:37], 13, v[36:37]
	v_lshl_add_u64 v[36:37], v[38:39], 0, v[36:37]
	v_lshl_add_u64 v[36:37], v[174:175], 2, v[36:37]
	global_load_dwordx4 v[56:59], v[36:37], off offset:576
	s_and_saveexec_b64 s[2:3], s[12:13]
	s_xor_b64 s[52:53], exec, s[2:3]
	v_add3_u32 v36, v223, v210, s62
	s_or_saveexec_b64 s[52:53], s[52:53]
	v_mov_b64_e32 v[38:39], s[24:25]
	s_xor_b64 exec, exec, s[52:53]
	v_lshl_add_u32 v36, v211, 8, v210
	v_mov_b64_e32 v[38:39], s[36:37]
	s_or_b64 exec, exec, s[52:53]
	v_ashrrev_i32_e32 v37, 31, v36
	v_lshlrev_b64 v[36:37], 13, v[36:37]
	v_lshl_add_u64 v[36:37], v[38:39], 0, v[36:37]
	v_lshl_add_u64 v[36:37], v[174:175], 2, v[36:37]
	global_load_dwordx4 v[52:55], v[36:37], off offset:576
	s_and_saveexec_b64 s[2:3], s[10:11]
	s_xor_b64 s[52:53], exec, s[2:3]
	v_add3_u32 v36, v224, v213, s62
	s_or_saveexec_b64 s[52:53], s[52:53]
	v_mov_b64_e32 v[38:39], s[24:25]
	s_xor_b64 exec, exec, s[52:53]
	v_lshl_add_u32 v36, v214, 8, v213
	v_mov_b64_e32 v[38:39], s[36:37]
	s_or_b64 exec, exec, s[52:53]
	v_ashrrev_i32_e32 v37, 31, v36
	v_lshlrev_b64 v[36:37], 13, v[36:37]
	v_lshl_add_u64 v[36:37], v[38:39], 0, v[36:37]
	v_lshl_add_u64 v[36:37], v[174:175], 2, v[36:37]
	global_load_dwordx4 v[48:51], v[36:37], off offset:576
	s_and_saveexec_b64 s[2:3], s[8:9]
	s_xor_b64 s[52:53], exec, s[2:3]
	v_add3_u32 v36, v225, v215, s62
	s_or_saveexec_b64 s[52:53], s[52:53]
	v_mov_b64_e32 v[38:39], s[24:25]
	s_xor_b64 exec, exec, s[52:53]
	v_lshl_add_u32 v36, v216, 8, v215
	v_mov_b64_e32 v[38:39], s[36:37]
	s_or_b64 exec, exec, s[52:53]
	v_ashrrev_i32_e32 v37, 31, v36
	v_lshlrev_b64 v[36:37], 13, v[36:37]
	v_lshl_add_u64 v[36:37], v[38:39], 0, v[36:37]
	v_lshl_add_u64 v[36:37], v[174:175], 2, v[36:37]
	global_load_dwordx4 v[44:47], v[36:37], off offset:576
	s_and_saveexec_b64 s[2:3], s[6:7]
	s_xor_b64 s[52:53], exec, s[2:3]
	v_add3_u32 v36, v226, v218, s62
	s_or_saveexec_b64 s[52:53], s[52:53]
	v_mov_b64_e32 v[38:39], s[24:25]
	s_xor_b64 exec, exec, s[52:53]
	v_lshl_add_u32 v36, v219, 8, v218
	v_mov_b64_e32 v[38:39], s[36:37]
	s_or_b64 exec, exec, s[52:53]
	v_ashrrev_i32_e32 v37, 31, v36
	v_lshlrev_b64 v[36:37], 13, v[36:37]
	v_lshl_add_u64 v[36:37], v[38:39], 0, v[36:37]
	v_lshl_add_u64 v[36:37], v[174:175], 2, v[36:37]
	global_load_dwordx4 v[40:43], v[36:37], off offset:576
	s_and_saveexec_b64 s[2:3], vcc
	s_xor_b64 s[52:53], exec, s[2:3]
	v_add3_u32 v36, v227, v221, s62
	s_or_saveexec_b64 s[52:53], s[52:53]
	v_mov_b64_e32 v[38:39], s[24:25]
	s_xor_b64 exec, exec, s[52:53]
	v_lshl_add_u32 v36, v222, 8, v221
	v_mov_b64_e32 v[38:39], s[36:37]
	s_or_b64 exec, exec, s[52:53]
	v_ashrrev_i32_e32 v37, 31, v36
	v_lshlrev_b64 v[36:37], 13, v[36:37]
	v_lshl_add_u64 v[36:37], v[38:39], 0, v[36:37]
	v_lshl_add_u64 v[36:37], v[174:175], 2, v[36:37]
	global_load_dwordx4 v[36:39], v[36:37], off offset:576
	s_and_saveexec_b64 s[2:3], s[18:19]
	s_xor_b64 s[18:19], exec, s[2:3]
	s_or_saveexec_b64 s[18:19], s[18:19]
	v_mov_b64_e32 v[68:69], s[24:25]
	s_xor_b64 exec, exec, s[18:19]
	v_mov_b64_e32 v[68:69], s[36:37]
	v_mov_b32_e32 v190, v191
	s_or_b64 exec, exec, s[18:19]
	v_ashrrev_i32_e32 v191, 31, v190
	s_waitcnt vmcnt(0)
; DI void epi_resid(const Acc& acc, const P& p, int brow, int bcol, int layer, int gch, bool from_input) {
;     ...
;             for (int ai = 0; ai < 2; ++ai)
; #pragma unroll
;                 for (int m = 0; m < 4; ++m) {
;                     const int r = brow + ai * 128 + wr * 64 + m * 16 + fr;
;                     *(f32x4*)(xrow(p, r) + c0) = xv[ai][m] + g * acc[ai][bj][m][n];
;                 }
	v_pk_fma_f32 v[28:29], v[28:29], v[32:33], v[64:65]
	v_lshlrev_b64 v[64:65], 13, v[190:191]
	v_lshl_add_u64 v[64:65], v[68:69], 0, v[64:65]
	v_pk_fma_f32 v[30:31], v[30:31], v[34:35], v[66:67]
	v_lshl_add_u64 v[64:65], v[174:175], 2, v[64:65]
	global_store_dwordx4 v[64:65], v[28:31], off offset:576
	s_and_saveexec_b64 s[2:3], s[16:17]
	s_xor_b64 s[16:17], exec, s[2:3]
	s_or_saveexec_b64 s[16:17], s[16:17]
	v_mov_b64_e32 v[28:29], s[24:25]
	s_xor_b64 exec, exec, s[16:17]
	v_mov_b64_e32 v[28:29], s[36:37]
	v_mov_b32_e32 v188, v189
	s_or_b64 exec, exec, s[16:17]
	v_ashrrev_i32_e32 v189, 31, v188
	v_lshlrev_b64 v[30:31], 13, v[188:189]
	v_lshl_add_u64 v[28:29], v[28:29], 0, v[30:31]
	v_pk_fma_f32 v[26:27], v[26:27], v[34:35], v[62:63]
	v_pk_fma_f32 v[24:25], v[24:25], v[32:33], v[60:61]
	v_lshl_add_u64 v[28:29], v[174:175], 2, v[28:29]
	global_store_dwordx4 v[28:29], v[24:27], off offset:576
	s_and_saveexec_b64 s[2:3], s[14:15]
	s_xor_b64 s[14:15], exec, s[2:3]
	s_or_saveexec_b64 s[14:15], s[14:15]
	v_mov_b64_e32 v[24:25], s[24:25]
	s_xor_b64 exec, exec, s[14:15]
	v_mov_b64_e32 v[24:25], s[36:37]
	v_mov_b32_e32 v186, v187
	s_or_b64 exec, exec, s[14:15]
	v_ashrrev_i32_e32 v187, 31, v186
	v_lshlrev_b64 v[26:27], 13, v[186:187]
	v_lshl_add_u64 v[24:25], v[24:25], 0, v[26:27]
	v_pk_fma_f32 v[22:23], v[22:23], v[34:35], v[58:59]
	v_pk_fma_f32 v[20:21], v[20:21], v[32:33], v[56:57]
	v_lshl_add_u64 v[24:25], v[174:175], 2, v[24:25]
	global_store_dwordx4 v[24:25], v[20:23], off offset:576
	s_and_saveexec_b64 s[2:3], s[12:13]
	s_xor_b64 s[12:13], exec, s[2:3]
	s_or_saveexec_b64 s[12:13], s[12:13]
	v_mov_b64_e32 v[20:21], s[24:25]
	s_xor_b64 exec, exec, s[12:13]
	v_mov_b64_e32 v[20:21], s[36:37]
	v_mov_b32_e32 v184, v185
	s_or_b64 exec, exec, s[12:13]
	v_ashrrev_i32_e32 v185, 31, v184
	v_lshlrev_b64 v[22:23], 13, v[184:185]
	v_lshl_add_u64 v[20:21], v[20:21], 0, v[22:23]
	v_pk_fma_f32 v[18:19], v[18:19], v[34:35], v[54:55]
	v_pk_fma_f32 v[16:17], v[16:17], v[32:33], v[52:53]
	v_lshl_add_u64 v[20:21], v[174:175], 2, v[20:21]
	global_store_dwordx4 v[20:21], v[16:19], off offset:576
	s_and_saveexec_b64 s[2:3], s[10:11]
	s_xor_b64 s[10:11], exec, s[2:3]
	s_or_saveexec_b64 s[10:11], s[10:11]
	v_mov_b64_e32 v[16:17], s[24:25]
	s_xor_b64 exec, exec, s[10:11]
	v_mov_b64_e32 v[16:17], s[36:37]
	v_mov_b32_e32 v182, v183
	s_or_b64 exec, exec, s[10:11]
	v_ashrrev_i32_e32 v183, 31, v182
	v_lshlrev_b64 v[18:19], 13, v[182:183]
	v_lshl_add_u64 v[16:17], v[16:17], 0, v[18:19]
	v_pk_fma_f32 v[14:15], v[14:15], v[34:35], v[50:51]
	v_pk_fma_f32 v[12:13], v[12:13], v[32:33], v[48:49]
	v_lshl_add_u64 v[16:17], v[174:175], 2, v[16:17]
	global_store_dwordx4 v[16:17], v[12:15], off offset:576
	s_and_saveexec_b64 s[2:3], s[8:9]
	s_xor_b64 s[8:9], exec, s[2:3]
	s_or_saveexec_b64 s[8:9], s[8:9]
	v_mov_b64_e32 v[12:13], s[24:25]
	s_xor_b64 exec, exec, s[8:9]
	v_mov_b64_e32 v[12:13], s[36:37]
	v_mov_b32_e32 v180, v181
	s_or_b64 exec, exec, s[8:9]
	v_ashrrev_i32_e32 v181, 31, v180
	v_lshlrev_b64 v[14:15], 13, v[180:181]
	v_lshl_add_u64 v[12:13], v[12:13], 0, v[14:15]
	v_pk_fma_f32 v[10:11], v[10:11], v[34:35], v[46:47]
	v_pk_fma_f32 v[8:9], v[8:9], v[32:33], v[44:45]
	v_lshl_add_u64 v[12:13], v[174:175], 2, v[12:13]
	global_store_dwordx4 v[12:13], v[8:11], off offset:576
	s_and_saveexec_b64 s[2:3], s[6:7]
	s_xor_b64 s[6:7], exec, s[2:3]
	s_or_saveexec_b64 s[6:7], s[6:7]
	v_mov_b64_e32 v[8:9], s[24:25]
	s_xor_b64 exec, exec, s[6:7]
	v_mov_b64_e32 v[8:9], s[36:37]
	v_mov_b32_e32 v178, v179
	s_or_b64 exec, exec, s[6:7]
	v_ashrrev_i32_e32 v179, 31, v178
	v_lshlrev_b64 v[10:11], 13, v[178:179]
	v_lshl_add_u64 v[8:9], v[8:9], 0, v[10:11]
	v_pk_fma_f32 v[6:7], v[6:7], v[34:35], v[42:43]
	v_pk_fma_f32 v[4:5], v[4:5], v[32:33], v[40:41]
	v_lshl_add_u64 v[8:9], v[174:175], 2, v[8:9]
	global_store_dwordx4 v[8:9], v[4:7], off offset:576
	s_and_saveexec_b64 s[2:3], vcc
	s_xor_b64 s[6:7], exec, s[2:3]
	s_or_saveexec_b64 s[6:7], s[6:7]
	v_mov_b64_e32 v[4:5], s[24:25]
	s_xor_b64 exec, exec, s[6:7]
	s_cbranch_execz .LBB0_1693
	v_mov_b64_e32 v[4:5], s[36:37]
	v_mov_b32_e32 v176, v177
	s_branch .LBB0_1693

; #define LAS __attribute__((address_space(3)))
; #define WAIT_V(n) asm volatile("s_waitcnt vmcnt(" #n ")" ::: "memory")
; #define WAIT_L(n) asm volatile("s_waitcnt lgkmcnt(" #n ")" ::: "memory")
; #define BAR __builtin_amdgcn_s_barrier()
; #define SCHED __builtin_amdgcn_sched_barrier(0)
; template <class Get, class Epi>
; DI void gemm_stream(LAS unsigned char* lds, const int K, const int ld, Get get, Epi epi) {
;     ...
;         for (int t = 0; t < nt; t += 2) {
;             const bool last = (t == nt - 2);
;             const char* a1 = cA + (size_t)(t + 1) * kstep;
;             const char* a2 = last ? nA : cA + (size_t)(t + 2) * kstep;
;             const char* b2 = last ? nB : cB + (size_t)(t + 2) * kstep;
;             const char* a3 = a2 + kstep;
;             const char* b3 = b2 + kstep;
;             LDB(B0, 0, 0); SCHED; LDA(At, 0, 0); STAGE(SAo(1, 1), a1 + hstep);
;             WAIT_L(8); BAR; WAIT_L(0); MMA(0, 0, At, B0); BAR; SCHED;
;             LDB(B1, 0, 1); STAGE(SBo(0, 0), b2);
;             BAR; WAIT_L(0); MMA(0, 1, At, B1); BAR;
;             LDA(At, 0, 1); STAGE(SAo(0, 0), a2);
;             BAR; WAIT_L(0); MMA(1, 0, At, B0); BAR; SCHED;
;             STAGE(SBo(0, 1), b2 + hstep);
;             WAIT_V(6); BAR; MMA(1, 1, At, B1); BAR;
;             LDB(B0, 1, 0); SCHED; LDA(At, 1, 0); STAGE(SAo(0, 1), a2 + hstep);
;             WAIT_L(8); BAR; WAIT_L(0); MMA(0, 0, At, B0); BAR; SCHED;
;             LDB(B1, 1, 1); STAGE(SBo(1, 0), b3);
;             BAR; WAIT_L(0); MMA(0, 1, At, B1); BAR;
; DI void phase_gemm_resid_ctx(const P& p, char* shm, const char* A, const char* W, int K, int S) {
;     const int nN = DM / 256, Kl = K / S, total = 4 * nN * S;
;     auto get = [&](int i, Unit& u) {
;         const long L = (long)i * gridDim.x + blockIdx.x;
;         if (L >= total) return false;
;         const int sl = (int)L % S, t = (int)L / S;
;         u.pm = (t / nN) * 17; u.pn = (t % nN) + 16 * sl;
;         u.A = A + ((size_t)u.pm * 256 * K + (size_t)sl * Kl) * 2;
;         u.B = W + ((size_t)(t % nN) * 256 * K + (size_t)sl * Kl) * 2;
;         return true;
;     };
;     auto epi = [&](const Acc& acc, const Unit& u) { epi_part(acc, p, u.pm * 256, (u.pn & 15) * 256, u.pn >> 4); };
;     gemm_stream((LAS unsigned char*)shm, Kl, K, get, epi);
; }
.LBB0_1964:
	ds_read_b128 v[144:147], v141
	ds_read_b128 v[148:151], v141 offset:1024
	ds_read_b128 v[152:155], v141 offset:2048
	ds_read_b128 v[156:159], v141 offset:3072
	s_add_u32 s38, s36, 0x100
	s_addc_u32 s39, s37, 0
	s_cmp_eq_u32 s77, 4
	s_cselect_b32 s53, s17, s39
	s_cselect_b32 s52, s16, s38
	s_cselect_b32 s41, s19, s76
	s_cselect_b32 s40, s18, s0
	v_lshl_add_u64 v[192:193], s[36:37], 0, v[134:135]
	s_add_i32 m0, s20, 0xc000
	ds_read_b128 v[160:163], v142
	ds_read_b128 v[164:167], v142 offset:1024
	ds_read_b128 v[168:171], v142 offset:2048
	ds_read_b128 v[172:175], v142 offset:3072
	ds_read_b128 v[176:179], v142 offset:4096
	ds_read_b128 v[180:183], v142 offset:5120
	ds_read_b128 v[184:187], v142 offset:6144
	ds_read_b128 v[188:191], v142 offset:7168
	global_load_lds_dwordx4 v[192:193], off
	v_lshl_add_u64 v[192:193], s[36:37], 0, v[136:137]
	s_add_i32 m0, s20, 0xe000
	s_nop 0
	global_load_lds_dwordx4 v[192:193], off
	s_waitcnt lgkmcnt(8)
	s_barrier
	s_waitcnt lgkmcnt(0)
	s_setprio 0
	s_waitcnt lgkmcnt(0)
	v_mfma_f32_16x16x32_bf16 v[124:127], v[144:147], v[160:163], v[124:127]
	v_mfma_f32_16x16x32_bf16 v[120:123], v[152:155], v[160:163], v[120:123]
	v_mfma_f32_16x16x32_bf16 v[116:119], v[144:147], v[168:171], v[116:119]
	v_mfma_f32_16x16x32_bf16 v[112:115], v[152:155], v[168:171], v[112:115]
	v_mfma_f32_16x16x32_bf16 v[104:107], v[144:147], v[176:179], v[104:107]
	v_mfma_f32_16x16x32_bf16 v[96:99], v[152:155], v[176:179], v[96:99]
	v_mfma_f32_16x16x32_bf16 v[88:91], v[144:147], v[184:187], v[88:91]
	v_mfma_f32_16x16x32_bf16 v[80:83], v[152:155], v[184:187], v[80:83]
	v_mfma_f32_16x16x32_bf16 v[124:127], v[148:151], v[164:167], v[124:127]
	v_mfma_f32_16x16x32_bf16 v[120:123], v[156:159], v[164:167], v[120:123]
	v_mfma_f32_16x16x32_bf16 v[116:119], v[148:151], v[172:175], v[116:119]
	v_mfma_f32_16x16x32_bf16 v[112:115], v[156:159], v[172:175], v[112:115]
	v_mfma_f32_16x16x32_bf16 v[104:107], v[148:151], v[180:183], v[104:107]
	v_mfma_f32_16x16x32_bf16 v[96:99], v[156:159], v[180:183], v[96:99]
	v_mfma_f32_16x16x32_bf16 v[88:91], v[148:151], v[188:191], v[88:91]
	v_mfma_f32_16x16x32_bf16 v[80:83], v[156:159], v[188:191], v[80:83]
	s_setprio 1
	s_barrier
	s_add_i32 s36, s56, s3
	v_lshl_add_u64 v[204:205], s[40:41], 0, v[130:131]
	s_mov_b32 m0, s36
	ds_read_b128 v[192:195], v143
	ds_read_b128 v[196:199], v143 offset:1024
	ds_read_b128 v[200:203], v143 offset:2048
	ds_read_b128 v[208:211], v143 offset:3072
	global_load_lds_dwordx4 v[204:205], off
	v_lshl_add_u64 v[212:213], s[40:41], 0, v[128:129]
	s_add_i32 m0, s36, 0x2000
	s_nop 0
	global_load_lds_dwordx4 v[212:213], off
	s_barrier
	s_waitcnt lgkmcnt(0)
	s_setprio 0
	s_waitcnt lgkmcnt(0)
	v_mfma_f32_16x16x32_bf16 v[108:111], v[192:195], v[160:163], v[108:111]
	v_mfma_f32_16x16x32_bf16 v[100:103], v[200:203], v[160:163], v[100:103]
	v_mfma_f32_16x16x32_bf16 v[92:95], v[192:195], v[168:171], v[92:95]
	v_mfma_f32_16x16x32_bf16 v[84:87], v[200:203], v[168:171], v[84:87]
	v_mfma_f32_16x16x32_bf16 v[76:79], v[192:195], v[176:179], v[76:79]
	v_mfma_f32_16x16x32_bf16 v[72:75], v[200:203], v[176:179], v[72:75]
	v_mfma_f32_16x16x32_bf16 v[68:71], v[192:195], v[184:187], v[68:71]
	v_mfma_f32_16x16x32_bf16 v[64:67], v[200:203], v[184:187], v[64:67]
	v_mfma_f32_16x16x32_bf16 v[108:111], v[196:199], v[164:167], v[108:111]
	v_mfma_f32_16x16x32_bf16 v[100:103], v[208:211], v[164:167], v[100:103]
	v_mfma_f32_16x16x32_bf16 v[92:95], v[196:199], v[172:175], v[92:95]
	v_mfma_f32_16x16x32_bf16 v[84:87], v[208:211], v[172:175], v[84:87]
	v_mfma_f32_16x16x32_bf16 v[76:79], v[196:199], v[180:183], v[76:79]
	v_mfma_f32_16x16x32_bf16 v[72:75], v[208:211], v[180:183], v[72:75]
	v_mfma_f32_16x16x32_bf16 v[68:71], v[196:199], v[188:191], v[68:71]
	v_mfma_f32_16x16x32_bf16 v[64:67], v[208:211], v[188:191], v[64:67]
	s_setprio 1
	s_mov_b32 m0, s20
	v_lshl_add_u64 v[214:215], s[52:53], 0, v[130:131]
	s_barrier
	ds_read_b128 v[160:163], v142 offset:16384
	ds_read_b128 v[164:167], v142 offset:17408
	ds_read_b128 v[168:171], v142 offset:18432
	ds_read_b128 v[172:175], v142 offset:19456
	ds_read_b128 v[176:179], v142 offset:20480
	ds_read_b128 v[180:183], v142 offset:21504
	ds_read_b128 v[184:187], v142 offset:22528
	ds_read_b128 v[188:191], v142 offset:23552
	global_load_lds_dwordx4 v[214:215], off
	v_lshl_add_u64 v[216:217], s[52:53], 0, v[128:129]
	s_mov_b32 m0, s21
	s_nop 0
	global_load_lds_dwordx4 v[216:217], off
	s_barrier
	s_waitcnt lgkmcnt(0)
	s_setprio 0
	s_waitcnt lgkmcnt(0)
	v_mfma_f32_16x16x32_bf16 v[60:63], v[144:147], v[160:163], v[60:63]
	v_mfma_f32_16x16x32_bf16 v[56:59], v[152:155], v[160:163], v[56:59]
	v_mfma_f32_16x16x32_bf16 v[52:55], v[144:147], v[168:171], v[52:55]
	v_mfma_f32_16x16x32_bf16 v[48:51], v[152:155], v[168:171], v[48:51]
	v_mfma_f32_16x16x32_bf16 v[40:43], v[144:147], v[176:179], v[40:43]
	v_mfma_f32_16x16x32_bf16 v[32:35], v[152:155], v[176:179], v[32:35]
	v_mfma_f32_16x16x32_bf16 v[24:27], v[144:147], v[184:187], v[24:27]
	v_mfma_f32_16x16x32_bf16 v[16:19], v[152:155], v[184:187], v[16:19]
	v_mfma_f32_16x16x32_bf16 v[60:63], v[148:151], v[164:167], v[60:63]
	v_mfma_f32_16x16x32_bf16 v[56:59], v[156:159], v[164:167], v[56:59]
	v_mfma_f32_16x16x32_bf16 v[52:55], v[148:151], v[172:175], v[52:55]
	v_mfma_f32_16x16x32_bf16 v[48:51], v[156:159], v[172:175], v[48:51]
	v_mfma_f32_16x16x32_bf16 v[40:43], v[148:151], v[180:183], v[40:43]
	v_mfma_f32_16x16x32_bf16 v[32:35], v[156:159], v[180:183], v[32:35]
	v_mfma_f32_16x16x32_bf16 v[24:27], v[148:151], v[188:191], v[24:27]
	v_mfma_f32_16x16x32_bf16 v[16:19], v[156:159], v[188:191], v[16:19]
	s_setprio 1
	s_barrier
; #define WAIT_V(n) asm volatile("s_waitcnt vmcnt(" #n ")" ::: "memory")
; #define WAIT_L(n) asm volatile("s_waitcnt lgkmcnt(" #n ")" ::: "memory")
; #define BAR __builtin_amdgcn_s_barrier()
; #define SCHED __builtin_amdgcn_sched_barrier(0)
; template <class Get, class Epi>
; DI void gemm_stream(LAS unsigned char* lds, const int K, const int ld, Get get, Epi epi) {
;     ...
;             STAGE(SBo(0, 1), b2 + hstep);
;             WAIT_V(6); BAR; MMA(1, 1, At, B1); BAR;
;             LDB(B0, 1, 0); SCHED; LDA(At, 1, 0); STAGE(SAo(0, 1), a2 + hstep);
;             WAIT_L(8); BAR; WAIT_L(0); MMA(0, 0, At, B0); BAR; SCHED;
;             LDB(B1, 1, 1); STAGE(SBo(1, 0), b3);
;             BAR; WAIT_L(0); MMA(0, 1, At, B1); BAR;
;             LDA(At, 1, 1); STAGE(SAo(1, 0), a3);
;             BAR; WAIT_L(0); MMA(1, 0, At, B0); BAR; SCHED;
	s_add_u32 s36, s40, 0x160000
	s_addc_u32 s37, s41, 0
	s_add_i32 s78, s57, s3
	v_lshl_add_u64 v[144:145], s[36:37], 0, v[130:131]
	s_mov_b32 m0, s78
	s_nop 0
	global_load_lds_dwordx4 v[144:145], off
	v_lshl_add_u64 v[144:145], s[36:37], 0, v[128:129]
	s_add_i32 m0, s78, 0x2000
	s_nop 0
	global_load_lds_dwordx4 v[144:145], off
	s_waitcnt vmcnt(6)
	s_barrier
	s_setprio 0
	v_mfma_f32_16x16x32_bf16 v[44:47], v[192:195], v[160:163], v[44:47]
	v_mfma_f32_16x16x32_bf16 v[36:39], v[200:203], v[160:163], v[36:39]
	v_mfma_f32_16x16x32_bf16 v[28:31], v[192:195], v[168:171], v[28:31]
	v_mfma_f32_16x16x32_bf16 v[20:23], v[200:203], v[168:171], v[20:23]
	v_mfma_f32_16x16x32_bf16 v[12:15], v[192:195], v[176:179], v[12:15]
	v_mfma_f32_16x16x32_bf16 v[8:11], v[200:203], v[176:179], v[8:11]
	v_mfma_f32_16x16x32_bf16 v[4:7], v[192:195], v[184:187], v[4:7]
	v_mfma_f32_16x16x32_bf16 v[0:3], v[200:203], v[184:187], v[0:3]
	v_mfma_f32_16x16x32_bf16 v[44:47], v[196:199], v[164:167], v[44:47]
	v_mfma_f32_16x16x32_bf16 v[36:39], v[208:211], v[164:167], v[36:39]
	v_mfma_f32_16x16x32_bf16 v[28:31], v[196:199], v[172:175], v[28:31]
	v_mfma_f32_16x16x32_bf16 v[20:23], v[208:211], v[172:175], v[20:23]
	v_mfma_f32_16x16x32_bf16 v[12:15], v[196:199], v[180:183], v[12:15]
	v_mfma_f32_16x16x32_bf16 v[8:11], v[208:211], v[180:183], v[8:11]
	v_mfma_f32_16x16x32_bf16 v[4:7], v[196:199], v[188:191], v[4:7]
	v_mfma_f32_16x16x32_bf16 v[0:3], v[208:211], v[188:191], v[0:3]
	s_setprio 1
	s_add_i32 s78, 16, 0x18000
	v_add_u32_e32 v132, s78, v140
	s_barrier
	ds_read_b128 v[144:147], v132
	ds_read_b128 v[148:151], v132 offset:1024
	ds_read_b128 v[152:155], v132 offset:2048
	ds_read_b128 v[156:159], v132 offset:3072
	s_add_u32 s36, s52, 0x160000
	s_addc_u32 s37, s53, 0
	s_mov_b32 m0, s23
	v_lshl_add_u64 v[192:193], s[36:37], 0, v[130:131]
	ds_read_b128 v[160:163], v142 offset:32768
	ds_read_b128 v[164:167], v142 offset:33792
	ds_read_b128 v[168:171], v142 offset:34816
	ds_read_b128 v[172:175], v142 offset:35840
	ds_read_b128 v[176:179], v142 offset:36864
	ds_read_b128 v[180:183], v142 offset:37888
	ds_read_b128 v[184:187], v142 offset:38912
	ds_read_b128 v[188:191], v142 offset:39936
	global_load_lds_dwordx4 v[192:193], off
	v_lshl_add_u64 v[192:193], s[36:37], 0, v[128:129]
	s_mov_b32 m0, s28
	s_nop 0
	global_load_lds_dwordx4 v[192:193], off
	s_waitcnt lgkmcnt(8)
	s_barrier
	s_waitcnt lgkmcnt(0)
	s_setprio 0
	s_waitcnt lgkmcnt(0)
	v_mfma_f32_16x16x32_bf16 v[124:127], v[144:147], v[160:163], v[124:127]
	v_mfma_f32_16x16x32_bf16 v[120:123], v[152:155], v[160:163], v[120:123]
	v_mfma_f32_16x16x32_bf16 v[116:119], v[144:147], v[168:171], v[116:119]
	v_mfma_f32_16x16x32_bf16 v[112:115], v[152:155], v[168:171], v[112:115]
	v_mfma_f32_16x16x32_bf16 v[104:107], v[144:147], v[176:179], v[104:107]
	v_mfma_f32_16x16x32_bf16 v[96:99], v[152:155], v[176:179], v[96:99]
	v_mfma_f32_16x16x32_bf16 v[88:91], v[144:147], v[184:187], v[88:91]
	v_mfma_f32_16x16x32_bf16 v[80:83], v[152:155], v[184:187], v[80:83]
	v_mfma_f32_16x16x32_bf16 v[124:127], v[148:151], v[164:167], v[124:127]
	v_mfma_f32_16x16x32_bf16 v[120:123], v[156:159], v[164:167], v[120:123]
	v_mfma_f32_16x16x32_bf16 v[116:119], v[148:151], v[172:175], v[116:119]
	v_mfma_f32_16x16x32_bf16 v[112:115], v[156:159], v[172:175], v[112:115]
	v_mfma_f32_16x16x32_bf16 v[104:107], v[148:151], v[180:183], v[104:107]
	v_mfma_f32_16x16x32_bf16 v[96:99], v[156:159], v[180:183], v[96:99]
	v_mfma_f32_16x16x32_bf16 v[88:91], v[148:151], v[188:191], v[88:91]
	v_mfma_f32_16x16x32_bf16 v[80:83], v[156:159], v[188:191], v[80:83]
	s_setprio 1
	s_barrier
	s_add_i32 s52, 16, 0x1c000
	s_add_i32 s36, s78, s3
	v_add_u32_e32 v132, s52, v140
	v_lshl_add_u64 v[204:205], v[204:205], 0, s[8:9]
	s_mov_b32 m0, s36
	ds_read_b128 v[192:195], v132
	ds_read_b128 v[196:199], v132 offset:1024
	ds_read_b128 v[200:203], v132 offset:2048
	ds_read_b128 v[208:211], v132 offset:3072
	global_load_lds_dwordx4 v[204:205], off
	v_lshl_add_u64 v[204:205], v[212:213], 0, s[8:9]
	s_add_i32 m0, s36, 0x2000
	s_nop 0
	global_load_lds_dwordx4 v[204:205], off
	s_barrier
	s_waitcnt lgkmcnt(0)
	s_setprio 0
	s_waitcnt lgkmcnt(0)
	v_mfma_f32_16x16x32_bf16 v[108:111], v[192:195], v[160:163], v[108:111]
	v_mfma_f32_16x16x32_bf16 v[100:103], v[200:203], v[160:163], v[100:103]
	v_mfma_f32_16x16x32_bf16 v[92:95], v[192:195], v[168:171], v[92:95]
	v_mfma_f32_16x16x32_bf16 v[84:87], v[200:203], v[168:171], v[84:87]
	v_mfma_f32_16x16x32_bf16 v[76:79], v[192:195], v[176:179], v[76:79]
	v_mfma_f32_16x16x32_bf16 v[72:75], v[200:203], v[176:179], v[72:75]
	v_mfma_f32_16x16x32_bf16 v[68:71], v[192:195], v[184:187], v[68:71]
	v_mfma_f32_16x16x32_bf16 v[64:67], v[200:203], v[184:187], v[64:67]
	v_mfma_f32_16x16x32_bf16 v[108:111], v[196:199], v[164:167], v[108:111]
	v_mfma_f32_16x16x32_bf16 v[100:103], v[208:211], v[164:167], v[100:103]
	v_mfma_f32_16x16x32_bf16 v[92:95], v[196:199], v[172:175], v[92:95]
	v_mfma_f32_16x16x32_bf16 v[84:87], v[208:211], v[172:175], v[84:87]
	v_mfma_f32_16x16x32_bf16 v[76:79], v[196:199], v[180:183], v[76:79]
	v_mfma_f32_16x16x32_bf16 v[72:75], v[208:211], v[180:183], v[72:75]
	v_mfma_f32_16x16x32_bf16 v[68:71], v[196:199], v[188:191], v[68:71]
	v_mfma_f32_16x16x32_bf16 v[64:67], v[208:211], v[188:191], v[64:67]
	s_setprio 1
	s_mov_b32 m0, s29
	v_lshl_add_u64 v[204:205], v[214:215], 0, s[8:9]
	s_barrier
	ds_read_b128 v[160:163], v142 offset:49152
	ds_read_b128 v[164:167], v142 offset:50176
	ds_read_b128 v[168:171], v142 offset:51200
	ds_read_b128 v[172:175], v142 offset:52224
	ds_read_b128 v[176:179], v142 offset:53248
	ds_read_b128 v[180:183], v142 offset:54272
	ds_read_b128 v[184:187], v142 offset:55296
	ds_read_b128 v[188:191], v142 offset:56320
	global_load_lds_dwordx4 v[204:205], off
	v_lshl_add_u64 v[204:205], v[216:217], 0, s[8:9]
	s_mov_b32 m0, s35
	s_nop 0
	global_load_lds_dwordx4 v[204:205], off
	s_barrier
; #define WAIT_V(n) asm volatile("s_waitcnt vmcnt(" #n ")" ::: "memory")
; #define WAIT_L(n) asm volatile("s_waitcnt lgkmcnt(" #n ")" ::: "memory")
; #define BAR __builtin_amdgcn_s_barrier()
; #define SCHED __builtin_amdgcn_sched_barrier(0)
; #define EPI_DONE do { } while (0)
; template <class Get, class Epi>
; DI void gemm_stream(LAS unsigned char* lds, const int K, const int ld, Get get, Epi epi) {
;     ...
;             BAR; WAIT_L(0); MMA(1, 0, At, B0); BAR; SCHED;
;             STAGE(SBo(1, 1), b3 + hstep);
;             WAIT_V(6); BAR; MMA(1, 1, At, B1); BAR;
;         }
;         epi(acc, cur);
; DI void epi_part(const Acc& acc, const P& p, int brow, int bcol, int sl) {
;     EPI_IDX
;     const int b = brow / PB;
;     float* part = (float*)(p.ws + O_PART) + ((size_t)sl * (NBATCH * CTXL) + b * CTXL) * DM;
; #pragma unroll
;     for (int ai = 0; ai < 2; ++ai)
; #pragma unroll
;         for (int m = 0; m < 4; ++m) {
;             float* rp = part + (size_t)(ai * 128 + wr * 64 + m * 16 + fr) * DM + bcol + wc * 32 + fq * 4;
; #pragma unroll
;             for (int bj = 0; bj < 2; ++bj)
; #pragma unroll
;                 for (int n = 0; n < 2; ++n) *(f32x4*)(rp + bj * 128 + n * 16) = acc[ai][bj][m][n];
;         }
;     EPI_DONE;
; }
	s_waitcnt lgkmcnt(0)
	s_setprio 0
	s_waitcnt lgkmcnt(0)
	v_mfma_f32_16x16x32_bf16 v[60:63], v[144:147], v[160:163], v[60:63]
	v_mfma_f32_16x16x32_bf16 v[56:59], v[152:155], v[160:163], v[56:59]
	v_mfma_f32_16x16x32_bf16 v[52:55], v[144:147], v[168:171], v[52:55]
	v_mfma_f32_16x16x32_bf16 v[48:51], v[152:155], v[168:171], v[48:51]
	v_mfma_f32_16x16x32_bf16 v[40:43], v[144:147], v[176:179], v[40:43]
	v_mfma_f32_16x16x32_bf16 v[32:35], v[152:155], v[176:179], v[32:35]
	v_mfma_f32_16x16x32_bf16 v[24:27], v[144:147], v[184:187], v[24:27]
	v_mfma_f32_16x16x32_bf16 v[16:19], v[152:155], v[184:187], v[16:19]
	v_mfma_f32_16x16x32_bf16 v[60:63], v[148:151], v[164:167], v[60:63]
	v_mfma_f32_16x16x32_bf16 v[56:59], v[156:159], v[164:167], v[56:59]
	v_mfma_f32_16x16x32_bf16 v[52:55], v[148:151], v[172:175], v[52:55]
	v_mfma_f32_16x16x32_bf16 v[48:51], v[156:159], v[172:175], v[48:51]
	v_mfma_f32_16x16x32_bf16 v[40:43], v[148:151], v[180:183], v[40:43]
	v_mfma_f32_16x16x32_bf16 v[32:35], v[156:159], v[180:183], v[32:35]
	v_mfma_f32_16x16x32_bf16 v[24:27], v[148:151], v[188:191], v[24:27]
	v_mfma_f32_16x16x32_bf16 v[16:19], v[156:159], v[188:191], v[16:19]
	s_setprio 1
	s_barrier
	s_add_u32 s36, s40, 0x160080
	s_addc_u32 s37, s41, 0
	s_add_i32 s40, s52, s3
	v_lshl_add_u64 v[144:145], s[36:37], 0, v[130:131]
	s_mov_b32 m0, s40
	s_nop 0
	global_load_lds_dwordx4 v[144:145], off
	v_lshl_add_u64 v[144:145], s[36:37], 0, v[128:129]
	s_add_i32 m0, s40, 0x2000
	s_nop 0
	global_load_lds_dwordx4 v[144:145], off
	s_waitcnt vmcnt(6)
	s_barrier
	s_setprio 0
	v_mfma_f32_16x16x32_bf16 v[44:47], v[192:195], v[160:163], v[44:47]
	v_mfma_f32_16x16x32_bf16 v[36:39], v[200:203], v[160:163], v[36:39]
	v_mfma_f32_16x16x32_bf16 v[28:31], v[192:195], v[168:171], v[28:31]
	v_mfma_f32_16x16x32_bf16 v[20:23], v[200:203], v[168:171], v[20:23]
	v_mfma_f32_16x16x32_bf16 v[12:15], v[192:195], v[176:179], v[12:15]
	v_mfma_f32_16x16x32_bf16 v[8:11], v[200:203], v[176:179], v[8:11]
	v_mfma_f32_16x16x32_bf16 v[4:7], v[192:195], v[184:187], v[4:7]
	v_mfma_f32_16x16x32_bf16 v[0:3], v[200:203], v[184:187], v[0:3]
	v_mfma_f32_16x16x32_bf16 v[44:47], v[196:199], v[164:167], v[44:47]
	v_mfma_f32_16x16x32_bf16 v[36:39], v[208:211], v[164:167], v[36:39]
	v_mfma_f32_16x16x32_bf16 v[28:31], v[196:199], v[172:175], v[28:31]
	v_mfma_f32_16x16x32_bf16 v[20:23], v[208:211], v[172:175], v[20:23]
	v_mfma_f32_16x16x32_bf16 v[12:15], v[196:199], v[180:183], v[12:15]
	v_mfma_f32_16x16x32_bf16 v[8:11], v[208:211], v[180:183], v[8:11]
	v_mfma_f32_16x16x32_bf16 v[4:7], v[196:199], v[188:191], v[4:7]
	v_mfma_f32_16x16x32_bf16 v[0:3], v[208:211], v[188:191], v[0:3]
	s_setprio 1
	s_add_i32 s77, s77, 2
	s_add_u32 s0, s0, 0x100
	s_addc_u32 s76, s76, 0
	s_cmp_gt_u32 s77, 5
	s_mov_b64 s[36:37], s[38:39]
	s_barrier
	s_cbranch_scc0 .LBB0_1964
	s_mul_hi_i32 s0, s75, 0x78787879
	s_lshr_b32 s37, s0, 31
	s_lshr_b32 s0, s0, 3
	s_ashr_i32 s36, s61, 4
	s_add_i32 s0, s0, s37
	s_ashr_i32 s37, s36, 31
	s_lshl_b32 s38, s0, 8
	s_ashr_i32 s39, s38, 31
	s_lshl_b64 s[36:37], s[36:37], 23
	s_add_u32 s0, s54, s36
	s_addc_u32 s40, s55, s37
	s_lshl_b64 s[36:37], s[38:39], 13
	s_add_u32 s0, s0, s36
	v_mov_b32_e32 v145, v206
	s_addc_u32 s37, s40, s37
	s_lshl_b32 s36, s61, 10
	s_and_b32 s36, s36, 0x3c00
	v_and_b32_e32 v132, 15, v145
	v_ashrrev_i32_e32 v144, 2, v145
	v_and_or_b32 v144, v144, s58, v132
	s_add_u32 s36, s0, s36
	v_lshlrev_b32_e32 v132, 1, v145
	s_addc_u32 s37, s37, 0
	v_and_b32_e32 v132, 0x180, v132
	v_lshl_add_u64 v[146:147], s[36:37], 0, v[132:133]
	v_and_b32_e32 v132, 48, v145
	v_ashrrev_i32_e32 v145, 31, v144
	v_lshl_add_u64 v[146:147], v[146:147], 0, v[132:133]
	v_lshlrev_b64 v[148:149], 13, v[144:145]
	v_lshl_add_u64 v[148:149], v[146:147], 0, v[148:149]
	global_store_dwordx4 v[148:149], v[124:127], off
	global_store_dwordx4 v[148:149], v[120:123], off offset:64
	global_store_dwordx4 v[148:149], v[108:111], off offset:512
	global_store_dwordx4 v[148:149], v[100:103], off offset:576
	s_mov_b32 s61, s74
	s_mov_b32 s75, s63
	v_or_b32_e32 v100, 16, v144
	v_ashrrev_i32_e32 v101, 31, v100
	v_lshlrev_b64 v[100:101], 13, v[100:101]
	v_lshl_add_u64 v[100:101], v[146:147], 0, v[100:101]
	global_store_dwordx4 v[100:101], v[116:119], off
	global_store_dwordx4 v[100:101], v[112:115], off offset:64
	global_store_dwordx4 v[100:101], v[92:95], off offset:512
	global_store_dwordx4 v[100:101], v[84:87], off offset:576
	s_mov_b64 s[38:39], s[18:19]
	s_mov_b64 s[36:37], s[16:17]
	v_or_b32_e32 v84, 32, v144
	v_ashrrev_i32_e32 v85, 31, v84
	v_lshlrev_b64 v[84:85], 13, v[84:85]
	v_lshl_add_u64 v[84:85], v[146:147], 0, v[84:85]
	global_store_dwordx4 v[84:85], v[104:107], off
	global_store_dwordx4 v[84:85], v[96:99], off offset:64
	global_store_dwordx4 v[84:85], v[76:79], off offset:512
	global_store_dwordx4 v[84:85], v[72:75], off offset:576
	s_nop 1
	v_or_b32_e32 v72, 48, v144
	v_ashrrev_i32_e32 v73, 31, v72
	v_lshlrev_b64 v[72:73], 13, v[72:73]
	v_lshl_add_u64 v[72:73], v[146:147], 0, v[72:73]
	global_store_dwordx4 v[72:73], v[88:91], off
	global_store_dwordx4 v[72:73], v[80:83], off offset:64
	global_store_dwordx4 v[72:73], v[68:71], off offset:512
	global_store_dwordx4 v[72:73], v[64:67], off offset:576
	s_nop 1
	v_add_co_u32_e32 v66, vcc, s59, v148
	v_lshl_add_u64 v[64:65], v[148:149], 0, s[10:11]
	s_nop 0
	v_addc_co_u32_e32 v67, vcc, 0, v149, vcc
	global_store_dwordx4 v[66:67], v[60:63], off
	global_store_dwordx4 v[64:65], v[56:59], off offset:64
	global_store_dwordx4 v[64:65], v[44:47], off offset:512
	global_store_dwordx4 v[64:65], v[36:39], off offset:576
	s_nop 1
	v_add_co_u32_e32 v38, vcc, s60, v148
	v_lshl_add_u64 v[36:37], v[148:149], 0, s[12:13]
	s_nop 0
	v_addc_co_u32_e32 v39, vcc, 0, v149, vcc
	global_store_dwordx4 v[38:39], v[52:55], off
	global_store_dwordx4 v[36:37], v[48:51], off offset:64
	global_store_dwordx4 v[36:37], v[28:31], off offset:512
	global_store_dwordx4 v[36:37], v[20:23], off offset:576
	s_nop 1
	v_add_co_u32_e32 v22, vcc, 0x140000, v148
	v_lshl_add_u64 v[20:21], v[148:149], 0, s[14:15]
	s_nop 0
	v_addc_co_u32_e32 v23, vcc, 0, v149, vcc
	global_store_dwordx4 v[22:23], v[40:43], off
	global_store_dwordx4 v[20:21], v[32:35], off offset:64
	global_store_dwordx4 v[20:21], v[12:15], off offset:512
	global_store_dwordx4 v[20:21], v[8:11], off offset:576
	s_nop 1
	v_add_co_u32_e32 v10, vcc, 0x160000, v148
	v_lshl_add_u64 v[8:9], v[148:149], 0, s[6:7]
	s_nop 0
	v_addc_co_u32_e32 v11, vcc, 0, v149, vcc
	s_and_b64 vcc, exec, s[4:5]
	global_store_dwordx4 v[10:11], v[24:27], off
	global_store_dwordx4 v[8:9], v[16:19], off offset:64
	global_store_dwordx4 v[8:9], v[4:7], off offset:512
	global_store_dwordx4 v[8:9], v[0:3], off offset:576
	s_cbranch_vccz .LBB0_1961
	s_waitcnt vmcnt(0)
	s_cmpk_gt_u32 s2, 0xff
	s_cbranch_scc1 .LBB0_1968
	s_barrier

; #define WAIT_V(n) asm volatile("s_waitcnt vmcnt(" #n ")" ::: "memory")
; #define WAIT_L(n) asm volatile("s_waitcnt lgkmcnt(" #n ")" ::: "memory")
; #define BAR __builtin_amdgcn_s_barrier()
; #define SCHED __builtin_amdgcn_sched_barrier(0)
; template <class Get, class Epi>
; DI void gemm_stream(LAS unsigned char* lds, const int K, const int ld, Get get, Epi epi) {
;     ...
;         for (int t = 0; t < nt; t += 2) {
;             const bool last = (t == nt - 2);
;             const char* a1 = cA + (size_t)(t + 1) * kstep;
;             const char* a2 = last ? nA : cA + (size_t)(t + 2) * kstep;
;             const char* b2 = last ? nB : cB + (size_t)(t + 2) * kstep;
;             const char* a3 = a2 + kstep;
;             const char* b3 = b2 + kstep;
;             LDB(B0, 0, 0); SCHED; LDA(At, 0, 0); STAGE(SAo(1, 1), a1 + hstep);
;             WAIT_L(8); BAR; WAIT_L(0); MMA(0, 0, At, B0); BAR; SCHED;
;             LDB(B1, 0, 1); STAGE(SBo(0, 0), b2);
;             BAR; WAIT_L(0); MMA(0, 1, At, B1); BAR;
;             LDA(At, 0, 1); STAGE(SAo(0, 0), a2);
;             BAR; WAIT_L(0); MMA(1, 0, At, B0); BAR; SCHED;
;             STAGE(SBo(0, 1), b2 + hstep);
;             WAIT_V(6); BAR; MMA(1, 1, At, B1); BAR;
;             LDB(B0, 1, 0); SCHED; LDA(At, 1, 0); STAGE(SAo(0, 1), a2 + hstep);
;             WAIT_L(8); BAR; WAIT_L(0); MMA(0, 0, At, B0); BAR; SCHED;
;             LDB(B1, 1, 1); STAGE(SBo(1, 0), b3);
;             BAR; WAIT_L(0); MMA(0, 1, At, B1); BAR;
; DI void phase_inproj1(const P& p, char* shm) {
;     ...
;     auto get = [&](int i, Unit& u) {
;         const long L = (long)i * gridDim.x + blockIdx.x;
;         if (L >= 3072 + 96) return false;
;         if (L < 3072) { int pm; tile_of((int)L, 64, 48, pm, u.pn); u.pm = (pm >> 4) * 17 + 1 + (pm & 15); }
;         else { const int j = (int)L - 3072; u.pm = (j / 24) * 17; u.pn = 8 + j % 24; }
;         const char* hp = H + (size_t)u.pm * 256 * DM * 2;
;         const char* wp = W + (size_t)u.pn * 256 * DM * 2;
;         const bool tr = u.pn >= 16 && u.pn < 32;
;         u.A = tr ? wp : hp; u.B = tr ? hp : wp;
;         return true;
;     };
.LBB0_2102:
	ds_read_b128 v[128:131], v209
	ds_read_b128 v[132:135], v209 offset:1024
	ds_read_b128 v[136:139], v209 offset:2048
	ds_read_b128 v[156:159], v209 offset:3072
	s_add_u32 s28, s64, 0xfff80080
	s_addc_u32 s29, s65, -1
	s_cmp_eq_u32 s7, 28
	s_cselect_b32 s77, s59, s29
	s_cselect_b32 s76, s58, s28
	s_cselect_b32 s75, s61, s3
	s_cselect_b32 s74, s60, s2
	v_lshl_add_u64 v[140:141], s[64:65], 0, v[148:149]
	s_add_i32 m0, s23, 0xc000
	ds_read_b128 v[160:163], v210
	ds_read_b128 v[164:167], v210 offset:1024
	ds_read_b128 v[168:171], v210 offset:2048
	ds_read_b128 v[172:175], v210 offset:3072
	ds_read_b128 v[176:179], v210 offset:4096
	ds_read_b128 v[180:183], v210 offset:5120
	ds_read_b128 v[184:187], v210 offset:6144
	ds_read_b128 v[188:191], v210 offset:7168
	global_load_lds_dwordx4 v[140:141], off
	v_lshl_add_u64 v[140:141], s[64:65], 0, v[150:151]
	s_add_i32 m0, s23, 0xe000
	s_nop 0
	global_load_lds_dwordx4 v[140:141], off
	s_waitcnt lgkmcnt(8)
	s_barrier
	s_waitcnt lgkmcnt(0)
	s_setprio 0
	s_waitcnt lgkmcnt(0)
	v_mfma_f32_16x16x32_bf16 v[124:127], v[128:131], v[160:163], v[124:127]
	v_mfma_f32_16x16x32_bf16 v[116:119], v[136:139], v[160:163], v[116:119]
	v_mfma_f32_16x16x32_bf16 v[108:111], v[128:131], v[168:171], v[108:111]
	v_mfma_f32_16x16x32_bf16 v[100:103], v[136:139], v[168:171], v[100:103]
	v_mfma_f32_16x16x32_bf16 v[92:95], v[128:131], v[176:179], v[92:95]
	v_mfma_f32_16x16x32_bf16 v[84:87], v[136:139], v[176:179], v[84:87]
	v_mfma_f32_16x16x32_bf16 v[76:79], v[128:131], v[184:187], v[76:79]
	v_mfma_f32_16x16x32_bf16 v[68:71], v[136:139], v[184:187], v[68:71]
	v_mfma_f32_16x16x32_bf16 v[124:127], v[132:135], v[164:167], v[124:127]
	v_mfma_f32_16x16x32_bf16 v[116:119], v[156:159], v[164:167], v[116:119]
	v_mfma_f32_16x16x32_bf16 v[108:111], v[132:135], v[172:175], v[108:111]
	v_mfma_f32_16x16x32_bf16 v[100:103], v[156:159], v[172:175], v[100:103]
	v_mfma_f32_16x16x32_bf16 v[92:95], v[132:135], v[180:183], v[92:95]
	v_mfma_f32_16x16x32_bf16 v[84:87], v[156:159], v[180:183], v[84:87]
	v_mfma_f32_16x16x32_bf16 v[76:79], v[132:135], v[188:191], v[76:79]
	v_mfma_f32_16x16x32_bf16 v[68:71], v[156:159], v[188:191], v[68:71]
	s_setprio 1
	s_barrier
	s_add_i32 s28, s90, s21
	v_lshl_add_u64 v[140:141], s[74:75], 0, v[142:143]
	s_mov_b32 m0, s28
	ds_read_b128 v[192:195], v211
	ds_read_b128 v[196:199], v211 offset:1024
	ds_read_b128 v[200:203], v211 offset:2048
	ds_read_b128 v[212:215], v211 offset:3072
	global_load_lds_dwordx4 v[140:141], off
	v_lshl_add_u64 v[204:205], s[74:75], 0, v[144:145]
	s_add_i32 m0, s28, 0x2000
	s_nop 0
	global_load_lds_dwordx4 v[204:205], off
	s_barrier
	s_waitcnt lgkmcnt(0)
	s_setprio 0
	s_waitcnt lgkmcnt(0)
	v_mfma_f32_16x16x32_bf16 v[120:123], v[192:195], v[160:163], v[120:123]
	v_mfma_f32_16x16x32_bf16 v[112:115], v[200:203], v[160:163], v[112:115]
	v_mfma_f32_16x16x32_bf16 v[104:107], v[192:195], v[168:171], v[104:107]
	v_mfma_f32_16x16x32_bf16 v[96:99], v[200:203], v[168:171], v[96:99]
	v_mfma_f32_16x16x32_bf16 v[88:91], v[192:195], v[176:179], v[88:91]
	v_mfma_f32_16x16x32_bf16 v[80:83], v[200:203], v[176:179], v[80:83]
	v_mfma_f32_16x16x32_bf16 v[72:75], v[192:195], v[184:187], v[72:75]
	v_mfma_f32_16x16x32_bf16 v[64:67], v[200:203], v[184:187], v[64:67]
	v_mfma_f32_16x16x32_bf16 v[120:123], v[196:199], v[164:167], v[120:123]
	v_mfma_f32_16x16x32_bf16 v[112:115], v[212:215], v[164:167], v[112:115]
	v_mfma_f32_16x16x32_bf16 v[104:107], v[196:199], v[172:175], v[104:107]
	v_mfma_f32_16x16x32_bf16 v[96:99], v[212:215], v[172:175], v[96:99]
	v_mfma_f32_16x16x32_bf16 v[88:91], v[196:199], v[180:183], v[88:91]
	v_mfma_f32_16x16x32_bf16 v[80:83], v[212:215], v[180:183], v[80:83]
	v_mfma_f32_16x16x32_bf16 v[72:75], v[196:199], v[188:191], v[72:75]
	v_mfma_f32_16x16x32_bf16 v[64:67], v[212:215], v[188:191], v[64:67]
	s_setprio 1
	s_mov_b32 m0, s23
	v_lshl_add_u64 v[216:217], s[76:77], 0, v[142:143]
	s_barrier
	ds_read_b128 v[160:163], v210 offset:16384
	ds_read_b128 v[164:167], v210 offset:17408
	ds_read_b128 v[168:171], v210 offset:18432
	ds_read_b128 v[172:175], v210 offset:19456
	ds_read_b128 v[176:179], v210 offset:20480
	ds_read_b128 v[180:183], v210 offset:21504
	ds_read_b128 v[184:187], v210 offset:22528
	ds_read_b128 v[188:191], v210 offset:23552
	global_load_lds_dwordx4 v[216:217], off
	v_lshl_add_u64 v[218:219], s[76:77], 0, v[144:145]
	s_mov_b32 m0, s35
	s_nop 0
	global_load_lds_dwordx4 v[218:219], off
	s_barrier
	s_waitcnt lgkmcnt(0)
	s_setprio 0
	s_waitcnt lgkmcnt(0)
	v_mfma_f32_16x16x32_bf16 v[60:63], v[128:131], v[160:163], v[60:63]
	v_mfma_f32_16x16x32_bf16 v[52:55], v[136:139], v[160:163], v[52:55]
	v_mfma_f32_16x16x32_bf16 v[44:47], v[128:131], v[168:171], v[44:47]
	v_mfma_f32_16x16x32_bf16 v[36:39], v[136:139], v[168:171], v[36:39]
	v_mfma_f32_16x16x32_bf16 v[28:31], v[128:131], v[176:179], v[28:31]
	v_mfma_f32_16x16x32_bf16 v[20:23], v[136:139], v[176:179], v[20:23]
	v_mfma_f32_16x16x32_bf16 v[12:15], v[128:131], v[184:187], v[12:15]
	v_mfma_f32_16x16x32_bf16 v[4:7], v[136:139], v[184:187], v[4:7]
	v_mfma_f32_16x16x32_bf16 v[60:63], v[132:135], v[164:167], v[60:63]
	v_mfma_f32_16x16x32_bf16 v[52:55], v[156:159], v[164:167], v[52:55]
	v_mfma_f32_16x16x32_bf16 v[44:47], v[132:135], v[172:175], v[44:47]
	v_mfma_f32_16x16x32_bf16 v[36:39], v[156:159], v[172:175], v[36:39]
	v_mfma_f32_16x16x32_bf16 v[28:31], v[132:135], v[180:183], v[28:31]
	v_mfma_f32_16x16x32_bf16 v[20:23], v[156:159], v[180:183], v[20:23]
	v_mfma_f32_16x16x32_bf16 v[12:15], v[132:135], v[188:191], v[12:15]
	v_mfma_f32_16x16x32_bf16 v[4:7], v[156:159], v[188:191], v[4:7]
	s_setprio 1
	s_barrier
; #define WAIT_V(n) asm volatile("s_waitcnt vmcnt(" #n ")" ::: "memory")
; #define WAIT_L(n) asm volatile("s_waitcnt lgkmcnt(" #n ")" ::: "memory")
; #define BAR __builtin_amdgcn_s_barrier()
; #define SCHED __builtin_amdgcn_sched_barrier(0)
; template <class Get, class Epi>
; DI void gemm_stream(LAS unsigned char* lds, const int K, const int ld, Get get, Epi epi) {
;     ...
;             STAGE(SBo(0, 1), b2 + hstep);
;             WAIT_V(6); BAR; MMA(1, 1, At, B1); BAR;
;             LDB(B0, 1, 0); SCHED; LDA(At, 1, 0); STAGE(SAo(0, 1), a2 + hstep);
;             WAIT_L(8); BAR; WAIT_L(0); MMA(0, 0, At, B0); BAR; SCHED;
;             LDB(B1, 1, 1); STAGE(SBo(1, 0), b3);
;             BAR; WAIT_L(0); MMA(0, 1, At, B1); BAR;
;             LDA(At, 1, 1); STAGE(SAo(1, 0), a3);
;             BAR; WAIT_L(0); MMA(1, 0, At, B0); BAR; SCHED;
	s_add_u32 s28, s74, 0x80000
	s_addc_u32 s29, s75, 0
	s_add_i32 s57, s91, s21
	v_lshl_add_u64 v[128:129], s[28:29], 0, v[142:143]
	s_mov_b32 m0, s57
	s_nop 0
	global_load_lds_dwordx4 v[128:129], off
	v_lshl_add_u64 v[128:129], s[28:29], 0, v[144:145]
	s_add_i32 m0, s57, 0x2000
	s_nop 0
	global_load_lds_dwordx4 v[128:129], off
	s_waitcnt vmcnt(6)
	s_barrier
	s_setprio 0
	v_mfma_f32_16x16x32_bf16 v[56:59], v[192:195], v[160:163], v[56:59]
	v_mfma_f32_16x16x32_bf16 v[48:51], v[200:203], v[160:163], v[48:51]
	v_mfma_f32_16x16x32_bf16 v[40:43], v[192:195], v[168:171], v[40:43]
	v_mfma_f32_16x16x32_bf16 v[32:35], v[200:203], v[168:171], v[32:35]
	v_mfma_f32_16x16x32_bf16 v[24:27], v[192:195], v[176:179], v[24:27]
	v_mfma_f32_16x16x32_bf16 v[16:19], v[200:203], v[176:179], v[16:19]
	v_mfma_f32_16x16x32_bf16 v[8:11], v[192:195], v[184:187], v[8:11]
	v_mfma_f32_16x16x32_bf16 v[0:3], v[200:203], v[184:187], v[0:3]
	v_mfma_f32_16x16x32_bf16 v[56:59], v[196:199], v[164:167], v[56:59]
	v_mfma_f32_16x16x32_bf16 v[48:51], v[212:215], v[164:167], v[48:51]
	v_mfma_f32_16x16x32_bf16 v[40:43], v[196:199], v[172:175], v[40:43]
	v_mfma_f32_16x16x32_bf16 v[32:35], v[212:215], v[172:175], v[32:35]
	v_mfma_f32_16x16x32_bf16 v[24:27], v[196:199], v[180:183], v[24:27]
	v_mfma_f32_16x16x32_bf16 v[16:19], v[212:215], v[180:183], v[16:19]
	v_mfma_f32_16x16x32_bf16 v[8:11], v[196:199], v[188:191], v[8:11]
	v_mfma_f32_16x16x32_bf16 v[0:3], v[212:215], v[188:191], v[0:3]
	s_setprio 1
	s_add_i32 s57, 16, 0x18000
	v_add_u32_e32 v146, s57, v208
	s_barrier
	ds_read_b128 v[128:131], v146
	ds_read_b128 v[132:135], v146 offset:1024
	ds_read_b128 v[136:139], v146 offset:2048
	ds_read_b128 v[156:159], v146 offset:3072
	s_add_u32 s28, s76, 0x80000
	s_addc_u32 s29, s77, 0
	s_mov_b32 m0, s55
	v_lshl_add_u64 v[192:193], s[28:29], 0, v[142:143]
	ds_read_b128 v[160:163], v210 offset:32768
	ds_read_b128 v[164:167], v210 offset:33792
	ds_read_b128 v[168:171], v210 offset:34816
	ds_read_b128 v[172:175], v210 offset:35840
	ds_read_b128 v[176:179], v210 offset:36864
	ds_read_b128 v[180:183], v210 offset:37888
	ds_read_b128 v[184:187], v210 offset:38912
	ds_read_b128 v[188:191], v210 offset:39936
	global_load_lds_dwordx4 v[192:193], off
	v_lshl_add_u64 v[192:193], s[28:29], 0, v[144:145]
	s_mov_b32 m0, s82
	s_nop 0
	global_load_lds_dwordx4 v[192:193], off
	s_waitcnt lgkmcnt(8)
	s_barrier
	s_waitcnt lgkmcnt(0)
	s_setprio 0
	s_waitcnt lgkmcnt(0)
	v_mfma_f32_16x16x32_bf16 v[124:127], v[128:131], v[160:163], v[124:127]
	v_mfma_f32_16x16x32_bf16 v[116:119], v[136:139], v[160:163], v[116:119]
	v_mfma_f32_16x16x32_bf16 v[108:111], v[128:131], v[168:171], v[108:111]
	v_mfma_f32_16x16x32_bf16 v[100:103], v[136:139], v[168:171], v[100:103]
	v_mfma_f32_16x16x32_bf16 v[92:95], v[128:131], v[176:179], v[92:95]
	v_mfma_f32_16x16x32_bf16 v[84:87], v[136:139], v[176:179], v[84:87]
	v_mfma_f32_16x16x32_bf16 v[76:79], v[128:131], v[184:187], v[76:79]
	v_mfma_f32_16x16x32_bf16 v[68:71], v[136:139], v[184:187], v[68:71]
	v_mfma_f32_16x16x32_bf16 v[124:127], v[132:135], v[164:167], v[124:127]
	v_mfma_f32_16x16x32_bf16 v[116:119], v[156:159], v[164:167], v[116:119]
	v_mfma_f32_16x16x32_bf16 v[108:111], v[132:135], v[172:175], v[108:111]
	v_mfma_f32_16x16x32_bf16 v[100:103], v[156:159], v[172:175], v[100:103]
	v_mfma_f32_16x16x32_bf16 v[92:95], v[132:135], v[180:183], v[92:95]
	v_mfma_f32_16x16x32_bf16 v[84:87], v[156:159], v[180:183], v[84:87]
	v_mfma_f32_16x16x32_bf16 v[76:79], v[132:135], v[188:191], v[76:79]
	v_mfma_f32_16x16x32_bf16 v[68:71], v[156:159], v[188:191], v[68:71]
	s_setprio 1
	s_barrier
	s_add_i32 s63, 16, 0x1c000
	s_add_i32 s28, s57, s21
	v_add_u32_e32 v146, s63, v208
	v_lshl_add_u64 v[140:141], v[140:141], 0, s[0:1]
	s_mov_b32 m0, s28
	ds_read_b128 v[192:195], v146
	ds_read_b128 v[196:199], v146 offset:1024
	ds_read_b128 v[200:203], v146 offset:2048
	ds_read_b128 v[212:215], v146 offset:3072
	global_load_lds_dwordx4 v[140:141], off
	v_lshl_add_u64 v[140:141], v[204:205], 0, s[0:1]
	s_add_i32 m0, s28, 0x2000
	s_nop 0
	global_load_lds_dwordx4 v[140:141], off
	s_barrier
	s_waitcnt lgkmcnt(0)
	s_setprio 0
	s_waitcnt lgkmcnt(0)
	v_mfma_f32_16x16x32_bf16 v[120:123], v[192:195], v[160:163], v[120:123]
	v_mfma_f32_16x16x32_bf16 v[112:115], v[200:203], v[160:163], v[112:115]
	v_mfma_f32_16x16x32_bf16 v[104:107], v[192:195], v[168:171], v[104:107]
	v_mfma_f32_16x16x32_bf16 v[96:99], v[200:203], v[168:171], v[96:99]
	v_mfma_f32_16x16x32_bf16 v[88:91], v[192:195], v[176:179], v[88:91]
	v_mfma_f32_16x16x32_bf16 v[80:83], v[200:203], v[176:179], v[80:83]
	v_mfma_f32_16x16x32_bf16 v[72:75], v[192:195], v[184:187], v[72:75]
	v_mfma_f32_16x16x32_bf16 v[64:67], v[200:203], v[184:187], v[64:67]
	v_mfma_f32_16x16x32_bf16 v[120:123], v[196:199], v[164:167], v[120:123]
	v_mfma_f32_16x16x32_bf16 v[112:115], v[212:215], v[164:167], v[112:115]
	v_mfma_f32_16x16x32_bf16 v[104:107], v[196:199], v[172:175], v[104:107]
	v_mfma_f32_16x16x32_bf16 v[96:99], v[212:215], v[172:175], v[96:99]
	v_mfma_f32_16x16x32_bf16 v[88:91], v[196:199], v[180:183], v[88:91]
	v_mfma_f32_16x16x32_bf16 v[80:83], v[212:215], v[180:183], v[80:83]
	v_mfma_f32_16x16x32_bf16 v[72:75], v[196:199], v[188:191], v[72:75]
	v_mfma_f32_16x16x32_bf16 v[64:67], v[212:215], v[188:191], v[64:67]
	s_setprio 1
	s_mov_b32 m0, s83
	v_lshl_add_u64 v[140:141], v[216:217], 0, s[0:1]
	s_barrier
	ds_read_b128 v[160:163], v210 offset:49152
	ds_read_b128 v[164:167], v210 offset:50176
	ds_read_b128 v[168:171], v210 offset:51200
	ds_read_b128 v[172:175], v210 offset:52224
	ds_read_b128 v[176:179], v210 offset:53248
	ds_read_b128 v[180:183], v210 offset:54272
	ds_read_b128 v[184:187], v210 offset:55296
	ds_read_b128 v[188:191], v210 offset:56320
	global_load_lds_dwordx4 v[140:141], off
	v_lshl_add_u64 v[140:141], v[218:219], 0, s[0:1]
	s_mov_b32 m0, s85
	s_nop 0
	global_load_lds_dwordx4 v[140:141], off
	s_barrier
; #define WAIT_V(n) asm volatile("s_waitcnt vmcnt(" #n ")" ::: "memory")
; #define WAIT_L(n) asm volatile("s_waitcnt lgkmcnt(" #n ")" ::: "memory")
; #define BAR __builtin_amdgcn_s_barrier()
; #define SCHED __builtin_amdgcn_sched_barrier(0)
; DI unsigned pk2(float lo, float hi) {
;     f32x2 v = {lo, hi};
;     bf16v2 r = __builtin_convertvector(v, bf16v2);
;     return __builtin_bit_cast(unsigned, r);
; }
; DI float bf2f(unsigned short b) { return __uint_as_float(((unsigned)b) << 16); }
; DI bf16x8 pack8(float a0, float a1, float a2, float a3, float a4, float a5, float a6, float a7) {
;     u32x4 p = {pk2(a0, a1), pk2(a2, a3), pk2(a4, a5), pk2(a6, a7)};
;     return __builtin_bit_cast(bf16x8, p);
; }
; DI void st4(bf16_t* dst, float a, float b, float c, float d) {
;     u32x2 v = {pk2(a, b), pk2(c, d)};
;     *(u32x2*)dst = v;
; }
; template <class Get, class Epi>
; DI void gemm_stream(LAS unsigned char* lds, const int K, const int ld, Get get, Epi epi) {
;     ...
;             BAR; WAIT_L(0); MMA(1, 0, At, B0); BAR; SCHED;
;             STAGE(SBo(1, 1), b3 + hstep);
;             WAIT_V(6); BAR; MMA(1, 1, At, B1); BAR;
; DI void phase_inproj1(const P& p, char* shm) {
;     ...
;     auto epi = [&](const Acc& acc, const Unit& u) {
;         const int brow = u.pm * 256, pn = u.pn;
;         const int b = u.pm / 17, pt = u.pm % 17;
;         const size_t latrow0 = (size_t)b * SEQ + (pt - 1) * 256;
;         if (pn < 8) epi_rope256(acc, p, brow, (bf16_t*)(p.ws + O_Q1), latrow0, pn * 256, 1.f);
;         else if (pn < 16) epi_rope256(acc, p, brow, (bf16_t*)(p.ws + O_K1), (size_t)brow, (pn - 8) * 256, 0.0625f);
;         else if (pn < 32) epi_T<32>(acc, (pn - 16) * 256, brow, (bf16_t*)(p.ws + O_V1T), 4096, nullptr);
;         else epi_plain(acc, 0, (bf16_t*)(p.ws + O_G1) + latrow0 * 4096, 4096, (pn - 32) * 256, nullptr);
	s_waitcnt lgkmcnt(0)
	s_setprio 0
	s_waitcnt lgkmcnt(0)
	v_mfma_f32_16x16x32_bf16 v[60:63], v[128:131], v[160:163], v[60:63]
	v_mfma_f32_16x16x32_bf16 v[52:55], v[136:139], v[160:163], v[52:55]
	v_mfma_f32_16x16x32_bf16 v[44:47], v[128:131], v[168:171], v[44:47]
	v_mfma_f32_16x16x32_bf16 v[36:39], v[136:139], v[168:171], v[36:39]
	v_mfma_f32_16x16x32_bf16 v[28:31], v[128:131], v[176:179], v[28:31]
	v_mfma_f32_16x16x32_bf16 v[20:23], v[136:139], v[176:179], v[20:23]
	v_mfma_f32_16x16x32_bf16 v[12:15], v[128:131], v[184:187], v[12:15]
	v_mfma_f32_16x16x32_bf16 v[4:7], v[136:139], v[184:187], v[4:7]
	v_mfma_f32_16x16x32_bf16 v[60:63], v[132:135], v[164:167], v[60:63]
	v_mfma_f32_16x16x32_bf16 v[52:55], v[156:159], v[164:167], v[52:55]
	v_mfma_f32_16x16x32_bf16 v[44:47], v[132:135], v[172:175], v[44:47]
	v_mfma_f32_16x16x32_bf16 v[36:39], v[156:159], v[172:175], v[36:39]
	v_mfma_f32_16x16x32_bf16 v[28:31], v[132:135], v[180:183], v[28:31]
	v_mfma_f32_16x16x32_bf16 v[20:23], v[156:159], v[180:183], v[20:23]
	v_mfma_f32_16x16x32_bf16 v[12:15], v[132:135], v[188:191], v[12:15]
	v_mfma_f32_16x16x32_bf16 v[4:7], v[156:159], v[188:191], v[4:7]
	s_setprio 1
	s_barrier
	s_add_u32 s28, s74, 0x80080
	s_addc_u32 s29, s75, 0
	s_add_i32 s57, s63, s21
	v_lshl_add_u64 v[128:129], s[28:29], 0, v[142:143]
	s_mov_b32 m0, s57
	s_nop 0
	global_load_lds_dwordx4 v[128:129], off
	v_lshl_add_u64 v[128:129], s[28:29], 0, v[144:145]
	s_add_i32 m0, s57, 0x2000
	s_nop 0
	global_load_lds_dwordx4 v[128:129], off
	s_waitcnt vmcnt(6)
	s_barrier
	s_setprio 0
	v_mfma_f32_16x16x32_bf16 v[56:59], v[192:195], v[160:163], v[56:59]
	v_mfma_f32_16x16x32_bf16 v[48:51], v[200:203], v[160:163], v[48:51]
	v_mfma_f32_16x16x32_bf16 v[40:43], v[192:195], v[168:171], v[40:43]
	v_mfma_f32_16x16x32_bf16 v[32:35], v[200:203], v[168:171], v[32:35]
	v_mfma_f32_16x16x32_bf16 v[24:27], v[192:195], v[176:179], v[24:27]
	v_mfma_f32_16x16x32_bf16 v[16:19], v[200:203], v[176:179], v[16:19]
	v_mfma_f32_16x16x32_bf16 v[8:11], v[192:195], v[184:187], v[8:11]
	v_mfma_f32_16x16x32_bf16 v[0:3], v[200:203], v[184:187], v[0:3]
	v_mfma_f32_16x16x32_bf16 v[56:59], v[196:199], v[164:167], v[56:59]
	v_mfma_f32_16x16x32_bf16 v[48:51], v[212:215], v[164:167], v[48:51]
	v_mfma_f32_16x16x32_bf16 v[40:43], v[196:199], v[172:175], v[40:43]
	v_mfma_f32_16x16x32_bf16 v[32:35], v[212:215], v[172:175], v[32:35]
	v_mfma_f32_16x16x32_bf16 v[24:27], v[196:199], v[180:183], v[24:27]
	v_mfma_f32_16x16x32_bf16 v[16:19], v[212:215], v[180:183], v[16:19]
	v_mfma_f32_16x16x32_bf16 v[8:11], v[196:199], v[188:191], v[8:11]
	v_mfma_f32_16x16x32_bf16 v[0:3], v[212:215], v[188:191], v[0:3]
	s_setprio 1
	s_add_i32 s7, s7, 2
	s_add_u32 s64, s64, 0x100
	s_addc_u32 s65, s65, 0
	s_add_u32 s2, s2, 0x100
	s_addc_u32 s3, s3, 0
	s_cmp_gt_u32 s7, 29
	s_barrier
	s_cbranch_scc0 .LBB0_2102
	s_mul_hi_i32 s2, s6, 0x78787879
	s_lshr_b32 s3, s2, 31
	s_ashr_i32 s2, s2, 3
	s_add_i32 s76, s2, s3
	s_mul_i32 s2, s76, 17
	s_lshl_b32 s74, s6, 8
	s_sub_i32 s6, s6, s2
	s_lshl_b32 s6, s6, 8
	s_ashr_i32 s77, s76, 31
	s_addk_i32 s6, 0xff00
	s_lshl_b64 s[2:3], s[76:77], 12
	s_ashr_i32 s7, s6, 31
	s_add_u32 s64, s2, s6
	s_addc_u32 s65, s3, s7
	s_cmp_gt_i32 s62, 7
	s_mov_b64 s[6:7], -1
	s_cbranch_scc0 .LBB0_2145
	s_cmp_gt_u32 s62, 15
	s_cbranch_scc0 .LBB0_2110
	s_cmp_gt_u32 s62, 31
	v_cvt_pk_bf16_f32 v204, v124, v125
	v_cvt_pk_bf16_f32 v205, v126, v127
	v_cvt_pk_bf16_f32 v202, v116, v117
	v_cvt_pk_bf16_f32 v203, v118, v119
	v_cvt_pk_bf16_f32 v200, v120, v121
	v_cvt_pk_bf16_f32 v201, v122, v123
	v_cvt_pk_bf16_f32 v198, v112, v113
	v_cvt_pk_bf16_f32 v199, v114, v115
	v_cvt_pk_bf16_f32 v196, v108, v109
	v_cvt_pk_bf16_f32 v197, v110, v111
	v_cvt_pk_bf16_f32 v194, v100, v101
	v_cvt_pk_bf16_f32 v195, v102, v103
	v_cvt_pk_bf16_f32 v192, v104, v105
	v_cvt_pk_bf16_f32 v193, v106, v107
	v_cvt_pk_bf16_f32 v190, v96, v97
	v_cvt_pk_bf16_f32 v191, v98, v99
	v_cvt_pk_bf16_f32 v188, v92, v93
	v_cvt_pk_bf16_f32 v189, v94, v95
	v_cvt_pk_bf16_f32 v186, v84, v85
	v_cvt_pk_bf16_f32 v187, v86, v87
	v_cvt_pk_bf16_f32 v184, v88, v89
	v_cvt_pk_bf16_f32 v185, v90, v91
	v_cvt_pk_bf16_f32 v182, v80, v81
	v_cvt_pk_bf16_f32 v183, v82, v83
	v_cvt_pk_bf16_f32 v180, v76, v77
	v_cvt_pk_bf16_f32 v181, v78, v79
	v_cvt_pk_bf16_f32 v178, v68, v69
	v_cvt_pk_bf16_f32 v179, v70, v71
	v_cvt_pk_bf16_f32 v176, v72, v73
	v_cvt_pk_bf16_f32 v177, v74, v75
	v_cvt_pk_bf16_f32 v174, v64, v65
	v_cvt_pk_bf16_f32 v175, v66, v67
	v_cvt_pk_bf16_f32 v172, v60, v61
	v_cvt_pk_bf16_f32 v173, v62, v63
	v_cvt_pk_bf16_f32 v170, v52, v53
	v_cvt_pk_bf16_f32 v171, v54, v55
	v_cvt_pk_bf16_f32 v168, v56, v57
	v_cvt_pk_bf16_f32 v169, v58, v59
	v_cvt_pk_bf16_f32 v166, v48, v49
	v_cvt_pk_bf16_f32 v167, v50, v51
	v_cvt_pk_bf16_f32 v164, v44, v45
	v_cvt_pk_bf16_f32 v165, v46, v47
	v_cvt_pk_bf16_f32 v162, v36, v37
	v_cvt_pk_bf16_f32 v163, v38, v39
	v_cvt_pk_bf16_f32 v160, v40, v41
	v_cvt_pk_bf16_f32 v161, v42, v43
	v_cvt_pk_bf16_f32 v158, v32, v33
	v_cvt_pk_bf16_f32 v159, v34, v35
	v_cvt_pk_bf16_f32 v156, v28, v29
	v_cvt_pk_bf16_f32 v157, v30, v31
	v_cvt_pk_bf16_f32 v140, v20, v21
	v_cvt_pk_bf16_f32 v141, v22, v23
	v_cvt_pk_bf16_f32 v138, v24, v25
	v_cvt_pk_bf16_f32 v139, v26, v27
	v_cvt_pk_bf16_f32 v136, v16, v17
	v_cvt_pk_bf16_f32 v137, v18, v19
	v_cvt_pk_bf16_f32 v134, v12, v13
	v_cvt_pk_bf16_f32 v135, v14, v15
	v_cvt_pk_bf16_f32 v132, v4, v5
	v_cvt_pk_bf16_f32 v133, v6, v7
	v_cvt_pk_bf16_f32 v130, v8, v9
	v_cvt_pk_bf16_f32 v131, v10, v11
	v_cvt_pk_bf16_f32 v128, v0, v1
	v_cvt_pk_bf16_f32 v129, v2, v3
	s_cbranch_scc0 .LBB0_2107
; DI void epi_plain(const Acc& acc, int brow, bf16_t* dst, int ld, int coff, const float* rs) {
;     ...
; #pragma unroll
;     for (int ai = 0; ai < 2; ++ai)
; #pragma unroll
;         for (int m = 0; m < 4; ++m) {
;             const int lr = ai * 128 + wr * 64 + m * 16 + fr;
;             const float s = rs ? rs[lr] : 1.f;
;             bf16_t* rp = dst + (size_t)(brow + lr) * ld + coff + wc * 32 + fq * 4;
; #pragma unroll
;             for (int bj = 0; bj < 2; ++bj)
; #pragma unroll
;                 for (int n = 0; n < 2; ++n) { const f32x4 v = acc[ai][bj][m][n]; st4(rp + bj * 128 + n * 16, v[0] * s, v[1] * s, v[2] * s, v[3] * s); }
;         }
; DI void phase_inproj1(const P& p, char* shm) {
;     ...
;         else epi_plain(acc, 0, (bf16_t*)(p.ws + O_G1) + latrow0 * 4096, 4096, (pn - 32) * 256, nullptr);
	s_lshl_b64 s[2:3], s[64:65], 13
	s_add_u32 s2, s26, s2
	s_addc_u32 s3, s27, s3
	v_mov_b32_e32 v146, v206
	s_lshl_b32 s6, s62, 9
	s_add_u32 s2, s2, s6
	v_and_b32_e32 v212, 15, v146
	v_ashrrev_i32_e32 v213, 2, v146
	v_and_or_b32 v212, v213, s92, v212
	s_addc_u32 s3, s3, 0
	v_lshrrev_b32_e32 v213, 1, v146
	v_and_b32_e32 v146, 0xc0, v146
	v_lshl_add_u64 v[214:215], s[2:3], 0, v[146:147]
	v_and_b32_e32 v146, 24, v213
	v_or_b32_e32 v218, 16, v212
	v_lshl_add_u64 v[214:215], v[214:215], 0, v[146:147]
	s_mov_b64 s[2:3], 0x1a3fc000
	v_ashrrev_i32_e32 v213, 31, v212
	v_ashrrev_i32_e32 v219, 31, v218
	v_lshl_add_u64 v[214:215], v[214:215], 0, s[2:3]
	v_lshlrev_b64 v[216:217], 13, v[212:213]
	v_lshlrev_b64 v[218:219], 13, v[218:219]
	v_lshl_add_u64 v[216:217], v[214:215], 0, v[216:217]
	v_lshl_add_u64 v[218:219], v[214:215], 0, v[218:219]
	global_store_dwordx2 v[216:217], v[204:205], off
	global_store_dwordx2 v[216:217], v[202:203], off offset:32
	global_store_dwordx2 v[216:217], v[200:201], off offset:256
	global_store_dwordx2 v[216:217], v[198:199], off offset:288
	global_store_dwordx2 v[218:219], v[196:197], off
	global_store_dwordx2 v[218:219], v[194:195], off offset:32
	global_store_dwordx2 v[218:219], v[192:193], off offset:256
	global_store_dwordx2 v[218:219], v[190:191], off offset:288
	v_or_b32_e32 v218, 32, v212
	v_or_b32_e32 v212, 48, v212
	v_ashrrev_i32_e32 v219, 31, v218
	v_ashrrev_i32_e32 v213, 31, v212
	v_lshlrev_b64 v[218:219], 13, v[218:219]
	v_lshlrev_b64 v[212:213], 13, v[212:213]
	v_lshl_add_u64 v[218:219], v[214:215], 0, v[218:219]
	v_lshl_add_u64 v[212:213], v[214:215], 0, v[212:213]
	s_mov_b64 s[2:3], 0x100000
	global_store_dwordx2 v[218:219], v[188:189], off
	global_store_dwordx2 v[218:219], v[186:187], off offset:32
	global_store_dwordx2 v[218:219], v[184:185], off offset:256
	global_store_dwordx2 v[218:219], v[182:183], off offset:288
	global_store_dwordx2 v[212:213], v[180:181], off
	global_store_dwordx2 v[212:213], v[178:179], off offset:32
	global_store_dwordx2 v[212:213], v[176:177], off offset:256
	global_store_dwordx2 v[212:213], v[174:175], off offset:288
	v_lshl_add_u64 v[212:213], v[216:217], 0, s[2:3]
	s_mov_b32 s2, 0x100000
	v_add_co_u32_e32 v214, vcc, s2, v216
	s_mov_b64 s[2:3], 0x120000
	s_nop 0
	v_addc_co_u32_e32 v215, vcc, 0, v217, vcc
	global_store_dwordx2 v[214:215], v[172:173], off
	global_store_dwordx2 v[212:213], v[170:171], off offset:32
	global_store_dwordx2 v[212:213], v[168:169], off offset:256
	global_store_dwordx2 v[212:213], v[166:167], off offset:288
	v_add_co_u32_e32 v214, vcc, s93, v216
	v_lshl_add_u64 v[212:213], v[216:217], 0, s[2:3]
	s_nop 0
	v_addc_co_u32_e32 v215, vcc, 0, v217, vcc
	global_store_dwordx2 v[214:215], v[164:165], off
	global_store_dwordx2 v[212:213], v[162:163], off offset:32
	global_store_dwordx2 v[212:213], v[160:161], off offset:256
	global_store_dwordx2 v[212:213], v[158:159], off offset:288
	v_add_co_u32_e32 v214, vcc, s94, v216
	v_lshl_add_u64 v[212:213], v[216:217], 0, s[16:17]
	s_nop 0
	v_addc_co_u32_e32 v215, vcc, 0, v217, vcc
	global_store_dwordx2 v[214:215], v[156:157], off
	global_store_dwordx2 v[212:213], v[140:141], off offset:32
	global_store_dwordx2 v[212:213], v[138:139], off offset:256
	global_store_dwordx2 v[212:213], v[136:137], off offset:288
	v_add_co_u32_e32 v214, vcc, s95, v216
	v_lshl_add_u64 v[212:213], v[216:217], 0, s[18:19]
	s_nop 0
	v_addc_co_u32_e32 v215, vcc, 0, v217, vcc
	global_store_dwordx2 v[214:215], v[134:135], off
	global_store_dwordx2 v[212:213], v[132:133], off offset:32
	global_store_dwordx2 v[212:213], v[130:131], off offset:256
	global_store_dwordx2 v[212:213], v[128:129], off offset:288
	s_mov_b64 s[6:7], 0

; DI void scan_item(const P& p, char* shm, int item) {
;     ...
;     auto p0_of = [&](int s) { return dir == 0 ? 32 * s : (s < 8 ? 224 - 32 * s : PB - 32 - 32 * (s - 8)); };
;     ...
;     auto flush_prev = [&](int sprev) {
;         const float* xp = (const float*)(shm + SC_X + (sprev & 1) * 16384 + vb * 4096) + lane_c * 16;
;         bf16_t* ob = OX + ((size_t)b * SEQ + pprev) * 4096 + h * 512 + vs * 128 + vb * 32;
;         const __amdgpu_buffer_rsrc_t rs = __builtin_amdgcn_make_buffer_rsrc(ob, 0, 0x7fffffff, 0x00020000);
; #pragma unroll
;         for (int g = 0; g < 4; ++g) {
;             const f32x4 x = *(const f32x4*)(xp + 4 * g);
; #pragma unroll
;             for (int j = 0; j < 4; ++j)
;                 __builtin_amdgcn_raw_buffer_store_b16((short)(pk2(oprev[4 * g + j] + x[j], 0.f) & 0xffffu), rs, flane * 2, (j + 8 * g) * 8192, 0);
;         }
;     };
;     ...
;     for (int s = 0; s < nsteps; ++s) {
;         if (dh == 0 && pprev >= 0) { flush_prev(s - 1); pprev = -1; }
;         const int lane = lane_c, l31 = l31_c, hh = hh_c;
;         unsigned Lrd = Lrd_c, Ltr = Ltr_c, vrow = vrow_c, qrow = qrow_c;
;         asm volatile("" : "+v"(Lrd), "+v"(Ltr), "+v"(vrow), "+v"(qrow));
;         const char* buf = shm + (s & 1) * SC_BUF;
;         const char* kimg = buf + SC_K + dh * 8192;
;         const char* qimg = buf + SC_Q + dh * 256 + qrow;
;         const int p0 = p0_of(s);
;         if (p0 >= CTXL) {
.LBB0_2237:
	s_cmp_gt_i32 s14, -1
	s_cselect_b64 s[8:9], -1, 0
	s_and_b64 s[8:9], s[16:17], s[8:9]
	s_andn2_b64 vcc, exec, s[8:9]
	s_cbranch_vccnz .LBB0_2239
	s_andn2_b32 s8, 0x4000, s87
	v_add_u32_e32 v88, s8, v193
	ds_read_b128 v[80:83], v88
	ds_read_b128 v[84:87], v88 offset:16
	s_lshl_b64 s[8:9], s[14:15], 13
	s_add_u32 s8, s75, s8
	s_addc_u32 s9, s76, s9
	s_waitcnt lgkmcnt(1)
	v_add_f32_e32 v80, v0, v80
	s_and_b32 s9, s9, 0xffff
	v_cvt_pk_bf16_f32 v80, v80, s0
	buffer_store_short v80, v175, s[8:11], 0 offen
	v_add_f32_e32 v80, v1, v81
	v_cvt_pk_bf16_f32 v80, v80, s0
	buffer_store_short v80, v175, s[8:11], s20 offen
	v_add_f32_e32 v80, v2, v82
	v_cvt_pk_bf16_f32 v80, v80, s0
	buffer_store_short v80, v175, s[8:11], s41 offen
	v_add_f32_e32 v80, v3, v83
	v_cvt_pk_bf16_f32 v80, v80, s0
	buffer_store_short v80, v175, s[8:11], s52 offen
	s_waitcnt lgkmcnt(0)
	v_add_f32_e32 v80, v4, v84
	v_cvt_pk_bf16_f32 v80, v80, s0
	buffer_store_short v80, v175, s[8:11], s23 offen
	v_add_f32_e32 v80, v5, v85
	v_cvt_pk_bf16_f32 v80, v80, s0
	buffer_store_short v80, v175, s[8:11], s53 offen
	v_add_f32_e32 v80, v6, v86
	v_cvt_pk_bf16_f32 v80, v80, s0
	buffer_store_short v80, v175, s[8:11], s54 offen
	ds_read_b128 v[80:83], v88 offset:32
	v_add_f32_e32 v84, v7, v87
	v_cvt_pk_bf16_f32 v84, v84, s0
	buffer_store_short v84, v175, s[8:11], s55 offen
	ds_read_b128 v[84:87], v88 offset:48
	s_waitcnt lgkmcnt(1)
	v_add_f32_e32 v80, v8, v80
	v_cvt_pk_bf16_f32 v80, v80, s0
	buffer_store_short v80, v175, s[8:11], s11 offen
	v_add_f32_e32 v80, v9, v81
	v_cvt_pk_bf16_f32 v80, v80, s0
	buffer_store_short v80, v175, s[8:11], s56 offen
	v_add_f32_e32 v80, v10, v82
	v_cvt_pk_bf16_f32 v80, v80, s0
	buffer_store_short v80, v175, s[8:11], s57 offen
	v_add_f32_e32 v80, v11, v83
	v_cvt_pk_bf16_f32 v80, v80, s0
	buffer_store_short v80, v175, s[8:11], s58 offen
	s_waitcnt lgkmcnt(0)
	v_add_f32_e32 v80, v12, v84
	v_cvt_pk_bf16_f32 v80, v80, s0
	buffer_store_short v80, v175, s[8:11], s59 offen
	v_add_f32_e32 v80, v13, v85
	v_cvt_pk_bf16_f32 v80, v80, s0
	buffer_store_short v80, v175, s[8:11], s60 offen
	v_add_f32_e32 v80, v14, v86
	v_cvt_pk_bf16_f32 v80, v80, s0
	buffer_store_short v80, v175, s[8:11], s61 offen
	v_add_f32_e32 v80, v15, v87
	v_cvt_pk_bf16_f32 v80, v80, s0
	s_mov_b32 s14, -1
	buffer_store_short v80, v175, s[8:11], s62 offen
.LBB0_2239:
	v_mov_b32_e32 v151, v167
	v_mov_b32_e32 v105, v133
	v_mov_b32_e32 v80, v177
	v_mov_b32_e32 v96, v188
	s_andn2_b64 vcc, exec, s[6:7]
	s_mov_b32 s91, s86
	s_cbranch_vccnz .LBB0_2244
	s_lshl_b32 s89, s88, 5
	s_cmp_gt_u32 s88, 7
	s_mov_b64 s[8:9], -1
	s_cbranch_scc0 .LBB0_2242
	s_sub_i32 s91, 0x11e0, s89
	s_mov_b64 s[8:9], 0

; DI void scan_item(const P& p, char* shm, int item) {
;     ...
;         const char* buf = shm + (s & 1) * SC_BUF;
;         const char* kimg = buf + SC_K + dh * 8192;
;         const char* qimg = buf + SC_Q + dh * 256 + qrow;
;         const int p0 = p0_of(s);
;         if (p0 >= CTXL) {
;             f32x16 pT;
; #pragma unroll
;             for (int r = 0; r < 16; ++r) pT[r] = 0.f;
; #pragma unroll
;             for (int s8 = 0; s8 < 8; ++s8) {
;                 const unsigned o = Lrd ^ (32u * s8);
;                 const bf16x8 a = *(const bf16x8*)(kimg + o);
;                 const bf16x8 bq = *(const bf16x8*)(qimg + 8 * hh + 32 * s8);
;                 pT = MFMA32(a, bq, pT);
;             }
; #pragma unroll
;             for (int r = 0; r < 16; ++r) pT[r] *= dmask[r];
;             bf16x8 pfr[2];
;             pfr[0] = PACK16(pT, 0);
;             pfr[1] = PACK16(pT, 1);
;             f32x16 o;
; #pragma unroll
;             for (int r = 0; r < 16; ++r) o[r] = 0.f;
; #pragma unroll
;             for (int db = 0; db < 4; ++db)
; #pragma unroll
;                 for (int s2 = 0; s2 < 2; ++s2) {
;                     const bf16x8 bfrag = PACK16(st[db], s2);
;                     const s16x4 qlo = *(const s16x4*)(qimg + db * 64 + 32 * s2), qhi = *(const s16x4*)(qimg + db * 64 + 32 * s2 + 16);
;                     const bf16x8 a2 = __builtin_shufflevector(qlo, qhi, 0, 1, 2, 3, 4, 5, 6, 7);
;                     o = MFMA32(a2, bfrag, o);
;                 }
; #pragma unroll
;             for (int r = 0; r < 16; ++r) o[r] *= qlane * __builtin_amdgcn_exp2f(lgs * (float)((r & 3) + 8 * (r >> 2)));
; #pragma unroll
;             for (int s2 = 0; s2 < 2; ++s2) {
;                 const char* vp = buf + SC_V + vrow + 8 * hh + 32 * s2;
;                 const s16x4 vlo = *(const s16x4*)vp, vhi = *(const s16x4*)(vp + 16);
;                 const bf16x8 b3 = __builtin_shufflevector(vlo, vhi, 0, 1, 2, 3, 4, 5, 6, 7);
;                 o = MFMA32(pfr[s2], b3, o);
;             }
;             if (dh == 1) {
;                 float* xp = (float*)(shm + SC_X + (s & 1) * 16384 + vb * 4096) + lane * 16;
; #pragma unroll
;                 for (int g = 0; g < 4; ++g) *(f32x4*)(xp + 4 * g) = (f32x4){o[4 * g], o[4 * g + 1], o[4 * g + 2], o[4 * g + 3]};
;             } else {
;                 oprev = o;
;                 pprev = p0 - CTXL;
;             }
.LBB0_2244:
	s_and_b32 s92, s88, 1
	s_mul_i32 s8, s92, 0xd200
	s_add_i32 s90, s8, 16
	s_add_i32 s89, s90, s85
	s_cmpk_lt_u32 s91, 0x100
	s_cbranch_scc1 .LBB0_2251
	s_add_i32 s8, s90, s83
	v_add_u32_e32 v196, s8, v80
	v_add_u32_e32 v80, s89, v96
	v_add_u32_e32 v102, v196, v166
	ds_read_b128 v[80:83], v80 offset:16896
	ds_read_b128 v[84:87], v102
	ds_read_b128 v[98:101], v102 offset:32
	v_xad_u32 v97, v96, 32, s89
	ds_read_b128 v[198:201], v97 offset:16896
	s_waitcnt lgkmcnt(2)
	v_mfma_f32_32x32x16_bf16 v[80:95], v[80:83], v[84:87], 0
	v_xad_u32 v97, v96, 64, s89
	v_cvt_pk_bf16_f32 v202, v72, v73
	v_cvt_pk_bf16_f32 v203, v74, v75
	v_cvt_pk_bf16_f32 v204, v76, v77
	v_cvt_pk_bf16_f32 v205, v78, v79
	s_mov_b64 s[8:9], -1
	s_and_b64 vcc, exec, s[36:37]
	s_waitcnt lgkmcnt(0)
	v_mfma_f32_32x32x16_bf16 v[80:95], v[198:201], v[98:101], v[80:95]
	ds_read_b128 v[98:101], v97 offset:16896
	ds_read_b128 v[198:201], v102 offset:64
	v_xor_b32_e32 v97, 0x60, v96
	v_add_u32_e32 v97, s89, v97
	s_waitcnt lgkmcnt(0)
	v_mfma_f32_32x32x16_bf16 v[80:95], v[98:101], v[198:201], v[80:95]
	ds_read_b128 v[98:101], v97 offset:16896
	ds_read_b128 v[198:201], v102 offset:96
	v_xor_b32_e32 v97, 0x80, v96
	v_add_u32_e32 v97, s89, v97
	s_waitcnt lgkmcnt(0)
	v_mfma_f32_32x32x16_bf16 v[80:95], v[98:101], v[198:201], v[80:95]
	ds_read_b128 v[98:101], v97 offset:16896
	ds_read_b128 v[198:201], v102 offset:128
	v_xor_b32_e32 v97, 0xa0, v96
	v_add_u32_e32 v97, s89, v97
	s_waitcnt lgkmcnt(0)
	v_mfma_f32_32x32x16_bf16 v[80:95], v[98:101], v[198:201], v[80:95]
	ds_read_b128 v[98:101], v97 offset:16896
	ds_read_b128 v[198:201], v102 offset:160
	v_xor_b32_e32 v97, 0xc0, v96
	v_add_u32_e32 v97, s89, v97
	v_xor_b32_e32 v96, 0xe0, v96
	v_add_u32_e32 v96, s89, v96
	s_waitcnt lgkmcnt(0)
	v_mfma_f32_32x32x16_bf16 v[80:95], v[98:101], v[198:201], v[80:95]
	ds_read_b128 v[98:101], v97 offset:16896
	ds_read_b128 v[198:201], v102 offset:192
	s_waitcnt lgkmcnt(0)
	v_mfma_f32_32x32x16_bf16 v[80:95], v[98:101], v[198:201], v[80:95]
	ds_read_b128 v[96:99], v96 offset:16896
	ds_read_b128 v[100:103], v102 offset:224
	s_waitcnt lgkmcnt(0)
	v_mfma_f32_32x32x16_bf16 v[80:95], v[96:99], v[100:103], v[80:95]
	s_nop 11
	v_mul_f32_e32 v84, v172, v84
	v_mul_f32_e32 v85, v173, v85
	v_mul_f32_e32 v86, v174, v86
	v_mul_f32_e32 v87, v176, v87
	v_cvt_pk_bf16_f32 v98, v84, v85
	v_cvt_pk_bf16_f32 v99, v86, v87
	ds_read2_b64 v[84:87], v196 offset1:2
	ds_read2_b64 v[198:201], v196 offset0:4 offset1:6
	v_mul_f32_e32 v80, v168, v80
	v_mul_f32_e32 v81, v169, v81
	v_mul_f32_e32 v82, v170, v82
	v_mul_f32_e32 v83, v171, v83
	v_mul_f32_e32 v88, v182, v88
	v_mul_f32_e32 v89, v183, v89
	v_mul_f32_e32 v90, v186, v90
	v_mul_f32_e32 v91, v184, v91
	v_mul_f32_e32 v92, v185, v92
	v_mul_f32_e32 v93, v180, v93
	v_mul_f32_e32 v94, v181, v94
	v_mul_f32_e32 v95, v179, v95
	v_cvt_pk_bf16_f32 v96, v80, v81
	v_cvt_pk_bf16_f32 v97, v82, v83
	v_cvt_pk_bf16_f32 v80, v64, v65
	v_cvt_pk_bf16_f32 v81, v66, v67
	v_cvt_pk_bf16_f32 v82, v68, v69
	v_cvt_pk_bf16_f32 v83, v70, v71
	v_cvt_pk_bf16_f32 v100, v88, v89
	v_cvt_pk_bf16_f32 v101, v90, v91
	v_cvt_pk_bf16_f32 v102, v92, v93
	v_cvt_pk_bf16_f32 v103, v94, v95
	s_waitcnt lgkmcnt(1)
	v_mfma_f32_32x32x16_bf16 v[80:95], v[84:87], v[80:83], 0
	s_waitcnt lgkmcnt(0)
	v_mfma_f32_32x32x16_bf16 v[80:95], v[198:201], v[202:205], v[80:95]
	ds_read2_b64 v[202:205], v196 offset0:8 offset1:10
	v_cvt_pk_bf16_f32 v198, v48, v49
	v_cvt_pk_bf16_f32 v199, v50, v51
	v_cvt_pk_bf16_f32 v200, v52, v53
	v_cvt_pk_bf16_f32 v201, v54, v55
	s_waitcnt lgkmcnt(0)
	s_nop 0
	v_mfma_f32_32x32x16_bf16 v[80:95], v[202:205], v[198:201], v[80:95]
	ds_read2_b64 v[202:205], v196 offset0:12 offset1:14
	v_cvt_pk_bf16_f32 v198, v56, v57
	v_cvt_pk_bf16_f32 v199, v58, v59
	v_cvt_pk_bf16_f32 v200, v60, v61
	v_cvt_pk_bf16_f32 v201, v62, v63
	s_waitcnt lgkmcnt(0)
	s_nop 0
	v_mfma_f32_32x32x16_bf16 v[80:95], v[202:205], v[198:201], v[80:95]
	ds_read2_b64 v[202:205], v196 offset0:16 offset1:18
	v_cvt_pk_bf16_f32 v198, v32, v33
	v_cvt_pk_bf16_f32 v199, v34, v35
	v_cvt_pk_bf16_f32 v200, v36, v37
	v_cvt_pk_bf16_f32 v201, v38, v39
	s_waitcnt lgkmcnt(0)
	s_nop 0
	v_mfma_f32_32x32x16_bf16 v[80:95], v[202:205], v[198:201], v[80:95]
	ds_read2_b64 v[202:205], v196 offset0:20 offset1:22
	v_cvt_pk_bf16_f32 v198, v40, v41
	v_cvt_pk_bf16_f32 v199, v42, v43
	v_cvt_pk_bf16_f32 v200, v44, v45
	v_cvt_pk_bf16_f32 v201, v46, v47
	s_waitcnt lgkmcnt(0)
	s_nop 0
	v_mfma_f32_32x32x16_bf16 v[80:95], v[202:205], v[198:201], v[80:95]
	ds_read2_b64 v[202:205], v196 offset0:24 offset1:26
	v_cvt_pk_bf16_f32 v198, v16, v17
	v_cvt_pk_bf16_f32 v199, v18, v19
	v_cvt_pk_bf16_f32 v200, v20, v21
	v_cvt_pk_bf16_f32 v201, v22, v23
	s_waitcnt lgkmcnt(0)
	s_nop 0
	v_mfma_f32_32x32x16_bf16 v[80:95], v[202:205], v[198:201], v[80:95]
	ds_read2_b64 v[202:205], v196 offset0:28 offset1:30
	v_cvt_pk_bf16_f32 v198, v24, v25
	v_cvt_pk_bf16_f32 v199, v26, v27
	v_cvt_pk_bf16_f32 v200, v28, v29
	v_cvt_pk_bf16_f32 v201, v30, v31
	v_add3_u32 v196, s90, v151, v166
	s_waitcnt lgkmcnt(0)
	v_mfma_f32_32x32x16_bf16 v[80:95], v[202:205], v[198:201], v[80:95]
	v_add_u32_e32 v200, 0x8000, v196
	ds_read2_b64 v[196:199], v200 offset0:64 offset1:66
	ds_read2_b64 v[200:203], v200 offset0:68 offset1:70
	s_nop 8
	v_pk_mul_f32 v[94:95], v[148:149], v[94:95]
	v_pk_mul_f32 v[92:93], v[146:147], v[92:93]
	v_pk_mul_f32 v[90:91], v[144:145], v[90:91]
	v_pk_mul_f32 v[88:89], v[142:143], v[88:89]
	v_pk_mul_f32 v[86:87], v[140:141], v[86:87]
	v_pk_mul_f32 v[84:85], v[138:139], v[84:85]
	v_pk_mul_f32 v[82:83], v[136:137], v[82:83]
	v_pk_mul_f32 v[80:81], v[134:135], v[80:81]
	s_waitcnt lgkmcnt(1)
	s_nop 0
	v_mfma_f32_32x32x16_bf16 v[80:95], v[96:99], v[196:199], v[80:95]
	s_waitcnt lgkmcnt(0)
	v_mfma_f32_32x32x16_bf16 v[80:95], v[100:103], v[200:203], v[80:95]
	s_cbranch_vccz .LBB0_2247
	s_add_i32 s93, s91, 0xffffff00
	s_mov_b64 s[8:9], 0
.LBB0_2247:
	s_andn2_b64 vcc, exec, s[8:9]
	s_cbranch_vccnz .LBB0_2249
	v_lshl_add_u32 v96, s92, 14, v187
	s_nop 7
	ds_write_b128 v96, v[80:83]
	ds_write_b128 v96, v[84:87] offset:16
	ds_write_b128 v96, v[88:91] offset:32
	ds_write_b128 v96, v[92:95] offset:48
	s_branch .LBB0_2250
.LBB0_2249:
	s_nop 8
	v_mov_b64_e32 v[0:1], v[80:81]
	v_mov_b64_e32 v[2:3], v[82:83]
	v_mov_b64_e32 v[4:5], v[84:85]
	v_mov_b64_e32 v[6:7], v[86:87]
	v_mov_b64_e32 v[8:9], v[88:89]
	v_mov_b64_e32 v[10:11], v[90:91]
	v_mov_b64_e32 v[12:13], v[92:93]
	v_mov_b64_e32 v[14:15], v[94:95]
	s_mov_b32 s14, s93

; DI float bf2f(unsigned short b) { return __uint_as_float(((unsigned)b) << 16); }
; DI void scan_item(const P& p, char* shm, int item) {
;     ...
;     auto p0_of = [&](int s) { return dir == 0 ? 32 * s : (s < 8 ? 224 - 32 * s : PB - 32 - 32 * (s - 8)); };
;     ...
;         *(bf16x8*)(buf + SC_V + ldsV) = vv;
;         float f[8];
; #pragma unroll
;         for (int e = 0; e < 8; ++e) {
;             const int j = (tid & 3) * 8 + e;
;             f[e] = bf2f((unsigned short)vv[e]) * __builtin_amdgcn_exp2f(lg2 * (float)(dir == 0 ? 31 - j : j));
;         }
;         *(bf16x8*)(buf + SC_VS + ldsV) = pack8(f[0], f[1], f[2], f[3], f[4], f[5], f[6], f[7]);
;     };
.LBB0_2261:
	s_waitcnt vmcnt(0)
	v_and_b32_e32 v81, 0xffff0000, v116
	v_lshlrev_b32_e32 v80, 16, v116
	v_and_b32_e32 v83, 0xffff0000, v117
	v_lshlrev_b32_e32 v82, 16, v117
	v_and_b32_e32 v85, 0xffff0000, v118
	v_lshlrev_b32_e32 v84, 16, v118
	v_and_b32_e32 v87, 0xffff0000, v119
	v_lshlrev_b32_e32 v86, 16, v119
	v_pk_mul_f32 v[80:81], v[154:155], v[80:81]
	v_pk_mul_f32 v[82:83], v[156:157], v[82:83]
	v_pk_mul_f32 v[84:85], v[158:159], v[84:85]
	v_pk_mul_f32 v[86:87], v[160:161], v[86:87]
	v_add_u32_e32 v88, s8, v104
	v_cvt_pk_bf16_f32 v80, v80, v81
	v_cvt_pk_bf16_f32 v81, v82, v83
	v_cvt_pk_bf16_f32 v82, v84, v85
	v_cvt_pk_bf16_f32 v83, v86, v87
	s_mov_b64 s[8:9], -1
	s_and_b64 vcc, exec, s[6:7]
	ds_write_b128 v88, v[116:119] offset:33280
	ds_write_b128 v88, v[80:83] offset:43520
	s_cbranch_vccz .LBB0_2267
	s_lshl_b32 s93, s88, 5
	s_add_i32 s93, s93, 64
	s_cmp_gt_u32 s88, 5
	s_cbranch_scc0 .LBB0_2264
	s_sub_i32 s92, 0x11e0, s93
	s_mov_b64 s[8:9], 0

; #define WAIT_V(n) asm volatile("s_waitcnt vmcnt(" #n ")" ::: "memory")
; #define WAIT_L(n) asm volatile("s_waitcnt lgkmcnt(" #n ")" ::: "memory")
; #define BAR __builtin_amdgcn_s_barrier()
; #define SCHED __builtin_amdgcn_sched_barrier(0)
; template <class Get, class Epi>
; DI void gemm_stream(LAS unsigned char* lds, const int K, const int ld, Get get, Epi epi) {
;     ...
;             LDB(B0, 0, 0); SCHED; LDA(At, 0, 0); STAGE(SAo(1, 1), a1 + hstep);
;             WAIT_L(8); BAR; WAIT_L(0); MMA(0, 0, At, B0); BAR; SCHED;
;             LDB(B1, 0, 1); STAGE(SBo(0, 0), b2);
;             BAR; WAIT_L(0); MMA(0, 1, At, B1); BAR;
;             LDA(At, 0, 1); STAGE(SAo(0, 0), a2);
;             BAR; WAIT_L(0); MMA(1, 0, At, B0); BAR; SCHED;
;             STAGE(SBo(0, 1), b2 + hstep);
;             WAIT_V(6); BAR; MMA(1, 1, At, B1); BAR;
;             LDB(B0, 1, 0); SCHED; LDA(At, 1, 0); STAGE(SAo(0, 1), a2 + hstep);
;             WAIT_L(8); BAR; WAIT_L(0); MMA(0, 0, At, B0); BAR; SCHED;
;             LDB(B1, 1, 1); STAGE(SBo(1, 0), b3);
;             BAR; WAIT_L(0); MMA(0, 1, At, B1); BAR;
.LBB0_2670:
	ds_read_b128 v[128:131], v198
	ds_read_b128 v[132:135], v198 offset:1024
	ds_read_b128 v[136:139], v198 offset:2048
	ds_read_b128 v[140:143], v198 offset:3072
	s_add_u32 s8, s6, 0x100
	s_addc_u32 s9, s7, 0
	s_cmp_eq_u32 s16, 60
	s_cselect_b32 s13, s39, s9
	s_cselect_b32 s12, s38, s8
	s_cselect_b32 s11, s41, s15
	s_cselect_b32 s10, s40, s14
	s_mov_b32 m0, s52
	v_lshl_add_u64 v[186:187], s[6:7], 0, v[168:169]
	ds_read_b128 v[144:147], v199
	ds_read_b128 v[148:151], v199 offset:1024
	ds_read_b128 v[152:155], v199 offset:2048
	ds_read_b128 v[156:159], v199 offset:3072
	ds_read_b128 v[160:163], v199 offset:4096
	ds_read_b128 v[174:177], v199 offset:5120
	ds_read_b128 v[178:181], v199 offset:6144
	ds_read_b128 v[182:185], v199 offset:7168
	global_load_lds_dwordx4 v[186:187], off
	v_lshl_add_u64 v[186:187], s[6:7], 0, v[170:171]
	s_mov_b32 m0, s53
	s_nop 0
	global_load_lds_dwordx4 v[186:187], off
	s_waitcnt lgkmcnt(8)
	s_barrier
	s_waitcnt lgkmcnt(0)
	s_setprio 0
	s_waitcnt lgkmcnt(0)
	v_mfma_f32_16x16x32_bf16 v[124:127], v[128:131], v[144:147], v[124:127]
	v_mfma_f32_16x16x32_bf16 v[92:95], v[136:139], v[144:147], v[92:95]
	v_mfma_f32_16x16x32_bf16 v[120:123], v[128:131], v[152:155], v[120:123]
	v_mfma_f32_16x16x32_bf16 v[88:91], v[136:139], v[152:155], v[88:91]
	v_mfma_f32_16x16x32_bf16 v[116:119], v[128:131], v[160:163], v[116:119]
	v_mfma_f32_16x16x32_bf16 v[84:87], v[136:139], v[160:163], v[84:87]
	v_mfma_f32_16x16x32_bf16 v[112:115], v[128:131], v[178:181], v[112:115]
	v_mfma_f32_16x16x32_bf16 v[80:83], v[136:139], v[178:181], v[80:83]
	v_mfma_f32_16x16x32_bf16 v[124:127], v[132:135], v[148:151], v[124:127]
	v_mfma_f32_16x16x32_bf16 v[92:95], v[140:143], v[148:151], v[92:95]
	v_mfma_f32_16x16x32_bf16 v[120:123], v[132:135], v[156:159], v[120:123]
	v_mfma_f32_16x16x32_bf16 v[88:91], v[140:143], v[156:159], v[88:91]
	v_mfma_f32_16x16x32_bf16 v[116:119], v[132:135], v[174:177], v[116:119]
	v_mfma_f32_16x16x32_bf16 v[84:87], v[140:143], v[174:177], v[84:87]
	v_mfma_f32_16x16x32_bf16 v[112:115], v[132:135], v[182:185], v[112:115]
	v_mfma_f32_16x16x32_bf16 v[80:83], v[140:143], v[182:185], v[80:83]
	s_setprio 1
	s_barrier
	s_mov_b32 m0, s58
	v_lshl_add_u64 v[204:205], s[10:11], 0, v[164:165]
	ds_read_b128 v[186:189], v200
	ds_read_b128 v[190:193], v200 offset:1024
	ds_read_b128 v[194:197], v200 offset:2048
	ds_read_b128 v[208:211], v200 offset:3072
	global_load_lds_dwordx4 v[204:205], off
	v_lshl_add_u64 v[212:213], s[10:11], 0, v[166:167]
	s_mov_b32 m0, s59
	s_nop 0
	global_load_lds_dwordx4 v[212:213], off
	s_barrier
	s_waitcnt lgkmcnt(0)
	s_setprio 0
	s_waitcnt lgkmcnt(0)
	v_mfma_f32_16x16x32_bf16 v[60:63], v[186:189], v[144:147], v[60:63]
	v_mfma_f32_16x16x32_bf16 v[28:31], v[194:197], v[144:147], v[28:31]
	v_mfma_f32_16x16x32_bf16 v[56:59], v[186:189], v[152:155], v[56:59]
	v_mfma_f32_16x16x32_bf16 v[24:27], v[194:197], v[152:155], v[24:27]
	v_mfma_f32_16x16x32_bf16 v[52:55], v[186:189], v[160:163], v[52:55]
	v_mfma_f32_16x16x32_bf16 v[20:23], v[194:197], v[160:163], v[20:23]
	v_mfma_f32_16x16x32_bf16 v[48:51], v[186:189], v[178:181], v[48:51]
	v_mfma_f32_16x16x32_bf16 v[16:19], v[194:197], v[178:181], v[16:19]
	v_mfma_f32_16x16x32_bf16 v[60:63], v[190:193], v[148:151], v[60:63]
	v_mfma_f32_16x16x32_bf16 v[28:31], v[208:211], v[148:151], v[28:31]
	v_mfma_f32_16x16x32_bf16 v[56:59], v[190:193], v[156:159], v[56:59]
	v_mfma_f32_16x16x32_bf16 v[24:27], v[208:211], v[156:159], v[24:27]
	v_mfma_f32_16x16x32_bf16 v[52:55], v[190:193], v[174:177], v[52:55]
	v_mfma_f32_16x16x32_bf16 v[20:23], v[208:211], v[174:177], v[20:23]
	v_mfma_f32_16x16x32_bf16 v[48:51], v[190:193], v[182:185], v[48:51]
	v_mfma_f32_16x16x32_bf16 v[16:19], v[208:211], v[182:185], v[16:19]
	s_setprio 1
	s_mov_b32 m0, s35
	v_lshl_add_u64 v[214:215], s[12:13], 0, v[164:165]
	s_barrier
	ds_read_b128 v[144:147], v199 offset:16384
	ds_read_b128 v[148:151], v199 offset:17408
	ds_read_b128 v[152:155], v199 offset:18432
	ds_read_b128 v[156:159], v199 offset:19456
	ds_read_b128 v[160:163], v199 offset:20480
	ds_read_b128 v[174:177], v199 offset:21504
	ds_read_b128 v[178:181], v199 offset:22528
	ds_read_b128 v[182:185], v199 offset:23552
	global_load_lds_dwordx4 v[214:215], off
	v_lshl_add_u64 v[216:217], s[12:13], 0, v[166:167]
	s_mov_b32 m0, s44
	s_nop 0
	global_load_lds_dwordx4 v[216:217], off
	s_barrier
	s_waitcnt lgkmcnt(0)
	s_setprio 0
	s_waitcnt lgkmcnt(0)
	v_mfma_f32_16x16x32_bf16 v[108:111], v[128:131], v[144:147], v[108:111]
	v_mfma_f32_16x16x32_bf16 v[76:79], v[136:139], v[144:147], v[76:79]
	v_mfma_f32_16x16x32_bf16 v[104:107], v[128:131], v[152:155], v[104:107]
	v_mfma_f32_16x16x32_bf16 v[72:75], v[136:139], v[152:155], v[72:75]
	v_mfma_f32_16x16x32_bf16 v[100:103], v[128:131], v[160:163], v[100:103]
	v_mfma_f32_16x16x32_bf16 v[68:71], v[136:139], v[160:163], v[68:71]
	v_mfma_f32_16x16x32_bf16 v[96:99], v[128:131], v[178:181], v[96:99]
	v_mfma_f32_16x16x32_bf16 v[64:67], v[136:139], v[178:181], v[64:67]
	v_mfma_f32_16x16x32_bf16 v[108:111], v[132:135], v[148:151], v[108:111]
	v_mfma_f32_16x16x32_bf16 v[76:79], v[140:143], v[148:151], v[76:79]
	v_mfma_f32_16x16x32_bf16 v[104:107], v[132:135], v[156:159], v[104:107]
	v_mfma_f32_16x16x32_bf16 v[72:75], v[140:143], v[156:159], v[72:75]
	v_mfma_f32_16x16x32_bf16 v[100:103], v[132:135], v[174:177], v[100:103]
	v_mfma_f32_16x16x32_bf16 v[68:71], v[140:143], v[174:177], v[68:71]
	v_mfma_f32_16x16x32_bf16 v[96:99], v[132:135], v[182:185], v[96:99]
	v_mfma_f32_16x16x32_bf16 v[64:67], v[140:143], v[182:185], v[64:67]
	s_setprio 1
	s_barrier
; #define WAIT_V(n) asm volatile("s_waitcnt vmcnt(" #n ")" ::: "memory")
; #define WAIT_L(n) asm volatile("s_waitcnt lgkmcnt(" #n ")" ::: "memory")
; #define BAR __builtin_amdgcn_s_barrier()
; #define SCHED __builtin_amdgcn_sched_barrier(0)
; template <class Get, class Epi>
; DI void gemm_stream(LAS unsigned char* lds, const int K, const int ld, Get get, Epi epi) {
;     ...
;             STAGE(SBo(0, 1), b2 + hstep);
;             WAIT_V(6); BAR; MMA(1, 1, At, B1); BAR;
;             LDB(B0, 1, 0); SCHED; LDA(At, 1, 0); STAGE(SAo(0, 1), a2 + hstep);
;             WAIT_L(8); BAR; WAIT_L(0); MMA(0, 0, At, B0); BAR; SCHED;
;             LDB(B1, 1, 1); STAGE(SBo(1, 0), b3);
;             BAR; WAIT_L(0); MMA(0, 1, At, B1); BAR;
;             LDA(At, 1, 1); STAGE(SAo(1, 0), a3);
;             BAR; WAIT_L(0); MMA(1, 0, At, B0); BAR; SCHED;
;             STAGE(SBo(1, 1), b3 + hstep);
;             WAIT_V(6); BAR; MMA(1, 1, At, B1); BAR;
	s_add_u32 s6, s10, 0x100000
	s_addc_u32 s7, s11, 0
	s_mov_b32 m0, s60
	v_lshl_add_u64 v[128:129], s[6:7], 0, v[164:165]
	global_load_lds_dwordx4 v[128:129], off
	v_lshl_add_u64 v[128:129], s[6:7], 0, v[166:167]
	s_mov_b32 m0, s61
	s_nop 0
	global_load_lds_dwordx4 v[128:129], off
	s_waitcnt vmcnt(6)
	s_barrier
	s_setprio 0
	v_mfma_f32_16x16x32_bf16 v[44:47], v[186:189], v[144:147], v[44:47]
	v_mfma_f32_16x16x32_bf16 v[12:15], v[194:197], v[144:147], v[12:15]
	v_mfma_f32_16x16x32_bf16 v[40:43], v[186:189], v[152:155], v[40:43]
	v_mfma_f32_16x16x32_bf16 v[8:11], v[194:197], v[152:155], v[8:11]
	v_mfma_f32_16x16x32_bf16 v[36:39], v[186:189], v[160:163], v[36:39]
	v_mfma_f32_16x16x32_bf16 v[4:7], v[194:197], v[160:163], v[4:7]
	v_mfma_f32_16x16x32_bf16 v[32:35], v[186:189], v[178:181], v[32:35]
	v_mfma_f32_16x16x32_bf16 v[0:3], v[194:197], v[178:181], v[0:3]
	v_mfma_f32_16x16x32_bf16 v[44:47], v[190:193], v[148:151], v[44:47]
	v_mfma_f32_16x16x32_bf16 v[12:15], v[208:211], v[148:151], v[12:15]
	v_mfma_f32_16x16x32_bf16 v[40:43], v[190:193], v[156:159], v[40:43]
	v_mfma_f32_16x16x32_bf16 v[8:11], v[208:211], v[156:159], v[8:11]
	v_mfma_f32_16x16x32_bf16 v[36:39], v[190:193], v[174:177], v[36:39]
	v_mfma_f32_16x16x32_bf16 v[4:7], v[208:211], v[174:177], v[4:7]
	v_mfma_f32_16x16x32_bf16 v[32:35], v[190:193], v[182:185], v[32:35]
	v_mfma_f32_16x16x32_bf16 v[0:3], v[208:211], v[182:185], v[0:3]
	s_setprio 1
	s_barrier
	ds_read_b128 v[128:131], v201
	ds_read_b128 v[132:135], v201 offset:1024
	ds_read_b128 v[136:139], v201 offset:2048
	ds_read_b128 v[140:143], v201 offset:3072
	s_add_u32 s6, s12, 0x100000
	s_addc_u32 s7, s13, 0
	s_mov_b32 m0, s45
	v_lshl_add_u64 v[186:187], s[6:7], 0, v[164:165]
	ds_read_b128 v[144:147], v199 offset:32768
	ds_read_b128 v[148:151], v199 offset:33792
	ds_read_b128 v[152:155], v199 offset:34816
	ds_read_b128 v[156:159], v199 offset:35840
	ds_read_b128 v[160:163], v199 offset:36864
	ds_read_b128 v[174:177], v199 offset:37888
	ds_read_b128 v[178:181], v199 offset:38912
	ds_read_b128 v[182:185], v199 offset:39936
	global_load_lds_dwordx4 v[186:187], off
	v_lshl_add_u64 v[186:187], s[6:7], 0, v[166:167]
	s_mov_b32 m0, s46
	s_nop 0
	global_load_lds_dwordx4 v[186:187], off
	s_waitcnt lgkmcnt(8)
	s_barrier
	s_waitcnt lgkmcnt(0)
	s_setprio 0
	s_waitcnt lgkmcnt(0)
	v_mfma_f32_16x16x32_bf16 v[124:127], v[128:131], v[144:147], v[124:127]
	v_mfma_f32_16x16x32_bf16 v[92:95], v[136:139], v[144:147], v[92:95]
	v_mfma_f32_16x16x32_bf16 v[120:123], v[128:131], v[152:155], v[120:123]
	v_mfma_f32_16x16x32_bf16 v[88:91], v[136:139], v[152:155], v[88:91]
	v_mfma_f32_16x16x32_bf16 v[116:119], v[128:131], v[160:163], v[116:119]
	v_mfma_f32_16x16x32_bf16 v[84:87], v[136:139], v[160:163], v[84:87]
	v_mfma_f32_16x16x32_bf16 v[112:115], v[128:131], v[178:181], v[112:115]
	v_mfma_f32_16x16x32_bf16 v[80:83], v[136:139], v[178:181], v[80:83]
	v_mfma_f32_16x16x32_bf16 v[124:127], v[132:135], v[148:151], v[124:127]
	v_mfma_f32_16x16x32_bf16 v[92:95], v[140:143], v[148:151], v[92:95]
	v_mfma_f32_16x16x32_bf16 v[120:123], v[132:135], v[156:159], v[120:123]
	v_mfma_f32_16x16x32_bf16 v[88:91], v[140:143], v[156:159], v[88:91]
	v_mfma_f32_16x16x32_bf16 v[116:119], v[132:135], v[174:177], v[116:119]
	v_mfma_f32_16x16x32_bf16 v[84:87], v[140:143], v[174:177], v[84:87]
	v_mfma_f32_16x16x32_bf16 v[112:115], v[132:135], v[182:185], v[112:115]
	v_mfma_f32_16x16x32_bf16 v[80:83], v[140:143], v[182:185], v[80:83]
	s_setprio 1
	s_barrier
	s_mov_b32 m0, s64
	v_lshl_add_u64 v[204:205], v[204:205], 0, s[0:1]
	ds_read_b128 v[186:189], v202
	ds_read_b128 v[190:193], v202 offset:1024
	ds_read_b128 v[194:197], v202 offset:2048
	ds_read_b128 v[208:211], v202 offset:3072
	global_load_lds_dwordx4 v[204:205], off
	v_lshl_add_u64 v[204:205], v[212:213], 0, s[0:1]
	s_mov_b32 m0, s65
	s_nop 0
	global_load_lds_dwordx4 v[204:205], off
	s_barrier
	s_waitcnt lgkmcnt(0)
	s_setprio 0
	s_waitcnt lgkmcnt(0)
	v_mfma_f32_16x16x32_bf16 v[60:63], v[186:189], v[144:147], v[60:63]
	v_mfma_f32_16x16x32_bf16 v[28:31], v[194:197], v[144:147], v[28:31]
	v_mfma_f32_16x16x32_bf16 v[56:59], v[186:189], v[152:155], v[56:59]
	v_mfma_f32_16x16x32_bf16 v[24:27], v[194:197], v[152:155], v[24:27]
	v_mfma_f32_16x16x32_bf16 v[52:55], v[186:189], v[160:163], v[52:55]
	v_mfma_f32_16x16x32_bf16 v[20:23], v[194:197], v[160:163], v[20:23]
	v_mfma_f32_16x16x32_bf16 v[48:51], v[186:189], v[178:181], v[48:51]
	v_mfma_f32_16x16x32_bf16 v[16:19], v[194:197], v[178:181], v[16:19]
	v_mfma_f32_16x16x32_bf16 v[60:63], v[190:193], v[148:151], v[60:63]
	v_mfma_f32_16x16x32_bf16 v[28:31], v[208:211], v[148:151], v[28:31]
	v_mfma_f32_16x16x32_bf16 v[56:59], v[190:193], v[156:159], v[56:59]
	v_mfma_f32_16x16x32_bf16 v[24:27], v[208:211], v[156:159], v[24:27]
	v_mfma_f32_16x16x32_bf16 v[52:55], v[190:193], v[174:177], v[52:55]
	v_mfma_f32_16x16x32_bf16 v[20:23], v[208:211], v[174:177], v[20:23]
	v_mfma_f32_16x16x32_bf16 v[48:51], v[190:193], v[182:185], v[48:51]
	v_mfma_f32_16x16x32_bf16 v[16:19], v[208:211], v[182:185], v[16:19]
	s_setprio 1
	s_mov_b32 m0, s47
	v_lshl_add_u64 v[204:205], v[214:215], 0, s[0:1]
	s_barrier
	ds_read_b128 v[144:147], v199 offset:49152
	ds_read_b128 v[148:151], v199 offset:50176
	ds_read_b128 v[152:155], v199 offset:51200
	ds_read_b128 v[156:159], v199 offset:52224
	ds_read_b128 v[160:163], v199 offset:53248
	ds_read_b128 v[174:177], v199 offset:54272
	ds_read_b128 v[178:181], v199 offset:55296
	ds_read_b128 v[182:185], v199 offset:56320
	global_load_lds_dwordx4 v[204:205], off
	v_lshl_add_u64 v[204:205], v[216:217], 0, s[0:1]
	s_mov_b32 m0, s48
	s_nop 0
	global_load_lds_dwordx4 v[204:205], off
	s_barrier
; #define WAIT_V(n) asm volatile("s_waitcnt vmcnt(" #n ")" ::: "memory")
; #define WAIT_L(n) asm volatile("s_waitcnt lgkmcnt(" #n ")" ::: "memory")
; #define BAR __builtin_amdgcn_s_barrier()
; #define SCHED __builtin_amdgcn_sched_barrier(0)
; template <class Get, class Epi>
; DI void gemm_stream(LAS unsigned char* lds, const int K, const int ld, Get get, Epi epi) {
;     ...
;             LDA(At, 1, 1); STAGE(SAo(1, 0), a3);
;             BAR; WAIT_L(0); MMA(1, 0, At, B0); BAR; SCHED;
;             STAGE(SBo(1, 1), b3 + hstep);
;             WAIT_V(6); BAR; MMA(1, 1, At, B1); BAR;
;         }
; DI void epi_resid(const Acc& acc, const P& p, int brow, int bcol, int layer, int gch, bool from_input) {
;     EPI_IDX
;     const float* gate = modv(p, layer, brow, gch);
; #pragma unroll
;     for (int bj = 0; bj < 2; ++bj)
; #pragma unroll
;         for (int n = 0; n < 2; ++n) {
;             const int c0 = bcol + bj * 128 + wc * 32 + n * 16 + fq * 4;
;             const f32x4 g = *(const f32x4*)(gate + c0);
;             f32x4 xv[2][4];
; #pragma unroll
;             for (int ai = 0; ai < 2; ++ai)
; #pragma unroll
;                 for (int m = 0; m < 4; ++m) {
;                     const int r = brow + ai * 128 + wr * 64 + m * 16 + fr;
;                     const float* sp = (from_input ? inrow(p, r) : xrow(p, r)) + c0;
;                     xv[ai][m] = *(const f32x4*)sp;
;                 }
	s_waitcnt lgkmcnt(0)
	s_setprio 0
	s_waitcnt lgkmcnt(0)
	v_mfma_f32_16x16x32_bf16 v[108:111], v[128:131], v[144:147], v[108:111]
	v_mfma_f32_16x16x32_bf16 v[76:79], v[136:139], v[144:147], v[76:79]
	v_mfma_f32_16x16x32_bf16 v[104:107], v[128:131], v[152:155], v[104:107]
	v_mfma_f32_16x16x32_bf16 v[72:75], v[136:139], v[152:155], v[72:75]
	v_mfma_f32_16x16x32_bf16 v[100:103], v[128:131], v[160:163], v[100:103]
	v_mfma_f32_16x16x32_bf16 v[68:71], v[136:139], v[160:163], v[68:71]
	v_mfma_f32_16x16x32_bf16 v[96:99], v[128:131], v[178:181], v[96:99]
	v_mfma_f32_16x16x32_bf16 v[64:67], v[136:139], v[178:181], v[64:67]
	v_mfma_f32_16x16x32_bf16 v[108:111], v[132:135], v[148:151], v[108:111]
	v_mfma_f32_16x16x32_bf16 v[76:79], v[140:143], v[148:151], v[76:79]
	v_mfma_f32_16x16x32_bf16 v[104:107], v[132:135], v[156:159], v[104:107]
	v_mfma_f32_16x16x32_bf16 v[72:75], v[140:143], v[156:159], v[72:75]
	v_mfma_f32_16x16x32_bf16 v[100:103], v[132:135], v[174:177], v[100:103]
	v_mfma_f32_16x16x32_bf16 v[68:71], v[140:143], v[174:177], v[68:71]
	v_mfma_f32_16x16x32_bf16 v[96:99], v[132:135], v[182:185], v[96:99]
	v_mfma_f32_16x16x32_bf16 v[64:67], v[140:143], v[182:185], v[64:67]
	s_setprio 1
	s_barrier
	s_add_u32 s6, s10, 0x100080
	s_addc_u32 s7, s11, 0
	s_mov_b32 m0, s68
	v_lshl_add_u64 v[128:129], s[6:7], 0, v[164:165]
	global_load_lds_dwordx4 v[128:129], off
	v_lshl_add_u64 v[128:129], s[6:7], 0, v[166:167]
	s_mov_b32 m0, s69
	s_nop 0
	global_load_lds_dwordx4 v[128:129], off
	s_waitcnt vmcnt(6)
	s_barrier
	s_setprio 0
	v_mfma_f32_16x16x32_bf16 v[44:47], v[186:189], v[144:147], v[44:47]
	v_mfma_f32_16x16x32_bf16 v[12:15], v[194:197], v[144:147], v[12:15]
	v_mfma_f32_16x16x32_bf16 v[40:43], v[186:189], v[152:155], v[40:43]
	v_mfma_f32_16x16x32_bf16 v[8:11], v[194:197], v[152:155], v[8:11]
	v_mfma_f32_16x16x32_bf16 v[36:39], v[186:189], v[160:163], v[36:39]
	v_mfma_f32_16x16x32_bf16 v[4:7], v[194:197], v[160:163], v[4:7]
	v_mfma_f32_16x16x32_bf16 v[32:35], v[186:189], v[178:181], v[32:35]
	v_mfma_f32_16x16x32_bf16 v[0:3], v[194:197], v[178:181], v[0:3]
	v_mfma_f32_16x16x32_bf16 v[44:47], v[190:193], v[148:151], v[44:47]
	v_mfma_f32_16x16x32_bf16 v[12:15], v[208:211], v[148:151], v[12:15]
	v_mfma_f32_16x16x32_bf16 v[40:43], v[190:193], v[156:159], v[40:43]
	v_mfma_f32_16x16x32_bf16 v[8:11], v[208:211], v[156:159], v[8:11]
	v_mfma_f32_16x16x32_bf16 v[36:39], v[190:193], v[174:177], v[36:39]
	v_mfma_f32_16x16x32_bf16 v[4:7], v[208:211], v[174:177], v[4:7]
	v_mfma_f32_16x16x32_bf16 v[32:35], v[190:193], v[182:185], v[32:35]
	v_mfma_f32_16x16x32_bf16 v[0:3], v[208:211], v[182:185], v[0:3]
	s_setprio 1
	s_add_i32 s16, s16, 2
	s_add_u32 s14, s14, 0x100
	s_addc_u32 s15, s15, 0
	s_cmp_gt_u32 s16, 61
	s_mov_b64 s[6:7], s[8:9]
	s_barrier
	s_cbranch_scc0 .LBB0_2670
	s_lshr_b32 s6, s3, 4
	s_lshl_b32 s3, s3, 8
	s_mulk_i32 s6, 0x1100
	s_and_b32 s3, s3, 0xf00
	s_add_i32 s3, s6, s3
	s_add_i32 s6, s3, 0x100
	s_lshl_b32 s7, s2, 8
	s_mul_hi_i32 s2, s6, 0x78787879
	s_lshr_b32 s3, s2, 31
	s_ashr_i32 s2, s2, 11
	s_add_i32 s2, s2, s3
	s_mul_i32 s3, s2, 0xffffef00
	s_mul_i32 s2, s2, 6
	s_add_i32 s3, s3, s6
	s_add_i32 s2, s2, 32
	s_cmpk_gt_i32 s3, 0xff
	v_mov_b32_e32 v132, v206
	s_cselect_b32 s2, s2, 56
	s_ashr_i32 s3, s2, 31
	v_lshrrev_b32_e32 v128, 1, v132
	v_lshrrev_b32_e32 v129, 2, v132
	s_lshl_b64 s[2:3], s[2:3], 13
	v_and_b32_e32 v128, 0x60, v128
	v_and_b32_e32 v129, 12, v129
	s_add_u32 s2, s26, s2
	v_or3_b32 v174, v128, s7, v129
	s_addc_u32 s3, s27, s3
	v_ashrrev_i32_e32 v175, 31, v174
	v_lshl_add_u64 v[192:193], v[174:175], 2, s[2:3]
	global_load_dwordx4 v[128:131], v[192:193], off
	v_ashrrev_i32_e32 v133, 2, v132
	v_and_b32_e32 v133, 0xffffffc0, v133
	v_and_or_b32 v132, v132, 15, s6
	v_add_u32_e32 v176, v132, v133
	v_mul_hi_i32 v132, v176, s54
	v_lshrrev_b32_e32 v133, 31, v132
	v_ashrrev_i32_e32 v132, 11, v132
	v_add_u32_e32 v204, v132, v133
	v_mad_i32_i24 v203, v204, s55, v176
	v_lshlrev_b32_e32 v213, 12, v204
	v_cmp_lt_i32_e64 s[18:19], s56, v203
	v_add3_u32 v190, v213, v203, s57
	s_and_saveexec_b64 s[2:3], s[18:19]
	s_xor_b64 s[6:7], exec, s[2:3]
	v_add3_u32 v132, v213, v203, s57
	s_or_saveexec_b64 s[6:7], s[6:7]
	v_mov_b64_e32 v[134:135], s[24:25]
	v_lshl_add_u32 v191, v204, 8, v203
	s_xor_b64 exec, exec, s[6:7]
	v_lshl_add_u32 v132, v204, 8, v203
	v_mov_b64_e32 v[134:135], s[36:37]
	s_or_b64 exec, exec, s[6:7]
	v_ashrrev_i32_e32 v133, 31, v132
	v_lshlrev_b64 v[132:133], 13, v[132:133]
	v_lshl_add_u64 v[132:133], v[134:135], 0, v[132:133]
	v_lshl_add_u64 v[132:133], v[174:175], 2, v[132:133]
	global_load_dwordx4 v[160:163], v[132:133], off
	v_or_b32_e32 v132, 16, v176
	v_mul_hi_i32 v133, v132, s54
	v_lshrrev_b32_e32 v134, 31, v133
	v_ashrrev_i32_e32 v133, 11, v133
	v_add_u32_e32 v208, v133, v134
	v_mad_i32_i24 v205, v208, s55, v132
	v_lshlrev_b32_e32 v218, 12, v208
	v_cmp_lt_i32_e64 s[16:17], s56, v205
	v_add3_u32 v188, v218, v205, s57
	s_and_saveexec_b64 s[2:3], s[16:17]
	s_xor_b64 s[6:7], exec, s[2:3]
	v_add3_u32 v132, v218, v205, s57
	s_or_saveexec_b64 s[6:7], s[6:7]
	v_mov_b64_e32 v[134:135], s[24:25]
	v_lshl_add_u32 v189, v208, 8, v205
	s_xor_b64 exec, exec, s[6:7]
	v_lshl_add_u32 v132, v208, 8, v205
	v_mov_b64_e32 v[134:135], s[36:37]
	s_or_b64 exec, exec, s[6:7]
	v_ashrrev_i32_e32 v133, 31, v132
	v_lshlrev_b64 v[132:133], 13, v[132:133]
	v_lshl_add_u64 v[132:133], v[134:135], 0, v[132:133]
	v_lshl_add_u64 v[132:133], v[174:175], 2, v[132:133]
	global_load_dwordx4 v[156:159], v[132:133], off
	v_or_b32_e32 v132, 32, v176
	v_mul_hi_i32 v133, v132, s54
	v_lshrrev_b32_e32 v134, 31, v133
	v_ashrrev_i32_e32 v133, 11, v133
	v_add_u32_e32 v210, v133, v134
; DI void epi_resid(const Acc& acc, const P& p, int brow, int bcol, int layer, int gch, bool from_input) {
;     ...
; #pragma unroll
;             for (int ai = 0; ai < 2; ++ai)
; #pragma unroll
;                 for (int m = 0; m < 4; ++m) {
;                     const int r = brow + ai * 128 + wr * 64 + m * 16 + fr;
;                     const float* sp = (from_input ? inrow(p, r) : xrow(p, r)) + c0;
;                     xv[ai][m] = *(const f32x4*)sp;
;                 }
	v_mad_i32_i24 v209, v210, s55, v132
	v_lshlrev_b32_e32 v221, 12, v210
	v_cmp_lt_i32_e64 s[14:15], s56, v209
	v_add3_u32 v186, v221, v209, s57
	s_and_saveexec_b64 s[2:3], s[14:15]
	s_xor_b64 s[6:7], exec, s[2:3]
	v_add3_u32 v132, v221, v209, s57
	s_or_saveexec_b64 s[6:7], s[6:7]
	v_mov_b64_e32 v[134:135], s[24:25]
	v_lshl_add_u32 v187, v210, 8, v209
	s_xor_b64 exec, exec, s[6:7]
	v_lshl_add_u32 v132, v210, 8, v209
	v_mov_b64_e32 v[134:135], s[36:37]
	s_or_b64 exec, exec, s[6:7]
	v_ashrrev_i32_e32 v133, 31, v132
	v_lshlrev_b64 v[132:133], 13, v[132:133]
	v_lshl_add_u64 v[132:133], v[134:135], 0, v[132:133]
	v_lshl_add_u64 v[132:133], v[174:175], 2, v[132:133]
	global_load_dwordx4 v[152:155], v[132:133], off
	v_or_b32_e32 v132, 48, v176
	v_mul_hi_i32 v133, v132, s54
	v_lshrrev_b32_e32 v134, 31, v133
	v_ashrrev_i32_e32 v133, 11, v133
	v_add_u32_e32 v212, v133, v134
	v_mad_i32_i24 v211, v212, s55, v132
	v_lshlrev_b32_e32 v224, 12, v212
	v_cmp_lt_i32_e64 s[12:13], s56, v211
	v_add3_u32 v184, v224, v211, s57
	s_and_saveexec_b64 s[2:3], s[12:13]
	s_xor_b64 s[6:7], exec, s[2:3]
	v_add3_u32 v132, v224, v211, s57
	s_or_saveexec_b64 s[6:7], s[6:7]
	v_mov_b64_e32 v[134:135], s[24:25]
	v_lshl_add_u32 v185, v212, 8, v211
	s_xor_b64 exec, exec, s[6:7]
	v_lshl_add_u32 v132, v212, 8, v211
	v_mov_b64_e32 v[134:135], s[36:37]
	s_or_b64 exec, exec, s[6:7]
	v_ashrrev_i32_e32 v133, 31, v132
	v_lshlrev_b64 v[132:133], 13, v[132:133]
	v_lshl_add_u64 v[132:133], v[134:135], 0, v[132:133]
	v_lshl_add_u64 v[132:133], v[174:175], 2, v[132:133]
	global_load_dwordx4 v[148:151], v[132:133], off
	v_add_u32_e32 v132, 0x80, v176
	v_mul_hi_i32 v133, v132, s54
	v_lshrrev_b32_e32 v134, 31, v133
	v_ashrrev_i32_e32 v133, 11, v133
	v_add_u32_e32 v215, v133, v134
	v_mad_i32_i24 v214, v215, s55, v132
	v_lshlrev_b32_e32 v225, 12, v215
	v_cmp_lt_i32_e64 s[10:11], s56, v214
	v_add3_u32 v182, v225, v214, s57
	s_and_saveexec_b64 s[2:3], s[10:11]
	s_xor_b64 s[6:7], exec, s[2:3]
	v_add3_u32 v132, v225, v214, s57
	s_or_saveexec_b64 s[6:7], s[6:7]
	v_mov_b64_e32 v[134:135], s[24:25]
	v_lshl_add_u32 v183, v215, 8, v214
	s_xor_b64 exec, exec, s[6:7]
	v_lshl_add_u32 v132, v215, 8, v214
	v_mov_b64_e32 v[134:135], s[36:37]
	s_or_b64 exec, exec, s[6:7]
	v_ashrrev_i32_e32 v133, 31, v132
	v_lshlrev_b64 v[132:133], 13, v[132:133]
	v_lshl_add_u64 v[132:133], v[134:135], 0, v[132:133]
	v_lshl_add_u64 v[132:133], v[174:175], 2, v[132:133]
	global_load_dwordx4 v[144:147], v[132:133], off
	v_add_u32_e32 v132, 0x90, v176
	v_mul_hi_i32 v133, v132, s54
	v_lshrrev_b32_e32 v134, 31, v133
	v_ashrrev_i32_e32 v133, 11, v133
	v_add_u32_e32 v217, v133, v134
	v_mad_i32_i24 v216, v217, s55, v132
	v_lshlrev_b32_e32 v226, 12, v217
	v_cmp_lt_i32_e64 s[8:9], s56, v216
	v_add3_u32 v180, v226, v216, s57
	s_and_saveexec_b64 s[2:3], s[8:9]
	s_xor_b64 s[6:7], exec, s[2:3]
	v_add3_u32 v132, v226, v216, s57
	s_or_saveexec_b64 s[6:7], s[6:7]
	v_mov_b64_e32 v[134:135], s[24:25]
	v_lshl_add_u32 v181, v217, 8, v216
	s_xor_b64 exec, exec, s[6:7]
	v_lshl_add_u32 v132, v217, 8, v216
	v_mov_b64_e32 v[134:135], s[36:37]
	s_or_b64 exec, exec, s[6:7]
	v_ashrrev_i32_e32 v133, 31, v132
	v_lshlrev_b64 v[132:133], 13, v[132:133]
	v_lshl_add_u64 v[132:133], v[134:135], 0, v[132:133]
	v_lshl_add_u64 v[132:133], v[174:175], 2, v[132:133]
	global_load_dwordx4 v[140:143], v[132:133], off
	v_add_u32_e32 v132, 0xa0, v176
	v_mul_hi_i32 v133, v132, s54
	v_lshrrev_b32_e32 v134, 31, v133
	v_ashrrev_i32_e32 v133, 11, v133
	v_add_u32_e32 v220, v133, v134
	v_mad_i32_i24 v219, v220, s55, v132
	v_lshlrev_b32_e32 v227, 12, v220
	v_cmp_lt_i32_e64 s[6:7], s56, v219
	v_add3_u32 v178, v227, v219, s57
	s_and_saveexec_b64 s[2:3], s[6:7]
	s_xor_b64 s[42:43], exec, s[2:3]
	v_add3_u32 v132, v227, v219, s57
	s_or_saveexec_b64 s[42:43], s[42:43]
	v_mov_b64_e32 v[134:135], s[24:25]
	v_lshl_add_u32 v179, v220, 8, v219
	s_xor_b64 exec, exec, s[42:43]
	v_lshl_add_u32 v132, v220, 8, v219
	v_mov_b64_e32 v[134:135], s[36:37]
	s_or_b64 exec, exec, s[42:43]
	v_ashrrev_i32_e32 v133, 31, v132
	v_lshlrev_b64 v[132:133], 13, v[132:133]
	v_lshl_add_u64 v[132:133], v[134:135], 0, v[132:133]
	v_lshl_add_u64 v[132:133], v[174:175], 2, v[132:133]
	global_load_dwordx4 v[136:139], v[132:133], off
	v_add_u32_e32 v132, 0xb0, v176
	v_mul_hi_i32 v133, v132, s54
	v_lshrrev_b32_e32 v134, 31, v133
	v_ashrrev_i32_e32 v133, 11, v133
	v_add_u32_e32 v223, v133, v134
	v_mad_i32_i24 v222, v223, s55, v132
	v_lshlrev_b32_e32 v228, 12, v223
	v_cmp_lt_i32_e32 vcc, s56, v222
	v_add3_u32 v176, v228, v222, s57
	s_and_saveexec_b64 s[2:3], vcc
	s_xor_b64 s[42:43], exec, s[2:3]
	v_add3_u32 v132, v228, v222, s57
	s_or_saveexec_b64 s[42:43], s[42:43]
	v_mov_b64_e32 v[134:135], s[24:25]
	v_lshl_add_u32 v177, v223, 8, v222
	s_xor_b64 exec, exec, s[42:43]
	v_lshl_add_u32 v132, v223, 8, v222
	v_mov_b64_e32 v[134:135], s[36:37]
	s_or_b64 exec, exec, s[42:43]
	v_ashrrev_i32_e32 v133, 31, v132
	v_lshlrev_b64 v[132:133], 13, v[132:133]
	v_lshl_add_u64 v[132:133], v[134:135], 0, v[132:133]
	v_lshl_add_u64 v[132:133], v[174:175], 2, v[132:133]
	global_load_dwordx4 v[132:135], v[132:133], off
	s_and_saveexec_b64 s[2:3], s[18:19]
	s_xor_b64 s[42:43], exec, s[2:3]
	v_add3_u32 v194, v213, v203, s57
	s_or_saveexec_b64 s[42:43], s[42:43]
	v_mov_b64_e32 v[196:197], s[24:25]
	s_xor_b64 exec, exec, s[42:43]
	v_lshl_add_u32 v194, v204, 8, v203
	v_mov_b64_e32 v[196:197], s[36:37]
	s_or_b64 exec, exec, s[42:43]
	v_ashrrev_i32_e32 v195, 31, v194
	s_waitcnt vmcnt(0)
; DI void epi_resid(const Acc& acc, const P& p, int brow, int bcol, int layer, int gch, bool from_input) {
;     ...
;             __builtin_amdgcn_sched_barrier(0);
; #pragma unroll
;             for (int ai = 0; ai < 2; ++ai)
; #pragma unroll
;                 for (int m = 0; m < 4; ++m) {
;                     const int r = brow + ai * 128 + wr * 64 + m * 16 + fr;
;                     *(f32x4*)(xrow(p, r) + c0) = xv[ai][m] + g * acc[ai][bj][m][n];
;                 }
;             __builtin_amdgcn_sched_barrier(0);
;         }
	v_pk_fma_f32 v[124:125], v[124:125], v[128:129], v[160:161]
	v_lshlrev_b64 v[160:161], 13, v[194:195]
	v_lshl_add_u64 v[160:161], v[196:197], 0, v[160:161]
	v_pk_fma_f32 v[126:127], v[126:127], v[130:131], v[162:163]
	v_lshl_add_u64 v[160:161], v[174:175], 2, v[160:161]
	global_store_dwordx4 v[160:161], v[124:127], off
	s_and_saveexec_b64 s[2:3], s[16:17]
	s_xor_b64 s[42:43], exec, s[2:3]
	v_add3_u32 v124, v218, v205, s57
	s_or_saveexec_b64 s[42:43], s[42:43]
	v_mov_b64_e32 v[126:127], s[24:25]
	s_xor_b64 exec, exec, s[42:43]
	v_lshl_add_u32 v124, v208, 8, v205
	v_mov_b64_e32 v[126:127], s[36:37]
	s_or_b64 exec, exec, s[42:43]
	v_ashrrev_i32_e32 v125, 31, v124
	v_lshlrev_b64 v[124:125], 13, v[124:125]
	v_lshl_add_u64 v[124:125], v[126:127], 0, v[124:125]
	v_pk_fma_f32 v[122:123], v[122:123], v[130:131], v[158:159]
	v_pk_fma_f32 v[120:121], v[120:121], v[128:129], v[156:157]
	v_lshl_add_u64 v[124:125], v[174:175], 2, v[124:125]
	global_store_dwordx4 v[124:125], v[120:123], off
	s_and_saveexec_b64 s[2:3], s[14:15]
	s_xor_b64 s[42:43], exec, s[2:3]
	v_add3_u32 v120, v221, v209, s57
	s_or_saveexec_b64 s[42:43], s[42:43]
	v_mov_b64_e32 v[122:123], s[24:25]
	s_xor_b64 exec, exec, s[42:43]
	v_lshl_add_u32 v120, v210, 8, v209
	v_mov_b64_e32 v[122:123], s[36:37]
	s_or_b64 exec, exec, s[42:43]
	v_ashrrev_i32_e32 v121, 31, v120
	v_lshlrev_b64 v[120:121], 13, v[120:121]
	v_lshl_add_u64 v[120:121], v[122:123], 0, v[120:121]
	v_pk_fma_f32 v[118:119], v[118:119], v[130:131], v[154:155]
	v_pk_fma_f32 v[116:117], v[116:117], v[128:129], v[152:153]
	v_lshl_add_u64 v[120:121], v[174:175], 2, v[120:121]
	global_store_dwordx4 v[120:121], v[116:119], off
	s_and_saveexec_b64 s[2:3], s[12:13]
	s_xor_b64 s[42:43], exec, s[2:3]
	v_add3_u32 v116, v224, v211, s57
	s_or_saveexec_b64 s[42:43], s[42:43]
	v_mov_b64_e32 v[118:119], s[24:25]
	s_xor_b64 exec, exec, s[42:43]
	v_lshl_add_u32 v116, v212, 8, v211
	v_mov_b64_e32 v[118:119], s[36:37]
	s_or_b64 exec, exec, s[42:43]
	v_ashrrev_i32_e32 v117, 31, v116
	v_lshlrev_b64 v[116:117], 13, v[116:117]
	v_lshl_add_u64 v[116:117], v[118:119], 0, v[116:117]
	v_pk_fma_f32 v[114:115], v[114:115], v[130:131], v[150:151]
	v_pk_fma_f32 v[112:113], v[112:113], v[128:129], v[148:149]
	v_lshl_add_u64 v[116:117], v[174:175], 2, v[116:117]
	global_store_dwordx4 v[116:117], v[112:115], off
	s_and_saveexec_b64 s[2:3], s[10:11]
	s_xor_b64 s[42:43], exec, s[2:3]
	v_add3_u32 v112, v225, v214, s57
	s_or_saveexec_b64 s[42:43], s[42:43]
	v_mov_b64_e32 v[114:115], s[24:25]
	s_xor_b64 exec, exec, s[42:43]
	v_lshl_add_u32 v112, v215, 8, v214
	v_mov_b64_e32 v[114:115], s[36:37]
	s_or_b64 exec, exec, s[42:43]
	v_ashrrev_i32_e32 v113, 31, v112
	v_lshlrev_b64 v[112:113], 13, v[112:113]
	v_lshl_add_u64 v[112:113], v[114:115], 0, v[112:113]
	v_pk_fma_f32 v[110:111], v[110:111], v[130:131], v[146:147]
	v_pk_fma_f32 v[108:109], v[108:109], v[128:129], v[144:145]
	v_lshl_add_u64 v[112:113], v[174:175], 2, v[112:113]
	global_store_dwordx4 v[112:113], v[108:111], off
	s_and_saveexec_b64 s[2:3], s[8:9]
	s_xor_b64 s[42:43], exec, s[2:3]
	v_add3_u32 v108, v226, v216, s57
	s_or_saveexec_b64 s[42:43], s[42:43]
	v_mov_b64_e32 v[110:111], s[24:25]
	s_xor_b64 exec, exec, s[42:43]
	v_lshl_add_u32 v108, v217, 8, v216
	v_mov_b64_e32 v[110:111], s[36:37]
	s_or_b64 exec, exec, s[42:43]
	v_ashrrev_i32_e32 v109, 31, v108
	v_lshlrev_b64 v[108:109], 13, v[108:109]
	v_lshl_add_u64 v[108:109], v[110:111], 0, v[108:109]
	v_pk_fma_f32 v[106:107], v[106:107], v[130:131], v[142:143]
	v_pk_fma_f32 v[104:105], v[104:105], v[128:129], v[140:141]
	v_lshl_add_u64 v[108:109], v[174:175], 2, v[108:109]
	global_store_dwordx4 v[108:109], v[104:107], off
	s_and_saveexec_b64 s[2:3], s[6:7]
	s_xor_b64 s[42:43], exec, s[2:3]
	v_add3_u32 v104, v227, v219, s57
	s_or_saveexec_b64 s[42:43], s[42:43]
	v_mov_b64_e32 v[106:107], s[24:25]
	s_xor_b64 exec, exec, s[42:43]
	v_lshl_add_u32 v104, v220, 8, v219
	v_mov_b64_e32 v[106:107], s[36:37]
	s_or_b64 exec, exec, s[42:43]
	v_ashrrev_i32_e32 v105, 31, v104
	v_lshlrev_b64 v[104:105], 13, v[104:105]
	v_lshl_add_u64 v[104:105], v[106:107], 0, v[104:105]
	v_pk_fma_f32 v[102:103], v[102:103], v[130:131], v[138:139]
	v_pk_fma_f32 v[100:101], v[100:101], v[128:129], v[136:137]
	v_lshl_add_u64 v[104:105], v[174:175], 2, v[104:105]
	global_store_dwordx4 v[104:105], v[100:103], off
	s_and_saveexec_b64 s[2:3], vcc
	s_xor_b64 s[42:43], exec, s[2:3]
	v_add3_u32 v100, v228, v222, s57
	s_or_saveexec_b64 s[42:43], s[42:43]
	v_mov_b64_e32 v[102:103], s[24:25]
	s_xor_b64 exec, exec, s[42:43]
	v_lshl_add_u32 v100, v223, 8, v222
	v_mov_b64_e32 v[102:103], s[36:37]
	s_or_b64 exec, exec, s[42:43]
	v_ashrrev_i32_e32 v101, 31, v100
	v_lshlrev_b64 v[100:101], 13, v[100:101]
	v_lshl_add_u64 v[100:101], v[102:103], 0, v[100:101]
	v_pk_fma_f32 v[98:99], v[98:99], v[130:131], v[134:135]
	v_pk_fma_f32 v[96:97], v[96:97], v[128:129], v[132:133]
	v_lshl_add_u64 v[100:101], v[174:175], 2, v[100:101]
	global_store_dwordx4 v[100:101], v[96:99], off
	global_load_dwordx4 v[96:99], v[192:193], off offset:64
	s_and_saveexec_b64 s[2:3], s[18:19]
	s_xor_b64 s[42:43], exec, s[2:3]
	v_add3_u32 v100, v213, v203, s57
	s_or_saveexec_b64 s[42:43], s[42:43]
	v_mov_b64_e32 v[102:103], s[24:25]
	s_xor_b64 exec, exec, s[42:43]
	v_lshl_add_u32 v100, v204, 8, v203
	v_mov_b64_e32 v[102:103], s[36:37]
	s_or_b64 exec, exec, s[42:43]
	v_ashrrev_i32_e32 v101, 31, v100
	v_lshlrev_b64 v[100:101], 13, v[100:101]
	v_lshl_add_u64 v[100:101], v[102:103], 0, v[100:101]
	v_lshl_add_u64 v[100:101], v[174:175], 2, v[100:101]
	global_load_dwordx4 v[128:131], v[100:101], off offset:64
	s_and_saveexec_b64 s[2:3], s[16:17]
; DI void epi_resid(const Acc& acc, const P& p, int brow, int bcol, int layer, int gch, bool from_input) {
;     ...
; #pragma unroll
;             for (int ai = 0; ai < 2; ++ai)
; #pragma unroll
;                 for (int m = 0; m < 4; ++m) {
;                     const int r = brow + ai * 128 + wr * 64 + m * 16 + fr;
;                     const float* sp = (from_input ? inrow(p, r) : xrow(p, r)) + c0;
;                     xv[ai][m] = *(const f32x4*)sp;
;                 }
;             __builtin_amdgcn_sched_barrier(0);
; #pragma unroll
;             for (int ai = 0; ai < 2; ++ai)
; #pragma unroll
;                 for (int m = 0; m < 4; ++m) {
;                     const int r = brow + ai * 128 + wr * 64 + m * 16 + fr;
;                     *(f32x4*)(xrow(p, r) + c0) = xv[ai][m] + g * acc[ai][bj][m][n];
;                 }
;             __builtin_amdgcn_sched_barrier(0);
;         }
	s_xor_b64 s[42:43], exec, s[2:3]
	v_add3_u32 v100, v218, v205, s57
	s_or_saveexec_b64 s[42:43], s[42:43]
	v_mov_b64_e32 v[102:103], s[24:25]
	s_xor_b64 exec, exec, s[42:43]
	v_lshl_add_u32 v100, v208, 8, v205
	v_mov_b64_e32 v[102:103], s[36:37]
	s_or_b64 exec, exec, s[42:43]
	v_ashrrev_i32_e32 v101, 31, v100
	v_lshlrev_b64 v[100:101], 13, v[100:101]
	v_lshl_add_u64 v[100:101], v[102:103], 0, v[100:101]
	v_lshl_add_u64 v[100:101], v[174:175], 2, v[100:101]
	global_load_dwordx4 v[124:127], v[100:101], off offset:64
	s_and_saveexec_b64 s[2:3], s[14:15]
	s_xor_b64 s[42:43], exec, s[2:3]
	v_add3_u32 v100, v221, v209, s57
	s_or_saveexec_b64 s[42:43], s[42:43]
	v_mov_b64_e32 v[102:103], s[24:25]
	s_xor_b64 exec, exec, s[42:43]
	v_lshl_add_u32 v100, v210, 8, v209
	v_mov_b64_e32 v[102:103], s[36:37]
	s_or_b64 exec, exec, s[42:43]
	v_ashrrev_i32_e32 v101, 31, v100
	v_lshlrev_b64 v[100:101], 13, v[100:101]
	v_lshl_add_u64 v[100:101], v[102:103], 0, v[100:101]
	v_lshl_add_u64 v[100:101], v[174:175], 2, v[100:101]
	global_load_dwordx4 v[120:123], v[100:101], off offset:64
	s_and_saveexec_b64 s[2:3], s[12:13]
	s_xor_b64 s[42:43], exec, s[2:3]
	v_add3_u32 v100, v224, v211, s57
	s_or_saveexec_b64 s[42:43], s[42:43]
	v_mov_b64_e32 v[102:103], s[24:25]
	s_xor_b64 exec, exec, s[42:43]
	v_lshl_add_u32 v100, v212, 8, v211
	v_mov_b64_e32 v[102:103], s[36:37]
	s_or_b64 exec, exec, s[42:43]
	v_ashrrev_i32_e32 v101, 31, v100
	v_lshlrev_b64 v[100:101], 13, v[100:101]
	v_lshl_add_u64 v[100:101], v[102:103], 0, v[100:101]
	v_lshl_add_u64 v[100:101], v[174:175], 2, v[100:101]
	global_load_dwordx4 v[116:119], v[100:101], off offset:64
	s_and_saveexec_b64 s[2:3], s[10:11]
	s_xor_b64 s[42:43], exec, s[2:3]
	v_add3_u32 v100, v225, v214, s57
	s_or_saveexec_b64 s[42:43], s[42:43]
	v_mov_b64_e32 v[102:103], s[24:25]
	s_xor_b64 exec, exec, s[42:43]
	v_lshl_add_u32 v100, v215, 8, v214
	v_mov_b64_e32 v[102:103], s[36:37]
	s_or_b64 exec, exec, s[42:43]
	v_ashrrev_i32_e32 v101, 31, v100
	v_lshlrev_b64 v[100:101], 13, v[100:101]
	v_lshl_add_u64 v[100:101], v[102:103], 0, v[100:101]
	v_lshl_add_u64 v[100:101], v[174:175], 2, v[100:101]
	global_load_dwordx4 v[112:115], v[100:101], off offset:64
	s_and_saveexec_b64 s[2:3], s[8:9]
	s_xor_b64 s[42:43], exec, s[2:3]
	v_add3_u32 v100, v226, v216, s57
	s_or_saveexec_b64 s[42:43], s[42:43]
	v_mov_b64_e32 v[102:103], s[24:25]
	s_xor_b64 exec, exec, s[42:43]
	v_lshl_add_u32 v100, v217, 8, v216
	v_mov_b64_e32 v[102:103], s[36:37]
	s_or_b64 exec, exec, s[42:43]
	v_ashrrev_i32_e32 v101, 31, v100
	v_lshlrev_b64 v[100:101], 13, v[100:101]
	v_lshl_add_u64 v[100:101], v[102:103], 0, v[100:101]
	v_lshl_add_u64 v[100:101], v[174:175], 2, v[100:101]
	global_load_dwordx4 v[108:111], v[100:101], off offset:64
	s_and_saveexec_b64 s[2:3], s[6:7]
	s_xor_b64 s[42:43], exec, s[2:3]
	v_add3_u32 v100, v227, v219, s57
	s_or_saveexec_b64 s[42:43], s[42:43]
	v_mov_b64_e32 v[102:103], s[24:25]
	s_xor_b64 exec, exec, s[42:43]
	v_lshl_add_u32 v100, v220, 8, v219
	v_mov_b64_e32 v[102:103], s[36:37]
	s_or_b64 exec, exec, s[42:43]
	v_ashrrev_i32_e32 v101, 31, v100
	v_lshlrev_b64 v[100:101], 13, v[100:101]
	v_lshl_add_u64 v[100:101], v[102:103], 0, v[100:101]
	v_lshl_add_u64 v[100:101], v[174:175], 2, v[100:101]
	global_load_dwordx4 v[104:107], v[100:101], off offset:64
	s_and_saveexec_b64 s[2:3], vcc
	s_xor_b64 s[42:43], exec, s[2:3]
	v_add3_u32 v100, v228, v222, s57
	s_or_saveexec_b64 s[42:43], s[42:43]
	v_mov_b64_e32 v[102:103], s[24:25]
	s_xor_b64 exec, exec, s[42:43]
	v_lshl_add_u32 v100, v223, 8, v222
	v_mov_b64_e32 v[102:103], s[36:37]
	s_or_b64 exec, exec, s[42:43]
	v_ashrrev_i32_e32 v101, 31, v100
	v_lshlrev_b64 v[100:101], 13, v[100:101]
	v_lshl_add_u64 v[100:101], v[102:103], 0, v[100:101]
	v_lshl_add_u64 v[100:101], v[174:175], 2, v[100:101]
	global_load_dwordx4 v[100:103], v[100:101], off offset:64
	s_and_saveexec_b64 s[2:3], s[18:19]
	s_xor_b64 s[42:43], exec, s[2:3]
	v_add3_u32 v132, v213, v203, s57
	s_or_saveexec_b64 s[42:43], s[42:43]
	v_mov_b64_e32 v[134:135], s[24:25]
	s_xor_b64 exec, exec, s[42:43]
	v_lshl_add_u32 v132, v204, 8, v203
	v_mov_b64_e32 v[134:135], s[36:37]
	s_or_b64 exec, exec, s[42:43]
	v_ashrrev_i32_e32 v133, 31, v132
	s_waitcnt vmcnt(0)
	v_pk_fma_f32 v[92:93], v[92:93], v[96:97], v[128:129]
	v_lshlrev_b64 v[128:129], 13, v[132:133]
	v_lshl_add_u64 v[128:129], v[134:135], 0, v[128:129]
	v_pk_fma_f32 v[94:95], v[94:95], v[98:99], v[130:131]
	v_lshl_add_u64 v[128:129], v[174:175], 2, v[128:129]
	global_store_dwordx4 v[128:129], v[92:95], off offset:64
	s_and_saveexec_b64 s[2:3], s[16:17]
	s_xor_b64 s[42:43], exec, s[2:3]
	v_add3_u32 v92, v218, v205, s57
	s_or_saveexec_b64 s[42:43], s[42:43]
	v_mov_b64_e32 v[94:95], s[24:25]
	s_xor_b64 exec, exec, s[42:43]
	v_lshl_add_u32 v92, v208, 8, v205
	v_mov_b64_e32 v[94:95], s[36:37]
	s_or_b64 exec, exec, s[42:43]
	v_ashrrev_i32_e32 v93, 31, v92
	v_lshlrev_b64 v[92:93], 13, v[92:93]
	v_lshl_add_u64 v[92:93], v[94:95], 0, v[92:93]
	v_pk_fma_f32 v[90:91], v[90:91], v[98:99], v[126:127]
	v_pk_fma_f32 v[88:89], v[88:89], v[96:97], v[124:125]
	v_lshl_add_u64 v[92:93], v[174:175], 2, v[92:93]
	global_store_dwordx4 v[92:93], v[88:91], off offset:64
	s_and_saveexec_b64 s[2:3], s[14:15]
	s_xor_b64 s[42:43], exec, s[2:3]
	v_add3_u32 v88, v221, v209, s57
	s_or_saveexec_b64 s[42:43], s[42:43]
	v_mov_b64_e32 v[90:91], s[24:25]
	s_xor_b64 exec, exec, s[42:43]
	v_lshl_add_u32 v88, v210, 8, v209
	v_mov_b64_e32 v[90:91], s[36:37]
	s_or_b64 exec, exec, s[42:43]
	v_ashrrev_i32_e32 v89, 31, v88
	v_lshlrev_b64 v[88:89], 13, v[88:89]
	v_lshl_add_u64 v[88:89], v[90:91], 0, v[88:89]
	v_pk_fma_f32 v[86:87], v[86:87], v[98:99], v[122:123]
; DI void epi_resid(const Acc& acc, const P& p, int brow, int bcol, int layer, int gch, bool from_input) {
;     ...
; #pragma unroll
;             for (int ai = 0; ai < 2; ++ai)
; #pragma unroll
;                 for (int m = 0; m < 4; ++m) {
;                     const int r = brow + ai * 128 + wr * 64 + m * 16 + fr;
;                     const float* sp = (from_input ? inrow(p, r) : xrow(p, r)) + c0;
;                     xv[ai][m] = *(const f32x4*)sp;
;                 }
;             __builtin_amdgcn_sched_barrier(0);
; #pragma unroll
;             for (int ai = 0; ai < 2; ++ai)
; #pragma unroll
;                 for (int m = 0; m < 4; ++m) {
;                     const int r = brow + ai * 128 + wr * 64 + m * 16 + fr;
;                     *(f32x4*)(xrow(p, r) + c0) = xv[ai][m] + g * acc[ai][bj][m][n];
;                 }
;             __builtin_amdgcn_sched_barrier(0);
;         }
	v_pk_fma_f32 v[84:85], v[84:85], v[96:97], v[120:121]
	v_lshl_add_u64 v[88:89], v[174:175], 2, v[88:89]
	global_store_dwordx4 v[88:89], v[84:87], off offset:64
	s_and_saveexec_b64 s[2:3], s[12:13]
	s_xor_b64 s[42:43], exec, s[2:3]
	v_add3_u32 v84, v224, v211, s57
	s_or_saveexec_b64 s[42:43], s[42:43]
	v_mov_b64_e32 v[86:87], s[24:25]
	s_xor_b64 exec, exec, s[42:43]
	v_lshl_add_u32 v84, v212, 8, v211
	v_mov_b64_e32 v[86:87], s[36:37]
	s_or_b64 exec, exec, s[42:43]
	v_ashrrev_i32_e32 v85, 31, v84
	v_lshlrev_b64 v[84:85], 13, v[84:85]
	v_lshl_add_u64 v[84:85], v[86:87], 0, v[84:85]
	v_pk_fma_f32 v[82:83], v[82:83], v[98:99], v[118:119]
	v_pk_fma_f32 v[80:81], v[80:81], v[96:97], v[116:117]
	v_lshl_add_u64 v[84:85], v[174:175], 2, v[84:85]
	global_store_dwordx4 v[84:85], v[80:83], off offset:64
	s_and_saveexec_b64 s[2:3], s[10:11]
	s_xor_b64 s[42:43], exec, s[2:3]
	v_add3_u32 v80, v225, v214, s57
	s_or_saveexec_b64 s[42:43], s[42:43]
	v_mov_b64_e32 v[82:83], s[24:25]
	s_xor_b64 exec, exec, s[42:43]
	v_lshl_add_u32 v80, v215, 8, v214
	v_mov_b64_e32 v[82:83], s[36:37]
	s_or_b64 exec, exec, s[42:43]
	v_ashrrev_i32_e32 v81, 31, v80
	v_lshlrev_b64 v[80:81], 13, v[80:81]
	v_lshl_add_u64 v[80:81], v[82:83], 0, v[80:81]
	v_pk_fma_f32 v[78:79], v[78:79], v[98:99], v[114:115]
	v_pk_fma_f32 v[76:77], v[76:77], v[96:97], v[112:113]
	v_lshl_add_u64 v[80:81], v[174:175], 2, v[80:81]
	global_store_dwordx4 v[80:81], v[76:79], off offset:64
	s_and_saveexec_b64 s[2:3], s[8:9]
	s_xor_b64 s[42:43], exec, s[2:3]
	v_add3_u32 v76, v226, v216, s57
	s_or_saveexec_b64 s[42:43], s[42:43]
	v_mov_b64_e32 v[78:79], s[24:25]
	s_xor_b64 exec, exec, s[42:43]
	v_lshl_add_u32 v76, v217, 8, v216
	v_mov_b64_e32 v[78:79], s[36:37]
	s_or_b64 exec, exec, s[42:43]
	v_ashrrev_i32_e32 v77, 31, v76
	v_lshlrev_b64 v[76:77], 13, v[76:77]
	v_lshl_add_u64 v[76:77], v[78:79], 0, v[76:77]
	v_pk_fma_f32 v[74:75], v[74:75], v[98:99], v[110:111]
	v_pk_fma_f32 v[72:73], v[72:73], v[96:97], v[108:109]
	v_lshl_add_u64 v[76:77], v[174:175], 2, v[76:77]
	global_store_dwordx4 v[76:77], v[72:75], off offset:64
	s_and_saveexec_b64 s[2:3], s[6:7]
	s_xor_b64 s[42:43], exec, s[2:3]
	v_add3_u32 v72, v227, v219, s57
	s_or_saveexec_b64 s[42:43], s[42:43]
	v_mov_b64_e32 v[74:75], s[24:25]
	s_xor_b64 exec, exec, s[42:43]
	v_lshl_add_u32 v72, v220, 8, v219
	v_mov_b64_e32 v[74:75], s[36:37]
	s_or_b64 exec, exec, s[42:43]
	v_ashrrev_i32_e32 v73, 31, v72
	v_lshlrev_b64 v[72:73], 13, v[72:73]
	v_lshl_add_u64 v[72:73], v[74:75], 0, v[72:73]
	v_pk_fma_f32 v[70:71], v[70:71], v[98:99], v[106:107]
	v_pk_fma_f32 v[68:69], v[68:69], v[96:97], v[104:105]
	v_lshl_add_u64 v[72:73], v[174:175], 2, v[72:73]
	global_store_dwordx4 v[72:73], v[68:71], off offset:64
	s_and_saveexec_b64 s[2:3], vcc
	s_xor_b64 s[42:43], exec, s[2:3]
	v_add3_u32 v68, v228, v222, s57
	s_or_saveexec_b64 s[42:43], s[42:43]
	v_mov_b64_e32 v[70:71], s[24:25]
	s_xor_b64 exec, exec, s[42:43]
	v_lshl_add_u32 v68, v223, 8, v222
	v_mov_b64_e32 v[70:71], s[36:37]
	s_or_b64 exec, exec, s[42:43]
	v_ashrrev_i32_e32 v69, 31, v68
	v_lshlrev_b64 v[68:69], 13, v[68:69]
	v_lshl_add_u64 v[68:69], v[70:71], 0, v[68:69]
	v_pk_fma_f32 v[66:67], v[66:67], v[98:99], v[102:103]
	v_pk_fma_f32 v[64:65], v[64:65], v[96:97], v[100:101]
	v_lshl_add_u64 v[68:69], v[174:175], 2, v[68:69]
	global_store_dwordx4 v[68:69], v[64:67], off offset:64
	global_load_dwordx4 v[64:67], v[192:193], off offset:512
	s_and_saveexec_b64 s[2:3], s[18:19]
	s_xor_b64 s[42:43], exec, s[2:3]
	v_add3_u32 v68, v213, v203, s57
	s_or_saveexec_b64 s[42:43], s[42:43]
	v_mov_b64_e32 v[70:71], s[24:25]
	s_xor_b64 exec, exec, s[42:43]
	v_lshl_add_u32 v68, v204, 8, v203
	v_mov_b64_e32 v[70:71], s[36:37]
	s_or_b64 exec, exec, s[42:43]
	v_ashrrev_i32_e32 v69, 31, v68
	v_lshlrev_b64 v[68:69], 13, v[68:69]
	v_lshl_add_u64 v[68:69], v[70:71], 0, v[68:69]
	v_lshl_add_u64 v[68:69], v[174:175], 2, v[68:69]
	global_load_dwordx4 v[96:99], v[68:69], off offset:512
	s_and_saveexec_b64 s[2:3], s[16:17]
	s_xor_b64 s[42:43], exec, s[2:3]
	v_add3_u32 v68, v218, v205, s57
	s_or_saveexec_b64 s[42:43], s[42:43]
	v_mov_b64_e32 v[70:71], s[24:25]
	s_xor_b64 exec, exec, s[42:43]
	v_lshl_add_u32 v68, v208, 8, v205
	v_mov_b64_e32 v[70:71], s[36:37]
	s_or_b64 exec, exec, s[42:43]
	v_ashrrev_i32_e32 v69, 31, v68
	v_lshlrev_b64 v[68:69], 13, v[68:69]
	v_lshl_add_u64 v[68:69], v[70:71], 0, v[68:69]
	v_lshl_add_u64 v[68:69], v[174:175], 2, v[68:69]
	global_load_dwordx4 v[92:95], v[68:69], off offset:512
	s_and_saveexec_b64 s[2:3], s[14:15]
	s_xor_b64 s[42:43], exec, s[2:3]
	v_add3_u32 v68, v221, v209, s57
	s_or_saveexec_b64 s[42:43], s[42:43]
	v_mov_b64_e32 v[70:71], s[24:25]
	s_xor_b64 exec, exec, s[42:43]
	v_lshl_add_u32 v68, v210, 8, v209
	v_mov_b64_e32 v[70:71], s[36:37]
	s_or_b64 exec, exec, s[42:43]
	v_ashrrev_i32_e32 v69, 31, v68
	v_lshlrev_b64 v[68:69], 13, v[68:69]
	v_lshl_add_u64 v[68:69], v[70:71], 0, v[68:69]
	v_lshl_add_u64 v[68:69], v[174:175], 2, v[68:69]
	global_load_dwordx4 v[88:91], v[68:69], off offset:512
	s_and_saveexec_b64 s[2:3], s[12:13]
	s_xor_b64 s[42:43], exec, s[2:3]
	v_add3_u32 v68, v224, v211, s57
	s_or_saveexec_b64 s[42:43], s[42:43]
	v_mov_b64_e32 v[70:71], s[24:25]
	s_xor_b64 exec, exec, s[42:43]
	v_lshl_add_u32 v68, v212, 8, v211
	v_mov_b64_e32 v[70:71], s[36:37]
	s_or_b64 exec, exec, s[42:43]
	v_ashrrev_i32_e32 v69, 31, v68
	v_lshlrev_b64 v[68:69], 13, v[68:69]
	v_lshl_add_u64 v[68:69], v[70:71], 0, v[68:69]
	v_lshl_add_u64 v[68:69], v[174:175], 2, v[68:69]
	global_load_dwordx4 v[84:87], v[68:69], off offset:512
	s_and_saveexec_b64 s[2:3], s[10:11]
	s_xor_b64 s[42:43], exec, s[2:3]
	v_add3_u32 v68, v225, v214, s57
; DI void epi_resid(const Acc& acc, const P& p, int brow, int bcol, int layer, int gch, bool from_input) {
;     ...
; #pragma unroll
;             for (int ai = 0; ai < 2; ++ai)
; #pragma unroll
;                 for (int m = 0; m < 4; ++m) {
;                     const int r = brow + ai * 128 + wr * 64 + m * 16 + fr;
;                     const float* sp = (from_input ? inrow(p, r) : xrow(p, r)) + c0;
;                     xv[ai][m] = *(const f32x4*)sp;
;                 }
;             __builtin_amdgcn_sched_barrier(0);
; #pragma unroll
;             for (int ai = 0; ai < 2; ++ai)
; #pragma unroll
;                 for (int m = 0; m < 4; ++m) {
;                     const int r = brow + ai * 128 + wr * 64 + m * 16 + fr;
;                     *(f32x4*)(xrow(p, r) + c0) = xv[ai][m] + g * acc[ai][bj][m][n];
;                 }
;             __builtin_amdgcn_sched_barrier(0);
;         }
	s_or_saveexec_b64 s[42:43], s[42:43]
	v_mov_b64_e32 v[70:71], s[24:25]
	s_xor_b64 exec, exec, s[42:43]
	v_lshl_add_u32 v68, v215, 8, v214
	v_mov_b64_e32 v[70:71], s[36:37]
	s_or_b64 exec, exec, s[42:43]
	v_ashrrev_i32_e32 v69, 31, v68
	v_lshlrev_b64 v[68:69], 13, v[68:69]
	v_lshl_add_u64 v[68:69], v[70:71], 0, v[68:69]
	v_lshl_add_u64 v[68:69], v[174:175], 2, v[68:69]
	global_load_dwordx4 v[80:83], v[68:69], off offset:512
	s_and_saveexec_b64 s[2:3], s[8:9]
	s_xor_b64 s[42:43], exec, s[2:3]
	v_add3_u32 v68, v226, v216, s57
	s_or_saveexec_b64 s[42:43], s[42:43]
	v_mov_b64_e32 v[70:71], s[24:25]
	s_xor_b64 exec, exec, s[42:43]
	v_lshl_add_u32 v68, v217, 8, v216
	v_mov_b64_e32 v[70:71], s[36:37]
	s_or_b64 exec, exec, s[42:43]
	v_ashrrev_i32_e32 v69, 31, v68
	v_lshlrev_b64 v[68:69], 13, v[68:69]
	v_lshl_add_u64 v[68:69], v[70:71], 0, v[68:69]
	v_lshl_add_u64 v[68:69], v[174:175], 2, v[68:69]
	global_load_dwordx4 v[76:79], v[68:69], off offset:512
	s_and_saveexec_b64 s[2:3], s[6:7]
	s_xor_b64 s[42:43], exec, s[2:3]
	v_add3_u32 v68, v227, v219, s57
	s_or_saveexec_b64 s[42:43], s[42:43]
	v_mov_b64_e32 v[70:71], s[24:25]
	s_xor_b64 exec, exec, s[42:43]
	v_lshl_add_u32 v68, v220, 8, v219
	v_mov_b64_e32 v[70:71], s[36:37]
	s_or_b64 exec, exec, s[42:43]
	v_ashrrev_i32_e32 v69, 31, v68
	v_lshlrev_b64 v[68:69], 13, v[68:69]
	v_lshl_add_u64 v[68:69], v[70:71], 0, v[68:69]
	v_lshl_add_u64 v[68:69], v[174:175], 2, v[68:69]
	global_load_dwordx4 v[72:75], v[68:69], off offset:512
	s_and_saveexec_b64 s[2:3], vcc
	s_xor_b64 s[42:43], exec, s[2:3]
	v_add3_u32 v68, v228, v222, s57
	s_or_saveexec_b64 s[42:43], s[42:43]
	v_mov_b64_e32 v[70:71], s[24:25]
	s_xor_b64 exec, exec, s[42:43]
	v_lshl_add_u32 v68, v223, 8, v222
	v_mov_b64_e32 v[70:71], s[36:37]
	s_or_b64 exec, exec, s[42:43]
	v_ashrrev_i32_e32 v69, 31, v68
	v_lshlrev_b64 v[68:69], 13, v[68:69]
	v_lshl_add_u64 v[68:69], v[70:71], 0, v[68:69]
	v_lshl_add_u64 v[68:69], v[174:175], 2, v[68:69]
	global_load_dwordx4 v[68:71], v[68:69], off offset:512
	s_and_saveexec_b64 s[2:3], s[18:19]
	s_xor_b64 s[42:43], exec, s[2:3]
	v_add3_u32 v100, v213, v203, s57
	s_or_saveexec_b64 s[42:43], s[42:43]
	v_mov_b64_e32 v[102:103], s[24:25]
	s_xor_b64 exec, exec, s[42:43]
	v_lshl_add_u32 v100, v204, 8, v203
	v_mov_b64_e32 v[102:103], s[36:37]
	s_or_b64 exec, exec, s[42:43]
	v_ashrrev_i32_e32 v101, 31, v100
	s_waitcnt vmcnt(0)
	v_pk_fma_f32 v[60:61], v[60:61], v[64:65], v[96:97]
	v_lshlrev_b64 v[96:97], 13, v[100:101]
	v_lshl_add_u64 v[96:97], v[102:103], 0, v[96:97]
	v_pk_fma_f32 v[62:63], v[62:63], v[66:67], v[98:99]
	v_lshl_add_u64 v[96:97], v[174:175], 2, v[96:97]
	global_store_dwordx4 v[96:97], v[60:63], off offset:512
	s_and_saveexec_b64 s[2:3], s[16:17]
	s_xor_b64 s[42:43], exec, s[2:3]
	v_add3_u32 v60, v218, v205, s57
	s_or_saveexec_b64 s[42:43], s[42:43]
	v_mov_b64_e32 v[62:63], s[24:25]
	s_xor_b64 exec, exec, s[42:43]
	v_lshl_add_u32 v60, v208, 8, v205
	v_mov_b64_e32 v[62:63], s[36:37]
	s_or_b64 exec, exec, s[42:43]
	v_ashrrev_i32_e32 v61, 31, v60
	v_lshlrev_b64 v[60:61], 13, v[60:61]
	v_lshl_add_u64 v[60:61], v[62:63], 0, v[60:61]
	v_pk_fma_f32 v[58:59], v[58:59], v[66:67], v[94:95]
	v_pk_fma_f32 v[56:57], v[56:57], v[64:65], v[92:93]
	v_lshl_add_u64 v[60:61], v[174:175], 2, v[60:61]
	global_store_dwordx4 v[60:61], v[56:59], off offset:512
	s_and_saveexec_b64 s[2:3], s[14:15]
	s_xor_b64 s[42:43], exec, s[2:3]
	v_add3_u32 v56, v221, v209, s57
	s_or_saveexec_b64 s[42:43], s[42:43]
	v_mov_b64_e32 v[58:59], s[24:25]
	s_xor_b64 exec, exec, s[42:43]
	v_lshl_add_u32 v56, v210, 8, v209
	v_mov_b64_e32 v[58:59], s[36:37]
	s_or_b64 exec, exec, s[42:43]
	v_ashrrev_i32_e32 v57, 31, v56
	v_lshlrev_b64 v[56:57], 13, v[56:57]
	v_lshl_add_u64 v[56:57], v[58:59], 0, v[56:57]
	v_pk_fma_f32 v[54:55], v[54:55], v[66:67], v[90:91]
	v_pk_fma_f32 v[52:53], v[52:53], v[64:65], v[88:89]
	v_lshl_add_u64 v[56:57], v[174:175], 2, v[56:57]
	global_store_dwordx4 v[56:57], v[52:55], off offset:512
	s_and_saveexec_b64 s[2:3], s[12:13]
	s_xor_b64 s[42:43], exec, s[2:3]
	v_add3_u32 v52, v224, v211, s57
	s_or_saveexec_b64 s[42:43], s[42:43]
	v_mov_b64_e32 v[54:55], s[24:25]
	s_xor_b64 exec, exec, s[42:43]
	v_lshl_add_u32 v52, v212, 8, v211
	v_mov_b64_e32 v[54:55], s[36:37]
	s_or_b64 exec, exec, s[42:43]
	v_ashrrev_i32_e32 v53, 31, v52
	v_lshlrev_b64 v[52:53], 13, v[52:53]
	v_lshl_add_u64 v[52:53], v[54:55], 0, v[52:53]
	v_pk_fma_f32 v[50:51], v[50:51], v[66:67], v[86:87]
	v_pk_fma_f32 v[48:49], v[48:49], v[64:65], v[84:85]
	v_lshl_add_u64 v[52:53], v[174:175], 2, v[52:53]
	global_store_dwordx4 v[52:53], v[48:51], off offset:512
	s_and_saveexec_b64 s[2:3], s[10:11]
	s_xor_b64 s[42:43], exec, s[2:3]
	v_add3_u32 v48, v225, v214, s57
	s_or_saveexec_b64 s[42:43], s[42:43]
	v_mov_b64_e32 v[50:51], s[24:25]
	s_xor_b64 exec, exec, s[42:43]
	v_lshl_add_u32 v48, v215, 8, v214
	v_mov_b64_e32 v[50:51], s[36:37]
	s_or_b64 exec, exec, s[42:43]
	v_ashrrev_i32_e32 v49, 31, v48
	v_lshlrev_b64 v[48:49], 13, v[48:49]
	v_lshl_add_u64 v[48:49], v[50:51], 0, v[48:49]
	v_pk_fma_f32 v[46:47], v[46:47], v[66:67], v[82:83]
	v_pk_fma_f32 v[44:45], v[44:45], v[64:65], v[80:81]
	v_lshl_add_u64 v[48:49], v[174:175], 2, v[48:49]
	global_store_dwordx4 v[48:49], v[44:47], off offset:512
	s_and_saveexec_b64 s[2:3], s[8:9]
	s_xor_b64 s[42:43], exec, s[2:3]
	v_add3_u32 v44, v226, v216, s57
	s_or_saveexec_b64 s[42:43], s[42:43]
	v_mov_b64_e32 v[46:47], s[24:25]
	s_xor_b64 exec, exec, s[42:43]
	v_lshl_add_u32 v44, v217, 8, v216
	v_mov_b64_e32 v[46:47], s[36:37]
	s_or_b64 exec, exec, s[42:43]
	v_ashrrev_i32_e32 v45, 31, v44
	v_lshlrev_b64 v[44:45], 13, v[44:45]
; DI void epi_resid(const Acc& acc, const P& p, int brow, int bcol, int layer, int gch, bool from_input) {
;     ...
; #pragma unroll
;             for (int ai = 0; ai < 2; ++ai)
; #pragma unroll
;                 for (int m = 0; m < 4; ++m) {
;                     const int r = brow + ai * 128 + wr * 64 + m * 16 + fr;
;                     const float* sp = (from_input ? inrow(p, r) : xrow(p, r)) + c0;
;                     xv[ai][m] = *(const f32x4*)sp;
;                 }
;             __builtin_amdgcn_sched_barrier(0);
; #pragma unroll
;             for (int ai = 0; ai < 2; ++ai)
; #pragma unroll
;                 for (int m = 0; m < 4; ++m) {
;                     const int r = brow + ai * 128 + wr * 64 + m * 16 + fr;
;                     *(f32x4*)(xrow(p, r) + c0) = xv[ai][m] + g * acc[ai][bj][m][n];
;                 }
;             __builtin_amdgcn_sched_barrier(0);
;         }
	v_lshl_add_u64 v[44:45], v[46:47], 0, v[44:45]
	v_pk_fma_f32 v[42:43], v[42:43], v[66:67], v[78:79]
	v_pk_fma_f32 v[40:41], v[40:41], v[64:65], v[76:77]
	v_lshl_add_u64 v[44:45], v[174:175], 2, v[44:45]
	global_store_dwordx4 v[44:45], v[40:43], off offset:512
	s_and_saveexec_b64 s[2:3], s[6:7]
	s_xor_b64 s[42:43], exec, s[2:3]
	v_add3_u32 v40, v227, v219, s57
	s_or_saveexec_b64 s[42:43], s[42:43]
	v_mov_b64_e32 v[42:43], s[24:25]
	s_xor_b64 exec, exec, s[42:43]
	v_lshl_add_u32 v40, v220, 8, v219
	v_mov_b64_e32 v[42:43], s[36:37]
	s_or_b64 exec, exec, s[42:43]
	v_ashrrev_i32_e32 v41, 31, v40
	v_lshlrev_b64 v[40:41], 13, v[40:41]
	v_lshl_add_u64 v[40:41], v[42:43], 0, v[40:41]
	v_pk_fma_f32 v[38:39], v[38:39], v[66:67], v[74:75]
	v_pk_fma_f32 v[36:37], v[36:37], v[64:65], v[72:73]
	v_lshl_add_u64 v[40:41], v[174:175], 2, v[40:41]
	global_store_dwordx4 v[40:41], v[36:39], off offset:512
	s_and_saveexec_b64 s[2:3], vcc
	s_xor_b64 s[42:43], exec, s[2:3]
	v_add3_u32 v36, v228, v222, s57
	s_or_saveexec_b64 s[42:43], s[42:43]
	v_mov_b64_e32 v[38:39], s[24:25]
	s_xor_b64 exec, exec, s[42:43]
	v_lshl_add_u32 v36, v223, 8, v222
	v_mov_b64_e32 v[38:39], s[36:37]
	s_or_b64 exec, exec, s[42:43]
	v_ashrrev_i32_e32 v37, 31, v36
	v_lshlrev_b64 v[36:37], 13, v[36:37]
	v_lshl_add_u64 v[36:37], v[38:39], 0, v[36:37]
	v_pk_fma_f32 v[34:35], v[34:35], v[66:67], v[70:71]
	v_pk_fma_f32 v[32:33], v[32:33], v[64:65], v[68:69]
	v_lshl_add_u64 v[36:37], v[174:175], 2, v[36:37]
	global_store_dwordx4 v[36:37], v[32:35], off offset:512
	global_load_dwordx4 v[32:35], v[192:193], off offset:576
	s_and_saveexec_b64 s[2:3], s[18:19]
	s_xor_b64 s[42:43], exec, s[2:3]
	v_add3_u32 v36, v213, v203, s57
	s_or_saveexec_b64 s[42:43], s[42:43]
	v_mov_b64_e32 v[38:39], s[24:25]
	s_xor_b64 exec, exec, s[42:43]
	v_lshl_add_u32 v36, v204, 8, v203
	v_mov_b64_e32 v[38:39], s[36:37]
	s_or_b64 exec, exec, s[42:43]
	v_ashrrev_i32_e32 v37, 31, v36
	v_lshlrev_b64 v[36:37], 13, v[36:37]
	v_lshl_add_u64 v[36:37], v[38:39], 0, v[36:37]
	v_lshl_add_u64 v[36:37], v[174:175], 2, v[36:37]
	global_load_dwordx4 v[64:67], v[36:37], off offset:576
	s_and_saveexec_b64 s[2:3], s[16:17]
	s_xor_b64 s[42:43], exec, s[2:3]
	v_add3_u32 v36, v218, v205, s57
	s_or_saveexec_b64 s[42:43], s[42:43]
	v_mov_b64_e32 v[38:39], s[24:25]
	s_xor_b64 exec, exec, s[42:43]
	v_lshl_add_u32 v36, v208, 8, v205
	v_mov_b64_e32 v[38:39], s[36:37]
	s_or_b64 exec, exec, s[42:43]
	v_ashrrev_i32_e32 v37, 31, v36
	v_lshlrev_b64 v[36:37], 13, v[36:37]
	v_lshl_add_u64 v[36:37], v[38:39], 0, v[36:37]
	v_lshl_add_u64 v[36:37], v[174:175], 2, v[36:37]
	global_load_dwordx4 v[60:63], v[36:37], off offset:576
	s_and_saveexec_b64 s[2:3], s[14:15]
	s_xor_b64 s[42:43], exec, s[2:3]
	v_add3_u32 v36, v221, v209, s57
	s_or_saveexec_b64 s[42:43], s[42:43]
	v_mov_b64_e32 v[38:39], s[24:25]
	s_xor_b64 exec, exec, s[42:43]
	v_lshl_add_u32 v36, v210, 8, v209
	v_mov_b64_e32 v[38:39], s[36:37]
	s_or_b64 exec, exec, s[42:43]
	v_ashrrev_i32_e32 v37, 31, v36
	v_lshlrev_b64 v[36:37], 13, v[36:37]
	v_lshl_add_u64 v[36:37], v[38:39], 0, v[36:37]
	v_lshl_add_u64 v[36:37], v[174:175], 2, v[36:37]
	global_load_dwordx4 v[56:59], v[36:37], off offset:576
	s_and_saveexec_b64 s[2:3], s[12:13]
	s_xor_b64 s[42:43], exec, s[2:3]
	v_add3_u32 v36, v224, v211, s57
	s_or_saveexec_b64 s[42:43], s[42:43]
	v_mov_b64_e32 v[38:39], s[24:25]
	s_xor_b64 exec, exec, s[42:43]
	v_lshl_add_u32 v36, v212, 8, v211
	v_mov_b64_e32 v[38:39], s[36:37]
	s_or_b64 exec, exec, s[42:43]
	v_ashrrev_i32_e32 v37, 31, v36
	v_lshlrev_b64 v[36:37], 13, v[36:37]
	v_lshl_add_u64 v[36:37], v[38:39], 0, v[36:37]
	v_lshl_add_u64 v[36:37], v[174:175], 2, v[36:37]
	global_load_dwordx4 v[52:55], v[36:37], off offset:576
	s_and_saveexec_b64 s[2:3], s[10:11]
	s_xor_b64 s[42:43], exec, s[2:3]
	v_add3_u32 v36, v225, v214, s57
	s_or_saveexec_b64 s[42:43], s[42:43]
	v_mov_b64_e32 v[38:39], s[24:25]
	s_xor_b64 exec, exec, s[42:43]
	v_lshl_add_u32 v36, v215, 8, v214
	v_mov_b64_e32 v[38:39], s[36:37]
	s_or_b64 exec, exec, s[42:43]
	v_ashrrev_i32_e32 v37, 31, v36
	v_lshlrev_b64 v[36:37], 13, v[36:37]
	v_lshl_add_u64 v[36:37], v[38:39], 0, v[36:37]
	v_lshl_add_u64 v[36:37], v[174:175], 2, v[36:37]
	global_load_dwordx4 v[48:51], v[36:37], off offset:576
	s_and_saveexec_b64 s[2:3], s[8:9]
	s_xor_b64 s[42:43], exec, s[2:3]
	v_add3_u32 v36, v226, v216, s57
	s_or_saveexec_b64 s[42:43], s[42:43]
	v_mov_b64_e32 v[38:39], s[24:25]
	s_xor_b64 exec, exec, s[42:43]
	v_lshl_add_u32 v36, v217, 8, v216
	v_mov_b64_e32 v[38:39], s[36:37]
	s_or_b64 exec, exec, s[42:43]
	v_ashrrev_i32_e32 v37, 31, v36
	v_lshlrev_b64 v[36:37], 13, v[36:37]
	v_lshl_add_u64 v[36:37], v[38:39], 0, v[36:37]
	v_lshl_add_u64 v[36:37], v[174:175], 2, v[36:37]
	global_load_dwordx4 v[44:47], v[36:37], off offset:576
	s_and_saveexec_b64 s[2:3], s[6:7]
	s_xor_b64 s[42:43], exec, s[2:3]
	v_add3_u32 v36, v227, v219, s57
	s_or_saveexec_b64 s[42:43], s[42:43]
	v_mov_b64_e32 v[38:39], s[24:25]
	s_xor_b64 exec, exec, s[42:43]
	v_lshl_add_u32 v36, v220, 8, v219
	v_mov_b64_e32 v[38:39], s[36:37]
	s_or_b64 exec, exec, s[42:43]
	v_ashrrev_i32_e32 v37, 31, v36
	v_lshlrev_b64 v[36:37], 13, v[36:37]
	v_lshl_add_u64 v[36:37], v[38:39], 0, v[36:37]
	v_lshl_add_u64 v[36:37], v[174:175], 2, v[36:37]
	global_load_dwordx4 v[40:43], v[36:37], off offset:576
	s_and_saveexec_b64 s[2:3], vcc
	s_xor_b64 s[42:43], exec, s[2:3]
	v_add3_u32 v36, v228, v222, s57
	s_or_saveexec_b64 s[42:43], s[42:43]
	v_mov_b64_e32 v[38:39], s[24:25]
	s_xor_b64 exec, exec, s[42:43]
	v_lshl_add_u32 v36, v223, 8, v222
	v_mov_b64_e32 v[38:39], s[36:37]
	s_or_b64 exec, exec, s[42:43]
	v_ashrrev_i32_e32 v37, 31, v36
	v_lshlrev_b64 v[36:37], 13, v[36:37]
	v_lshl_add_u64 v[36:37], v[38:39], 0, v[36:37]
	v_lshl_add_u64 v[36:37], v[174:175], 2, v[36:37]
	global_load_dwordx4 v[36:39], v[36:37], off offset:576
	s_and_saveexec_b64 s[2:3], s[18:19]
	s_xor_b64 s[18:19], exec, s[2:3]
	s_or_saveexec_b64 s[18:19], s[18:19]
	v_mov_b64_e32 v[68:69], s[24:25]
	s_xor_b64 exec, exec, s[18:19]
	v_mov_b64_e32 v[68:69], s[36:37]
	v_mov_b32_e32 v190, v191
	s_or_b64 exec, exec, s[18:19]
	v_ashrrev_i32_e32 v191, 31, v190
	s_waitcnt vmcnt(0)
; DI void epi_resid(const Acc& acc, const P& p, int brow, int bcol, int layer, int gch, bool from_input) {
;     ...
;             __builtin_amdgcn_sched_barrier(0);
; #pragma unroll
;             for (int ai = 0; ai < 2; ++ai)
; #pragma unroll
;                 for (int m = 0; m < 4; ++m) {
;                     const int r = brow + ai * 128 + wr * 64 + m * 16 + fr;
;                     *(f32x4*)(xrow(p, r) + c0) = xv[ai][m] + g * acc[ai][bj][m][n];
;                 }
;             __builtin_amdgcn_sched_barrier(0);
;         }
	v_pk_fma_f32 v[28:29], v[28:29], v[32:33], v[64:65]
	v_lshlrev_b64 v[64:65], 13, v[190:191]
	v_lshl_add_u64 v[64:65], v[68:69], 0, v[64:65]
	v_pk_fma_f32 v[30:31], v[30:31], v[34:35], v[66:67]
	v_lshl_add_u64 v[64:65], v[174:175], 2, v[64:65]
	global_store_dwordx4 v[64:65], v[28:31], off offset:576
	s_and_saveexec_b64 s[2:3], s[16:17]
	s_xor_b64 s[16:17], exec, s[2:3]
	s_or_saveexec_b64 s[16:17], s[16:17]
	v_mov_b64_e32 v[28:29], s[24:25]
	s_xor_b64 exec, exec, s[16:17]
	v_mov_b64_e32 v[28:29], s[36:37]
	v_mov_b32_e32 v188, v189
	s_or_b64 exec, exec, s[16:17]
	v_ashrrev_i32_e32 v189, 31, v188
	v_lshlrev_b64 v[30:31], 13, v[188:189]
	v_lshl_add_u64 v[28:29], v[28:29], 0, v[30:31]
	v_pk_fma_f32 v[26:27], v[26:27], v[34:35], v[62:63]
	v_pk_fma_f32 v[24:25], v[24:25], v[32:33], v[60:61]
	v_lshl_add_u64 v[28:29], v[174:175], 2, v[28:29]
	global_store_dwordx4 v[28:29], v[24:27], off offset:576
	s_and_saveexec_b64 s[2:3], s[14:15]
	s_xor_b64 s[14:15], exec, s[2:3]
	s_or_saveexec_b64 s[14:15], s[14:15]
	v_mov_b64_e32 v[24:25], s[24:25]
	s_xor_b64 exec, exec, s[14:15]
	v_mov_b64_e32 v[24:25], s[36:37]
	v_mov_b32_e32 v186, v187
	s_or_b64 exec, exec, s[14:15]
	v_ashrrev_i32_e32 v187, 31, v186
	v_lshlrev_b64 v[26:27], 13, v[186:187]
	v_lshl_add_u64 v[24:25], v[24:25], 0, v[26:27]
	v_pk_fma_f32 v[22:23], v[22:23], v[34:35], v[58:59]
	v_pk_fma_f32 v[20:21], v[20:21], v[32:33], v[56:57]
	v_lshl_add_u64 v[24:25], v[174:175], 2, v[24:25]
	global_store_dwordx4 v[24:25], v[20:23], off offset:576
	s_and_saveexec_b64 s[2:3], s[12:13]
	s_xor_b64 s[12:13], exec, s[2:3]
	s_or_saveexec_b64 s[12:13], s[12:13]
	v_mov_b64_e32 v[20:21], s[24:25]
	s_xor_b64 exec, exec, s[12:13]
	v_mov_b64_e32 v[20:21], s[36:37]
	v_mov_b32_e32 v184, v185
	s_or_b64 exec, exec, s[12:13]
	v_ashrrev_i32_e32 v185, 31, v184
	v_lshlrev_b64 v[22:23], 13, v[184:185]
	v_lshl_add_u64 v[20:21], v[20:21], 0, v[22:23]
	v_pk_fma_f32 v[18:19], v[18:19], v[34:35], v[54:55]
	v_pk_fma_f32 v[16:17], v[16:17], v[32:33], v[52:53]
	v_lshl_add_u64 v[20:21], v[174:175], 2, v[20:21]
	global_store_dwordx4 v[20:21], v[16:19], off offset:576
	s_and_saveexec_b64 s[2:3], s[10:11]
	s_xor_b64 s[10:11], exec, s[2:3]
	s_or_saveexec_b64 s[10:11], s[10:11]
	v_mov_b64_e32 v[16:17], s[24:25]
	s_xor_b64 exec, exec, s[10:11]
	v_mov_b64_e32 v[16:17], s[36:37]
	v_mov_b32_e32 v182, v183
	s_or_b64 exec, exec, s[10:11]
	v_ashrrev_i32_e32 v183, 31, v182
	v_lshlrev_b64 v[18:19], 13, v[182:183]
	v_lshl_add_u64 v[16:17], v[16:17], 0, v[18:19]
	v_pk_fma_f32 v[14:15], v[14:15], v[34:35], v[50:51]
	v_pk_fma_f32 v[12:13], v[12:13], v[32:33], v[48:49]
	v_lshl_add_u64 v[16:17], v[174:175], 2, v[16:17]
	global_store_dwordx4 v[16:17], v[12:15], off offset:576
	s_and_saveexec_b64 s[2:3], s[8:9]
	s_xor_b64 s[8:9], exec, s[2:3]
	s_or_saveexec_b64 s[8:9], s[8:9]
	v_mov_b64_e32 v[12:13], s[24:25]
	s_xor_b64 exec, exec, s[8:9]
	v_mov_b64_e32 v[12:13], s[36:37]
	v_mov_b32_e32 v180, v181
	s_or_b64 exec, exec, s[8:9]
	v_ashrrev_i32_e32 v181, 31, v180
	v_lshlrev_b64 v[14:15], 13, v[180:181]
	v_lshl_add_u64 v[12:13], v[12:13], 0, v[14:15]
	v_pk_fma_f32 v[10:11], v[10:11], v[34:35], v[46:47]
	v_pk_fma_f32 v[8:9], v[8:9], v[32:33], v[44:45]
	v_lshl_add_u64 v[12:13], v[174:175], 2, v[12:13]
	global_store_dwordx4 v[12:13], v[8:11], off offset:576
	s_and_saveexec_b64 s[2:3], s[6:7]
	s_xor_b64 s[6:7], exec, s[2:3]
	s_or_saveexec_b64 s[6:7], s[6:7]
	v_mov_b64_e32 v[8:9], s[24:25]
	s_xor_b64 exec, exec, s[6:7]
	v_mov_b64_e32 v[8:9], s[36:37]
	v_mov_b32_e32 v178, v179
	s_or_b64 exec, exec, s[6:7]
	v_ashrrev_i32_e32 v179, 31, v178
	v_lshlrev_b64 v[10:11], 13, v[178:179]
	v_lshl_add_u64 v[8:9], v[8:9], 0, v[10:11]
	v_pk_fma_f32 v[6:7], v[6:7], v[34:35], v[42:43]
	v_pk_fma_f32 v[4:5], v[4:5], v[32:33], v[40:41]
	v_lshl_add_u64 v[8:9], v[174:175], 2, v[8:9]
	global_store_dwordx4 v[8:9], v[4:7], off offset:576
	s_and_saveexec_b64 s[2:3], vcc
	s_xor_b64 s[6:7], exec, s[2:3]
	s_or_saveexec_b64 s[6:7], s[6:7]
	v_mov_b64_e32 v[4:5], s[24:25]
	s_xor_b64 exec, exec, s[6:7]
	s_cbranch_execz .LBB0_2666
	v_mov_b64_e32 v[4:5], s[36:37]
	v_mov_b32_e32 v176, v177
	s_branch .LBB0_2666

; #define WAIT_V(n) asm volatile("s_waitcnt vmcnt(" #n ")" ::: "memory")
; #define WAIT_L(n) asm volatile("s_waitcnt lgkmcnt(" #n ")" ::: "memory")
; #define BAR __builtin_amdgcn_s_barrier()
; #define SCHED __builtin_amdgcn_sched_barrier(0)
; template <class Get, class Epi>
; DI void gemm_stream(LAS unsigned char* lds, const int K, const int ld, Get get, Epi epi) {
;     ...
;             LDB(B0, 0, 0); SCHED; LDA(At, 0, 0); STAGE(SAo(1, 1), a1 + hstep);
;             WAIT_L(8); BAR; WAIT_L(0); MMA(0, 0, At, B0); BAR; SCHED;
;             LDB(B1, 0, 1); STAGE(SBo(0, 0), b2);
;             BAR; WAIT_L(0); MMA(0, 1, At, B1); BAR;
;             LDA(At, 0, 1); STAGE(SAo(0, 0), a2);
;             BAR; WAIT_L(0); MMA(1, 0, At, B0); BAR; SCHED;
;             STAGE(SBo(0, 1), b2 + hstep);
;             WAIT_V(6); BAR; MMA(1, 1, At, B1); BAR;
;             LDB(B0, 1, 0); SCHED; LDA(At, 1, 0); STAGE(SAo(0, 1), a2 + hstep);
;             WAIT_L(8); BAR; WAIT_L(0); MMA(0, 0, At, B0); BAR; SCHED;
;             LDB(B1, 1, 1); STAGE(SBo(1, 0), b3);
;             BAR; WAIT_L(0); MMA(0, 1, At, B1); BAR;
.LBB0_3046:
	ds_read_b128 v[148:151], v142
	ds_read_b128 v[152:155], v142 offset:1024
	ds_read_b128 v[156:159], v142 offset:2048
	ds_read_b128 v[160:163], v142 offset:3072
	s_add_u32 s14, s12, 0xfff80080
	s_addc_u32 s15, s13, -1
	s_cmp_eq_u32 s56, 28
	s_cselect_b32 s17, s9, s15
	s_cselect_b32 s16, s8, s14
	s_cselect_b32 s15, s11, s55
	s_cselect_b32 s14, s10, s0
	s_mov_b32 m0, s38
	v_lshl_add_u64 v[140:141], s[12:13], 0, v[134:135]
	ds_read_b128 v[164:167], v143
	ds_read_b128 v[168:171], v143 offset:1024
	ds_read_b128 v[172:175], v143 offset:2048
	ds_read_b128 v[176:179], v143 offset:3072
	ds_read_b128 v[180:183], v143 offset:4096
	ds_read_b128 v[184:187], v143 offset:5120
	ds_read_b128 v[188:191], v143 offset:6144
	ds_read_b128 v[192:195], v143 offset:7168
	global_load_lds_dwordx4 v[140:141], off
	v_lshl_add_u64 v[140:141], s[12:13], 0, v[136:137]
	s_mov_b32 m0, s39
	s_nop 0
	global_load_lds_dwordx4 v[140:141], off
	s_waitcnt lgkmcnt(8)
	s_barrier
	s_waitcnt lgkmcnt(0)
	s_setprio 0
	s_waitcnt lgkmcnt(0)
	v_mfma_f32_16x16x32_bf16 v[124:127], v[148:151], v[164:167], v[124:127]
	v_mfma_f32_16x16x32_bf16 v[116:119], v[156:159], v[164:167], v[116:119]
	v_mfma_f32_16x16x32_bf16 v[108:111], v[148:151], v[172:175], v[108:111]
	v_mfma_f32_16x16x32_bf16 v[100:103], v[156:159], v[172:175], v[100:103]
	v_mfma_f32_16x16x32_bf16 v[92:95], v[148:151], v[180:183], v[92:95]
	v_mfma_f32_16x16x32_bf16 v[84:87], v[156:159], v[180:183], v[84:87]
	v_mfma_f32_16x16x32_bf16 v[76:79], v[148:151], v[188:191], v[76:79]
	v_mfma_f32_16x16x32_bf16 v[68:71], v[156:159], v[188:191], v[68:71]
	v_mfma_f32_16x16x32_bf16 v[124:127], v[152:155], v[168:171], v[124:127]
	v_mfma_f32_16x16x32_bf16 v[116:119], v[160:163], v[168:171], v[116:119]
	v_mfma_f32_16x16x32_bf16 v[108:111], v[152:155], v[176:179], v[108:111]
	v_mfma_f32_16x16x32_bf16 v[100:103], v[160:163], v[176:179], v[100:103]
	v_mfma_f32_16x16x32_bf16 v[92:95], v[152:155], v[184:187], v[92:95]
	v_mfma_f32_16x16x32_bf16 v[84:87], v[160:163], v[184:187], v[84:87]
	v_mfma_f32_16x16x32_bf16 v[76:79], v[152:155], v[192:195], v[76:79]
	v_mfma_f32_16x16x32_bf16 v[68:71], v[160:163], v[192:195], v[68:71]
	s_setprio 1
	s_barrier
	s_mov_b32 m0, s40
	v_lshl_add_u64 v[140:141], s[14:15], 0, v[130:131]
	ds_read_b128 v[196:199], v144
	ds_read_b128 v[200:203], v144 offset:1024
	ds_read_b128 v[208:211], v144 offset:2048
	ds_read_b128 v[212:215], v144 offset:3072
	global_load_lds_dwordx4 v[140:141], off
	v_lshl_add_u64 v[204:205], s[14:15], 0, v[128:129]
	s_mov_b32 m0, s41
	s_nop 0
	global_load_lds_dwordx4 v[204:205], off
	s_barrier
	s_waitcnt lgkmcnt(0)
	s_setprio 0
	s_waitcnt lgkmcnt(0)
	v_mfma_f32_16x16x32_bf16 v[120:123], v[196:199], v[164:167], v[120:123]
	v_mfma_f32_16x16x32_bf16 v[112:115], v[208:211], v[164:167], v[112:115]
	v_mfma_f32_16x16x32_bf16 v[104:107], v[196:199], v[172:175], v[104:107]
	v_mfma_f32_16x16x32_bf16 v[96:99], v[208:211], v[172:175], v[96:99]
	v_mfma_f32_16x16x32_bf16 v[88:91], v[196:199], v[180:183], v[88:91]
	v_mfma_f32_16x16x32_bf16 v[80:83], v[208:211], v[180:183], v[80:83]
	v_mfma_f32_16x16x32_bf16 v[72:75], v[196:199], v[188:191], v[72:75]
	v_mfma_f32_16x16x32_bf16 v[64:67], v[208:211], v[188:191], v[64:67]
	v_mfma_f32_16x16x32_bf16 v[120:123], v[200:203], v[168:171], v[120:123]
	v_mfma_f32_16x16x32_bf16 v[112:115], v[212:215], v[168:171], v[112:115]
	v_mfma_f32_16x16x32_bf16 v[104:107], v[200:203], v[176:179], v[104:107]
	v_mfma_f32_16x16x32_bf16 v[96:99], v[212:215], v[176:179], v[96:99]
	v_mfma_f32_16x16x32_bf16 v[88:91], v[200:203], v[184:187], v[88:91]
	v_mfma_f32_16x16x32_bf16 v[80:83], v[212:215], v[184:187], v[80:83]
	v_mfma_f32_16x16x32_bf16 v[72:75], v[200:203], v[192:195], v[72:75]
	v_mfma_f32_16x16x32_bf16 v[64:67], v[212:215], v[192:195], v[64:67]
	s_setprio 1
	s_mov_b32 m0, s19
	v_lshl_add_u64 v[216:217], s[16:17], 0, v[130:131]
	s_barrier
	ds_read_b128 v[164:167], v143 offset:16384
	ds_read_b128 v[168:171], v143 offset:17408
	ds_read_b128 v[172:175], v143 offset:18432
	ds_read_b128 v[176:179], v143 offset:19456
	ds_read_b128 v[180:183], v143 offset:20480
	ds_read_b128 v[184:187], v143 offset:21504
	ds_read_b128 v[188:191], v143 offset:22528
	ds_read_b128 v[192:195], v143 offset:23552
	global_load_lds_dwordx4 v[216:217], off
	v_lshl_add_u64 v[218:219], s[16:17], 0, v[128:129]
	s_mov_b32 m0, s20
	s_nop 0
	global_load_lds_dwordx4 v[218:219], off
	s_barrier
	s_waitcnt lgkmcnt(0)
	s_setprio 0
	s_waitcnt lgkmcnt(0)
	v_mfma_f32_16x16x32_bf16 v[60:63], v[148:151], v[164:167], v[60:63]
	v_mfma_f32_16x16x32_bf16 v[52:55], v[156:159], v[164:167], v[52:55]
	v_mfma_f32_16x16x32_bf16 v[44:47], v[148:151], v[172:175], v[44:47]
	v_mfma_f32_16x16x32_bf16 v[36:39], v[156:159], v[172:175], v[36:39]
	v_mfma_f32_16x16x32_bf16 v[28:31], v[148:151], v[180:183], v[28:31]
	v_mfma_f32_16x16x32_bf16 v[20:23], v[156:159], v[180:183], v[20:23]
	v_mfma_f32_16x16x32_bf16 v[12:15], v[148:151], v[188:191], v[12:15]
	v_mfma_f32_16x16x32_bf16 v[4:7], v[156:159], v[188:191], v[4:7]
	v_mfma_f32_16x16x32_bf16 v[60:63], v[152:155], v[168:171], v[60:63]
	v_mfma_f32_16x16x32_bf16 v[52:55], v[160:163], v[168:171], v[52:55]
	v_mfma_f32_16x16x32_bf16 v[44:47], v[152:155], v[176:179], v[44:47]
	v_mfma_f32_16x16x32_bf16 v[36:39], v[160:163], v[176:179], v[36:39]
	v_mfma_f32_16x16x32_bf16 v[28:31], v[152:155], v[184:187], v[28:31]
	v_mfma_f32_16x16x32_bf16 v[20:23], v[160:163], v[184:187], v[20:23]
	v_mfma_f32_16x16x32_bf16 v[12:15], v[152:155], v[192:195], v[12:15]
	v_mfma_f32_16x16x32_bf16 v[4:7], v[160:163], v[192:195], v[4:7]
	s_setprio 1
	s_barrier
; #define WAIT_V(n) asm volatile("s_waitcnt vmcnt(" #n ")" ::: "memory")
; #define WAIT_L(n) asm volatile("s_waitcnt lgkmcnt(" #n ")" ::: "memory")
; #define BAR __builtin_amdgcn_s_barrier()
; #define SCHED __builtin_amdgcn_sched_barrier(0)
; template <class Get, class Epi>
; DI void gemm_stream(LAS unsigned char* lds, const int K, const int ld, Get get, Epi epi) {
;     ...
;             STAGE(SBo(0, 1), b2 + hstep);
;             WAIT_V(6); BAR; MMA(1, 1, At, B1); BAR;
;             LDB(B0, 1, 0); SCHED; LDA(At, 1, 0); STAGE(SAo(0, 1), a2 + hstep);
;             WAIT_L(8); BAR; WAIT_L(0); MMA(0, 0, At, B0); BAR; SCHED;
;             LDB(B1, 1, 1); STAGE(SBo(1, 0), b3);
;             BAR; WAIT_L(0); MMA(0, 1, At, B1); BAR;
;             LDA(At, 1, 1); STAGE(SAo(1, 0), a3);
;             BAR; WAIT_L(0); MMA(1, 0, At, B0); BAR; SCHED;
;             STAGE(SBo(1, 1), b3 + hstep);
;             WAIT_V(6); BAR; MMA(1, 1, At, B1); BAR;
	s_add_u32 s58, s14, 0x80000
	s_addc_u32 s59, s15, 0
	s_mov_b32 m0, s42
	v_lshl_add_u64 v[148:149], s[58:59], 0, v[130:131]
	global_load_lds_dwordx4 v[148:149], off
	v_lshl_add_u64 v[148:149], s[58:59], 0, v[128:129]
	s_mov_b32 m0, s43
	s_nop 0
	global_load_lds_dwordx4 v[148:149], off
	s_waitcnt vmcnt(6)
	s_barrier
	s_setprio 0
	v_mfma_f32_16x16x32_bf16 v[56:59], v[196:199], v[164:167], v[56:59]
	v_mfma_f32_16x16x32_bf16 v[48:51], v[208:211], v[164:167], v[48:51]
	v_mfma_f32_16x16x32_bf16 v[40:43], v[196:199], v[172:175], v[40:43]
	v_mfma_f32_16x16x32_bf16 v[32:35], v[208:211], v[172:175], v[32:35]
	v_mfma_f32_16x16x32_bf16 v[24:27], v[196:199], v[180:183], v[24:27]
	v_mfma_f32_16x16x32_bf16 v[16:19], v[208:211], v[180:183], v[16:19]
	v_mfma_f32_16x16x32_bf16 v[8:11], v[196:199], v[188:191], v[8:11]
	v_mfma_f32_16x16x32_bf16 v[0:3], v[208:211], v[188:191], v[0:3]
	v_mfma_f32_16x16x32_bf16 v[56:59], v[200:203], v[168:171], v[56:59]
	v_mfma_f32_16x16x32_bf16 v[48:51], v[212:215], v[168:171], v[48:51]
	v_mfma_f32_16x16x32_bf16 v[40:43], v[200:203], v[176:179], v[40:43]
	v_mfma_f32_16x16x32_bf16 v[32:35], v[212:215], v[176:179], v[32:35]
	v_mfma_f32_16x16x32_bf16 v[24:27], v[200:203], v[184:187], v[24:27]
	v_mfma_f32_16x16x32_bf16 v[16:19], v[212:215], v[184:187], v[16:19]
	v_mfma_f32_16x16x32_bf16 v[8:11], v[200:203], v[192:195], v[8:11]
	v_mfma_f32_16x16x32_bf16 v[0:3], v[212:215], v[192:195], v[0:3]
	s_setprio 1
	s_barrier
	ds_read_b128 v[148:151], v145
	ds_read_b128 v[152:155], v145 offset:1024
	ds_read_b128 v[156:159], v145 offset:2048
	ds_read_b128 v[160:163], v145 offset:3072
	s_add_u32 s16, s16, 0x80000
	s_addc_u32 s17, s17, 0
	s_mov_b32 m0, s21
	v_lshl_add_u64 v[196:197], s[16:17], 0, v[130:131]
	ds_read_b128 v[164:167], v143 offset:32768
	ds_read_b128 v[168:171], v143 offset:33792
	ds_read_b128 v[172:175], v143 offset:34816
	ds_read_b128 v[176:179], v143 offset:35840
	ds_read_b128 v[180:183], v143 offset:36864
	ds_read_b128 v[184:187], v143 offset:37888
	ds_read_b128 v[188:191], v143 offset:38912
	ds_read_b128 v[192:195], v143 offset:39936
	global_load_lds_dwordx4 v[196:197], off
	v_lshl_add_u64 v[196:197], s[16:17], 0, v[128:129]
	s_mov_b32 m0, s28
	s_nop 0
	global_load_lds_dwordx4 v[196:197], off
	s_waitcnt lgkmcnt(8)
	s_barrier
	s_waitcnt lgkmcnt(0)
	s_setprio 0
	s_waitcnt lgkmcnt(0)
	v_mfma_f32_16x16x32_bf16 v[124:127], v[148:151], v[164:167], v[124:127]
	v_mfma_f32_16x16x32_bf16 v[116:119], v[156:159], v[164:167], v[116:119]
	v_mfma_f32_16x16x32_bf16 v[108:111], v[148:151], v[172:175], v[108:111]
	v_mfma_f32_16x16x32_bf16 v[100:103], v[156:159], v[172:175], v[100:103]
	v_mfma_f32_16x16x32_bf16 v[92:95], v[148:151], v[180:183], v[92:95]
	v_mfma_f32_16x16x32_bf16 v[84:87], v[156:159], v[180:183], v[84:87]
	v_mfma_f32_16x16x32_bf16 v[76:79], v[148:151], v[188:191], v[76:79]
	v_mfma_f32_16x16x32_bf16 v[68:71], v[156:159], v[188:191], v[68:71]
	v_mfma_f32_16x16x32_bf16 v[124:127], v[152:155], v[168:171], v[124:127]
	v_mfma_f32_16x16x32_bf16 v[116:119], v[160:163], v[168:171], v[116:119]
	v_mfma_f32_16x16x32_bf16 v[108:111], v[152:155], v[176:179], v[108:111]
	v_mfma_f32_16x16x32_bf16 v[100:103], v[160:163], v[176:179], v[100:103]
	v_mfma_f32_16x16x32_bf16 v[92:95], v[152:155], v[184:187], v[92:95]
	v_mfma_f32_16x16x32_bf16 v[84:87], v[160:163], v[184:187], v[84:87]
	v_mfma_f32_16x16x32_bf16 v[76:79], v[152:155], v[192:195], v[76:79]
	v_mfma_f32_16x16x32_bf16 v[68:71], v[160:163], v[192:195], v[68:71]
	s_setprio 1
	s_barrier
	s_mov_b32 m0, s44
	v_lshl_add_u64 v[140:141], v[140:141], 0, s[6:7]
	ds_read_b128 v[196:199], v146
	ds_read_b128 v[200:203], v146 offset:1024
	ds_read_b128 v[208:211], v146 offset:2048
	ds_read_b128 v[212:215], v146 offset:3072
	global_load_lds_dwordx4 v[140:141], off
	v_lshl_add_u64 v[140:141], v[204:205], 0, s[6:7]
	s_mov_b32 m0, s45
	s_nop 0
	global_load_lds_dwordx4 v[140:141], off
	s_barrier
	s_waitcnt lgkmcnt(0)
	s_setprio 0
	s_waitcnt lgkmcnt(0)
	v_mfma_f32_16x16x32_bf16 v[120:123], v[196:199], v[164:167], v[120:123]
	v_mfma_f32_16x16x32_bf16 v[112:115], v[208:211], v[164:167], v[112:115]
	v_mfma_f32_16x16x32_bf16 v[104:107], v[196:199], v[172:175], v[104:107]
	v_mfma_f32_16x16x32_bf16 v[96:99], v[208:211], v[172:175], v[96:99]
	v_mfma_f32_16x16x32_bf16 v[88:91], v[196:199], v[180:183], v[88:91]
	v_mfma_f32_16x16x32_bf16 v[80:83], v[208:211], v[180:183], v[80:83]
	v_mfma_f32_16x16x32_bf16 v[72:75], v[196:199], v[188:191], v[72:75]
	v_mfma_f32_16x16x32_bf16 v[64:67], v[208:211], v[188:191], v[64:67]
	v_mfma_f32_16x16x32_bf16 v[120:123], v[200:203], v[168:171], v[120:123]
	v_mfma_f32_16x16x32_bf16 v[112:115], v[212:215], v[168:171], v[112:115]
	v_mfma_f32_16x16x32_bf16 v[104:107], v[200:203], v[176:179], v[104:107]
	v_mfma_f32_16x16x32_bf16 v[96:99], v[212:215], v[176:179], v[96:99]
	v_mfma_f32_16x16x32_bf16 v[88:91], v[200:203], v[184:187], v[88:91]
	v_mfma_f32_16x16x32_bf16 v[80:83], v[212:215], v[184:187], v[80:83]
	v_mfma_f32_16x16x32_bf16 v[72:75], v[200:203], v[192:195], v[72:75]
	v_mfma_f32_16x16x32_bf16 v[64:67], v[212:215], v[192:195], v[64:67]
	s_setprio 1
	s_mov_b32 m0, s29
	v_lshl_add_u64 v[140:141], v[216:217], 0, s[6:7]
	s_barrier
	ds_read_b128 v[164:167], v143 offset:49152
	ds_read_b128 v[168:171], v143 offset:50176
	ds_read_b128 v[172:175], v143 offset:51200
	ds_read_b128 v[176:179], v143 offset:52224
	ds_read_b128 v[180:183], v143 offset:53248
	ds_read_b128 v[184:187], v143 offset:54272
	ds_read_b128 v[188:191], v143 offset:55296
	ds_read_b128 v[192:195], v143 offset:56320
	global_load_lds_dwordx4 v[140:141], off
	v_lshl_add_u64 v[140:141], v[218:219], 0, s[6:7]
	s_mov_b32 m0, s36
	s_nop 0
	global_load_lds_dwordx4 v[140:141], off
	s_barrier
; DI float silu_f(float g) { return g * __builtin_amdgcn_rcpf(1.f + __builtin_amdgcn_exp2f(-LOG2E * g)); }
; #define WAIT_V(n) asm volatile("s_waitcnt vmcnt(" #n ")" ::: "memory")
; #define WAIT_L(n) asm volatile("s_waitcnt lgkmcnt(" #n ")" ::: "memory")
; #define BAR __builtin_amdgcn_s_barrier()
; #define SCHED __builtin_amdgcn_sched_barrier(0)
; template <class Get, class Epi>
; DI void gemm_stream(LAS unsigned char* lds, const int K, const int ld, Get get, Epi epi) {
;     ...
;             LDA(At, 1, 1); STAGE(SAo(1, 0), a3);
;             BAR; WAIT_L(0); MMA(1, 0, At, B0); BAR; SCHED;
;             STAGE(SBo(1, 1), b3 + hstep);
;             WAIT_V(6); BAR; MMA(1, 1, At, B1); BAR;
;         }
; DI void epi_swiglu(const Acc& acc, int brow, int pn, bf16_t* hid) {
;     EPI_IDX
; #pragma unroll
;     for (int ai = 0; ai < 2; ++ai)
; #pragma unroll
;         for (int m = 0; m < 4; ++m) {
;             const int r = brow + ai * 128 + wr * 64 + m * 16 + fr;
;             bf16_t* rp = hid + (size_t)r * FF + pn * 128 + wc * 32 + fq * 4;
; #pragma unroll
;             for (int n = 0; n < 2; ++n) {
;                 const f32x4 g = acc[ai][0][m][n], u = acc[ai][1][m][n];
;                 float o[4];
; #pragma unroll
;                 for (int j = 0; j < 4; ++j) o[j] = silu_f(g[j]) * u[j];
;                 st4(rp + n * 16, o[0], o[1], o[2], o[3]);
;             }
	s_waitcnt lgkmcnt(0)
	s_setprio 0
	s_waitcnt lgkmcnt(0)
	v_mfma_f32_16x16x32_bf16 v[60:63], v[148:151], v[164:167], v[60:63]
	v_mfma_f32_16x16x32_bf16 v[52:55], v[156:159], v[164:167], v[52:55]
	v_mfma_f32_16x16x32_bf16 v[44:47], v[148:151], v[172:175], v[44:47]
	v_mfma_f32_16x16x32_bf16 v[36:39], v[156:159], v[172:175], v[36:39]
	v_mfma_f32_16x16x32_bf16 v[28:31], v[148:151], v[180:183], v[28:31]
	v_mfma_f32_16x16x32_bf16 v[20:23], v[156:159], v[180:183], v[20:23]
	v_mfma_f32_16x16x32_bf16 v[12:15], v[148:151], v[188:191], v[12:15]
	v_mfma_f32_16x16x32_bf16 v[4:7], v[156:159], v[188:191], v[4:7]
	v_mfma_f32_16x16x32_bf16 v[60:63], v[152:155], v[168:171], v[60:63]
	v_mfma_f32_16x16x32_bf16 v[52:55], v[160:163], v[168:171], v[52:55]
	v_mfma_f32_16x16x32_bf16 v[44:47], v[152:155], v[176:179], v[44:47]
	v_mfma_f32_16x16x32_bf16 v[36:39], v[160:163], v[176:179], v[36:39]
	v_mfma_f32_16x16x32_bf16 v[28:31], v[152:155], v[184:187], v[28:31]
	v_mfma_f32_16x16x32_bf16 v[20:23], v[160:163], v[184:187], v[20:23]
	v_mfma_f32_16x16x32_bf16 v[12:15], v[152:155], v[192:195], v[12:15]
	v_mfma_f32_16x16x32_bf16 v[4:7], v[160:163], v[192:195], v[4:7]
	s_setprio 1
	s_barrier
	s_add_u32 s14, s14, 0x80080
	s_addc_u32 s15, s15, 0
	s_mov_b32 m0, s46
	v_lshl_add_u64 v[140:141], s[14:15], 0, v[130:131]
	global_load_lds_dwordx4 v[140:141], off
	v_lshl_add_u64 v[140:141], s[14:15], 0, v[128:129]
	s_mov_b32 m0, s47
	s_nop 0
	global_load_lds_dwordx4 v[140:141], off
	s_waitcnt vmcnt(6)
	s_barrier
	s_setprio 0
	v_mfma_f32_16x16x32_bf16 v[56:59], v[196:199], v[164:167], v[56:59]
	v_mfma_f32_16x16x32_bf16 v[48:51], v[208:211], v[164:167], v[48:51]
	v_mfma_f32_16x16x32_bf16 v[40:43], v[196:199], v[172:175], v[40:43]
	v_mfma_f32_16x16x32_bf16 v[32:35], v[208:211], v[172:175], v[32:35]
	v_mfma_f32_16x16x32_bf16 v[24:27], v[196:199], v[180:183], v[24:27]
	v_mfma_f32_16x16x32_bf16 v[16:19], v[208:211], v[180:183], v[16:19]
	v_mfma_f32_16x16x32_bf16 v[8:11], v[196:199], v[188:191], v[8:11]
	v_mfma_f32_16x16x32_bf16 v[0:3], v[208:211], v[188:191], v[0:3]
	v_mfma_f32_16x16x32_bf16 v[56:59], v[200:203], v[168:171], v[56:59]
	v_mfma_f32_16x16x32_bf16 v[48:51], v[212:215], v[168:171], v[48:51]
	v_mfma_f32_16x16x32_bf16 v[40:43], v[200:203], v[176:179], v[40:43]
	v_mfma_f32_16x16x32_bf16 v[32:35], v[212:215], v[176:179], v[32:35]
	v_mfma_f32_16x16x32_bf16 v[24:27], v[200:203], v[184:187], v[24:27]
	v_mfma_f32_16x16x32_bf16 v[16:19], v[212:215], v[184:187], v[16:19]
	v_mfma_f32_16x16x32_bf16 v[8:11], v[200:203], v[192:195], v[8:11]
	v_mfma_f32_16x16x32_bf16 v[0:3], v[212:215], v[192:195], v[0:3]
	s_setprio 1
	s_add_i32 s56, s56, 2
	s_add_u32 s12, s12, 0x100
	s_addc_u32 s13, s13, 0
	s_add_u32 s0, s0, 0x100
	s_addc_u32 s55, s55, 0
	s_cmp_gt_u32 s56, 29
	s_barrier
	s_cbranch_scc0 .LBB0_3046
	s_lshr_b32 s0, s53, 4
	s_lshl_b32 s12, s53, 8
	s_mulk_i32 s0, 0x1100
	s_and_b32 s12, s12, 0xf00
	s_add_i32 s0, s0, s12
	s_lshl_b32 s12, s54, 7
	s_ashr_i32 s13, s12, 31
	s_addk_i32 s0, 0x100
	v_mov_b32_e32 v132, v206
	s_lshl_b64 s[12:13], s[12:13], 1
	s_add_u32 s12, s23, s12
	v_ashrrev_i32_e32 v140, 2, v132
	v_and_b32_e32 v140, 0xffffffc0, v140
	v_and_or_b32 v141, v132, 15, s0
	s_addc_u32 s13, s35, s13
	v_lshrrev_b32_e32 v148, 1, v132
	v_and_b32_e32 v132, 0xc0, v132
	v_add_u32_e32 v147, v141, v140
	v_lshl_add_u64 v[140:141], s[12:13], 0, v[132:133]
	v_and_b32_e32 v132, 24, v148
	v_mul_f32_e32 v148, 0xbfb8aa3b, v124
	v_exp_f32_e32 v148, v148
	v_mul_f32_e32 v149, 0xbfb8aa3b, v125
	v_exp_f32_e32 v149, v149
	v_lshl_add_u64 v[140:141], v[140:141], 0, v[132:133]
	v_add_f32_e32 v132, 1.0, v148
	v_rcp_f32_e32 v148, v132
	v_add_f32_e32 v132, 1.0, v149
	v_mul_f32_e32 v149, 0xbfb8aa3b, v126
	v_exp_f32_e32 v150, v149
	v_mul_f32_e32 v149, 0xbfb8aa3b, v127
	v_exp_f32_e32 v151, v149
	v_rcp_f32_e32 v149, v132
	v_add_f32_e32 v132, 1.0, v150
	v_rcp_f32_e32 v150, v132
	v_add_f32_e32 v132, 1.0, v151
	v_rcp_f32_e32 v151, v132
	v_pk_mul_f32 v[124:125], v[124:125], v[148:149]
	v_mad_i64_i32 v[152:153], s[12:13], v147, s37, v[140:141]
	v_pk_mul_f32 v[120:121], v[124:125], v[120:121]
	v_pk_mul_f32 v[124:125], v[126:127], v[150:151]
	v_cvt_pk_bf16_f32 v120, v120, v121
	v_mul_f32_e32 v121, 0xbfb8aa3b, v116
	v_pk_mul_f32 v[122:123], v[124:125], v[122:123]
	v_exp_f32_e32 v124, v121
	v_mul_f32_e32 v121, 0xbfb8aa3b, v117
	v_exp_f32_e32 v125, v121
	v_cvt_pk_bf16_f32 v121, v122, v123
	v_add_f32_e32 v122, 1.0, v124
	v_mul_f32_e32 v124, 0xbfb8aa3b, v118
	v_add_f32_e32 v123, 1.0, v125
	v_mul_f32_e32 v125, 0xbfb8aa3b, v119
	v_exp_f32_e32 v124, v124
	v_exp_f32_e32 v125, v125
	v_rcp_f32_e32 v122, v122
	v_rcp_f32_e32 v123, v123
	v_add_f32_e32 v124, 1.0, v124
	v_add_f32_e32 v125, 1.0, v125
	v_rcp_f32_e32 v124, v124
	v_rcp_f32_e32 v125, v125
	v_pk_mul_f32 v[116:117], v[116:117], v[122:123]
	s_and_b64 vcc, exec, s[4:5]
	v_pk_mul_f32 v[112:113], v[116:117], v[112:113]
	v_pk_mul_f32 v[116:117], v[118:119], v[124:125]
	v_cvt_pk_bf16_f32 v112, v112, v113
	v_pk_mul_f32 v[114:115], v[116:117], v[114:115]
	v_or_b32_e32 v116, 16, v147
	v_cvt_pk_bf16_f32 v113, v114, v115
	global_store_dwordx2 v[152:153], v[112:113], off offset:32
	v_mul_f32_e32 v112, 0xbfb8aa3b, v108
	v_mul_f32_e32 v113, 0xbfb8aa3b, v109
	v_exp_f32_e32 v112, v112
	v_exp_f32_e32 v113, v113
	v_mul_f32_e32 v114, 0xbfb8aa3b, v110
	v_mul_f32_e32 v115, 0xbfb8aa3b, v111
	v_exp_f32_e32 v114, v114
	v_exp_f32_e32 v115, v115
	v_add_f32_e32 v112, 1.0, v112
	v_add_f32_e32 v113, 1.0, v113
	v_rcp_f32_e32 v112, v112
	v_rcp_f32_e32 v113, v113
	v_add_f32_e32 v114, 1.0, v114
	v_add_f32_e32 v115, 1.0, v115
	v_rcp_f32_e32 v114, v114
	v_rcp_f32_e32 v115, v115
	v_pk_mul_f32 v[108:109], v[108:109], v[112:113]
; DI float silu_f(float g) { return g * __builtin_amdgcn_rcpf(1.f + __builtin_amdgcn_exp2f(-LOG2E * g)); }
; DI void epi_swiglu(const Acc& acc, int brow, int pn, bf16_t* hid) {
;     EPI_IDX
; #pragma unroll
;     for (int ai = 0; ai < 2; ++ai)
; #pragma unroll
;         for (int m = 0; m < 4; ++m) {
;             const int r = brow + ai * 128 + wr * 64 + m * 16 + fr;
;             bf16_t* rp = hid + (size_t)r * FF + pn * 128 + wc * 32 + fq * 4;
; #pragma unroll
;             for (int n = 0; n < 2; ++n) {
;                 const f32x4 g = acc[ai][0][m][n], u = acc[ai][1][m][n];
;                 float o[4];
; #pragma unroll
;                 for (int j = 0; j < 4; ++j) o[j] = silu_f(g[j]) * u[j];
;                 st4(rp + n * 16, o[0], o[1], o[2], o[3]);
;             }
	v_mad_i64_i32 v[116:117], s[12:13], v116, s37, v[140:141]
	v_pk_mul_f32 v[104:105], v[108:109], v[104:105]
	v_pk_mul_f32 v[108:109], v[110:111], v[114:115]
	v_cvt_pk_bf16_f32 v104, v104, v105
	v_mul_f32_e32 v105, 0xbfb8aa3b, v100
	v_pk_mul_f32 v[106:107], v[108:109], v[106:107]
	v_exp_f32_e32 v108, v105
	v_mul_f32_e32 v105, 0xbfb8aa3b, v101
	v_exp_f32_e32 v109, v105
	v_cvt_pk_bf16_f32 v105, v106, v107
	v_add_f32_e32 v106, 1.0, v108
	v_mul_f32_e32 v108, 0xbfb8aa3b, v102
	v_add_f32_e32 v107, 1.0, v109
	v_mul_f32_e32 v109, 0xbfb8aa3b, v103
	v_exp_f32_e32 v108, v108
	v_exp_f32_e32 v109, v109
	v_rcp_f32_e32 v106, v106
	v_rcp_f32_e32 v107, v107
	v_add_f32_e32 v108, 1.0, v108
	v_add_f32_e32 v109, 1.0, v109
	v_rcp_f32_e32 v108, v108
	v_rcp_f32_e32 v109, v109
	v_pk_mul_f32 v[100:101], v[100:101], v[106:107]
	s_mov_b32 s54, s49
	v_pk_mul_f32 v[96:97], v[100:101], v[96:97]
	v_pk_mul_f32 v[100:101], v[102:103], v[108:109]
	v_cvt_pk_bf16_f32 v96, v96, v97
	v_pk_mul_f32 v[98:99], v[100:101], v[98:99]
	v_or_b32_e32 v100, 32, v147
	v_cvt_pk_bf16_f32 v97, v98, v99
	global_store_dwordx2 v[116:117], v[96:97], off offset:32
	v_mul_f32_e32 v96, 0xbfb8aa3b, v92
	v_mul_f32_e32 v97, 0xbfb8aa3b, v93
	v_exp_f32_e32 v96, v96
	v_exp_f32_e32 v97, v97
	v_mul_f32_e32 v98, 0xbfb8aa3b, v94
	v_mul_f32_e32 v99, 0xbfb8aa3b, v95
	v_exp_f32_e32 v98, v98
	v_exp_f32_e32 v99, v99
	v_add_f32_e32 v96, 1.0, v96
	v_add_f32_e32 v97, 1.0, v97
	v_rcp_f32_e32 v96, v96
	v_rcp_f32_e32 v97, v97
	v_add_f32_e32 v98, 1.0, v98
	v_add_f32_e32 v99, 1.0, v99
	v_rcp_f32_e32 v98, v98
	v_rcp_f32_e32 v99, v99
	v_pk_mul_f32 v[92:93], v[92:93], v[96:97]
	v_mad_i64_i32 v[100:101], s[12:13], v100, s37, v[140:141]
	v_pk_mul_f32 v[88:89], v[92:93], v[88:89]
	v_pk_mul_f32 v[92:93], v[94:95], v[98:99]
	v_cvt_pk_bf16_f32 v88, v88, v89
	v_mul_f32_e32 v89, 0xbfb8aa3b, v84
	v_pk_mul_f32 v[90:91], v[92:93], v[90:91]
	v_exp_f32_e32 v92, v89
	v_mul_f32_e32 v89, 0xbfb8aa3b, v85
	v_exp_f32_e32 v93, v89
	v_cvt_pk_bf16_f32 v89, v90, v91
	v_add_f32_e32 v90, 1.0, v92
	v_mul_f32_e32 v92, 0xbfb8aa3b, v86
	v_add_f32_e32 v91, 1.0, v93
	v_mul_f32_e32 v93, 0xbfb8aa3b, v87
	v_exp_f32_e32 v92, v92
	v_exp_f32_e32 v93, v93
	v_rcp_f32_e32 v90, v90
	v_rcp_f32_e32 v91, v91
	v_add_f32_e32 v92, 1.0, v92
	v_add_f32_e32 v93, 1.0, v93
	v_rcp_f32_e32 v92, v92
	v_rcp_f32_e32 v93, v93
	v_pk_mul_f32 v[84:85], v[84:85], v[90:91]
	s_mov_b32 s53, s52
	v_pk_mul_f32 v[80:81], v[84:85], v[80:81]
	v_pk_mul_f32 v[84:85], v[86:87], v[92:93]
	v_cvt_pk_bf16_f32 v80, v80, v81
	v_pk_mul_f32 v[82:83], v[84:85], v[82:83]
	v_or_b32_e32 v84, 48, v147
	v_cvt_pk_bf16_f32 v81, v82, v83
	global_store_dwordx2 v[100:101], v[80:81], off offset:32
	v_mul_f32_e32 v80, 0xbfb8aa3b, v76
	v_mul_f32_e32 v81, 0xbfb8aa3b, v77
	v_exp_f32_e32 v80, v80
	v_exp_f32_e32 v81, v81
	v_mul_f32_e32 v82, 0xbfb8aa3b, v78
	v_mul_f32_e32 v83, 0xbfb8aa3b, v79
	v_exp_f32_e32 v82, v82
	v_exp_f32_e32 v83, v83
	v_add_f32_e32 v80, 1.0, v80
	v_add_f32_e32 v81, 1.0, v81
	v_rcp_f32_e32 v80, v80
	v_rcp_f32_e32 v81, v81
	v_add_f32_e32 v82, 1.0, v82
	v_add_f32_e32 v83, 1.0, v83
	v_rcp_f32_e32 v82, v82
	v_rcp_f32_e32 v83, v83
	v_pk_mul_f32 v[76:77], v[76:77], v[80:81]
	v_mad_i64_i32 v[84:85], s[12:13], v84, s37, v[140:141]
	v_pk_mul_f32 v[72:73], v[76:77], v[72:73]
	v_pk_mul_f32 v[76:77], v[78:79], v[82:83]
	v_cvt_pk_bf16_f32 v72, v72, v73
	v_mul_f32_e32 v73, 0xbfb8aa3b, v68
	v_pk_mul_f32 v[74:75], v[76:77], v[74:75]
	v_exp_f32_e32 v76, v73
	v_mul_f32_e32 v73, 0xbfb8aa3b, v69
	v_exp_f32_e32 v77, v73
	v_cvt_pk_bf16_f32 v73, v74, v75
	v_add_f32_e32 v74, 1.0, v76
	v_mul_f32_e32 v76, 0xbfb8aa3b, v70
	v_add_f32_e32 v75, 1.0, v77
	v_mul_f32_e32 v77, 0xbfb8aa3b, v71
	v_exp_f32_e32 v76, v76
	v_exp_f32_e32 v77, v77
	v_rcp_f32_e32 v74, v74
	v_rcp_f32_e32 v75, v75
	v_add_f32_e32 v76, 1.0, v76
	v_add_f32_e32 v77, 1.0, v77
	v_rcp_f32_e32 v76, v76
	v_rcp_f32_e32 v77, v77
	v_pk_mul_f32 v[68:69], v[68:69], v[74:75]
	s_mov_b64 s[14:15], s[10:11]
	v_pk_mul_f32 v[64:65], v[68:69], v[64:65]
	v_pk_mul_f32 v[68:69], v[70:71], v[76:77]
	v_cvt_pk_bf16_f32 v64, v64, v65
	v_pk_mul_f32 v[66:67], v[68:69], v[66:67]
	v_add_u32_e32 v68, 0x80, v147
	v_cvt_pk_bf16_f32 v65, v66, v67
	global_store_dwordx2 v[84:85], v[64:65], off offset:32
	v_mul_f32_e32 v64, 0xbfb8aa3b, v60
	v_mul_f32_e32 v65, 0xbfb8aa3b, v61
	v_exp_f32_e32 v64, v64
	v_exp_f32_e32 v65, v65
	v_mul_f32_e32 v66, 0xbfb8aa3b, v62
	v_mul_f32_e32 v67, 0xbfb8aa3b, v63
	v_exp_f32_e32 v66, v66
	v_exp_f32_e32 v67, v67
	v_add_f32_e32 v64, 1.0, v64
	v_add_f32_e32 v65, 1.0, v65
	v_rcp_f32_e32 v64, v64
	v_rcp_f32_e32 v65, v65
	v_add_f32_e32 v66, 1.0, v66
	v_add_f32_e32 v67, 1.0, v67
	v_rcp_f32_e32 v66, v66
	v_rcp_f32_e32 v67, v67
	v_pk_mul_f32 v[60:61], v[60:61], v[64:65]
	v_mad_i64_i32 v[68:69], s[12:13], v68, s37, v[140:141]
	v_pk_mul_f32 v[56:57], v[60:61], v[56:57]
	v_pk_mul_f32 v[60:61], v[62:63], v[66:67]
	v_cvt_pk_bf16_f32 v56, v56, v57
	v_mul_f32_e32 v57, 0xbfb8aa3b, v52
	v_pk_mul_f32 v[58:59], v[60:61], v[58:59]
	v_exp_f32_e32 v60, v57
	v_mul_f32_e32 v57, 0xbfb8aa3b, v53
	v_exp_f32_e32 v61, v57
	v_cvt_pk_bf16_f32 v57, v58, v59
	v_add_f32_e32 v58, 1.0, v60
	v_mul_f32_e32 v60, 0xbfb8aa3b, v54
	v_add_f32_e32 v59, 1.0, v61
	v_mul_f32_e32 v61, 0xbfb8aa3b, v55
	v_exp_f32_e32 v60, v60
	v_exp_f32_e32 v61, v61
	v_rcp_f32_e32 v58, v58
	v_rcp_f32_e32 v59, v59
	v_add_f32_e32 v60, 1.0, v60
	v_add_f32_e32 v61, 1.0, v61
; DI float silu_f(float g) { return g * __builtin_amdgcn_rcpf(1.f + __builtin_amdgcn_exp2f(-LOG2E * g)); }
; DI void epi_swiglu(const Acc& acc, int brow, int pn, bf16_t* hid) {
;     EPI_IDX
; #pragma unroll
;     for (int ai = 0; ai < 2; ++ai)
; #pragma unroll
;         for (int m = 0; m < 4; ++m) {
;             const int r = brow + ai * 128 + wr * 64 + m * 16 + fr;
;             bf16_t* rp = hid + (size_t)r * FF + pn * 128 + wc * 32 + fq * 4;
; #pragma unroll
;             for (int n = 0; n < 2; ++n) {
;                 const f32x4 g = acc[ai][0][m][n], u = acc[ai][1][m][n];
;                 float o[4];
; #pragma unroll
;                 for (int j = 0; j < 4; ++j) o[j] = silu_f(g[j]) * u[j];
;                 st4(rp + n * 16, o[0], o[1], o[2], o[3]);
;             }
	v_rcp_f32_e32 v60, v60
	v_rcp_f32_e32 v61, v61
	v_pk_mul_f32 v[52:53], v[52:53], v[58:59]
	global_store_dwordx2 v[152:153], v[120:121], off
	v_pk_mul_f32 v[48:49], v[52:53], v[48:49]
	v_pk_mul_f32 v[52:53], v[54:55], v[60:61]
	v_cvt_pk_bf16_f32 v48, v48, v49
	v_pk_mul_f32 v[50:51], v[52:53], v[50:51]
	v_add_u32_e32 v52, 0x90, v147
	v_cvt_pk_bf16_f32 v49, v50, v51
	global_store_dwordx2 v[68:69], v[48:49], off offset:32
	v_mul_f32_e32 v48, 0xbfb8aa3b, v44
	v_mul_f32_e32 v49, 0xbfb8aa3b, v45
	v_exp_f32_e32 v48, v48
	v_exp_f32_e32 v49, v49
	v_mul_f32_e32 v50, 0xbfb8aa3b, v46
	v_mul_f32_e32 v51, 0xbfb8aa3b, v47
	v_exp_f32_e32 v50, v50
	v_exp_f32_e32 v51, v51
	v_add_f32_e32 v48, 1.0, v48
	v_add_f32_e32 v49, 1.0, v49
	v_rcp_f32_e32 v48, v48
	v_rcp_f32_e32 v49, v49
	v_add_f32_e32 v50, 1.0, v50
	v_add_f32_e32 v51, 1.0, v51
	v_rcp_f32_e32 v50, v50
	v_rcp_f32_e32 v51, v51
	v_pk_mul_f32 v[44:45], v[44:45], v[48:49]
	v_mad_i64_i32 v[52:53], s[12:13], v52, s37, v[140:141]
	v_pk_mul_f32 v[40:41], v[44:45], v[40:41]
	v_pk_mul_f32 v[44:45], v[46:47], v[50:51]
	v_cvt_pk_bf16_f32 v40, v40, v41
	v_mul_f32_e32 v41, 0xbfb8aa3b, v36
	v_pk_mul_f32 v[42:43], v[44:45], v[42:43]
	v_exp_f32_e32 v44, v41
	v_mul_f32_e32 v41, 0xbfb8aa3b, v37
	v_exp_f32_e32 v45, v41
	v_cvt_pk_bf16_f32 v41, v42, v43
	v_add_f32_e32 v42, 1.0, v44
	v_mul_f32_e32 v44, 0xbfb8aa3b, v38
	v_add_f32_e32 v43, 1.0, v45
	v_mul_f32_e32 v45, 0xbfb8aa3b, v39
	v_exp_f32_e32 v44, v44
	v_exp_f32_e32 v45, v45
	v_rcp_f32_e32 v42, v42
	v_rcp_f32_e32 v43, v43
	v_add_f32_e32 v44, 1.0, v44
	v_add_f32_e32 v45, 1.0, v45
	v_rcp_f32_e32 v44, v44
	v_rcp_f32_e32 v45, v45
	v_pk_mul_f32 v[36:37], v[36:37], v[42:43]
	global_store_dwordx2 v[116:117], v[104:105], off
	v_pk_mul_f32 v[32:33], v[36:37], v[32:33]
	v_pk_mul_f32 v[36:37], v[38:39], v[44:45]
	v_cvt_pk_bf16_f32 v32, v32, v33
	v_pk_mul_f32 v[34:35], v[36:37], v[34:35]
	v_add_u32_e32 v36, 0xa0, v147
	v_cvt_pk_bf16_f32 v33, v34, v35
	global_store_dwordx2 v[52:53], v[32:33], off offset:32
	v_mul_f32_e32 v32, 0xbfb8aa3b, v28
	v_mul_f32_e32 v33, 0xbfb8aa3b, v29
	v_exp_f32_e32 v32, v32
	v_exp_f32_e32 v33, v33
	v_mul_f32_e32 v34, 0xbfb8aa3b, v30
	v_mul_f32_e32 v35, 0xbfb8aa3b, v31
	v_exp_f32_e32 v34, v34
	v_exp_f32_e32 v35, v35
	v_add_f32_e32 v32, 1.0, v32
	v_add_f32_e32 v33, 1.0, v33
	v_rcp_f32_e32 v32, v32
	v_rcp_f32_e32 v33, v33
	v_add_f32_e32 v34, 1.0, v34
	v_add_f32_e32 v35, 1.0, v35
	v_rcp_f32_e32 v34, v34
	v_rcp_f32_e32 v35, v35
	v_pk_mul_f32 v[28:29], v[28:29], v[32:33]
	v_mad_i64_i32 v[36:37], s[12:13], v36, s37, v[140:141]
	v_pk_mul_f32 v[24:25], v[28:29], v[24:25]
	v_pk_mul_f32 v[28:29], v[30:31], v[34:35]
	v_cvt_pk_bf16_f32 v24, v24, v25
	v_mul_f32_e32 v25, 0xbfb8aa3b, v20
	v_pk_mul_f32 v[26:27], v[28:29], v[26:27]
	v_exp_f32_e32 v28, v25
	v_mul_f32_e32 v25, 0xbfb8aa3b, v21
	v_exp_f32_e32 v29, v25
	v_cvt_pk_bf16_f32 v25, v26, v27
	v_add_f32_e32 v26, 1.0, v28
	v_mul_f32_e32 v28, 0xbfb8aa3b, v22
	v_add_f32_e32 v27, 1.0, v29
	v_mul_f32_e32 v29, 0xbfb8aa3b, v23
	v_exp_f32_e32 v28, v28
	v_exp_f32_e32 v29, v29
	v_rcp_f32_e32 v26, v26
	v_rcp_f32_e32 v27, v27
	v_add_f32_e32 v28, 1.0, v28
	v_add_f32_e32 v29, 1.0, v29
	v_rcp_f32_e32 v28, v28
	v_rcp_f32_e32 v29, v29
	v_pk_mul_f32 v[20:21], v[20:21], v[26:27]
	global_store_dwordx2 v[100:101], v[88:89], off
	v_pk_mul_f32 v[16:17], v[20:21], v[16:17]
	v_pk_mul_f32 v[20:21], v[22:23], v[28:29]
	v_cvt_pk_bf16_f32 v16, v16, v17
	v_pk_mul_f32 v[18:19], v[20:21], v[18:19]
	v_add_u32_e32 v20, 0xb0, v147
	v_cvt_pk_bf16_f32 v17, v18, v19
	global_store_dwordx2 v[36:37], v[16:17], off offset:32
	v_mul_f32_e32 v16, 0xbfb8aa3b, v12
	v_mul_f32_e32 v17, 0xbfb8aa3b, v13
	v_exp_f32_e32 v16, v16
	v_exp_f32_e32 v17, v17
	v_mul_f32_e32 v18, 0xbfb8aa3b, v14
	v_mul_f32_e32 v19, 0xbfb8aa3b, v15
	v_exp_f32_e32 v18, v18
	v_exp_f32_e32 v19, v19
	v_add_f32_e32 v16, 1.0, v16
	v_add_f32_e32 v17, 1.0, v17
	v_rcp_f32_e32 v16, v16
	v_rcp_f32_e32 v17, v17
	v_add_f32_e32 v18, 1.0, v18
	v_add_f32_e32 v19, 1.0, v19
	v_rcp_f32_e32 v18, v18
	v_rcp_f32_e32 v19, v19
	v_pk_mul_f32 v[12:13], v[12:13], v[16:17]
	v_mad_i64_i32 v[20:21], s[12:13], v20, s37, v[140:141]
	v_pk_mul_f32 v[8:9], v[12:13], v[8:9]
	v_pk_mul_f32 v[12:13], v[14:15], v[18:19]
	v_cvt_pk_bf16_f32 v8, v8, v9
	v_mul_f32_e32 v9, 0xbfb8aa3b, v4
	v_pk_mul_f32 v[10:11], v[12:13], v[10:11]
	v_exp_f32_e32 v12, v9
	v_mul_f32_e32 v9, 0xbfb8aa3b, v5
	v_exp_f32_e32 v13, v9
	v_cvt_pk_bf16_f32 v9, v10, v11
	v_add_f32_e32 v10, 1.0, v12
	v_mul_f32_e32 v12, 0xbfb8aa3b, v6
	v_add_f32_e32 v11, 1.0, v13
	v_mul_f32_e32 v13, 0xbfb8aa3b, v7
	v_exp_f32_e32 v12, v12
	v_exp_f32_e32 v13, v13
	v_rcp_f32_e32 v10, v10
	v_rcp_f32_e32 v11, v11
	v_add_f32_e32 v12, 1.0, v12
	v_add_f32_e32 v13, 1.0, v13
	v_rcp_f32_e32 v12, v12
	v_rcp_f32_e32 v13, v13
	v_pk_mul_f32 v[4:5], v[4:5], v[10:11]
	s_mov_b64 s[12:13], s[8:9]
	v_pk_mul_f32 v[0:1], v[4:5], v[0:1]
	v_pk_mul_f32 v[4:5], v[6:7], v[12:13]
	v_cvt_pk_bf16_f32 v0, v0, v1
	v_pk_mul_f32 v[2:3], v[4:5], v[2:3]
	global_store_dwordx2 v[84:85], v[72:73], off
	v_cvt_pk_bf16_f32 v1, v2, v3
	global_store_dwordx2 v[68:69], v[56:57], off
	global_store_dwordx2 v[52:53], v[40:41], off
	global_store_dwordx2 v[36:37], v[24:25], off
	global_store_dwordx2 v[20:21], v[8:9], off
	global_store_dwordx2 v[20:21], v[0:1], off offset:32
	s_cbranch_vccz .LBB0_3043
	s_waitcnt vmcnt(0)
	s_cmpk_gt_u32 s2, 0xff
	s_cbranch_scc1 .LBB0_3050
	s_barrier

; #define WAIT_V(n) asm volatile("s_waitcnt vmcnt(" #n ")" ::: "memory")
; #define WAIT_L(n) asm volatile("s_waitcnt lgkmcnt(" #n ")" ::: "memory")
; #define BAR __builtin_amdgcn_s_barrier()
; #define SCHED __builtin_amdgcn_sched_barrier(0)
; template <class Get, class Epi>
; DI void gemm_stream(LAS unsigned char* lds, const int K, const int ld, Get get, Epi epi) {
;     ...
;             LDB(B0, 0, 0); SCHED; LDA(At, 0, 0); STAGE(SAo(1, 1), a1 + hstep);
;             WAIT_L(8); BAR; WAIT_L(0); MMA(0, 0, At, B0); BAR; SCHED;
;             LDB(B1, 0, 1); STAGE(SBo(0, 0), b2);
;             BAR; WAIT_L(0); MMA(0, 1, At, B1); BAR;
;             LDA(At, 0, 1); STAGE(SAo(0, 0), a2);
;             BAR; WAIT_L(0); MMA(1, 0, At, B0); BAR; SCHED;
;             STAGE(SBo(0, 1), b2 + hstep);
;             WAIT_V(6); BAR; MMA(1, 1, At, B1); BAR;
;             LDB(B0, 1, 0); SCHED; LDA(At, 1, 0); STAGE(SAo(0, 1), a2 + hstep);
;             WAIT_L(8); BAR; WAIT_L(0); MMA(0, 0, At, B0); BAR; SCHED;
;             LDB(B1, 1, 1); STAGE(SBo(1, 0), b3);
;             BAR; WAIT_L(0); MMA(0, 1, At, B1); BAR;
.LBB0_3113:
	ds_read_b128 v[128:131], v199
	ds_read_b128 v[132:135], v199 offset:1024
	ds_read_b128 v[136:139], v199 offset:2048
	ds_read_b128 v[140:143], v199 offset:3072
	s_add_u32 s6, s4, 0x100
	s_addc_u32 s7, s5, 0
	s_cmpk_eq_i32 s16, 0x54
	s_cselect_b32 s11, s37, s7
	s_cselect_b32 s10, s36, s6
	s_cselect_b32 s9, s39, s15
	s_cselect_b32 s8, s38, s14
	s_mov_b32 m0, s54
	v_lshl_add_u64 v[186:187], s[4:5], 0, v[168:169]
	ds_read_b128 v[144:147], v200
	ds_read_b128 v[148:151], v200 offset:1024
	ds_read_b128 v[152:155], v200 offset:2048
	ds_read_b128 v[156:159], v200 offset:3072
	ds_read_b128 v[160:163], v200 offset:4096
	ds_read_b128 v[174:177], v200 offset:5120
	ds_read_b128 v[178:181], v200 offset:6144
	ds_read_b128 v[182:185], v200 offset:7168
	global_load_lds_dwordx4 v[186:187], off
	v_lshl_add_u64 v[186:187], s[4:5], 0, v[170:171]
	s_mov_b32 m0, s55
	s_nop 0
	global_load_lds_dwordx4 v[186:187], off
	s_waitcnt lgkmcnt(8)
	s_barrier
	s_waitcnt lgkmcnt(0)
	s_setprio 0
	s_waitcnt lgkmcnt(0)
	v_mfma_f32_16x16x32_bf16 v[124:127], v[128:131], v[144:147], v[124:127]
	v_mfma_f32_16x16x32_bf16 v[92:95], v[136:139], v[144:147], v[92:95]
	v_mfma_f32_16x16x32_bf16 v[120:123], v[128:131], v[152:155], v[120:123]
	v_mfma_f32_16x16x32_bf16 v[88:91], v[136:139], v[152:155], v[88:91]
	v_mfma_f32_16x16x32_bf16 v[116:119], v[128:131], v[160:163], v[116:119]
	v_mfma_f32_16x16x32_bf16 v[84:87], v[136:139], v[160:163], v[84:87]
	v_mfma_f32_16x16x32_bf16 v[112:115], v[128:131], v[178:181], v[112:115]
	v_mfma_f32_16x16x32_bf16 v[80:83], v[136:139], v[178:181], v[80:83]
	v_mfma_f32_16x16x32_bf16 v[124:127], v[132:135], v[148:151], v[124:127]
	v_mfma_f32_16x16x32_bf16 v[92:95], v[140:143], v[148:151], v[92:95]
	v_mfma_f32_16x16x32_bf16 v[120:123], v[132:135], v[156:159], v[120:123]
	v_mfma_f32_16x16x32_bf16 v[88:91], v[140:143], v[156:159], v[88:91]
	v_mfma_f32_16x16x32_bf16 v[116:119], v[132:135], v[174:177], v[116:119]
	v_mfma_f32_16x16x32_bf16 v[84:87], v[140:143], v[174:177], v[84:87]
	v_mfma_f32_16x16x32_bf16 v[112:115], v[132:135], v[182:185], v[112:115]
	v_mfma_f32_16x16x32_bf16 v[80:83], v[140:143], v[182:185], v[80:83]
	s_setprio 1
	s_barrier
	s_mov_b32 m0, s56
	v_lshl_add_u64 v[208:209], s[8:9], 0, v[164:165]
	ds_read_b128 v[186:189], v201
	ds_read_b128 v[190:193], v201 offset:1024
	ds_read_b128 v[194:197], v201 offset:2048
	ds_read_b128 v[202:205], v201 offset:3072
	global_load_lds_dwordx4 v[208:209], off
	v_lshl_add_u64 v[210:211], s[8:9], 0, v[166:167]
	s_mov_b32 m0, s57
	s_nop 0
	global_load_lds_dwordx4 v[210:211], off
	s_barrier
	s_waitcnt lgkmcnt(0)
	s_setprio 0
	s_waitcnt lgkmcnt(0)
	v_mfma_f32_16x16x32_bf16 v[60:63], v[186:189], v[144:147], v[60:63]
	v_mfma_f32_16x16x32_bf16 v[28:31], v[194:197], v[144:147], v[28:31]
	v_mfma_f32_16x16x32_bf16 v[56:59], v[186:189], v[152:155], v[56:59]
	v_mfma_f32_16x16x32_bf16 v[24:27], v[194:197], v[152:155], v[24:27]
	v_mfma_f32_16x16x32_bf16 v[52:55], v[186:189], v[160:163], v[52:55]
	v_mfma_f32_16x16x32_bf16 v[20:23], v[194:197], v[160:163], v[20:23]
	v_mfma_f32_16x16x32_bf16 v[48:51], v[186:189], v[178:181], v[48:51]
	v_mfma_f32_16x16x32_bf16 v[16:19], v[194:197], v[178:181], v[16:19]
	v_mfma_f32_16x16x32_bf16 v[60:63], v[190:193], v[148:151], v[60:63]
	v_mfma_f32_16x16x32_bf16 v[28:31], v[202:205], v[148:151], v[28:31]
	v_mfma_f32_16x16x32_bf16 v[56:59], v[190:193], v[156:159], v[56:59]
	v_mfma_f32_16x16x32_bf16 v[24:27], v[202:205], v[156:159], v[24:27]
	v_mfma_f32_16x16x32_bf16 v[52:55], v[190:193], v[174:177], v[52:55]
	v_mfma_f32_16x16x32_bf16 v[20:23], v[202:205], v[174:177], v[20:23]
	v_mfma_f32_16x16x32_bf16 v[48:51], v[190:193], v[182:185], v[48:51]
	v_mfma_f32_16x16x32_bf16 v[16:19], v[202:205], v[182:185], v[16:19]
	s_setprio 1
	s_mov_b32 m0, s33
	v_lshl_add_u64 v[212:213], s[10:11], 0, v[164:165]
	s_barrier
	ds_read_b128 v[144:147], v200 offset:16384
	ds_read_b128 v[148:151], v200 offset:17408
	ds_read_b128 v[152:155], v200 offset:18432
	ds_read_b128 v[156:159], v200 offset:19456
	ds_read_b128 v[160:163], v200 offset:20480
	ds_read_b128 v[174:177], v200 offset:21504
	ds_read_b128 v[178:181], v200 offset:22528
	ds_read_b128 v[182:185], v200 offset:23552
	global_load_lds_dwordx4 v[212:213], off
	v_lshl_add_u64 v[214:215], s[10:11], 0, v[166:167]
	s_mov_b32 m0, s42
	s_nop 0
	global_load_lds_dwordx4 v[214:215], off
	s_barrier
	s_waitcnt lgkmcnt(0)
	s_setprio 0
	s_waitcnt lgkmcnt(0)
	v_mfma_f32_16x16x32_bf16 v[108:111], v[128:131], v[144:147], v[108:111]
	v_mfma_f32_16x16x32_bf16 v[76:79], v[136:139], v[144:147], v[76:79]
	v_mfma_f32_16x16x32_bf16 v[104:107], v[128:131], v[152:155], v[104:107]
	v_mfma_f32_16x16x32_bf16 v[72:75], v[136:139], v[152:155], v[72:75]
	v_mfma_f32_16x16x32_bf16 v[100:103], v[128:131], v[160:163], v[100:103]
	v_mfma_f32_16x16x32_bf16 v[68:71], v[136:139], v[160:163], v[68:71]
	v_mfma_f32_16x16x32_bf16 v[96:99], v[128:131], v[178:181], v[96:99]
	v_mfma_f32_16x16x32_bf16 v[64:67], v[136:139], v[178:181], v[64:67]
	v_mfma_f32_16x16x32_bf16 v[108:111], v[132:135], v[148:151], v[108:111]
	v_mfma_f32_16x16x32_bf16 v[76:79], v[140:143], v[148:151], v[76:79]
	v_mfma_f32_16x16x32_bf16 v[104:107], v[132:135], v[156:159], v[104:107]
	v_mfma_f32_16x16x32_bf16 v[72:75], v[140:143], v[156:159], v[72:75]
	v_mfma_f32_16x16x32_bf16 v[100:103], v[132:135], v[174:177], v[100:103]
	v_mfma_f32_16x16x32_bf16 v[68:71], v[140:143], v[174:177], v[68:71]
	v_mfma_f32_16x16x32_bf16 v[96:99], v[132:135], v[182:185], v[96:99]
	v_mfma_f32_16x16x32_bf16 v[64:67], v[140:143], v[182:185], v[64:67]
	s_setprio 1
	s_barrier
; #define WAIT_V(n) asm volatile("s_waitcnt vmcnt(" #n ")" ::: "memory")
; #define WAIT_L(n) asm volatile("s_waitcnt lgkmcnt(" #n ")" ::: "memory")
; #define BAR __builtin_amdgcn_s_barrier()
; #define SCHED __builtin_amdgcn_sched_barrier(0)
; template <class Get, class Epi>
; DI void gemm_stream(LAS unsigned char* lds, const int K, const int ld, Get get, Epi epi) {
;     ...
;             STAGE(SBo(0, 1), b2 + hstep);
;             WAIT_V(6); BAR; MMA(1, 1, At, B1); BAR;
;             LDB(B0, 1, 0); SCHED; LDA(At, 1, 0); STAGE(SAo(0, 1), a2 + hstep);
;             WAIT_L(8); BAR; WAIT_L(0); MMA(0, 0, At, B0); BAR; SCHED;
;             LDB(B1, 1, 1); STAGE(SBo(1, 0), b3);
;             BAR; WAIT_L(0); MMA(0, 1, At, B1); BAR;
;             LDA(At, 1, 1); STAGE(SAo(1, 0), a3);
;             BAR; WAIT_L(0); MMA(1, 0, At, B0); BAR; SCHED;
;             STAGE(SBo(1, 1), b3 + hstep);
;             WAIT_V(6); BAR; MMA(1, 1, At, B1); BAR;
	s_add_u32 s4, s8, 0x160000
	s_addc_u32 s5, s9, 0
	s_mov_b32 m0, s58
	v_lshl_add_u64 v[128:129], s[4:5], 0, v[164:165]
	global_load_lds_dwordx4 v[128:129], off
	v_lshl_add_u64 v[128:129], s[4:5], 0, v[166:167]
	s_mov_b32 m0, s59
	s_nop 0
	global_load_lds_dwordx4 v[128:129], off
	s_waitcnt vmcnt(6)
	s_barrier
	s_setprio 0
	v_mfma_f32_16x16x32_bf16 v[44:47], v[186:189], v[144:147], v[44:47]
	v_mfma_f32_16x16x32_bf16 v[12:15], v[194:197], v[144:147], v[12:15]
	v_mfma_f32_16x16x32_bf16 v[40:43], v[186:189], v[152:155], v[40:43]
	v_mfma_f32_16x16x32_bf16 v[8:11], v[194:197], v[152:155], v[8:11]
	v_mfma_f32_16x16x32_bf16 v[36:39], v[186:189], v[160:163], v[36:39]
	v_mfma_f32_16x16x32_bf16 v[4:7], v[194:197], v[160:163], v[4:7]
	v_mfma_f32_16x16x32_bf16 v[32:35], v[186:189], v[178:181], v[32:35]
	v_mfma_f32_16x16x32_bf16 v[0:3], v[194:197], v[178:181], v[0:3]
	v_mfma_f32_16x16x32_bf16 v[44:47], v[190:193], v[148:151], v[44:47]
	v_mfma_f32_16x16x32_bf16 v[12:15], v[202:205], v[148:151], v[12:15]
	v_mfma_f32_16x16x32_bf16 v[40:43], v[190:193], v[156:159], v[40:43]
	v_mfma_f32_16x16x32_bf16 v[8:11], v[202:205], v[156:159], v[8:11]
	v_mfma_f32_16x16x32_bf16 v[36:39], v[190:193], v[174:177], v[36:39]
	v_mfma_f32_16x16x32_bf16 v[4:7], v[202:205], v[174:177], v[4:7]
	v_mfma_f32_16x16x32_bf16 v[32:35], v[190:193], v[182:185], v[32:35]
	v_mfma_f32_16x16x32_bf16 v[0:3], v[202:205], v[182:185], v[0:3]
	s_setprio 1
	s_add_i32 s17, 16, 0x18000
	v_add_u32_e32 v140, s17, v198
	s_barrier
	ds_read_b128 v[128:131], v140
	ds_read_b128 v[132:135], v140 offset:1024
	ds_read_b128 v[136:139], v140 offset:2048
	ds_read_b128 v[140:143], v140 offset:3072
	s_add_u32 s4, s10, 0x160000
	s_addc_u32 s5, s11, 0
	s_mov_b32 m0, s43
	v_lshl_add_u64 v[186:187], s[4:5], 0, v[164:165]
	ds_read_b128 v[144:147], v200 offset:32768
	ds_read_b128 v[148:151], v200 offset:33792
	ds_read_b128 v[152:155], v200 offset:34816
	ds_read_b128 v[156:159], v200 offset:35840
	ds_read_b128 v[160:163], v200 offset:36864
	ds_read_b128 v[174:177], v200 offset:37888
	ds_read_b128 v[178:181], v200 offset:38912
	ds_read_b128 v[182:185], v200 offset:39936
	global_load_lds_dwordx4 v[186:187], off
	v_lshl_add_u64 v[186:187], s[4:5], 0, v[166:167]
	s_mov_b32 m0, s44
	s_nop 0
	global_load_lds_dwordx4 v[186:187], off
	s_waitcnt lgkmcnt(8)
	s_barrier
	s_waitcnt lgkmcnt(0)
	s_setprio 0
	s_waitcnt lgkmcnt(0)
	v_mfma_f32_16x16x32_bf16 v[124:127], v[128:131], v[144:147], v[124:127]
	v_mfma_f32_16x16x32_bf16 v[92:95], v[136:139], v[144:147], v[92:95]
	v_mfma_f32_16x16x32_bf16 v[120:123], v[128:131], v[152:155], v[120:123]
	v_mfma_f32_16x16x32_bf16 v[88:91], v[136:139], v[152:155], v[88:91]
	v_mfma_f32_16x16x32_bf16 v[116:119], v[128:131], v[160:163], v[116:119]
	v_mfma_f32_16x16x32_bf16 v[84:87], v[136:139], v[160:163], v[84:87]
	v_mfma_f32_16x16x32_bf16 v[112:115], v[128:131], v[178:181], v[112:115]
	v_mfma_f32_16x16x32_bf16 v[80:83], v[136:139], v[178:181], v[80:83]
	v_mfma_f32_16x16x32_bf16 v[124:127], v[132:135], v[148:151], v[124:127]
	v_mfma_f32_16x16x32_bf16 v[92:95], v[140:143], v[148:151], v[92:95]
	v_mfma_f32_16x16x32_bf16 v[120:123], v[132:135], v[156:159], v[120:123]
	v_mfma_f32_16x16x32_bf16 v[88:91], v[140:143], v[156:159], v[88:91]
	v_mfma_f32_16x16x32_bf16 v[116:119], v[132:135], v[174:177], v[116:119]
	v_mfma_f32_16x16x32_bf16 v[84:87], v[140:143], v[174:177], v[84:87]
	v_mfma_f32_16x16x32_bf16 v[112:115], v[132:135], v[182:185], v[112:115]
	v_mfma_f32_16x16x32_bf16 v[80:83], v[140:143], v[182:185], v[80:83]
	s_setprio 1
	s_barrier
	s_add_i32 s10, 16, 0x1c000
	s_add_i32 s4, s17, s21
	v_add_u32_e32 v202, s10, v198
	v_lshl_add_u64 v[208:209], v[208:209], 0, s[0:1]
	s_mov_b32 m0, s4
	ds_read_b128 v[186:189], v202
	ds_read_b128 v[190:193], v202 offset:1024
	ds_read_b128 v[194:197], v202 offset:2048
	ds_read_b128 v[202:205], v202 offset:3072
	global_load_lds_dwordx4 v[208:209], off
	v_lshl_add_u64 v[208:209], v[210:211], 0, s[0:1]
	s_add_i32 m0, s4, 0x2000
	s_nop 0
	global_load_lds_dwordx4 v[208:209], off
	s_barrier
	s_waitcnt lgkmcnt(0)
	s_setprio 0
	s_waitcnt lgkmcnt(0)
	v_mfma_f32_16x16x32_bf16 v[60:63], v[186:189], v[144:147], v[60:63]
	v_mfma_f32_16x16x32_bf16 v[28:31], v[194:197], v[144:147], v[28:31]
	v_mfma_f32_16x16x32_bf16 v[56:59], v[186:189], v[152:155], v[56:59]
	v_mfma_f32_16x16x32_bf16 v[24:27], v[194:197], v[152:155], v[24:27]
	v_mfma_f32_16x16x32_bf16 v[52:55], v[186:189], v[160:163], v[52:55]
	v_mfma_f32_16x16x32_bf16 v[20:23], v[194:197], v[160:163], v[20:23]
	v_mfma_f32_16x16x32_bf16 v[48:51], v[186:189], v[178:181], v[48:51]
	v_mfma_f32_16x16x32_bf16 v[16:19], v[194:197], v[178:181], v[16:19]
	v_mfma_f32_16x16x32_bf16 v[60:63], v[190:193], v[148:151], v[60:63]
	v_mfma_f32_16x16x32_bf16 v[28:31], v[202:205], v[148:151], v[28:31]
	v_mfma_f32_16x16x32_bf16 v[56:59], v[190:193], v[156:159], v[56:59]
	v_mfma_f32_16x16x32_bf16 v[24:27], v[202:205], v[156:159], v[24:27]
	v_mfma_f32_16x16x32_bf16 v[52:55], v[190:193], v[174:177], v[52:55]
	v_mfma_f32_16x16x32_bf16 v[20:23], v[202:205], v[174:177], v[20:23]
	v_mfma_f32_16x16x32_bf16 v[48:51], v[190:193], v[182:185], v[48:51]
	v_mfma_f32_16x16x32_bf16 v[16:19], v[202:205], v[182:185], v[16:19]
	s_setprio 1
	s_mov_b32 m0, s45
	v_lshl_add_u64 v[208:209], v[212:213], 0, s[0:1]
	s_barrier
	ds_read_b128 v[144:147], v200 offset:49152
	ds_read_b128 v[148:151], v200 offset:50176
	ds_read_b128 v[152:155], v200 offset:51200
	ds_read_b128 v[156:159], v200 offset:52224
	ds_read_b128 v[160:163], v200 offset:53248
	ds_read_b128 v[174:177], v200 offset:54272
	ds_read_b128 v[178:181], v200 offset:55296
	ds_read_b128 v[182:185], v200 offset:56320
	global_load_lds_dwordx4 v[208:209], off
	v_lshl_add_u64 v[208:209], v[214:215], 0, s[0:1]
	s_mov_b32 m0, s46
	s_nop 0
	global_load_lds_dwordx4 v[208:209], off
	s_barrier
; #define WAIT_V(n) asm volatile("s_waitcnt vmcnt(" #n ")" ::: "memory")
; #define WAIT_L(n) asm volatile("s_waitcnt lgkmcnt(" #n ")" ::: "memory")
; #define BAR __builtin_amdgcn_s_barrier()
; #define SCHED __builtin_amdgcn_sched_barrier(0)
; template <class Get, class Epi>
; DI void gemm_stream(LAS unsigned char* lds, const int K, const int ld, Get get, Epi epi) {
;     ...
;             LDA(At, 1, 1); STAGE(SAo(1, 0), a3);
;             BAR; WAIT_L(0); MMA(1, 0, At, B0); BAR; SCHED;
;             STAGE(SBo(1, 1), b3 + hstep);
;             WAIT_V(6); BAR; MMA(1, 1, At, B1); BAR;
;         }
; DI void epi_resid(const Acc& acc, const P& p, int brow, int bcol, int layer, int gch, bool from_input) {
;     EPI_IDX
;     const float* gate = modv(p, layer, brow, gch);
; #pragma unroll
;     for (int bj = 0; bj < 2; ++bj)
; #pragma unroll
;         for (int n = 0; n < 2; ++n) {
;             const int c0 = bcol + bj * 128 + wc * 32 + n * 16 + fq * 4;
;             const f32x4 g = *(const f32x4*)(gate + c0);
;             f32x4 xv[2][4];
; #pragma unroll
;             for (int ai = 0; ai < 2; ++ai)
; #pragma unroll
;                 for (int m = 0; m < 4; ++m) {
;                     const int r = brow + ai * 128 + wr * 64 + m * 16 + fr;
;                     const float* sp = (from_input ? inrow(p, r) : xrow(p, r)) + c0;
;                     xv[ai][m] = *(const f32x4*)sp;
;                 }
	s_waitcnt lgkmcnt(0)
	s_setprio 0
	s_waitcnt lgkmcnt(0)
	v_mfma_f32_16x16x32_bf16 v[108:111], v[128:131], v[144:147], v[108:111]
	v_mfma_f32_16x16x32_bf16 v[76:79], v[136:139], v[144:147], v[76:79]
	v_mfma_f32_16x16x32_bf16 v[104:107], v[128:131], v[152:155], v[104:107]
	v_mfma_f32_16x16x32_bf16 v[72:75], v[136:139], v[152:155], v[72:75]
	v_mfma_f32_16x16x32_bf16 v[100:103], v[128:131], v[160:163], v[100:103]
	v_mfma_f32_16x16x32_bf16 v[68:71], v[136:139], v[160:163], v[68:71]
	v_mfma_f32_16x16x32_bf16 v[96:99], v[128:131], v[178:181], v[96:99]
	v_mfma_f32_16x16x32_bf16 v[64:67], v[136:139], v[178:181], v[64:67]
	v_mfma_f32_16x16x32_bf16 v[108:111], v[132:135], v[148:151], v[108:111]
	v_mfma_f32_16x16x32_bf16 v[76:79], v[140:143], v[148:151], v[76:79]
	v_mfma_f32_16x16x32_bf16 v[104:107], v[132:135], v[156:159], v[104:107]
	v_mfma_f32_16x16x32_bf16 v[72:75], v[140:143], v[156:159], v[72:75]
	v_mfma_f32_16x16x32_bf16 v[100:103], v[132:135], v[174:177], v[100:103]
	v_mfma_f32_16x16x32_bf16 v[68:71], v[140:143], v[174:177], v[68:71]
	v_mfma_f32_16x16x32_bf16 v[96:99], v[132:135], v[182:185], v[96:99]
	v_mfma_f32_16x16x32_bf16 v[64:67], v[140:143], v[182:185], v[64:67]
	s_setprio 1
	s_barrier
	s_add_u32 s4, s8, 0x160080
	s_addc_u32 s5, s9, 0
	s_add_i32 s8, s10, s21
	v_lshl_add_u64 v[128:129], s[4:5], 0, v[164:165]
	s_mov_b32 m0, s8
	s_nop 0
	global_load_lds_dwordx4 v[128:129], off
	v_lshl_add_u64 v[128:129], s[4:5], 0, v[166:167]
	s_add_i32 m0, s8, 0x2000
	s_nop 0
	global_load_lds_dwordx4 v[128:129], off
	s_waitcnt vmcnt(6)
	s_barrier
	s_setprio 0
	v_mfma_f32_16x16x32_bf16 v[44:47], v[186:189], v[144:147], v[44:47]
	v_mfma_f32_16x16x32_bf16 v[12:15], v[194:197], v[144:147], v[12:15]
	v_mfma_f32_16x16x32_bf16 v[40:43], v[186:189], v[152:155], v[40:43]
	v_mfma_f32_16x16x32_bf16 v[8:11], v[194:197], v[152:155], v[8:11]
	v_mfma_f32_16x16x32_bf16 v[36:39], v[186:189], v[160:163], v[36:39]
	v_mfma_f32_16x16x32_bf16 v[4:7], v[194:197], v[160:163], v[4:7]
	v_mfma_f32_16x16x32_bf16 v[32:35], v[186:189], v[178:181], v[32:35]
	v_mfma_f32_16x16x32_bf16 v[0:3], v[194:197], v[178:181], v[0:3]
	v_mfma_f32_16x16x32_bf16 v[44:47], v[190:193], v[148:151], v[44:47]
	v_mfma_f32_16x16x32_bf16 v[12:15], v[202:205], v[148:151], v[12:15]
	v_mfma_f32_16x16x32_bf16 v[40:43], v[190:193], v[156:159], v[40:43]
	v_mfma_f32_16x16x32_bf16 v[8:11], v[202:205], v[156:159], v[8:11]
	v_mfma_f32_16x16x32_bf16 v[36:39], v[190:193], v[174:177], v[36:39]
	v_mfma_f32_16x16x32_bf16 v[4:7], v[202:205], v[174:177], v[4:7]
	v_mfma_f32_16x16x32_bf16 v[32:35], v[190:193], v[182:185], v[32:35]
	v_mfma_f32_16x16x32_bf16 v[0:3], v[202:205], v[182:185], v[0:3]
	s_setprio 1
	s_add_i32 s16, s16, 2
	s_add_u32 s14, s14, 0x100
	s_addc_u32 s15, s15, 0
	s_cmpk_gt_u32 s16, 0x55
	s_mov_b64 s[4:5], s[6:7]
	s_barrier
	s_cbranch_scc0 .LBB0_3113
	s_lshr_b32 s4, s13, 4
	s_lshl_b32 s5, s13, 8
	s_mulk_i32 s4, 0x1100
	s_and_b32 s5, s5, 0xf00
	s_add_i32 s4, s4, s5
	s_add_i32 s6, s4, 0x100
	s_mul_hi_i32 s4, s6, 0x78787879
	s_lshr_b32 s5, s4, 31
	s_ashr_i32 s4, s4, 11
	s_add_i32 s4, s4, s5
	s_mul_i32 s5, s4, 0xffffef00
	s_mul_i32 s4, s4, 6
	s_lshl_b32 s7, s12, 8
	s_add_i32 s5, s5, s6
	s_add_i32 s4, s4, 35
	s_cmpk_gt_i32 s5, 0xff
	v_mov_b32_e32 v132, v206
	s_cselect_b32 s4, s4, 59
	s_ashr_i32 s5, s4, 31
	v_lshrrev_b32_e32 v128, 1, v132
	v_lshrrev_b32_e32 v129, 2, v132
	s_lshl_b64 s[4:5], s[4:5], 13
	v_and_b32_e32 v128, 0x60, v128
	v_and_b32_e32 v129, 12, v129
	s_add_u32 s4, s26, s4
	v_or3_b32 v174, v128, s7, v129
	s_addc_u32 s5, s27, s5
	v_ashrrev_i32_e32 v175, 31, v174
	v_lshl_add_u64 v[192:193], v[174:175], 2, s[4:5]
	global_load_dwordx4 v[128:131], v[192:193], off
	v_ashrrev_i32_e32 v133, 2, v132
	v_and_b32_e32 v133, 0xffffffc0, v133
	v_and_or_b32 v132, v132, 15, s6
	v_add_u32_e32 v176, v132, v133
	v_mul_hi_i32 v132, v176, s48
	v_lshrrev_b32_e32 v133, 31, v132
	v_ashrrev_i32_e32 v132, 11, v132
	v_add_u32_e32 v203, v132, v133
	v_mad_i32_i24 v202, v203, s49, v176
	v_lshlrev_b32_e32 v212, 12, v203
	v_cmp_lt_i32_e64 s[16:17], s52, v202
	v_add3_u32 v190, v212, v202, s53
	s_and_saveexec_b64 s[4:5], s[16:17]
	s_xor_b64 s[4:5], exec, s[4:5]
	v_add3_u32 v132, v212, v202, s53
	s_or_saveexec_b64 s[4:5], s[4:5]
	v_mov_b64_e32 v[134:135], s[24:25]
	v_lshl_add_u32 v191, v203, 8, v202
	s_xor_b64 exec, exec, s[4:5]
	v_lshl_add_u32 v132, v203, 8, v202
	v_mov_b64_e32 v[134:135], s[18:19]
	s_or_b64 exec, exec, s[4:5]
	v_ashrrev_i32_e32 v133, 31, v132
	v_lshlrev_b64 v[132:133], 13, v[132:133]
	v_lshl_add_u64 v[132:133], v[134:135], 0, v[132:133]
	v_lshl_add_u64 v[132:133], v[174:175], 2, v[132:133]
	global_load_dwordx4 v[160:163], v[132:133], off
	v_or_b32_e32 v132, 16, v176
	v_mul_hi_i32 v133, v132, s48
	v_lshrrev_b32_e32 v134, 31, v133
	v_ashrrev_i32_e32 v133, 11, v133
	v_add_u32_e32 v205, v133, v134
	v_mad_i32_i24 v204, v205, s49, v132
	v_lshlrev_b32_e32 v217, 12, v205
	v_cmp_lt_i32_e64 s[14:15], s52, v204
	v_add3_u32 v188, v217, v204, s53
	s_and_saveexec_b64 s[4:5], s[14:15]
	s_xor_b64 s[4:5], exec, s[4:5]
	v_add3_u32 v132, v217, v204, s53
	s_or_saveexec_b64 s[4:5], s[4:5]
	v_mov_b64_e32 v[134:135], s[24:25]
	v_lshl_add_u32 v189, v205, 8, v204
	s_xor_b64 exec, exec, s[4:5]
	v_lshl_add_u32 v132, v205, 8, v204
	v_mov_b64_e32 v[134:135], s[18:19]
	s_or_b64 exec, exec, s[4:5]
	v_ashrrev_i32_e32 v133, 31, v132
	v_lshlrev_b64 v[132:133], 13, v[132:133]
	v_lshl_add_u64 v[132:133], v[134:135], 0, v[132:133]
	v_lshl_add_u64 v[132:133], v[174:175], 2, v[132:133]
	global_load_dwordx4 v[156:159], v[132:133], off
	v_or_b32_e32 v132, 32, v176
	v_mul_hi_i32 v133, v132, s48
	v_lshrrev_b32_e32 v134, 31, v133
	v_ashrrev_i32_e32 v133, 11, v133
; DI void epi_resid(const Acc& acc, const P& p, int brow, int bcol, int layer, int gch, bool from_input) {
;     ...
;             f32x4 xv[2][4];
; #pragma unroll
;             for (int ai = 0; ai < 2; ++ai)
; #pragma unroll
;                 for (int m = 0; m < 4; ++m) {
;                     const int r = brow + ai * 128 + wr * 64 + m * 16 + fr;
;                     const float* sp = (from_input ? inrow(p, r) : xrow(p, r)) + c0;
;                     xv[ai][m] = *(const f32x4*)sp;
;                 }
	v_add_u32_e32 v209, v133, v134
	v_mad_i32_i24 v208, v209, s49, v132
	v_lshlrev_b32_e32 v220, 12, v209
	v_cmp_lt_i32_e64 s[12:13], s52, v208
	v_add3_u32 v186, v220, v208, s53
	s_and_saveexec_b64 s[4:5], s[12:13]
	s_xor_b64 s[4:5], exec, s[4:5]
	v_add3_u32 v132, v220, v208, s53
	s_or_saveexec_b64 s[4:5], s[4:5]
	v_mov_b64_e32 v[134:135], s[24:25]
	v_lshl_add_u32 v187, v209, 8, v208
	s_xor_b64 exec, exec, s[4:5]
	v_lshl_add_u32 v132, v209, 8, v208
	v_mov_b64_e32 v[134:135], s[18:19]
	s_or_b64 exec, exec, s[4:5]
	v_ashrrev_i32_e32 v133, 31, v132
	v_lshlrev_b64 v[132:133], 13, v[132:133]
	v_lshl_add_u64 v[132:133], v[134:135], 0, v[132:133]
	v_lshl_add_u64 v[132:133], v[174:175], 2, v[132:133]
	global_load_dwordx4 v[152:155], v[132:133], off
	v_or_b32_e32 v132, 48, v176
	v_mul_hi_i32 v133, v132, s48
	v_lshrrev_b32_e32 v134, 31, v133
	v_ashrrev_i32_e32 v133, 11, v133
	v_add_u32_e32 v211, v133, v134
	v_mad_i32_i24 v210, v211, s49, v132
	v_lshlrev_b32_e32 v223, 12, v211
	v_cmp_lt_i32_e64 s[10:11], s52, v210
	v_add3_u32 v184, v223, v210, s53
	s_and_saveexec_b64 s[4:5], s[10:11]
	s_xor_b64 s[4:5], exec, s[4:5]
	v_add3_u32 v132, v223, v210, s53
	s_or_saveexec_b64 s[4:5], s[4:5]
	v_mov_b64_e32 v[134:135], s[24:25]
	v_lshl_add_u32 v185, v211, 8, v210
	s_xor_b64 exec, exec, s[4:5]
	v_lshl_add_u32 v132, v211, 8, v210
	v_mov_b64_e32 v[134:135], s[18:19]
	s_or_b64 exec, exec, s[4:5]
	v_ashrrev_i32_e32 v133, 31, v132
	v_lshlrev_b64 v[132:133], 13, v[132:133]
	v_lshl_add_u64 v[132:133], v[134:135], 0, v[132:133]
	v_lshl_add_u64 v[132:133], v[174:175], 2, v[132:133]
	global_load_dwordx4 v[148:151], v[132:133], off
	v_add_u32_e32 v132, 0x80, v176
	v_mul_hi_i32 v133, v132, s48
	v_lshrrev_b32_e32 v134, 31, v133
	v_ashrrev_i32_e32 v133, 11, v133
	v_add_u32_e32 v214, v133, v134
	v_mad_i32_i24 v213, v214, s49, v132
	v_lshlrev_b32_e32 v224, 12, v214
	v_cmp_lt_i32_e64 s[8:9], s52, v213
	v_add3_u32 v182, v224, v213, s53
	s_and_saveexec_b64 s[4:5], s[8:9]
	s_xor_b64 s[4:5], exec, s[4:5]
	v_add3_u32 v132, v224, v213, s53
	s_or_saveexec_b64 s[4:5], s[4:5]
	v_mov_b64_e32 v[134:135], s[24:25]
	v_lshl_add_u32 v183, v214, 8, v213
	s_xor_b64 exec, exec, s[4:5]
	v_lshl_add_u32 v132, v214, 8, v213
	v_mov_b64_e32 v[134:135], s[18:19]
	s_or_b64 exec, exec, s[4:5]
	v_ashrrev_i32_e32 v133, 31, v132
	v_lshlrev_b64 v[132:133], 13, v[132:133]
	v_lshl_add_u64 v[132:133], v[134:135], 0, v[132:133]
	v_lshl_add_u64 v[132:133], v[174:175], 2, v[132:133]
	global_load_dwordx4 v[144:147], v[132:133], off
	v_add_u32_e32 v132, 0x90, v176
	v_mul_hi_i32 v133, v132, s48
	v_lshrrev_b32_e32 v134, 31, v133
	v_ashrrev_i32_e32 v133, 11, v133
	v_add_u32_e32 v216, v133, v134
	v_mad_i32_i24 v215, v216, s49, v132
	v_lshlrev_b32_e32 v225, 12, v216
	v_cmp_lt_i32_e64 s[6:7], s52, v215
	v_add3_u32 v180, v225, v215, s53
	s_and_saveexec_b64 s[4:5], s[6:7]
	s_xor_b64 s[4:5], exec, s[4:5]
	v_add3_u32 v132, v225, v215, s53
	s_or_saveexec_b64 s[4:5], s[4:5]
	v_mov_b64_e32 v[134:135], s[24:25]
	v_lshl_add_u32 v181, v216, 8, v215
	s_xor_b64 exec, exec, s[4:5]
	v_lshl_add_u32 v132, v216, 8, v215
	v_mov_b64_e32 v[134:135], s[18:19]
	s_or_b64 exec, exec, s[4:5]
	v_ashrrev_i32_e32 v133, 31, v132
	v_lshlrev_b64 v[132:133], 13, v[132:133]
	v_lshl_add_u64 v[132:133], v[134:135], 0, v[132:133]
	v_lshl_add_u64 v[132:133], v[174:175], 2, v[132:133]
	global_load_dwordx4 v[140:143], v[132:133], off
	v_add_u32_e32 v132, 0xa0, v176
	v_mul_hi_i32 v133, v132, s48
	v_lshrrev_b32_e32 v134, 31, v133
	v_ashrrev_i32_e32 v133, 11, v133
	v_add_u32_e32 v219, v133, v134
	v_mad_i32_i24 v218, v219, s49, v132
	v_lshlrev_b32_e32 v226, 12, v219
	v_cmp_lt_i32_e64 s[4:5], s52, v218
	v_add3_u32 v178, v226, v218, s53
	s_and_saveexec_b64 s[28:29], s[4:5]
	s_xor_b64 s[40:41], exec, s[28:29]
	v_add3_u32 v132, v226, v218, s53
	s_or_saveexec_b64 s[40:41], s[40:41]
	v_mov_b64_e32 v[134:135], s[24:25]
	v_lshl_add_u32 v179, v219, 8, v218
	s_xor_b64 exec, exec, s[40:41]
	v_lshl_add_u32 v132, v219, 8, v218
	v_mov_b64_e32 v[134:135], s[18:19]
	s_or_b64 exec, exec, s[40:41]
	v_ashrrev_i32_e32 v133, 31, v132
	v_lshlrev_b64 v[132:133], 13, v[132:133]
	v_lshl_add_u64 v[132:133], v[134:135], 0, v[132:133]
	v_lshl_add_u64 v[132:133], v[174:175], 2, v[132:133]
	global_load_dwordx4 v[136:139], v[132:133], off
	v_add_u32_e32 v132, 0xb0, v176
	v_mul_hi_i32 v133, v132, s48
	v_lshrrev_b32_e32 v134, 31, v133
	v_ashrrev_i32_e32 v133, 11, v133
	v_add_u32_e32 v222, v133, v134
	v_mad_i32_i24 v221, v222, s49, v132
	v_lshlrev_b32_e32 v227, 12, v222
	v_cmp_lt_i32_e32 vcc, s52, v221
	v_add3_u32 v176, v227, v221, s53
	s_and_saveexec_b64 s[28:29], vcc
	s_xor_b64 s[40:41], exec, s[28:29]
	v_add3_u32 v132, v227, v221, s53
	s_or_saveexec_b64 s[40:41], s[40:41]
	v_mov_b64_e32 v[134:135], s[24:25]
	v_lshl_add_u32 v177, v222, 8, v221
	s_xor_b64 exec, exec, s[40:41]
	v_lshl_add_u32 v132, v222, 8, v221
	v_mov_b64_e32 v[134:135], s[18:19]
	s_or_b64 exec, exec, s[40:41]
	v_ashrrev_i32_e32 v133, 31, v132
	v_lshlrev_b64 v[132:133], 13, v[132:133]
	v_lshl_add_u64 v[132:133], v[134:135], 0, v[132:133]
	v_lshl_add_u64 v[132:133], v[174:175], 2, v[132:133]
	global_load_dwordx4 v[132:135], v[132:133], off
	s_and_saveexec_b64 s[28:29], s[16:17]
	s_xor_b64 s[40:41], exec, s[28:29]
	v_add3_u32 v194, v212, v202, s53
	s_or_saveexec_b64 s[40:41], s[40:41]
	v_mov_b64_e32 v[196:197], s[24:25]
	s_xor_b64 exec, exec, s[40:41]
	v_lshl_add_u32 v194, v203, 8, v202
	v_mov_b64_e32 v[196:197], s[18:19]
	s_or_b64 exec, exec, s[40:41]
	v_ashrrev_i32_e32 v195, 31, v194
	s_waitcnt vmcnt(0)
; DI void epi_resid(const Acc& acc, const P& p, int brow, int bcol, int layer, int gch, bool from_input) {
;     ...
;             __builtin_amdgcn_sched_barrier(0);
; #pragma unroll
;             for (int ai = 0; ai < 2; ++ai)
; #pragma unroll
;                 for (int m = 0; m < 4; ++m) {
;                     const int r = brow + ai * 128 + wr * 64 + m * 16 + fr;
;                     *(f32x4*)(xrow(p, r) + c0) = xv[ai][m] + g * acc[ai][bj][m][n];
;                 }
;             __builtin_amdgcn_sched_barrier(0);
;         }
	v_pk_fma_f32 v[124:125], v[124:125], v[128:129], v[160:161]
	v_lshlrev_b64 v[160:161], 13, v[194:195]
	v_lshl_add_u64 v[160:161], v[196:197], 0, v[160:161]
	v_pk_fma_f32 v[126:127], v[126:127], v[130:131], v[162:163]
	v_lshl_add_u64 v[160:161], v[174:175], 2, v[160:161]
	global_store_dwordx4 v[160:161], v[124:127], off
	s_and_saveexec_b64 s[28:29], s[14:15]
	s_xor_b64 s[40:41], exec, s[28:29]
	v_add3_u32 v124, v217, v204, s53
	s_or_saveexec_b64 s[40:41], s[40:41]
	v_mov_b64_e32 v[126:127], s[24:25]
	s_xor_b64 exec, exec, s[40:41]
	v_lshl_add_u32 v124, v205, 8, v204
	v_mov_b64_e32 v[126:127], s[18:19]
	s_or_b64 exec, exec, s[40:41]
	v_ashrrev_i32_e32 v125, 31, v124
	v_lshlrev_b64 v[124:125], 13, v[124:125]
	v_lshl_add_u64 v[124:125], v[126:127], 0, v[124:125]
	v_pk_fma_f32 v[122:123], v[122:123], v[130:131], v[158:159]
	v_pk_fma_f32 v[120:121], v[120:121], v[128:129], v[156:157]
	v_lshl_add_u64 v[124:125], v[174:175], 2, v[124:125]
	global_store_dwordx4 v[124:125], v[120:123], off
	s_and_saveexec_b64 s[28:29], s[12:13]
	s_xor_b64 s[40:41], exec, s[28:29]
	v_add3_u32 v120, v220, v208, s53
	s_or_saveexec_b64 s[40:41], s[40:41]
	v_mov_b64_e32 v[122:123], s[24:25]
	s_xor_b64 exec, exec, s[40:41]
	v_lshl_add_u32 v120, v209, 8, v208
	v_mov_b64_e32 v[122:123], s[18:19]
	s_or_b64 exec, exec, s[40:41]
	v_ashrrev_i32_e32 v121, 31, v120
	v_lshlrev_b64 v[120:121], 13, v[120:121]
	v_lshl_add_u64 v[120:121], v[122:123], 0, v[120:121]
	v_pk_fma_f32 v[118:119], v[118:119], v[130:131], v[154:155]
	v_pk_fma_f32 v[116:117], v[116:117], v[128:129], v[152:153]
	v_lshl_add_u64 v[120:121], v[174:175], 2, v[120:121]
	global_store_dwordx4 v[120:121], v[116:119], off
	s_and_saveexec_b64 s[28:29], s[10:11]
	s_xor_b64 s[40:41], exec, s[28:29]
	v_add3_u32 v116, v223, v210, s53
	s_or_saveexec_b64 s[40:41], s[40:41]
	v_mov_b64_e32 v[118:119], s[24:25]
	s_xor_b64 exec, exec, s[40:41]
	v_lshl_add_u32 v116, v211, 8, v210
	v_mov_b64_e32 v[118:119], s[18:19]
	s_or_b64 exec, exec, s[40:41]
	v_ashrrev_i32_e32 v117, 31, v116
	v_lshlrev_b64 v[116:117], 13, v[116:117]
	v_lshl_add_u64 v[116:117], v[118:119], 0, v[116:117]
	v_pk_fma_f32 v[114:115], v[114:115], v[130:131], v[150:151]
	v_pk_fma_f32 v[112:113], v[112:113], v[128:129], v[148:149]
	v_lshl_add_u64 v[116:117], v[174:175], 2, v[116:117]
	global_store_dwordx4 v[116:117], v[112:115], off
	s_and_saveexec_b64 s[28:29], s[8:9]
	s_xor_b64 s[40:41], exec, s[28:29]
	v_add3_u32 v112, v224, v213, s53
	s_or_saveexec_b64 s[40:41], s[40:41]
	v_mov_b64_e32 v[114:115], s[24:25]
	s_xor_b64 exec, exec, s[40:41]
	v_lshl_add_u32 v112, v214, 8, v213
	v_mov_b64_e32 v[114:115], s[18:19]
	s_or_b64 exec, exec, s[40:41]
	v_ashrrev_i32_e32 v113, 31, v112
	v_lshlrev_b64 v[112:113], 13, v[112:113]
	v_lshl_add_u64 v[112:113], v[114:115], 0, v[112:113]
	v_pk_fma_f32 v[110:111], v[110:111], v[130:131], v[146:147]
	v_pk_fma_f32 v[108:109], v[108:109], v[128:129], v[144:145]
	v_lshl_add_u64 v[112:113], v[174:175], 2, v[112:113]
	global_store_dwordx4 v[112:113], v[108:111], off
	s_and_saveexec_b64 s[28:29], s[6:7]
	s_xor_b64 s[40:41], exec, s[28:29]
	v_add3_u32 v108, v225, v215, s53
	s_or_saveexec_b64 s[40:41], s[40:41]
	v_mov_b64_e32 v[110:111], s[24:25]
	s_xor_b64 exec, exec, s[40:41]
	v_lshl_add_u32 v108, v216, 8, v215
	v_mov_b64_e32 v[110:111], s[18:19]
	s_or_b64 exec, exec, s[40:41]
	v_ashrrev_i32_e32 v109, 31, v108
	v_lshlrev_b64 v[108:109], 13, v[108:109]
	v_lshl_add_u64 v[108:109], v[110:111], 0, v[108:109]
	v_pk_fma_f32 v[106:107], v[106:107], v[130:131], v[142:143]
	v_pk_fma_f32 v[104:105], v[104:105], v[128:129], v[140:141]
	v_lshl_add_u64 v[108:109], v[174:175], 2, v[108:109]
	global_store_dwordx4 v[108:109], v[104:107], off
	s_and_saveexec_b64 s[28:29], s[4:5]
	s_xor_b64 s[40:41], exec, s[28:29]
	v_add3_u32 v104, v226, v218, s53
	s_or_saveexec_b64 s[40:41], s[40:41]
	v_mov_b64_e32 v[106:107], s[24:25]
	s_xor_b64 exec, exec, s[40:41]
	v_lshl_add_u32 v104, v219, 8, v218
	v_mov_b64_e32 v[106:107], s[18:19]
	s_or_b64 exec, exec, s[40:41]
	v_ashrrev_i32_e32 v105, 31, v104
	v_lshlrev_b64 v[104:105], 13, v[104:105]
	v_lshl_add_u64 v[104:105], v[106:107], 0, v[104:105]
	v_pk_fma_f32 v[102:103], v[102:103], v[130:131], v[138:139]
	v_pk_fma_f32 v[100:101], v[100:101], v[128:129], v[136:137]
	v_lshl_add_u64 v[104:105], v[174:175], 2, v[104:105]
	global_store_dwordx4 v[104:105], v[100:103], off
	s_and_saveexec_b64 s[28:29], vcc
	s_xor_b64 s[40:41], exec, s[28:29]
	v_add3_u32 v100, v227, v221, s53
	s_or_saveexec_b64 s[40:41], s[40:41]
	v_mov_b64_e32 v[102:103], s[24:25]
	s_xor_b64 exec, exec, s[40:41]
	v_lshl_add_u32 v100, v222, 8, v221
	v_mov_b64_e32 v[102:103], s[18:19]
	s_or_b64 exec, exec, s[40:41]
	v_ashrrev_i32_e32 v101, 31, v100
	v_lshlrev_b64 v[100:101], 13, v[100:101]
	v_lshl_add_u64 v[100:101], v[102:103], 0, v[100:101]
	v_pk_fma_f32 v[98:99], v[98:99], v[130:131], v[134:135]
	v_pk_fma_f32 v[96:97], v[96:97], v[128:129], v[132:133]
	v_lshl_add_u64 v[100:101], v[174:175], 2, v[100:101]
	global_store_dwordx4 v[100:101], v[96:99], off
	global_load_dwordx4 v[96:99], v[192:193], off offset:64
	s_and_saveexec_b64 s[28:29], s[16:17]
	s_xor_b64 s[40:41], exec, s[28:29]
	v_add3_u32 v100, v212, v202, s53
	s_or_saveexec_b64 s[40:41], s[40:41]
	v_mov_b64_e32 v[102:103], s[24:25]
	s_xor_b64 exec, exec, s[40:41]
	v_lshl_add_u32 v100, v203, 8, v202
	v_mov_b64_e32 v[102:103], s[18:19]
	s_or_b64 exec, exec, s[40:41]
	v_ashrrev_i32_e32 v101, 31, v100
	v_lshlrev_b64 v[100:101], 13, v[100:101]
	v_lshl_add_u64 v[100:101], v[102:103], 0, v[100:101]
	v_lshl_add_u64 v[100:101], v[174:175], 2, v[100:101]
	global_load_dwordx4 v[128:131], v[100:101], off offset:64
; DI void epi_resid(const Acc& acc, const P& p, int brow, int bcol, int layer, int gch, bool from_input) {
;     ...
; #pragma unroll
;             for (int ai = 0; ai < 2; ++ai)
; #pragma unroll
;                 for (int m = 0; m < 4; ++m) {
;                     const int r = brow + ai * 128 + wr * 64 + m * 16 + fr;
;                     const float* sp = (from_input ? inrow(p, r) : xrow(p, r)) + c0;
;                     xv[ai][m] = *(const f32x4*)sp;
;                 }
	s_and_saveexec_b64 s[28:29], s[14:15]
	s_xor_b64 s[40:41], exec, s[28:29]
	v_add3_u32 v100, v217, v204, s53
	s_or_saveexec_b64 s[40:41], s[40:41]
	v_mov_b64_e32 v[102:103], s[24:25]
	s_xor_b64 exec, exec, s[40:41]
	v_lshl_add_u32 v100, v205, 8, v204
	v_mov_b64_e32 v[102:103], s[18:19]
	s_or_b64 exec, exec, s[40:41]
	v_ashrrev_i32_e32 v101, 31, v100
	v_lshlrev_b64 v[100:101], 13, v[100:101]
	v_lshl_add_u64 v[100:101], v[102:103], 0, v[100:101]
	v_lshl_add_u64 v[100:101], v[174:175], 2, v[100:101]
	global_load_dwordx4 v[124:127], v[100:101], off offset:64
	s_and_saveexec_b64 s[28:29], s[12:13]
	s_xor_b64 s[40:41], exec, s[28:29]
	v_add3_u32 v100, v220, v208, s53
	s_or_saveexec_b64 s[40:41], s[40:41]
	v_mov_b64_e32 v[102:103], s[24:25]
	s_xor_b64 exec, exec, s[40:41]
	v_lshl_add_u32 v100, v209, 8, v208
	v_mov_b64_e32 v[102:103], s[18:19]
	s_or_b64 exec, exec, s[40:41]
	v_ashrrev_i32_e32 v101, 31, v100
	v_lshlrev_b64 v[100:101], 13, v[100:101]
	v_lshl_add_u64 v[100:101], v[102:103], 0, v[100:101]
	v_lshl_add_u64 v[100:101], v[174:175], 2, v[100:101]
	global_load_dwordx4 v[120:123], v[100:101], off offset:64
	s_and_saveexec_b64 s[28:29], s[10:11]
	s_xor_b64 s[40:41], exec, s[28:29]
	v_add3_u32 v100, v223, v210, s53
	s_or_saveexec_b64 s[40:41], s[40:41]
	v_mov_b64_e32 v[102:103], s[24:25]
	s_xor_b64 exec, exec, s[40:41]
	v_lshl_add_u32 v100, v211, 8, v210
	v_mov_b64_e32 v[102:103], s[18:19]
	s_or_b64 exec, exec, s[40:41]
	v_ashrrev_i32_e32 v101, 31, v100
	v_lshlrev_b64 v[100:101], 13, v[100:101]
	v_lshl_add_u64 v[100:101], v[102:103], 0, v[100:101]
	v_lshl_add_u64 v[100:101], v[174:175], 2, v[100:101]
	global_load_dwordx4 v[116:119], v[100:101], off offset:64
	s_and_saveexec_b64 s[28:29], s[8:9]
	s_xor_b64 s[40:41], exec, s[28:29]
	v_add3_u32 v100, v224, v213, s53
	s_or_saveexec_b64 s[40:41], s[40:41]
	v_mov_b64_e32 v[102:103], s[24:25]
	s_xor_b64 exec, exec, s[40:41]
	v_lshl_add_u32 v100, v214, 8, v213
	v_mov_b64_e32 v[102:103], s[18:19]
	s_or_b64 exec, exec, s[40:41]
	v_ashrrev_i32_e32 v101, 31, v100
	v_lshlrev_b64 v[100:101], 13, v[100:101]
	v_lshl_add_u64 v[100:101], v[102:103], 0, v[100:101]
	v_lshl_add_u64 v[100:101], v[174:175], 2, v[100:101]
	global_load_dwordx4 v[112:115], v[100:101], off offset:64
	s_and_saveexec_b64 s[28:29], s[6:7]
	s_xor_b64 s[40:41], exec, s[28:29]
	v_add3_u32 v100, v225, v215, s53
	s_or_saveexec_b64 s[40:41], s[40:41]
	v_mov_b64_e32 v[102:103], s[24:25]
	s_xor_b64 exec, exec, s[40:41]
	v_lshl_add_u32 v100, v216, 8, v215
	v_mov_b64_e32 v[102:103], s[18:19]
	s_or_b64 exec, exec, s[40:41]
	v_ashrrev_i32_e32 v101, 31, v100
	v_lshlrev_b64 v[100:101], 13, v[100:101]
	v_lshl_add_u64 v[100:101], v[102:103], 0, v[100:101]
	v_lshl_add_u64 v[100:101], v[174:175], 2, v[100:101]
	global_load_dwordx4 v[108:111], v[100:101], off offset:64
	s_and_saveexec_b64 s[28:29], s[4:5]
	s_xor_b64 s[40:41], exec, s[28:29]
	v_add3_u32 v100, v226, v218, s53
	s_or_saveexec_b64 s[40:41], s[40:41]
	v_mov_b64_e32 v[102:103], s[24:25]
	s_xor_b64 exec, exec, s[40:41]
	v_lshl_add_u32 v100, v219, 8, v218
	v_mov_b64_e32 v[102:103], s[18:19]
	s_or_b64 exec, exec, s[40:41]
	v_ashrrev_i32_e32 v101, 31, v100
	v_lshlrev_b64 v[100:101], 13, v[100:101]
	v_lshl_add_u64 v[100:101], v[102:103], 0, v[100:101]
	v_lshl_add_u64 v[100:101], v[174:175], 2, v[100:101]
	global_load_dwordx4 v[104:107], v[100:101], off offset:64
	s_and_saveexec_b64 s[28:29], vcc
	s_xor_b64 s[40:41], exec, s[28:29]
	v_add3_u32 v100, v227, v221, s53
	s_or_saveexec_b64 s[40:41], s[40:41]
	v_mov_b64_e32 v[102:103], s[24:25]
	s_xor_b64 exec, exec, s[40:41]
	v_lshl_add_u32 v100, v222, 8, v221
	v_mov_b64_e32 v[102:103], s[18:19]
	s_or_b64 exec, exec, s[40:41]
	v_ashrrev_i32_e32 v101, 31, v100
	v_lshlrev_b64 v[100:101], 13, v[100:101]
	v_lshl_add_u64 v[100:101], v[102:103], 0, v[100:101]
	v_lshl_add_u64 v[100:101], v[174:175], 2, v[100:101]
	global_load_dwordx4 v[100:103], v[100:101], off offset:64
	s_and_saveexec_b64 s[28:29], s[16:17]
	s_xor_b64 s[40:41], exec, s[28:29]
	v_add3_u32 v132, v212, v202, s53
	s_or_saveexec_b64 s[40:41], s[40:41]
	v_mov_b64_e32 v[134:135], s[24:25]
	s_xor_b64 exec, exec, s[40:41]
	v_lshl_add_u32 v132, v203, 8, v202
	v_mov_b64_e32 v[134:135], s[18:19]
	s_or_b64 exec, exec, s[40:41]
	v_ashrrev_i32_e32 v133, 31, v132
	s_waitcnt vmcnt(0)
; #define EPI_DONE do { } while (0)
; DI void epi_resid(const Acc& acc, const P& p, int brow, int bcol, int layer, int gch, bool from_input) {
;     EPI_IDX
;     const float* gate = modv(p, layer, brow, gch);
; #pragma unroll
;     for (int bj = 0; bj < 2; ++bj)
; #pragma unroll
;         for (int n = 0; n < 2; ++n) {
;             const int c0 = bcol + bj * 128 + wc * 32 + n * 16 + fq * 4;
;             const f32x4 g = *(const f32x4*)(gate + c0);
;             f32x4 xv[2][4];
; #pragma unroll
;             for (int ai = 0; ai < 2; ++ai)
; #pragma unroll
;                 for (int m = 0; m < 4; ++m) {
;                     const int r = brow + ai * 128 + wr * 64 + m * 16 + fr;
;                     const float* sp = (from_input ? inrow(p, r) : xrow(p, r)) + c0;
;                     xv[ai][m] = *(const f32x4*)sp;
;                 }
;             __builtin_amdgcn_sched_barrier(0);
; #pragma unroll
;             for (int ai = 0; ai < 2; ++ai)
; #pragma unroll
;                 for (int m = 0; m < 4; ++m) {
;                     const int r = brow + ai * 128 + wr * 64 + m * 16 + fr;
;                     *(f32x4*)(xrow(p, r) + c0) = xv[ai][m] + g * acc[ai][bj][m][n];
;                 }
;             __builtin_amdgcn_sched_barrier(0);
;         }
;     EPI_DONE;
; }
	v_pk_fma_f32 v[92:93], v[92:93], v[96:97], v[128:129]
	v_lshlrev_b64 v[128:129], 13, v[132:133]
	v_lshl_add_u64 v[128:129], v[134:135], 0, v[128:129]
	v_pk_fma_f32 v[94:95], v[94:95], v[98:99], v[130:131]
	v_lshl_add_u64 v[128:129], v[174:175], 2, v[128:129]
	global_store_dwordx4 v[128:129], v[92:95], off offset:64
	s_and_saveexec_b64 s[28:29], s[14:15]
	s_xor_b64 s[40:41], exec, s[28:29]
	v_add3_u32 v92, v217, v204, s53
	s_or_saveexec_b64 s[40:41], s[40:41]
	v_mov_b64_e32 v[94:95], s[24:25]
	s_xor_b64 exec, exec, s[40:41]
	v_lshl_add_u32 v92, v205, 8, v204
	v_mov_b64_e32 v[94:95], s[18:19]
	s_or_b64 exec, exec, s[40:41]
	v_ashrrev_i32_e32 v93, 31, v92
	v_lshlrev_b64 v[92:93], 13, v[92:93]
	v_lshl_add_u64 v[92:93], v[94:95], 0, v[92:93]
	v_pk_fma_f32 v[90:91], v[90:91], v[98:99], v[126:127]
	v_pk_fma_f32 v[88:89], v[88:89], v[96:97], v[124:125]
	v_lshl_add_u64 v[92:93], v[174:175], 2, v[92:93]
	global_store_dwordx4 v[92:93], v[88:91], off offset:64
	s_and_saveexec_b64 s[28:29], s[12:13]
	s_xor_b64 s[40:41], exec, s[28:29]
	v_add3_u32 v88, v220, v208, s53
	s_or_saveexec_b64 s[40:41], s[40:41]
	v_mov_b64_e32 v[90:91], s[24:25]
	s_xor_b64 exec, exec, s[40:41]
	v_lshl_add_u32 v88, v209, 8, v208
	v_mov_b64_e32 v[90:91], s[18:19]
	s_or_b64 exec, exec, s[40:41]
	v_ashrrev_i32_e32 v89, 31, v88
	v_lshlrev_b64 v[88:89], 13, v[88:89]
	v_lshl_add_u64 v[88:89], v[90:91], 0, v[88:89]
	v_pk_fma_f32 v[86:87], v[86:87], v[98:99], v[122:123]
	v_pk_fma_f32 v[84:85], v[84:85], v[96:97], v[120:121]
	v_lshl_add_u64 v[88:89], v[174:175], 2, v[88:89]
	global_store_dwordx4 v[88:89], v[84:87], off offset:64
	s_and_saveexec_b64 s[28:29], s[10:11]
	s_xor_b64 s[40:41], exec, s[28:29]
	v_add3_u32 v84, v223, v210, s53
	s_or_saveexec_b64 s[40:41], s[40:41]
	v_mov_b64_e32 v[86:87], s[24:25]
	s_xor_b64 exec, exec, s[40:41]
	v_lshl_add_u32 v84, v211, 8, v210
	v_mov_b64_e32 v[86:87], s[18:19]
	s_or_b64 exec, exec, s[40:41]
	v_ashrrev_i32_e32 v85, 31, v84
	v_lshlrev_b64 v[84:85], 13, v[84:85]
	v_lshl_add_u64 v[84:85], v[86:87], 0, v[84:85]
	v_pk_fma_f32 v[82:83], v[82:83], v[98:99], v[118:119]
	v_pk_fma_f32 v[80:81], v[80:81], v[96:97], v[116:117]
	v_lshl_add_u64 v[84:85], v[174:175], 2, v[84:85]
	global_store_dwordx4 v[84:85], v[80:83], off offset:64
	s_and_saveexec_b64 s[28:29], s[8:9]
	s_xor_b64 s[40:41], exec, s[28:29]
	v_add3_u32 v80, v224, v213, s53
	s_or_saveexec_b64 s[40:41], s[40:41]
	v_mov_b64_e32 v[82:83], s[24:25]
	s_xor_b64 exec, exec, s[40:41]
	v_lshl_add_u32 v80, v214, 8, v213
	v_mov_b64_e32 v[82:83], s[18:19]
	s_or_b64 exec, exec, s[40:41]
	v_ashrrev_i32_e32 v81, 31, v80
	v_lshlrev_b64 v[80:81], 13, v[80:81]
	v_lshl_add_u64 v[80:81], v[82:83], 0, v[80:81]
	v_pk_fma_f32 v[78:79], v[78:79], v[98:99], v[114:115]
	v_pk_fma_f32 v[76:77], v[76:77], v[96:97], v[112:113]
	v_lshl_add_u64 v[80:81], v[174:175], 2, v[80:81]
	global_store_dwordx4 v[80:81], v[76:79], off offset:64
	s_and_saveexec_b64 s[28:29], s[6:7]
	s_xor_b64 s[40:41], exec, s[28:29]
	v_add3_u32 v76, v225, v215, s53
	s_or_saveexec_b64 s[40:41], s[40:41]
	v_mov_b64_e32 v[78:79], s[24:25]
	s_xor_b64 exec, exec, s[40:41]
	v_lshl_add_u32 v76, v216, 8, v215
	v_mov_b64_e32 v[78:79], s[18:19]
	s_or_b64 exec, exec, s[40:41]
	v_ashrrev_i32_e32 v77, 31, v76
	v_lshlrev_b64 v[76:77], 13, v[76:77]
	v_lshl_add_u64 v[76:77], v[78:79], 0, v[76:77]
	v_pk_fma_f32 v[74:75], v[74:75], v[98:99], v[110:111]
	v_pk_fma_f32 v[72:73], v[72:73], v[96:97], v[108:109]
	v_lshl_add_u64 v[76:77], v[174:175], 2, v[76:77]
	global_store_dwordx4 v[76:77], v[72:75], off offset:64
	s_and_saveexec_b64 s[28:29], s[4:5]
	s_xor_b64 s[40:41], exec, s[28:29]
	v_add3_u32 v72, v226, v218, s53
	s_or_saveexec_b64 s[40:41], s[40:41]
	v_mov_b64_e32 v[74:75], s[24:25]
	s_xor_b64 exec, exec, s[40:41]
	v_lshl_add_u32 v72, v219, 8, v218
	v_mov_b64_e32 v[74:75], s[18:19]
	s_or_b64 exec, exec, s[40:41]
	v_ashrrev_i32_e32 v73, 31, v72
	v_lshlrev_b64 v[72:73], 13, v[72:73]
	v_lshl_add_u64 v[72:73], v[74:75], 0, v[72:73]
	v_pk_fma_f32 v[70:71], v[70:71], v[98:99], v[106:107]
	v_pk_fma_f32 v[68:69], v[68:69], v[96:97], v[104:105]
	v_lshl_add_u64 v[72:73], v[174:175], 2, v[72:73]
	global_store_dwordx4 v[72:73], v[68:71], off offset:64
	s_and_saveexec_b64 s[28:29], vcc
	s_xor_b64 s[40:41], exec, s[28:29]
	v_add3_u32 v68, v227, v221, s53
	s_or_saveexec_b64 s[40:41], s[40:41]
	v_mov_b64_e32 v[70:71], s[24:25]
	s_xor_b64 exec, exec, s[40:41]
	v_lshl_add_u32 v68, v222, 8, v221
	v_mov_b64_e32 v[70:71], s[18:19]
	s_or_b64 exec, exec, s[40:41]
	v_ashrrev_i32_e32 v69, 31, v68
	v_lshlrev_b64 v[68:69], 13, v[68:69]
	v_lshl_add_u64 v[68:69], v[70:71], 0, v[68:69]
	v_pk_fma_f32 v[66:67], v[66:67], v[98:99], v[102:103]
	v_pk_fma_f32 v[64:65], v[64:65], v[96:97], v[100:101]
	v_lshl_add_u64 v[68:69], v[174:175], 2, v[68:69]
	global_store_dwordx4 v[68:69], v[64:67], off offset:64
	global_load_dwordx4 v[64:67], v[192:193], off offset:512
	s_and_saveexec_b64 s[28:29], s[16:17]
	s_xor_b64 s[40:41], exec, s[28:29]
	v_add3_u32 v68, v212, v202, s53
	s_or_saveexec_b64 s[40:41], s[40:41]
	v_mov_b64_e32 v[70:71], s[24:25]
	s_xor_b64 exec, exec, s[40:41]
	v_lshl_add_u32 v68, v203, 8, v202
	v_mov_b64_e32 v[70:71], s[18:19]
	s_or_b64 exec, exec, s[40:41]
	v_ashrrev_i32_e32 v69, 31, v68
	v_lshlrev_b64 v[68:69], 13, v[68:69]
	v_lshl_add_u64 v[68:69], v[70:71], 0, v[68:69]
	v_lshl_add_u64 v[68:69], v[174:175], 2, v[68:69]
	global_load_dwordx4 v[96:99], v[68:69], off offset:512
	s_and_saveexec_b64 s[28:29], s[14:15]
	s_xor_b64 s[40:41], exec, s[28:29]
	v_add3_u32 v68, v217, v204, s53
	s_or_saveexec_b64 s[40:41], s[40:41]
	v_mov_b64_e32 v[70:71], s[24:25]
	s_xor_b64 exec, exec, s[40:41]
; #define EPI_DONE do { } while (0)
; DI void epi_resid(const Acc& acc, const P& p, int brow, int bcol, int layer, int gch, bool from_input) {
;     EPI_IDX
;     const float* gate = modv(p, layer, brow, gch);
; #pragma unroll
;     for (int bj = 0; bj < 2; ++bj)
; #pragma unroll
;         for (int n = 0; n < 2; ++n) {
;             const int c0 = bcol + bj * 128 + wc * 32 + n * 16 + fq * 4;
;             const f32x4 g = *(const f32x4*)(gate + c0);
;             f32x4 xv[2][4];
; #pragma unroll
;             for (int ai = 0; ai < 2; ++ai)
; #pragma unroll
;                 for (int m = 0; m < 4; ++m) {
;                     const int r = brow + ai * 128 + wr * 64 + m * 16 + fr;
;                     const float* sp = (from_input ? inrow(p, r) : xrow(p, r)) + c0;
;                     xv[ai][m] = *(const f32x4*)sp;
;                 }
;             __builtin_amdgcn_sched_barrier(0);
; #pragma unroll
;             for (int ai = 0; ai < 2; ++ai)
; #pragma unroll
;                 for (int m = 0; m < 4; ++m) {
;                     const int r = brow + ai * 128 + wr * 64 + m * 16 + fr;
;                     *(f32x4*)(xrow(p, r) + c0) = xv[ai][m] + g * acc[ai][bj][m][n];
;                 }
;             __builtin_amdgcn_sched_barrier(0);
;         }
;     EPI_DONE;
; }
	v_lshl_add_u32 v68, v205, 8, v204
	v_mov_b64_e32 v[70:71], s[18:19]
	s_or_b64 exec, exec, s[40:41]
	v_ashrrev_i32_e32 v69, 31, v68
	v_lshlrev_b64 v[68:69], 13, v[68:69]
	v_lshl_add_u64 v[68:69], v[70:71], 0, v[68:69]
	v_lshl_add_u64 v[68:69], v[174:175], 2, v[68:69]
	global_load_dwordx4 v[92:95], v[68:69], off offset:512
	s_and_saveexec_b64 s[28:29], s[12:13]
	s_xor_b64 s[40:41], exec, s[28:29]
	v_add3_u32 v68, v220, v208, s53
	s_or_saveexec_b64 s[40:41], s[40:41]
	v_mov_b64_e32 v[70:71], s[24:25]
	s_xor_b64 exec, exec, s[40:41]
	v_lshl_add_u32 v68, v209, 8, v208
	v_mov_b64_e32 v[70:71], s[18:19]
	s_or_b64 exec, exec, s[40:41]
	v_ashrrev_i32_e32 v69, 31, v68
	v_lshlrev_b64 v[68:69], 13, v[68:69]
	v_lshl_add_u64 v[68:69], v[70:71], 0, v[68:69]
	v_lshl_add_u64 v[68:69], v[174:175], 2, v[68:69]
	global_load_dwordx4 v[88:91], v[68:69], off offset:512
	s_and_saveexec_b64 s[28:29], s[10:11]
	s_xor_b64 s[40:41], exec, s[28:29]
	v_add3_u32 v68, v223, v210, s53
	s_or_saveexec_b64 s[40:41], s[40:41]
	v_mov_b64_e32 v[70:71], s[24:25]
	s_xor_b64 exec, exec, s[40:41]
	v_lshl_add_u32 v68, v211, 8, v210
	v_mov_b64_e32 v[70:71], s[18:19]
	s_or_b64 exec, exec, s[40:41]
	v_ashrrev_i32_e32 v69, 31, v68
	v_lshlrev_b64 v[68:69], 13, v[68:69]
	v_lshl_add_u64 v[68:69], v[70:71], 0, v[68:69]
	v_lshl_add_u64 v[68:69], v[174:175], 2, v[68:69]
	global_load_dwordx4 v[84:87], v[68:69], off offset:512
	s_and_saveexec_b64 s[28:29], s[8:9]
	s_xor_b64 s[40:41], exec, s[28:29]
	v_add3_u32 v68, v224, v213, s53
	s_or_saveexec_b64 s[40:41], s[40:41]
	v_mov_b64_e32 v[70:71], s[24:25]
	s_xor_b64 exec, exec, s[40:41]
	v_lshl_add_u32 v68, v214, 8, v213
	v_mov_b64_e32 v[70:71], s[18:19]
	s_or_b64 exec, exec, s[40:41]
	v_ashrrev_i32_e32 v69, 31, v68
	v_lshlrev_b64 v[68:69], 13, v[68:69]
	v_lshl_add_u64 v[68:69], v[70:71], 0, v[68:69]
	v_lshl_add_u64 v[68:69], v[174:175], 2, v[68:69]
	global_load_dwordx4 v[80:83], v[68:69], off offset:512
	s_and_saveexec_b64 s[28:29], s[6:7]
	s_xor_b64 s[40:41], exec, s[28:29]
	v_add3_u32 v68, v225, v215, s53
	s_or_saveexec_b64 s[40:41], s[40:41]
	v_mov_b64_e32 v[70:71], s[24:25]
	s_xor_b64 exec, exec, s[40:41]
	v_lshl_add_u32 v68, v216, 8, v215
	v_mov_b64_e32 v[70:71], s[18:19]
	s_or_b64 exec, exec, s[40:41]
	v_ashrrev_i32_e32 v69, 31, v68
	v_lshlrev_b64 v[68:69], 13, v[68:69]
	v_lshl_add_u64 v[68:69], v[70:71], 0, v[68:69]
	v_lshl_add_u64 v[68:69], v[174:175], 2, v[68:69]
	global_load_dwordx4 v[76:79], v[68:69], off offset:512
	s_and_saveexec_b64 s[28:29], s[4:5]
	s_xor_b64 s[40:41], exec, s[28:29]
	v_add3_u32 v68, v226, v218, s53
	s_or_saveexec_b64 s[40:41], s[40:41]
	v_mov_b64_e32 v[70:71], s[24:25]
	s_xor_b64 exec, exec, s[40:41]
	v_lshl_add_u32 v68, v219, 8, v218
	v_mov_b64_e32 v[70:71], s[18:19]
	s_or_b64 exec, exec, s[40:41]
	v_ashrrev_i32_e32 v69, 31, v68
	v_lshlrev_b64 v[68:69], 13, v[68:69]
	v_lshl_add_u64 v[68:69], v[70:71], 0, v[68:69]
	v_lshl_add_u64 v[68:69], v[174:175], 2, v[68:69]
	global_load_dwordx4 v[72:75], v[68:69], off offset:512
	s_and_saveexec_b64 s[28:29], vcc
	s_xor_b64 s[40:41], exec, s[28:29]
	v_add3_u32 v68, v227, v221, s53
	s_or_saveexec_b64 s[40:41], s[40:41]
	v_mov_b64_e32 v[70:71], s[24:25]
	s_xor_b64 exec, exec, s[40:41]
	v_lshl_add_u32 v68, v222, 8, v221
	v_mov_b64_e32 v[70:71], s[18:19]
	s_or_b64 exec, exec, s[40:41]
	v_ashrrev_i32_e32 v69, 31, v68
	v_lshlrev_b64 v[68:69], 13, v[68:69]
	v_lshl_add_u64 v[68:69], v[70:71], 0, v[68:69]
	v_lshl_add_u64 v[68:69], v[174:175], 2, v[68:69]
	global_load_dwordx4 v[68:71], v[68:69], off offset:512
	s_and_saveexec_b64 s[28:29], s[16:17]
	s_xor_b64 s[40:41], exec, s[28:29]
	v_add3_u32 v100, v212, v202, s53
	s_or_saveexec_b64 s[40:41], s[40:41]
	v_mov_b64_e32 v[102:103], s[24:25]
	s_xor_b64 exec, exec, s[40:41]
	v_lshl_add_u32 v100, v203, 8, v202
	v_mov_b64_e32 v[102:103], s[18:19]
	s_or_b64 exec, exec, s[40:41]
	v_ashrrev_i32_e32 v101, 31, v100
	s_waitcnt vmcnt(0)
	v_pk_fma_f32 v[60:61], v[60:61], v[64:65], v[96:97]
	v_lshlrev_b64 v[96:97], 13, v[100:101]
	v_lshl_add_u64 v[96:97], v[102:103], 0, v[96:97]
	v_pk_fma_f32 v[62:63], v[62:63], v[66:67], v[98:99]
	v_lshl_add_u64 v[96:97], v[174:175], 2, v[96:97]
	global_store_dwordx4 v[96:97], v[60:63], off offset:512
	s_and_saveexec_b64 s[28:29], s[14:15]
	s_xor_b64 s[40:41], exec, s[28:29]
	v_add3_u32 v60, v217, v204, s53
	s_or_saveexec_b64 s[40:41], s[40:41]
	v_mov_b64_e32 v[62:63], s[24:25]
	s_xor_b64 exec, exec, s[40:41]
	v_lshl_add_u32 v60, v205, 8, v204
	v_mov_b64_e32 v[62:63], s[18:19]
	s_or_b64 exec, exec, s[40:41]
	v_ashrrev_i32_e32 v61, 31, v60
	v_lshlrev_b64 v[60:61], 13, v[60:61]
	v_lshl_add_u64 v[60:61], v[62:63], 0, v[60:61]
	v_pk_fma_f32 v[58:59], v[58:59], v[66:67], v[94:95]
	v_pk_fma_f32 v[56:57], v[56:57], v[64:65], v[92:93]
	v_lshl_add_u64 v[60:61], v[174:175], 2, v[60:61]
	global_store_dwordx4 v[60:61], v[56:59], off offset:512
	s_and_saveexec_b64 s[28:29], s[12:13]
	s_xor_b64 s[40:41], exec, s[28:29]
	v_add3_u32 v56, v220, v208, s53
	s_or_saveexec_b64 s[40:41], s[40:41]
	v_mov_b64_e32 v[58:59], s[24:25]
	s_xor_b64 exec, exec, s[40:41]
	v_lshl_add_u32 v56, v209, 8, v208
	v_mov_b64_e32 v[58:59], s[18:19]
	s_or_b64 exec, exec, s[40:41]
	v_ashrrev_i32_e32 v57, 31, v56
	v_lshlrev_b64 v[56:57], 13, v[56:57]
	v_lshl_add_u64 v[56:57], v[58:59], 0, v[56:57]
	v_pk_fma_f32 v[54:55], v[54:55], v[66:67], v[90:91]
	v_pk_fma_f32 v[52:53], v[52:53], v[64:65], v[88:89]
	v_lshl_add_u64 v[56:57], v[174:175], 2, v[56:57]
	global_store_dwordx4 v[56:57], v[52:55], off offset:512
	s_and_saveexec_b64 s[28:29], s[10:11]
	s_xor_b64 s[40:41], exec, s[28:29]
	v_add3_u32 v52, v223, v210, s53
	s_or_saveexec_b64 s[40:41], s[40:41]
; #define EPI_DONE do { } while (0)
; DI void epi_resid(const Acc& acc, const P& p, int brow, int bcol, int layer, int gch, bool from_input) {
;     EPI_IDX
;     const float* gate = modv(p, layer, brow, gch);
; #pragma unroll
;     for (int bj = 0; bj < 2; ++bj)
; #pragma unroll
;         for (int n = 0; n < 2; ++n) {
;             const int c0 = bcol + bj * 128 + wc * 32 + n * 16 + fq * 4;
;             const f32x4 g = *(const f32x4*)(gate + c0);
;             f32x4 xv[2][4];
; #pragma unroll
;             for (int ai = 0; ai < 2; ++ai)
; #pragma unroll
;                 for (int m = 0; m < 4; ++m) {
;                     const int r = brow + ai * 128 + wr * 64 + m * 16 + fr;
;                     const float* sp = (from_input ? inrow(p, r) : xrow(p, r)) + c0;
;                     xv[ai][m] = *(const f32x4*)sp;
;                 }
;             __builtin_amdgcn_sched_barrier(0);
; #pragma unroll
;             for (int ai = 0; ai < 2; ++ai)
; #pragma unroll
;                 for (int m = 0; m < 4; ++m) {
;                     const int r = brow + ai * 128 + wr * 64 + m * 16 + fr;
;                     *(f32x4*)(xrow(p, r) + c0) = xv[ai][m] + g * acc[ai][bj][m][n];
;                 }
;             __builtin_amdgcn_sched_barrier(0);
;         }
;     EPI_DONE;
; }
	v_mov_b64_e32 v[54:55], s[24:25]
	s_xor_b64 exec, exec, s[40:41]
	v_lshl_add_u32 v52, v211, 8, v210
	v_mov_b64_e32 v[54:55], s[18:19]
	s_or_b64 exec, exec, s[40:41]
	v_ashrrev_i32_e32 v53, 31, v52
	v_lshlrev_b64 v[52:53], 13, v[52:53]
	v_lshl_add_u64 v[52:53], v[54:55], 0, v[52:53]
	v_pk_fma_f32 v[50:51], v[50:51], v[66:67], v[86:87]
	v_pk_fma_f32 v[48:49], v[48:49], v[64:65], v[84:85]
	v_lshl_add_u64 v[52:53], v[174:175], 2, v[52:53]
	global_store_dwordx4 v[52:53], v[48:51], off offset:512
	s_and_saveexec_b64 s[28:29], s[8:9]
	s_xor_b64 s[40:41], exec, s[28:29]
	v_add3_u32 v48, v224, v213, s53
	s_or_saveexec_b64 s[40:41], s[40:41]
	v_mov_b64_e32 v[50:51], s[24:25]
	s_xor_b64 exec, exec, s[40:41]
	v_lshl_add_u32 v48, v214, 8, v213
	v_mov_b64_e32 v[50:51], s[18:19]
	s_or_b64 exec, exec, s[40:41]
	v_ashrrev_i32_e32 v49, 31, v48
	v_lshlrev_b64 v[48:49], 13, v[48:49]
	v_lshl_add_u64 v[48:49], v[50:51], 0, v[48:49]
	v_pk_fma_f32 v[46:47], v[46:47], v[66:67], v[82:83]
	v_pk_fma_f32 v[44:45], v[44:45], v[64:65], v[80:81]
	v_lshl_add_u64 v[48:49], v[174:175], 2, v[48:49]
	global_store_dwordx4 v[48:49], v[44:47], off offset:512
	s_and_saveexec_b64 s[28:29], s[6:7]
	s_xor_b64 s[40:41], exec, s[28:29]
	v_add3_u32 v44, v225, v215, s53
	s_or_saveexec_b64 s[40:41], s[40:41]
	v_mov_b64_e32 v[46:47], s[24:25]
	s_xor_b64 exec, exec, s[40:41]
	v_lshl_add_u32 v44, v216, 8, v215
	v_mov_b64_e32 v[46:47], s[18:19]
	s_or_b64 exec, exec, s[40:41]
	v_ashrrev_i32_e32 v45, 31, v44
	v_lshlrev_b64 v[44:45], 13, v[44:45]
	v_lshl_add_u64 v[44:45], v[46:47], 0, v[44:45]
	v_pk_fma_f32 v[42:43], v[42:43], v[66:67], v[78:79]
	v_pk_fma_f32 v[40:41], v[40:41], v[64:65], v[76:77]
	v_lshl_add_u64 v[44:45], v[174:175], 2, v[44:45]
	global_store_dwordx4 v[44:45], v[40:43], off offset:512
	s_and_saveexec_b64 s[28:29], s[4:5]
	s_xor_b64 s[40:41], exec, s[28:29]
	v_add3_u32 v40, v226, v218, s53
	s_or_saveexec_b64 s[40:41], s[40:41]
	v_mov_b64_e32 v[42:43], s[24:25]
	s_xor_b64 exec, exec, s[40:41]
	v_lshl_add_u32 v40, v219, 8, v218
	v_mov_b64_e32 v[42:43], s[18:19]
	s_or_b64 exec, exec, s[40:41]
	v_ashrrev_i32_e32 v41, 31, v40
	v_lshlrev_b64 v[40:41], 13, v[40:41]
	v_lshl_add_u64 v[40:41], v[42:43], 0, v[40:41]
	v_pk_fma_f32 v[38:39], v[38:39], v[66:67], v[74:75]
	v_pk_fma_f32 v[36:37], v[36:37], v[64:65], v[72:73]
	v_lshl_add_u64 v[40:41], v[174:175], 2, v[40:41]
	global_store_dwordx4 v[40:41], v[36:39], off offset:512
	s_and_saveexec_b64 s[28:29], vcc
	s_xor_b64 s[40:41], exec, s[28:29]
	v_add3_u32 v36, v227, v221, s53
	s_or_saveexec_b64 s[40:41], s[40:41]
	v_mov_b64_e32 v[38:39], s[24:25]
	s_xor_b64 exec, exec, s[40:41]
	v_lshl_add_u32 v36, v222, 8, v221
	v_mov_b64_e32 v[38:39], s[18:19]
	s_or_b64 exec, exec, s[40:41]
	v_ashrrev_i32_e32 v37, 31, v36
	v_lshlrev_b64 v[36:37], 13, v[36:37]
	v_lshl_add_u64 v[36:37], v[38:39], 0, v[36:37]
	v_pk_fma_f32 v[34:35], v[34:35], v[66:67], v[70:71]
	v_pk_fma_f32 v[32:33], v[32:33], v[64:65], v[68:69]
	v_lshl_add_u64 v[36:37], v[174:175], 2, v[36:37]
	global_store_dwordx4 v[36:37], v[32:35], off offset:512
	global_load_dwordx4 v[32:35], v[192:193], off offset:576
	s_and_saveexec_b64 s[28:29], s[16:17]
	s_xor_b64 s[40:41], exec, s[28:29]
	v_add3_u32 v36, v212, v202, s53
	s_or_saveexec_b64 s[40:41], s[40:41]
	v_mov_b64_e32 v[38:39], s[24:25]
	s_xor_b64 exec, exec, s[40:41]
	v_lshl_add_u32 v36, v203, 8, v202
	v_mov_b64_e32 v[38:39], s[18:19]
	s_or_b64 exec, exec, s[40:41]
	v_ashrrev_i32_e32 v37, 31, v36
	v_lshlrev_b64 v[36:37], 13, v[36:37]
	v_lshl_add_u64 v[36:37], v[38:39], 0, v[36:37]
	v_lshl_add_u64 v[36:37], v[174:175], 2, v[36:37]
	global_load_dwordx4 v[64:67], v[36:37], off offset:576
	s_and_saveexec_b64 s[28:29], s[14:15]
	s_xor_b64 s[40:41], exec, s[28:29]
	v_add3_u32 v36, v217, v204, s53
	s_or_saveexec_b64 s[40:41], s[40:41]
	v_mov_b64_e32 v[38:39], s[24:25]
	s_xor_b64 exec, exec, s[40:41]
	v_lshl_add_u32 v36, v205, 8, v204
	v_mov_b64_e32 v[38:39], s[18:19]
	s_or_b64 exec, exec, s[40:41]
	v_ashrrev_i32_e32 v37, 31, v36
	v_lshlrev_b64 v[36:37], 13, v[36:37]
	v_lshl_add_u64 v[36:37], v[38:39], 0, v[36:37]
	v_lshl_add_u64 v[36:37], v[174:175], 2, v[36:37]
	global_load_dwordx4 v[60:63], v[36:37], off offset:576
	s_and_saveexec_b64 s[28:29], s[12:13]
	s_xor_b64 s[40:41], exec, s[28:29]
	v_add3_u32 v36, v220, v208, s53
	s_or_saveexec_b64 s[40:41], s[40:41]
	v_mov_b64_e32 v[38:39], s[24:25]
	s_xor_b64 exec, exec, s[40:41]
	v_lshl_add_u32 v36, v209, 8, v208
	v_mov_b64_e32 v[38:39], s[18:19]
	s_or_b64 exec, exec, s[40:41]
	v_ashrrev_i32_e32 v37, 31, v36
	v_lshlrev_b64 v[36:37], 13, v[36:37]
	v_lshl_add_u64 v[36:37], v[38:39], 0, v[36:37]
	v_lshl_add_u64 v[36:37], v[174:175], 2, v[36:37]
	global_load_dwordx4 v[56:59], v[36:37], off offset:576
	s_and_saveexec_b64 s[28:29], s[10:11]
	s_xor_b64 s[40:41], exec, s[28:29]
	v_add3_u32 v36, v223, v210, s53
	s_or_saveexec_b64 s[40:41], s[40:41]
	v_mov_b64_e32 v[38:39], s[24:25]
	s_xor_b64 exec, exec, s[40:41]
	v_lshl_add_u32 v36, v211, 8, v210
	v_mov_b64_e32 v[38:39], s[18:19]
	s_or_b64 exec, exec, s[40:41]
	v_ashrrev_i32_e32 v37, 31, v36
	v_lshlrev_b64 v[36:37], 13, v[36:37]
	v_lshl_add_u64 v[36:37], v[38:39], 0, v[36:37]
	v_lshl_add_u64 v[36:37], v[174:175], 2, v[36:37]
	global_load_dwordx4 v[52:55], v[36:37], off offset:576
	s_and_saveexec_b64 s[28:29], s[8:9]
	s_xor_b64 s[40:41], exec, s[28:29]
	v_add3_u32 v36, v224, v213, s53
	s_or_saveexec_b64 s[40:41], s[40:41]
	v_mov_b64_e32 v[38:39], s[24:25]
	s_xor_b64 exec, exec, s[40:41]
	v_lshl_add_u32 v36, v214, 8, v213
	v_mov_b64_e32 v[38:39], s[18:19]
	s_or_b64 exec, exec, s[40:41]
	v_ashrrev_i32_e32 v37, 31, v36
	v_lshlrev_b64 v[36:37], 13, v[36:37]
; #define EPI_DONE do { } while (0)
; DI void epi_resid(const Acc& acc, const P& p, int brow, int bcol, int layer, int gch, bool from_input) {
;     EPI_IDX
;     const float* gate = modv(p, layer, brow, gch);
; #pragma unroll
;     for (int bj = 0; bj < 2; ++bj)
; #pragma unroll
;         for (int n = 0; n < 2; ++n) {
;             const int c0 = bcol + bj * 128 + wc * 32 + n * 16 + fq * 4;
;             const f32x4 g = *(const f32x4*)(gate + c0);
;             f32x4 xv[2][4];
; #pragma unroll
;             for (int ai = 0; ai < 2; ++ai)
; #pragma unroll
;                 for (int m = 0; m < 4; ++m) {
;                     const int r = brow + ai * 128 + wr * 64 + m * 16 + fr;
;                     const float* sp = (from_input ? inrow(p, r) : xrow(p, r)) + c0;
;                     xv[ai][m] = *(const f32x4*)sp;
;                 }
;             __builtin_amdgcn_sched_barrier(0);
; #pragma unroll
;             for (int ai = 0; ai < 2; ++ai)
; #pragma unroll
;                 for (int m = 0; m < 4; ++m) {
;                     const int r = brow + ai * 128 + wr * 64 + m * 16 + fr;
;                     *(f32x4*)(xrow(p, r) + c0) = xv[ai][m] + g * acc[ai][bj][m][n];
;                 }
;             __builtin_amdgcn_sched_barrier(0);
;         }
;     EPI_DONE;
; }
	v_lshl_add_u64 v[36:37], v[38:39], 0, v[36:37]
	v_lshl_add_u64 v[36:37], v[174:175], 2, v[36:37]
	global_load_dwordx4 v[48:51], v[36:37], off offset:576
	s_and_saveexec_b64 s[28:29], s[6:7]
	s_xor_b64 s[40:41], exec, s[28:29]
	v_add3_u32 v36, v225, v215, s53
	s_or_saveexec_b64 s[40:41], s[40:41]
	v_mov_b64_e32 v[38:39], s[24:25]
	s_xor_b64 exec, exec, s[40:41]
	v_lshl_add_u32 v36, v216, 8, v215
	v_mov_b64_e32 v[38:39], s[18:19]
	s_or_b64 exec, exec, s[40:41]
	v_ashrrev_i32_e32 v37, 31, v36
	v_lshlrev_b64 v[36:37], 13, v[36:37]
	v_lshl_add_u64 v[36:37], v[38:39], 0, v[36:37]
	v_lshl_add_u64 v[36:37], v[174:175], 2, v[36:37]
	global_load_dwordx4 v[44:47], v[36:37], off offset:576
	s_and_saveexec_b64 s[28:29], s[4:5]
	s_xor_b64 s[40:41], exec, s[28:29]
	v_add3_u32 v36, v226, v218, s53
	s_or_saveexec_b64 s[40:41], s[40:41]
	v_mov_b64_e32 v[38:39], s[24:25]
	s_xor_b64 exec, exec, s[40:41]
	v_lshl_add_u32 v36, v219, 8, v218
	v_mov_b64_e32 v[38:39], s[18:19]
	s_or_b64 exec, exec, s[40:41]
	v_ashrrev_i32_e32 v37, 31, v36
	v_lshlrev_b64 v[36:37], 13, v[36:37]
	v_lshl_add_u64 v[36:37], v[38:39], 0, v[36:37]
	v_lshl_add_u64 v[36:37], v[174:175], 2, v[36:37]
	global_load_dwordx4 v[40:43], v[36:37], off offset:576
	s_and_saveexec_b64 s[28:29], vcc
	s_xor_b64 s[40:41], exec, s[28:29]
	v_add3_u32 v36, v227, v221, s53
	s_or_saveexec_b64 s[40:41], s[40:41]
	v_mov_b64_e32 v[38:39], s[24:25]
	s_xor_b64 exec, exec, s[40:41]
	v_lshl_add_u32 v36, v222, 8, v221
	v_mov_b64_e32 v[38:39], s[18:19]
	s_or_b64 exec, exec, s[40:41]
	v_ashrrev_i32_e32 v37, 31, v36
	v_lshlrev_b64 v[36:37], 13, v[36:37]
	v_lshl_add_u64 v[36:37], v[38:39], 0, v[36:37]
	v_lshl_add_u64 v[36:37], v[174:175], 2, v[36:37]
	global_load_dwordx4 v[36:39], v[36:37], off offset:576
	s_and_saveexec_b64 s[28:29], s[16:17]
	s_xor_b64 s[16:17], exec, s[28:29]
	s_or_saveexec_b64 s[16:17], s[16:17]
	v_mov_b64_e32 v[68:69], s[24:25]
	s_xor_b64 exec, exec, s[16:17]
	v_mov_b64_e32 v[68:69], s[18:19]
	v_mov_b32_e32 v190, v191
	s_or_b64 exec, exec, s[16:17]
	v_ashrrev_i32_e32 v191, 31, v190
	s_waitcnt vmcnt(0)
	v_pk_fma_f32 v[28:29], v[28:29], v[32:33], v[64:65]
	v_lshlrev_b64 v[64:65], 13, v[190:191]
	v_lshl_add_u64 v[64:65], v[68:69], 0, v[64:65]
	v_pk_fma_f32 v[30:31], v[30:31], v[34:35], v[66:67]
	v_lshl_add_u64 v[64:65], v[174:175], 2, v[64:65]
	global_store_dwordx4 v[64:65], v[28:31], off offset:576
	s_and_saveexec_b64 s[16:17], s[14:15]
	s_xor_b64 s[14:15], exec, s[16:17]
	s_or_saveexec_b64 s[14:15], s[14:15]
	v_mov_b64_e32 v[28:29], s[24:25]
	s_xor_b64 exec, exec, s[14:15]
	v_mov_b64_e32 v[28:29], s[18:19]
	v_mov_b32_e32 v188, v189
	s_or_b64 exec, exec, s[14:15]
	v_ashrrev_i32_e32 v189, 31, v188
	v_lshlrev_b64 v[30:31], 13, v[188:189]
	v_lshl_add_u64 v[28:29], v[28:29], 0, v[30:31]
	v_pk_fma_f32 v[26:27], v[26:27], v[34:35], v[62:63]
	v_pk_fma_f32 v[24:25], v[24:25], v[32:33], v[60:61]
	v_lshl_add_u64 v[28:29], v[174:175], 2, v[28:29]
	global_store_dwordx4 v[28:29], v[24:27], off offset:576
	s_and_saveexec_b64 s[16:17], s[12:13]
	s_xor_b64 s[12:13], exec, s[16:17]
	s_mov_b64 s[14:15], s[24:25]
	s_or_saveexec_b64 s[12:13], s[12:13]
	v_mov_b64_e32 v[24:25], s[14:15]
	s_xor_b64 exec, exec, s[12:13]
	v_mov_b64_e32 v[24:25], s[18:19]
	v_mov_b32_e32 v186, v187
	s_or_b64 exec, exec, s[12:13]
	v_ashrrev_i32_e32 v187, 31, v186
	v_lshlrev_b64 v[26:27], 13, v[186:187]
	v_lshl_add_u64 v[24:25], v[24:25], 0, v[26:27]
	v_pk_fma_f32 v[22:23], v[22:23], v[34:35], v[58:59]
	v_pk_fma_f32 v[20:21], v[20:21], v[32:33], v[56:57]
	v_lshl_add_u64 v[24:25], v[174:175], 2, v[24:25]
	global_store_dwordx4 v[24:25], v[20:23], off offset:576
	s_and_saveexec_b64 s[14:15], s[10:11]
	s_xor_b64 s[10:11], exec, s[14:15]
	s_mov_b64 s[12:13], s[24:25]
	s_or_saveexec_b64 s[10:11], s[10:11]
	v_mov_b64_e32 v[20:21], s[12:13]
	s_xor_b64 exec, exec, s[10:11]
	v_mov_b64_e32 v[20:21], s[18:19]
	v_mov_b32_e32 v184, v185
	s_or_b64 exec, exec, s[10:11]
	v_ashrrev_i32_e32 v185, 31, v184
	v_lshlrev_b64 v[22:23], 13, v[184:185]
	v_lshl_add_u64 v[20:21], v[20:21], 0, v[22:23]
	v_pk_fma_f32 v[18:19], v[18:19], v[34:35], v[54:55]
	v_pk_fma_f32 v[16:17], v[16:17], v[32:33], v[52:53]
	v_lshl_add_u64 v[20:21], v[174:175], 2, v[20:21]
	global_store_dwordx4 v[20:21], v[16:19], off offset:576
	s_and_saveexec_b64 s[12:13], s[8:9]
	s_xor_b64 s[8:9], exec, s[12:13]
	s_mov_b64 s[10:11], s[24:25]
	s_or_saveexec_b64 s[8:9], s[8:9]
	v_mov_b64_e32 v[16:17], s[10:11]
	s_xor_b64 exec, exec, s[8:9]
	v_mov_b64_e32 v[16:17], s[18:19]
	v_mov_b32_e32 v182, v183
	s_or_b64 exec, exec, s[8:9]
	v_ashrrev_i32_e32 v183, 31, v182
	v_lshlrev_b64 v[18:19], 13, v[182:183]
	v_lshl_add_u64 v[16:17], v[16:17], 0, v[18:19]
	v_pk_fma_f32 v[14:15], v[14:15], v[34:35], v[50:51]
	v_pk_fma_f32 v[12:13], v[12:13], v[32:33], v[48:49]
	v_lshl_add_u64 v[16:17], v[174:175], 2, v[16:17]
	global_store_dwordx4 v[16:17], v[12:15], off offset:576
	s_and_saveexec_b64 s[10:11], s[6:7]
	s_xor_b64 s[6:7], exec, s[10:11]
	s_mov_b64 s[8:9], s[24:25]
	s_or_saveexec_b64 s[6:7], s[6:7]
	v_mov_b64_e32 v[12:13], s[8:9]
	s_xor_b64 exec, exec, s[6:7]
	v_mov_b64_e32 v[12:13], s[18:19]
	v_mov_b32_e32 v180, v181
	s_or_b64 exec, exec, s[6:7]
	v_ashrrev_i32_e32 v181, 31, v180
	v_lshlrev_b64 v[14:15], 13, v[180:181]
	v_lshl_add_u64 v[12:13], v[12:13], 0, v[14:15]
	v_pk_fma_f32 v[10:11], v[10:11], v[34:35], v[46:47]
	v_pk_fma_f32 v[8:9], v[8:9], v[32:33], v[44:45]
	v_lshl_add_u64 v[12:13], v[174:175], 2, v[12:13]
	global_store_dwordx4 v[12:13], v[8:11], off offset:576
	s_and_saveexec_b64 s[8:9], s[4:5]
	s_xor_b64 s[4:5], exec, s[8:9]
	s_mov_b64 s[6:7], s[24:25]
	s_or_saveexec_b64 s[4:5], s[4:5]
	v_mov_b64_e32 v[8:9], s[6:7]
	s_xor_b64 exec, exec, s[4:5]
	v_mov_b64_e32 v[8:9], s[18:19]
	v_mov_b32_e32 v178, v179
	s_or_b64 exec, exec, s[4:5]
	v_ashrrev_i32_e32 v179, 31, v178
	v_lshlrev_b64 v[10:11], 13, v[178:179]
	v_lshl_add_u64 v[8:9], v[8:9], 0, v[10:11]
	v_pk_fma_f32 v[6:7], v[6:7], v[34:35], v[42:43]
	v_pk_fma_f32 v[4:5], v[4:5], v[32:33], v[40:41]
	v_lshl_add_u64 v[8:9], v[174:175], 2, v[8:9]
	global_store_dwordx4 v[8:9], v[4:7], off offset:576
	s_and_saveexec_b64 s[6:7], vcc
	s_xor_b64 s[6:7], exec, s[6:7]
	s_mov_b64 s[4:5], s[24:25]
	s_or_saveexec_b64 s[6:7], s[6:7]
	v_mov_b64_e32 v[4:5], s[4:5]
	s_xor_b64 exec, exec, s[6:7]
	s_cbranch_execz .LBB0_3109
	v_mov_b64_e32 v[4:5], s[18:19]
	v_mov_b32_e32 v176, v177
	s_branch .LBB0_3109

; __global__ void __launch_bounds__(NTHR) fwd_megakernel(P p) {
	.amdhsa_kernel _Z14fwd_megakernel1P
		.amdhsa_group_segment_fixed_size 16
		.amdhsa_private_segment_fixed_size 0
		.amdhsa_kernarg_size 464
		.amdhsa_user_sgpr_count 2
		.amdhsa_user_sgpr_dispatch_ptr 0
		.amdhsa_user_sgpr_queue_ptr 0
		.amdhsa_user_sgpr_kernarg_segment_ptr 1
		.amdhsa_user_sgpr_dispatch_id 0
		.amdhsa_user_sgpr_kernarg_preload_length 0
		.amdhsa_user_sgpr_kernarg_preload_offset 0
		.amdhsa_user_sgpr_private_segment_size 0
		.amdhsa_uses_dynamic_stack 0
		.amdhsa_enable_private_segment 0
		.amdhsa_system_sgpr_workgroup_id_x 1
		.amdhsa_system_sgpr_workgroup_id_y 0
		.amdhsa_system_sgpr_workgroup_id_z 0
		.amdhsa_system_sgpr_workgroup_info 0
		.amdhsa_system_vgpr_workitem_id 2
		.amdhsa_next_free_vgpr 255
		.amdhsa_next_free_sgpr 98
		.amdhsa_accum_offset 256
		.amdhsa_reserve_vcc 1
		.amdhsa_float_round_mode_32 0
		.amdhsa_float_round_mode_16_64 0
		.amdhsa_float_denorm_mode_32 3
		.amdhsa_float_denorm_mode_16_64 3
		.amdhsa_dx10_clamp 1
		.amdhsa_ieee_mode 1
		.amdhsa_fp16_overflow 0
		.amdhsa_tg_split 0
		.amdhsa_exception_fp_ieee_invalid_op 0
		.amdhsa_exception_fp_denorm_src 0
		.amdhsa_exception_fp_ieee_div_zero 0
		.amdhsa_exception_fp_ieee_overflow 0
		.amdhsa_exception_fp_ieee_underflow 0
		.amdhsa_exception_fp_ieee_inexact 0
		.amdhsa_exception_int_div_zero 0
	.end_amdhsa_kernel

; __global__ void __launch_bounds__(NTHR) fwd_megakernel(P p) {
amdhsa.kernels:
  - .agpr_count:     0
    .args:
      - .offset:         0
        .size:           208
        .value_kind:     by_value
      - .offset:         208
        .size:           4
        .value_kind:     hidden_block_count_x
      - .offset:         212
        .size:           4
        .value_kind:     hidden_block_count_y
      - .offset:         216
        .size:           4
        .value_kind:     hidden_block_count_z
      - .offset:         220
        .size:           2
        .value_kind:     hidden_group_size_x
      - .offset:         222
        .size:           2
        .value_kind:     hidden_group_size_y
      - .offset:         224
        .size:           2
        .value_kind:     hidden_group_size_z
      - .offset:         226
        .size:           2
        .value_kind:     hidden_remainder_x
      - .offset:         228
        .size:           2
        .value_kind:     hidden_remainder_y
      - .offset:         230
        .size:           2
        .value_kind:     hidden_remainder_z
      - .offset:         248
        .size:           8
        .value_kind:     hidden_global_offset_x
      - .offset:         256
        .size:           8
        .value_kind:     hidden_global_offset_y
      - .offset:         264
        .size:           8
        .value_kind:     hidden_global_offset_z
      - .offset:         272
        .size:           2
        .value_kind:     hidden_grid_dims
      - .offset:         296
        .size:           8
        .value_kind:     hidden_multigrid_sync_arg
      - .offset:         328
        .size:           4
        .value_kind:     hidden_dynamic_lds_size
    .group_segment_fixed_size: 16
    .kernarg_segment_align: 8
    .kernarg_segment_size: 464
    .language:       OpenCL C
    .language_version:
      - 2
      - 0
    .max_flat_workgroup_size: 512
    .name:           _Z14fwd_megakernel1P
    .private_segment_fixed_size: 0
    .sgpr_count:     104
    .sgpr_spill_count: 16
    .symbol:         _Z14fwd_megakernel1P.kd
    .uniform_work_group_size: 1
    .uses_dynamic_stack: false
    .vgpr_count:     255
    .vgpr_spill_count: 0
    .wavefront_size: 64
